# MFMA block hand-off with priority staging: closing barrier issued 2 MFMAs early; finishing wave runs its last pair at prio 1 after the barrier while the partner runs its first pair at prio 0 (s_setpri
# speedup vs baseline: 1.0144x; 1.0116x over previous
.LBB0_183:
	s_ashr_i32 s13, s12, 31
	s_lshl_b64 s[24:25], s[12:13], 19
	s_add_u32 s24, s80, s24
	s_addc_u32 s25, s81, s25
	s_and_b64 s[30:31], s[4:5], exec
	s_cselect_b32 s13, s25, s45
	s_cselect_b32 s66, s24, s44
	s_ashr_i32 s11, s10, 31
	s_lshl_b64 s[30:31], s[10:11], 19
	s_add_u32 s30, s52, s30
	s_addc_u32 s31, s53, s31
	s_and_b64 s[48:49], s[4:5], exec
	s_cselect_b32 s11, s31, s47
	s_cselect_b32 s67, s30, s46
	s_add_u32 s44, s44, 0x40080
	s_addc_u32 s45, s45, 0
	s_add_u32 s68, s46, 0x100
	s_addc_u32 s69, s47, 0
	s_mov_b32 s70, -2
	ds_read_b128 v[140:143], v147
	ds_read_b128 v[150:153], v147 offset:1024
	ds_read_b128 v[154:157], v147 offset:2048
	ds_read_b128 v[158:161], v147 offset:3072
	ds_read_b128 v[162:165], v148
	ds_read_b128 v[166:169], v148 offset:1024
	ds_read_b128 v[170:173], v148 offset:2048
	ds_read_b128 v[174:177], v148 offset:3072
	s_add_u32 s18, s44, 0xfffc0080
	s_addc_u32 s19, s45, -1
	s_cmp_eq_u32 s70, 12
	s_cselect_b32 s49, s13, s19
	s_cselect_b32 s48, s66, s18
	s_cselect_b32 s47, s11, s69
	s_cselect_b32 s46, s67, s68
	v_lshl_add_u64 v[178:179], s[44:45], 0, v[132:133]
	s_add_i32 m0, s37, 0xc000
	ds_read_b128 v[184:187], v149
	ds_read_b128 v[188:191], v149 offset:1024
	ds_read_b128 v[192:195], v149 offset:2048
	ds_read_b128 v[196:199], v149 offset:3072
	ds_read_b128 v[200:203], v149 offset:4096
	ds_read_b128 v[204:207], v149 offset:5120
	ds_read_b128 v[208:211], v149 offset:6144
	ds_read_b128 v[212:215], v149 offset:7168
	global_load_lds_dwordx4 v[178:179], off
	v_lshl_add_u64 v[178:179], s[44:45], 0, v[134:135]
	s_add_i32 m0, s37, 0xe000
	s_nop 0
	global_load_lds_dwordx4 v[178:179], off
	s_waitcnt vmcnt(8)
	s_waitcnt lgkmcnt(0)
	s_barrier
	s_waitcnt lgkmcnt(0)
	v_mfma_f32_16x16x32_bf16 v[124:127], v[140:143], v[184:187], 0
	v_mfma_f32_16x16x32_bf16 v[124:127], v[150:153], v[188:191], v[124:127]
	s_setprio 1
	v_mfma_f32_16x16x32_bf16 v[120:123], v[154:157], v[184:187], 0
	v_mfma_f32_16x16x32_bf16 v[120:123], v[158:161], v[188:191], v[120:123]
	v_mfma_f32_16x16x32_bf16 v[108:111], v[140:143], v[192:195], 0
	v_mfma_f32_16x16x32_bf16 v[108:111], v[150:153], v[196:199], v[108:111]
	v_mfma_f32_16x16x32_bf16 v[104:107], v[154:157], v[192:195], 0
	v_mfma_f32_16x16x32_bf16 v[104:107], v[158:161], v[196:199], v[104:107]
	v_mfma_f32_16x16x32_bf16 v[92:95], v[140:143], v[200:203], 0
	v_mfma_f32_16x16x32_bf16 v[92:95], v[150:153], v[204:207], v[92:95]
	v_mfma_f32_16x16x32_bf16 v[88:91], v[154:157], v[200:203], 0
	v_mfma_f32_16x16x32_bf16 v[88:91], v[158:161], v[204:207], v[88:91]
	v_mfma_f32_16x16x32_bf16 v[76:79], v[140:143], v[208:211], 0
	v_mfma_f32_16x16x32_bf16 v[76:79], v[150:153], v[212:215], v[76:79]
	v_mfma_f32_16x16x32_bf16 v[72:75], v[154:157], v[208:211], 0
	v_mfma_f32_16x16x32_bf16 v[72:75], v[158:161], v[212:215], v[72:75]
	v_mfma_f32_16x16x32_bf16 v[116:119], v[162:165], v[184:187], 0
	v_mfma_f32_16x16x32_bf16 v[116:119], v[166:169], v[188:191], v[116:119]
	v_mfma_f32_16x16x32_bf16 v[112:115], v[170:173], v[184:187], 0
	v_mfma_f32_16x16x32_bf16 v[112:115], v[174:177], v[188:191], v[112:115]
	v_mfma_f32_16x16x32_bf16 v[100:103], v[162:165], v[192:195], 0
	v_mfma_f32_16x16x32_bf16 v[100:103], v[166:169], v[196:199], v[100:103]
	v_mfma_f32_16x16x32_bf16 v[96:99], v[170:173], v[192:195], 0
	v_mfma_f32_16x16x32_bf16 v[96:99], v[174:177], v[196:199], v[96:99]
	v_mfma_f32_16x16x32_bf16 v[84:87], v[162:165], v[200:203], 0
	v_mfma_f32_16x16x32_bf16 v[84:87], v[166:169], v[204:207], v[84:87]
	v_mfma_f32_16x16x32_bf16 v[80:83], v[170:173], v[200:203], 0
	v_mfma_f32_16x16x32_bf16 v[80:83], v[174:177], v[204:207], v[80:83]
	v_mfma_f32_16x16x32_bf16 v[68:71], v[162:165], v[208:211], 0
	v_mfma_f32_16x16x32_bf16 v[68:71], v[166:169], v[212:215], v[68:71]
	s_barrier
	v_mfma_f32_16x16x32_bf16 v[64:67], v[170:173], v[208:211], 0
	v_mfma_f32_16x16x32_bf16 v[64:67], v[174:177], v[212:215], v[64:67]
	s_setprio 0
	s_add_i32 s18, s62, s54
	v_lshl_add_u64 v[178:179], s[46:47], 0, v[130:131]
	s_mov_b32 m0, s18
	ds_read_b128 v[184:187], v149 offset:16384
	ds_read_b128 v[188:191], v149 offset:17408
	ds_read_b128 v[192:195], v149 offset:18432
	ds_read_b128 v[196:199], v149 offset:19456
	ds_read_b128 v[200:203], v149 offset:20480
	ds_read_b128 v[204:207], v149 offset:21504
	ds_read_b128 v[208:211], v149 offset:22528
	ds_read_b128 v[212:215], v149 offset:23552
	global_load_lds_dwordx4 v[178:179], off
	s_add_i32 m0, s18, 0x2000
	s_add_u32 s72, s46, 0x40000
	v_lshl_add_u64 v[216:217], s[46:47], 0, v[128:129]
	s_addc_u32 s73, s47, 0
	s_add_i32 s18, s63, s54
	global_load_lds_dwordx4 v[216:217], off
	v_lshl_add_u64 v[218:219], s[72:73], 0, v[130:131]
	s_mov_b32 m0, s18
	v_lshl_add_u64 v[220:221], s[48:49], 0, v[128:129]
	global_load_lds_dwordx4 v[218:219], off
	v_lshl_add_u64 v[218:219], s[72:73], 0, v[128:129]
	s_add_i32 m0, s18, 0x2000
	s_nop 0
	global_load_lds_dwordx4 v[218:219], off
	v_lshl_add_u64 v[218:219], s[48:49], 0, v[130:131]
	s_mov_b32 m0, s37
	s_nop 0
	global_load_lds_dwordx4 v[218:219], off
	s_mov_b32 m0, s56
	s_nop 0
	global_load_lds_dwordx4 v[220:221], off
	s_waitcnt vmcnt(8)
	s_waitcnt lgkmcnt(0)
	s_barrier
	s_waitcnt lgkmcnt(0)
	v_mfma_f32_16x16x32_bf16 v[60:63], v[140:143], v[184:187], 0
	v_mfma_f32_16x16x32_bf16 v[60:63], v[150:153], v[188:191], v[60:63]
	s_setprio 1
	v_mfma_f32_16x16x32_bf16 v[56:59], v[154:157], v[184:187], 0
	v_mfma_f32_16x16x32_bf16 v[56:59], v[158:161], v[188:191], v[56:59]
	v_mfma_f32_16x16x32_bf16 v[44:47], v[140:143], v[192:195], 0
	v_mfma_f32_16x16x32_bf16 v[44:47], v[150:153], v[196:199], v[44:47]
	v_mfma_f32_16x16x32_bf16 v[40:43], v[154:157], v[192:195], 0
	v_mfma_f32_16x16x32_bf16 v[40:43], v[158:161], v[196:199], v[40:43]
	v_mfma_f32_16x16x32_bf16 v[28:31], v[140:143], v[200:203], 0
	v_mfma_f32_16x16x32_bf16 v[28:31], v[150:153], v[204:207], v[28:31]
	v_mfma_f32_16x16x32_bf16 v[24:27], v[154:157], v[200:203], 0
	v_mfma_f32_16x16x32_bf16 v[24:27], v[158:161], v[204:207], v[24:27]
	v_mfma_f32_16x16x32_bf16 v[12:15], v[140:143], v[208:211], 0
	v_mfma_f32_16x16x32_bf16 v[12:15], v[150:153], v[212:215], v[12:15]
	v_mfma_f32_16x16x32_bf16 v[8:11], v[154:157], v[208:211], 0
	v_mfma_f32_16x16x32_bf16 v[8:11], v[158:161], v[212:215], v[8:11]
	v_mfma_f32_16x16x32_bf16 v[52:55], v[162:165], v[184:187], 0
	v_mfma_f32_16x16x32_bf16 v[52:55], v[166:169], v[188:191], v[52:55]
	v_mfma_f32_16x16x32_bf16 v[48:51], v[170:173], v[184:187], 0
	v_mfma_f32_16x16x32_bf16 v[48:51], v[174:177], v[188:191], v[48:51]
	v_mfma_f32_16x16x32_bf16 v[36:39], v[162:165], v[192:195], 0
	v_mfma_f32_16x16x32_bf16 v[36:39], v[166:169], v[196:199], v[36:39]
	v_mfma_f32_16x16x32_bf16 v[32:35], v[170:173], v[192:195], 0
	v_mfma_f32_16x16x32_bf16 v[32:35], v[174:177], v[196:199], v[32:35]
	v_mfma_f32_16x16x32_bf16 v[20:23], v[162:165], v[200:203], 0
	v_mfma_f32_16x16x32_bf16 v[20:23], v[166:169], v[204:207], v[20:23]
	v_mfma_f32_16x16x32_bf16 v[16:19], v[170:173], v[200:203], 0
	v_mfma_f32_16x16x32_bf16 v[16:19], v[174:177], v[204:207], v[16:19]
	v_mfma_f32_16x16x32_bf16 v[4:7], v[162:165], v[208:211], 0
	v_mfma_f32_16x16x32_bf16 v[4:7], v[166:169], v[212:215], v[4:7]
	s_barrier
	v_mfma_f32_16x16x32_bf16 v[0:3], v[170:173], v[208:211], 0
	v_mfma_f32_16x16x32_bf16 v[0:3], v[174:177], v[212:215], v[0:3]
	s_setprio 0
	s_branch .Lmid_gemm0
.LBB0_184:
	ds_read_b128 v[140:143], v147
	ds_read_b128 v[150:153], v147 offset:1024
	ds_read_b128 v[154:157], v147 offset:2048
	ds_read_b128 v[158:161], v147 offset:3072
	ds_read_b128 v[162:165], v148
	ds_read_b128 v[166:169], v148 offset:1024
	ds_read_b128 v[170:173], v148 offset:2048
	ds_read_b128 v[174:177], v148 offset:3072
	s_add_u32 s18, s44, 0xfffc0080
	s_addc_u32 s19, s45, -1
	s_cmp_eq_u32 s70, 12
	s_cselect_b32 s49, s13, s19
	s_cselect_b32 s48, s66, s18
	s_cselect_b32 s47, s11, s69
	s_cselect_b32 s46, s67, s68
	v_lshl_add_u64 v[178:179], s[44:45], 0, v[132:133]
	s_add_i32 m0, s37, 0xc000
	ds_read_b128 v[184:187], v149
	ds_read_b128 v[188:191], v149 offset:1024
	ds_read_b128 v[192:195], v149 offset:2048
	ds_read_b128 v[196:199], v149 offset:3072
	ds_read_b128 v[200:203], v149 offset:4096
	ds_read_b128 v[204:207], v149 offset:5120
	ds_read_b128 v[208:211], v149 offset:6144
	ds_read_b128 v[212:215], v149 offset:7168
	global_load_lds_dwordx4 v[178:179], off
	v_lshl_add_u64 v[178:179], s[44:45], 0, v[134:135]
	s_add_i32 m0, s37, 0xe000
	s_nop 0
	global_load_lds_dwordx4 v[178:179], off
	s_waitcnt vmcnt(8)
	s_waitcnt lgkmcnt(0)
	s_barrier
	s_waitcnt lgkmcnt(0)
	v_mfma_f32_16x16x32_bf16 v[124:127], v[140:143], v[184:187], v[124:127]
	v_mfma_f32_16x16x32_bf16 v[124:127], v[150:153], v[188:191], v[124:127]
	s_setprio 1
	v_mfma_f32_16x16x32_bf16 v[120:123], v[154:157], v[184:187], v[120:123]
	v_mfma_f32_16x16x32_bf16 v[120:123], v[158:161], v[188:191], v[120:123]
	v_mfma_f32_16x16x32_bf16 v[108:111], v[140:143], v[192:195], v[108:111]
	v_mfma_f32_16x16x32_bf16 v[108:111], v[150:153], v[196:199], v[108:111]
	v_mfma_f32_16x16x32_bf16 v[104:107], v[154:157], v[192:195], v[104:107]
	v_mfma_f32_16x16x32_bf16 v[104:107], v[158:161], v[196:199], v[104:107]
	v_mfma_f32_16x16x32_bf16 v[92:95], v[140:143], v[200:203], v[92:95]
	v_mfma_f32_16x16x32_bf16 v[92:95], v[150:153], v[204:207], v[92:95]
	v_mfma_f32_16x16x32_bf16 v[88:91], v[154:157], v[200:203], v[88:91]
	v_mfma_f32_16x16x32_bf16 v[88:91], v[158:161], v[204:207], v[88:91]
	v_mfma_f32_16x16x32_bf16 v[76:79], v[140:143], v[208:211], v[76:79]
	v_mfma_f32_16x16x32_bf16 v[76:79], v[150:153], v[212:215], v[76:79]
	v_mfma_f32_16x16x32_bf16 v[72:75], v[154:157], v[208:211], v[72:75]
	v_mfma_f32_16x16x32_bf16 v[72:75], v[158:161], v[212:215], v[72:75]
	v_mfma_f32_16x16x32_bf16 v[116:119], v[162:165], v[184:187], v[116:119]
	v_mfma_f32_16x16x32_bf16 v[116:119], v[166:169], v[188:191], v[116:119]
	v_mfma_f32_16x16x32_bf16 v[112:115], v[170:173], v[184:187], v[112:115]
	v_mfma_f32_16x16x32_bf16 v[112:115], v[174:177], v[188:191], v[112:115]
	v_mfma_f32_16x16x32_bf16 v[100:103], v[162:165], v[192:195], v[100:103]
	v_mfma_f32_16x16x32_bf16 v[100:103], v[166:169], v[196:199], v[100:103]
	v_mfma_f32_16x16x32_bf16 v[96:99], v[170:173], v[192:195], v[96:99]
	v_mfma_f32_16x16x32_bf16 v[96:99], v[174:177], v[196:199], v[96:99]
	v_mfma_f32_16x16x32_bf16 v[84:87], v[162:165], v[200:203], v[84:87]
	v_mfma_f32_16x16x32_bf16 v[84:87], v[166:169], v[204:207], v[84:87]
	v_mfma_f32_16x16x32_bf16 v[80:83], v[170:173], v[200:203], v[80:83]
	v_mfma_f32_16x16x32_bf16 v[80:83], v[174:177], v[204:207], v[80:83]
	v_mfma_f32_16x16x32_bf16 v[68:71], v[162:165], v[208:211], v[68:71]
	v_mfma_f32_16x16x32_bf16 v[68:71], v[166:169], v[212:215], v[68:71]
	s_barrier
	v_mfma_f32_16x16x32_bf16 v[64:67], v[170:173], v[208:211], v[64:67]
	v_mfma_f32_16x16x32_bf16 v[64:67], v[174:177], v[212:215], v[64:67]
	s_setprio 0
	s_add_i32 s18, s62, s54
	v_lshl_add_u64 v[178:179], s[46:47], 0, v[130:131]
	s_mov_b32 m0, s18
	ds_read_b128 v[184:187], v149 offset:16384
	ds_read_b128 v[188:191], v149 offset:17408
	ds_read_b128 v[192:195], v149 offset:18432
	ds_read_b128 v[196:199], v149 offset:19456
	ds_read_b128 v[200:203], v149 offset:20480
	ds_read_b128 v[204:207], v149 offset:21504
	ds_read_b128 v[208:211], v149 offset:22528
	ds_read_b128 v[212:215], v149 offset:23552
	global_load_lds_dwordx4 v[178:179], off
	s_add_i32 m0, s18, 0x2000
	s_add_u32 s72, s46, 0x40000
	v_lshl_add_u64 v[216:217], s[46:47], 0, v[128:129]
	s_addc_u32 s73, s47, 0
	s_add_i32 s18, s63, s54
	global_load_lds_dwordx4 v[216:217], off
	v_lshl_add_u64 v[218:219], s[72:73], 0, v[130:131]
	s_mov_b32 m0, s18
	v_lshl_add_u64 v[220:221], s[48:49], 0, v[128:129]
	global_load_lds_dwordx4 v[218:219], off
	v_lshl_add_u64 v[218:219], s[72:73], 0, v[128:129]
	s_add_i32 m0, s18, 0x2000
	s_nop 0
	global_load_lds_dwordx4 v[218:219], off
	v_lshl_add_u64 v[218:219], s[48:49], 0, v[130:131]
	s_mov_b32 m0, s37
	s_nop 0
	global_load_lds_dwordx4 v[218:219], off
	s_mov_b32 m0, s56
	s_nop 0
	global_load_lds_dwordx4 v[220:221], off
	s_waitcnt vmcnt(8)
	s_waitcnt lgkmcnt(0)
	s_barrier
	s_waitcnt lgkmcnt(0)
	v_mfma_f32_16x16x32_bf16 v[60:63], v[140:143], v[184:187], v[60:63]
	v_mfma_f32_16x16x32_bf16 v[60:63], v[150:153], v[188:191], v[60:63]
	s_setprio 1
	v_mfma_f32_16x16x32_bf16 v[56:59], v[154:157], v[184:187], v[56:59]
	v_mfma_f32_16x16x32_bf16 v[56:59], v[158:161], v[188:191], v[56:59]
	v_mfma_f32_16x16x32_bf16 v[44:47], v[140:143], v[192:195], v[44:47]
	v_mfma_f32_16x16x32_bf16 v[44:47], v[150:153], v[196:199], v[44:47]
	v_mfma_f32_16x16x32_bf16 v[40:43], v[154:157], v[192:195], v[40:43]
	v_mfma_f32_16x16x32_bf16 v[40:43], v[158:161], v[196:199], v[40:43]
	v_mfma_f32_16x16x32_bf16 v[28:31], v[140:143], v[200:203], v[28:31]
	v_mfma_f32_16x16x32_bf16 v[28:31], v[150:153], v[204:207], v[28:31]
	v_mfma_f32_16x16x32_bf16 v[24:27], v[154:157], v[200:203], v[24:27]
	v_mfma_f32_16x16x32_bf16 v[24:27], v[158:161], v[204:207], v[24:27]
	v_mfma_f32_16x16x32_bf16 v[12:15], v[140:143], v[208:211], v[12:15]
	v_mfma_f32_16x16x32_bf16 v[12:15], v[150:153], v[212:215], v[12:15]
	v_mfma_f32_16x16x32_bf16 v[8:11], v[154:157], v[208:211], v[8:11]
	v_mfma_f32_16x16x32_bf16 v[8:11], v[158:161], v[212:215], v[8:11]
	v_mfma_f32_16x16x32_bf16 v[52:55], v[162:165], v[184:187], v[52:55]
	v_mfma_f32_16x16x32_bf16 v[52:55], v[166:169], v[188:191], v[52:55]
	v_mfma_f32_16x16x32_bf16 v[48:51], v[170:173], v[184:187], v[48:51]
	v_mfma_f32_16x16x32_bf16 v[48:51], v[174:177], v[188:191], v[48:51]
	v_mfma_f32_16x16x32_bf16 v[36:39], v[162:165], v[192:195], v[36:39]
	v_mfma_f32_16x16x32_bf16 v[36:39], v[166:169], v[196:199], v[36:39]
	v_mfma_f32_16x16x32_bf16 v[32:35], v[170:173], v[192:195], v[32:35]
	v_mfma_f32_16x16x32_bf16 v[32:35], v[174:177], v[196:199], v[32:35]
	v_mfma_f32_16x16x32_bf16 v[20:23], v[162:165], v[200:203], v[20:23]
	v_mfma_f32_16x16x32_bf16 v[20:23], v[166:169], v[204:207], v[20:23]
	v_mfma_f32_16x16x32_bf16 v[16:19], v[170:173], v[200:203], v[16:19]
	v_mfma_f32_16x16x32_bf16 v[16:19], v[174:177], v[204:207], v[16:19]
	v_mfma_f32_16x16x32_bf16 v[4:7], v[162:165], v[208:211], v[4:7]
	v_mfma_f32_16x16x32_bf16 v[4:7], v[166:169], v[212:215], v[4:7]
	s_barrier
	v_mfma_f32_16x16x32_bf16 v[0:3], v[170:173], v[208:211], v[0:3]
	v_mfma_f32_16x16x32_bf16 v[0:3], v[174:177], v[212:215], v[0:3]
	s_setprio 0
.Lmid_gemm0:
	s_add_i32 s18, 0, 0x18000
	s_add_i32 s19, 0, 0x1c000
	v_add_u32_e32 v158, s18, v145
	v_add_u32_e32 v174, s19, v145
	ds_read_b128 v[140:143], v158
	ds_read_b128 v[150:153], v158 offset:1024
	ds_read_b128 v[154:157], v158 offset:2048
	ds_read_b128 v[158:161], v158 offset:3072
	ds_read_b128 v[162:165], v174
	ds_read_b128 v[166:169], v174 offset:1024
	ds_read_b128 v[170:173], v174 offset:2048
	ds_read_b128 v[174:177], v174 offset:3072
	s_add_u32 s48, s48, 0x40000
	s_addc_u32 s49, s49, 0
	s_mov_b32 m0, s57
	v_lshl_add_u64 v[222:223], s[48:49], 0, v[130:131]
	ds_read_b128 v[184:187], v149 offset:32768
	ds_read_b128 v[188:191], v149 offset:33792
	ds_read_b128 v[192:195], v149 offset:34816
	ds_read_b128 v[196:199], v149 offset:35840
	ds_read_b128 v[200:203], v149 offset:36864
	ds_read_b128 v[204:207], v149 offset:37888
	ds_read_b128 v[208:211], v149 offset:38912
	ds_read_b128 v[212:215], v149 offset:39936
	global_load_lds_dwordx4 v[222:223], off
	v_lshl_add_u64 v[222:223], s[48:49], 0, v[128:129]
	s_mov_b32 m0, s58
	s_nop 0
	global_load_lds_dwordx4 v[222:223], off
	s_waitcnt vmcnt(8)
	s_waitcnt lgkmcnt(0)
	s_barrier
	s_waitcnt lgkmcnt(0)
	v_mfma_f32_16x16x32_bf16 v[124:127], v[140:143], v[184:187], v[124:127]
	v_mfma_f32_16x16x32_bf16 v[124:127], v[150:153], v[188:191], v[124:127]
	s_setprio 1
	v_mfma_f32_16x16x32_bf16 v[120:123], v[154:157], v[184:187], v[120:123]
	v_mfma_f32_16x16x32_bf16 v[120:123], v[158:161], v[188:191], v[120:123]
	v_mfma_f32_16x16x32_bf16 v[108:111], v[140:143], v[192:195], v[108:111]
	v_mfma_f32_16x16x32_bf16 v[108:111], v[150:153], v[196:199], v[108:111]
	v_mfma_f32_16x16x32_bf16 v[104:107], v[154:157], v[192:195], v[104:107]
	v_mfma_f32_16x16x32_bf16 v[104:107], v[158:161], v[196:199], v[104:107]
	v_mfma_f32_16x16x32_bf16 v[92:95], v[140:143], v[200:203], v[92:95]
	v_mfma_f32_16x16x32_bf16 v[92:95], v[150:153], v[204:207], v[92:95]
	v_mfma_f32_16x16x32_bf16 v[88:91], v[154:157], v[200:203], v[88:91]
	v_mfma_f32_16x16x32_bf16 v[88:91], v[158:161], v[204:207], v[88:91]
	v_mfma_f32_16x16x32_bf16 v[76:79], v[140:143], v[208:211], v[76:79]
	v_mfma_f32_16x16x32_bf16 v[76:79], v[150:153], v[212:215], v[76:79]
	v_mfma_f32_16x16x32_bf16 v[72:75], v[154:157], v[208:211], v[72:75]
	v_mfma_f32_16x16x32_bf16 v[72:75], v[158:161], v[212:215], v[72:75]
	v_mfma_f32_16x16x32_bf16 v[116:119], v[162:165], v[184:187], v[116:119]
	v_mfma_f32_16x16x32_bf16 v[116:119], v[166:169], v[188:191], v[116:119]
	v_mfma_f32_16x16x32_bf16 v[112:115], v[170:173], v[184:187], v[112:115]
	v_mfma_f32_16x16x32_bf16 v[112:115], v[174:177], v[188:191], v[112:115]
	v_mfma_f32_16x16x32_bf16 v[100:103], v[162:165], v[192:195], v[100:103]
	v_mfma_f32_16x16x32_bf16 v[100:103], v[166:169], v[196:199], v[100:103]
	v_mfma_f32_16x16x32_bf16 v[96:99], v[170:173], v[192:195], v[96:99]
	v_mfma_f32_16x16x32_bf16 v[96:99], v[174:177], v[196:199], v[96:99]
	v_mfma_f32_16x16x32_bf16 v[84:87], v[162:165], v[200:203], v[84:87]
	v_mfma_f32_16x16x32_bf16 v[84:87], v[166:169], v[204:207], v[84:87]
	v_mfma_f32_16x16x32_bf16 v[80:83], v[170:173], v[200:203], v[80:83]
	v_mfma_f32_16x16x32_bf16 v[80:83], v[174:177], v[204:207], v[80:83]
	v_mfma_f32_16x16x32_bf16 v[68:71], v[162:165], v[208:211], v[68:71]
	v_mfma_f32_16x16x32_bf16 v[68:71], v[166:169], v[212:215], v[68:71]
	s_barrier
	v_mfma_f32_16x16x32_bf16 v[64:67], v[170:173], v[208:211], v[64:67]
	v_mfma_f32_16x16x32_bf16 v[64:67], v[174:177], v[212:215], v[64:67]
	s_setprio 0
	s_add_i32 s18, s18, s54
	v_lshl_add_u64 v[178:179], v[178:179], 0, s[6:7]
	s_mov_b32 m0, s18
	ds_read_b128 v[184:187], v149 offset:49152
	ds_read_b128 v[188:191], v149 offset:50176
	ds_read_b128 v[192:195], v149 offset:51200
	ds_read_b128 v[196:199], v149 offset:52224
	ds_read_b128 v[200:203], v149 offset:53248
	ds_read_b128 v[204:207], v149 offset:54272
	ds_read_b128 v[208:211], v149 offset:55296
	ds_read_b128 v[212:215], v149 offset:56320
	global_load_lds_dwordx4 v[178:179], off
	s_add_i32 m0, s18, 0x2000
	s_add_u32 s46, s46, 0x40080
	v_lshl_add_u64 v[178:179], v[216:217], 0, s[6:7]
	s_addc_u32 s47, s47, 0
	s_add_i32 s18, s19, s54
	global_load_lds_dwordx4 v[178:179], off
	v_lshl_add_u64 v[178:179], s[46:47], 0, v[130:131]
	s_mov_b32 m0, s18
	s_nop 0
	global_load_lds_dwordx4 v[178:179], off
	v_lshl_add_u64 v[178:179], s[46:47], 0, v[128:129]
	s_add_i32 m0, s18, 0x2000
	s_nop 0
	global_load_lds_dwordx4 v[178:179], off
	v_lshl_add_u64 v[178:179], v[218:219], 0, s[6:7]
	s_mov_b32 m0, s60
	s_nop 0
	global_load_lds_dwordx4 v[178:179], off
	v_lshl_add_u64 v[178:179], v[220:221], 0, s[6:7]
	s_mov_b32 m0, s61
	s_nop 0
	global_load_lds_dwordx4 v[178:179], off
	s_waitcnt vmcnt(8)
	s_waitcnt lgkmcnt(0)
	s_barrier
	s_waitcnt lgkmcnt(0)
	v_mfma_f32_16x16x32_bf16 v[60:63], v[140:143], v[184:187], v[60:63]
	v_mfma_f32_16x16x32_bf16 v[60:63], v[150:153], v[188:191], v[60:63]
	s_setprio 1
	v_mfma_f32_16x16x32_bf16 v[56:59], v[154:157], v[184:187], v[56:59]
	v_mfma_f32_16x16x32_bf16 v[56:59], v[158:161], v[188:191], v[56:59]
	v_mfma_f32_16x16x32_bf16 v[44:47], v[140:143], v[192:195], v[44:47]
	v_mfma_f32_16x16x32_bf16 v[44:47], v[150:153], v[196:199], v[44:47]
	v_mfma_f32_16x16x32_bf16 v[40:43], v[154:157], v[192:195], v[40:43]
	v_mfma_f32_16x16x32_bf16 v[40:43], v[158:161], v[196:199], v[40:43]
	v_mfma_f32_16x16x32_bf16 v[28:31], v[140:143], v[200:203], v[28:31]
	v_mfma_f32_16x16x32_bf16 v[28:31], v[150:153], v[204:207], v[28:31]
	v_mfma_f32_16x16x32_bf16 v[24:27], v[154:157], v[200:203], v[24:27]
	v_mfma_f32_16x16x32_bf16 v[24:27], v[158:161], v[204:207], v[24:27]
	v_mfma_f32_16x16x32_bf16 v[12:15], v[140:143], v[208:211], v[12:15]
	v_mfma_f32_16x16x32_bf16 v[12:15], v[150:153], v[212:215], v[12:15]
	v_mfma_f32_16x16x32_bf16 v[8:11], v[154:157], v[208:211], v[8:11]
	v_mfma_f32_16x16x32_bf16 v[8:11], v[158:161], v[212:215], v[8:11]
	v_mfma_f32_16x16x32_bf16 v[52:55], v[162:165], v[184:187], v[52:55]
	v_mfma_f32_16x16x32_bf16 v[52:55], v[166:169], v[188:191], v[52:55]
	v_mfma_f32_16x16x32_bf16 v[48:51], v[170:173], v[184:187], v[48:51]
	v_mfma_f32_16x16x32_bf16 v[48:51], v[174:177], v[188:191], v[48:51]
	v_mfma_f32_16x16x32_bf16 v[36:39], v[162:165], v[192:195], v[36:39]
	v_mfma_f32_16x16x32_bf16 v[36:39], v[166:169], v[196:199], v[36:39]
	v_mfma_f32_16x16x32_bf16 v[32:35], v[170:173], v[192:195], v[32:35]
	v_mfma_f32_16x16x32_bf16 v[32:35], v[174:177], v[196:199], v[32:35]
	v_mfma_f32_16x16x32_bf16 v[20:23], v[162:165], v[200:203], v[20:23]
	v_mfma_f32_16x16x32_bf16 v[20:23], v[166:169], v[204:207], v[20:23]
	v_mfma_f32_16x16x32_bf16 v[16:19], v[170:173], v[200:203], v[16:19]
	v_mfma_f32_16x16x32_bf16 v[16:19], v[174:177], v[204:207], v[16:19]
	v_mfma_f32_16x16x32_bf16 v[4:7], v[162:165], v[208:211], v[4:7]
	v_mfma_f32_16x16x32_bf16 v[4:7], v[166:169], v[212:215], v[4:7]
	s_barrier
	v_mfma_f32_16x16x32_bf16 v[0:3], v[170:173], v[208:211], v[0:3]
	v_mfma_f32_16x16x32_bf16 v[0:3], v[174:177], v[212:215], v[0:3]
	s_setprio 0
	s_add_i32 s70, s70, 2
	s_add_u32 s44, s44, 0x100
	s_addc_u32 s45, s45, 0
	s_add_u32 s68, s68, 0x100
	s_addc_u32 s69, s69, 0
	s_cmp_gt_u32 s70, 13
	s_cbranch_scc0 .LBB0_184
	s_and_b64 vcc, exec, s[8:9]
	s_cbranch_vccz .LBB0_187
	s_barrier

.LBB0_263:
	s_add_u32 s84, s54, 0x100
	s_addc_u32 s85, s55, 0
	s_mov_b32 s86, -2
	ds_read_b128 v[152:155], v149
	ds_read_b128 v[156:159], v149 offset:1024
	ds_read_b128 v[160:163], v149 offset:2048
	ds_read_b128 v[164:167], v149 offset:3072
	ds_read_b128 v[168:171], v150
	ds_read_b128 v[172:175], v150 offset:1024
	ds_read_b128 v[176:179], v150 offset:2048
	ds_read_b128 v[184:187], v150 offset:3072
	s_add_u32 s54, s52, 0x100
	s_addc_u32 s55, s53, 0
	s_cmp_eq_u32 s86, 40
	s_cselect_b32 s59, s7, s55
	s_cselect_b32 s58, s6, s54
	s_cselect_b32 s57, s49, s85
	s_cselect_b32 s56, s48, s84
	v_lshl_add_u64 v[144:145], s[52:53], 0, v[136:137]
	s_add_i32 m0, s63, 0xc000
	ds_read_b128 v[188:191], v151
	ds_read_b128 v[192:195], v151 offset:1024
	ds_read_b128 v[196:199], v151 offset:2048
	ds_read_b128 v[200:203], v151 offset:3072
	ds_read_b128 v[204:207], v151 offset:4096
	ds_read_b128 v[208:211], v151 offset:5120
	ds_read_b128 v[212:215], v151 offset:6144
	ds_read_b128 v[216:219], v151 offset:7168
	global_load_lds_dwordx4 v[144:145], off
	v_lshl_add_u64 v[144:145], s[52:53], 0, v[138:139]
	s_add_i32 m0, s63, 0xe000
	s_nop 0
	global_load_lds_dwordx4 v[144:145], off
	s_waitcnt vmcnt(8)
	s_waitcnt lgkmcnt(0)
	s_barrier
	s_waitcnt lgkmcnt(0)
	v_mfma_f32_16x16x32_bf16 v[124:127], v[152:155], v[188:191], 0
	v_mfma_f32_16x16x32_bf16 v[124:127], v[156:159], v[192:195], v[124:127]
	s_setprio 1
	v_mfma_f32_16x16x32_bf16 v[120:123], v[160:163], v[188:191], 0
	v_mfma_f32_16x16x32_bf16 v[120:123], v[164:167], v[192:195], v[120:123]
	v_mfma_f32_16x16x32_bf16 v[116:119], v[152:155], v[196:199], 0
	v_mfma_f32_16x16x32_bf16 v[116:119], v[156:159], v[200:203], v[116:119]
	v_mfma_f32_16x16x32_bf16 v[108:111], v[160:163], v[196:199], 0
	v_mfma_f32_16x16x32_bf16 v[108:111], v[164:167], v[200:203], v[108:111]
	v_mfma_f32_16x16x32_bf16 v[100:103], v[152:155], v[204:207], 0
	v_mfma_f32_16x16x32_bf16 v[100:103], v[156:159], v[208:211], v[100:103]
	v_mfma_f32_16x16x32_bf16 v[92:95], v[160:163], v[204:207], 0
	v_mfma_f32_16x16x32_bf16 v[92:95], v[164:167], v[208:211], v[92:95]
	v_mfma_f32_16x16x32_bf16 v[84:87], v[152:155], v[212:215], 0
	v_mfma_f32_16x16x32_bf16 v[84:87], v[156:159], v[216:219], v[84:87]
	v_mfma_f32_16x16x32_bf16 v[76:79], v[160:163], v[212:215], 0
	v_mfma_f32_16x16x32_bf16 v[76:79], v[164:167], v[216:219], v[76:79]
	v_mfma_f32_16x16x32_bf16 v[112:115], v[168:171], v[188:191], 0
	v_mfma_f32_16x16x32_bf16 v[112:115], v[172:175], v[192:195], v[112:115]
	v_mfma_f32_16x16x32_bf16 v[104:107], v[176:179], v[188:191], 0
	v_mfma_f32_16x16x32_bf16 v[104:107], v[184:187], v[192:195], v[104:107]
	v_mfma_f32_16x16x32_bf16 v[96:99], v[168:171], v[196:199], 0
	v_mfma_f32_16x16x32_bf16 v[96:99], v[172:175], v[200:203], v[96:99]
	v_mfma_f32_16x16x32_bf16 v[88:91], v[176:179], v[196:199], 0
	v_mfma_f32_16x16x32_bf16 v[88:91], v[184:187], v[200:203], v[88:91]
	v_mfma_f32_16x16x32_bf16 v[80:83], v[168:171], v[204:207], 0
	v_mfma_f32_16x16x32_bf16 v[80:83], v[172:175], v[208:211], v[80:83]
	v_mfma_f32_16x16x32_bf16 v[72:75], v[176:179], v[204:207], 0
	v_mfma_f32_16x16x32_bf16 v[72:75], v[184:187], v[208:211], v[72:75]
	v_mfma_f32_16x16x32_bf16 v[68:71], v[168:171], v[212:215], 0
	v_mfma_f32_16x16x32_bf16 v[68:71], v[172:175], v[216:219], v[68:71]
	s_barrier
	v_mfma_f32_16x16x32_bf16 v[64:67], v[176:179], v[212:215], 0
	v_mfma_f32_16x16x32_bf16 v[64:67], v[184:187], v[216:219], v[64:67]
	s_setprio 0
	s_add_i32 s18, s70, s62
	v_lshl_add_u64 v[144:145], s[56:57], 0, v[130:131]
	s_mov_b32 m0, s18
	ds_read_b128 v[188:191], v151 offset:16384
	ds_read_b128 v[192:195], v151 offset:17408
	ds_read_b128 v[196:199], v151 offset:18432
	ds_read_b128 v[200:203], v151 offset:19456
	ds_read_b128 v[204:207], v151 offset:20480
	ds_read_b128 v[208:211], v151 offset:21504
	ds_read_b128 v[212:215], v151 offset:22528
	ds_read_b128 v[216:219], v151 offset:23552
	global_load_lds_dwordx4 v[144:145], off
	s_add_i32 m0, s18, 0x2000
	s_add_u32 s52, s56, 0xb0000
	v_lshl_add_u64 v[220:221], s[56:57], 0, v[134:135]
	s_addc_u32 s53, s57, 0
	s_add_i32 s18, s71, s62
	global_load_lds_dwordx4 v[220:221], off
	v_lshl_add_u64 v[222:223], s[52:53], 0, v[130:131]
	s_mov_b32 m0, s18
	v_lshl_add_u64 v[224:225], s[58:59], 0, v[132:133]
	global_load_lds_dwordx4 v[222:223], off
	v_lshl_add_u64 v[222:223], s[52:53], 0, v[134:135]
	s_add_i32 m0, s18, 0x2000
	s_nop 0
	global_load_lds_dwordx4 v[222:223], off
	v_lshl_add_u64 v[222:223], s[58:59], 0, v[128:129]
	s_mov_b32 m0, s63
	s_nop 0
	global_load_lds_dwordx4 v[222:223], off
	s_mov_b32 m0, s64
	s_nop 0
	global_load_lds_dwordx4 v[224:225], off
	s_waitcnt vmcnt(8)
	s_waitcnt lgkmcnt(0)
	s_barrier
	s_waitcnt lgkmcnt(0)
	v_mfma_f32_16x16x32_bf16 v[60:63], v[152:155], v[188:191], 0
	v_mfma_f32_16x16x32_bf16 v[60:63], v[156:159], v[192:195], v[60:63]
	s_setprio 1
	v_mfma_f32_16x16x32_bf16 v[56:59], v[160:163], v[188:191], 0
	v_mfma_f32_16x16x32_bf16 v[56:59], v[164:167], v[192:195], v[56:59]
	v_mfma_f32_16x16x32_bf16 v[52:55], v[152:155], v[196:199], 0
	v_mfma_f32_16x16x32_bf16 v[52:55], v[156:159], v[200:203], v[52:55]
	v_mfma_f32_16x16x32_bf16 v[44:47], v[160:163], v[196:199], 0
	v_mfma_f32_16x16x32_bf16 v[44:47], v[164:167], v[200:203], v[44:47]
	v_mfma_f32_16x16x32_bf16 v[36:39], v[152:155], v[204:207], 0
	v_mfma_f32_16x16x32_bf16 v[36:39], v[156:159], v[208:211], v[36:39]
	v_mfma_f32_16x16x32_bf16 v[28:31], v[160:163], v[204:207], 0
	v_mfma_f32_16x16x32_bf16 v[28:31], v[164:167], v[208:211], v[28:31]
	v_mfma_f32_16x16x32_bf16 v[20:23], v[152:155], v[212:215], 0
	v_mfma_f32_16x16x32_bf16 v[20:23], v[156:159], v[216:219], v[20:23]
	v_mfma_f32_16x16x32_bf16 v[12:15], v[160:163], v[212:215], 0
	v_mfma_f32_16x16x32_bf16 v[12:15], v[164:167], v[216:219], v[12:15]
	v_mfma_f32_16x16x32_bf16 v[48:51], v[168:171], v[188:191], 0
	v_mfma_f32_16x16x32_bf16 v[48:51], v[172:175], v[192:195], v[48:51]
	v_mfma_f32_16x16x32_bf16 v[40:43], v[176:179], v[188:191], 0
	v_mfma_f32_16x16x32_bf16 v[40:43], v[184:187], v[192:195], v[40:43]
	v_mfma_f32_16x16x32_bf16 v[32:35], v[168:171], v[196:199], 0
	v_mfma_f32_16x16x32_bf16 v[32:35], v[172:175], v[200:203], v[32:35]
	v_mfma_f32_16x16x32_bf16 v[24:27], v[176:179], v[196:199], 0
	v_mfma_f32_16x16x32_bf16 v[24:27], v[184:187], v[200:203], v[24:27]
	v_mfma_f32_16x16x32_bf16 v[16:19], v[168:171], v[204:207], 0
	v_mfma_f32_16x16x32_bf16 v[16:19], v[172:175], v[208:211], v[16:19]
	v_mfma_f32_16x16x32_bf16 v[8:11], v[176:179], v[204:207], 0
	v_mfma_f32_16x16x32_bf16 v[8:11], v[184:187], v[208:211], v[8:11]
	v_mfma_f32_16x16x32_bf16 v[4:7], v[168:171], v[212:215], 0
	v_mfma_f32_16x16x32_bf16 v[4:7], v[172:175], v[216:219], v[4:7]
	s_barrier
	v_mfma_f32_16x16x32_bf16 v[0:3], v[176:179], v[212:215], 0
	v_mfma_f32_16x16x32_bf16 v[0:3], v[184:187], v[216:219], v[0:3]
	s_setprio 0
	s_branch .Lmid_gemm1
.LBB0_264:
	ds_read_b128 v[152:155], v149
	ds_read_b128 v[156:159], v149 offset:1024
	ds_read_b128 v[160:163], v149 offset:2048
	ds_read_b128 v[164:167], v149 offset:3072
	ds_read_b128 v[168:171], v150
	ds_read_b128 v[172:175], v150 offset:1024
	ds_read_b128 v[176:179], v150 offset:2048
	ds_read_b128 v[184:187], v150 offset:3072
	s_add_u32 s54, s52, 0x100
	s_addc_u32 s55, s53, 0
	s_cmp_eq_u32 s86, 40
	s_cselect_b32 s59, s7, s55
	s_cselect_b32 s58, s6, s54
	s_cselect_b32 s57, s49, s85
	s_cselect_b32 s56, s48, s84
	v_lshl_add_u64 v[144:145], s[52:53], 0, v[136:137]
	s_add_i32 m0, s63, 0xc000
	ds_read_b128 v[188:191], v151
	ds_read_b128 v[192:195], v151 offset:1024
	ds_read_b128 v[196:199], v151 offset:2048
	ds_read_b128 v[200:203], v151 offset:3072
	ds_read_b128 v[204:207], v151 offset:4096
	ds_read_b128 v[208:211], v151 offset:5120
	ds_read_b128 v[212:215], v151 offset:6144
	ds_read_b128 v[216:219], v151 offset:7168
	global_load_lds_dwordx4 v[144:145], off
	v_lshl_add_u64 v[144:145], s[52:53], 0, v[138:139]
	s_add_i32 m0, s63, 0xe000
	s_nop 0
	global_load_lds_dwordx4 v[144:145], off
	s_waitcnt vmcnt(8)
	s_waitcnt lgkmcnt(0)
	s_barrier
	s_waitcnt lgkmcnt(0)
	v_mfma_f32_16x16x32_bf16 v[124:127], v[152:155], v[188:191], v[124:127]
	v_mfma_f32_16x16x32_bf16 v[124:127], v[156:159], v[192:195], v[124:127]
	s_setprio 1
	v_mfma_f32_16x16x32_bf16 v[120:123], v[160:163], v[188:191], v[120:123]
	v_mfma_f32_16x16x32_bf16 v[120:123], v[164:167], v[192:195], v[120:123]
	v_mfma_f32_16x16x32_bf16 v[116:119], v[152:155], v[196:199], v[116:119]
	v_mfma_f32_16x16x32_bf16 v[116:119], v[156:159], v[200:203], v[116:119]
	v_mfma_f32_16x16x32_bf16 v[108:111], v[160:163], v[196:199], v[108:111]
	v_mfma_f32_16x16x32_bf16 v[108:111], v[164:167], v[200:203], v[108:111]
	v_mfma_f32_16x16x32_bf16 v[100:103], v[152:155], v[204:207], v[100:103]
	v_mfma_f32_16x16x32_bf16 v[100:103], v[156:159], v[208:211], v[100:103]
	v_mfma_f32_16x16x32_bf16 v[92:95], v[160:163], v[204:207], v[92:95]
	v_mfma_f32_16x16x32_bf16 v[92:95], v[164:167], v[208:211], v[92:95]
	v_mfma_f32_16x16x32_bf16 v[84:87], v[152:155], v[212:215], v[84:87]
	v_mfma_f32_16x16x32_bf16 v[84:87], v[156:159], v[216:219], v[84:87]
	v_mfma_f32_16x16x32_bf16 v[76:79], v[160:163], v[212:215], v[76:79]
	v_mfma_f32_16x16x32_bf16 v[76:79], v[164:167], v[216:219], v[76:79]
	v_mfma_f32_16x16x32_bf16 v[112:115], v[168:171], v[188:191], v[112:115]
	v_mfma_f32_16x16x32_bf16 v[112:115], v[172:175], v[192:195], v[112:115]
	v_mfma_f32_16x16x32_bf16 v[104:107], v[176:179], v[188:191], v[104:107]
	v_mfma_f32_16x16x32_bf16 v[104:107], v[184:187], v[192:195], v[104:107]
	v_mfma_f32_16x16x32_bf16 v[96:99], v[168:171], v[196:199], v[96:99]
	v_mfma_f32_16x16x32_bf16 v[96:99], v[172:175], v[200:203], v[96:99]
	v_mfma_f32_16x16x32_bf16 v[88:91], v[176:179], v[196:199], v[88:91]
	v_mfma_f32_16x16x32_bf16 v[88:91], v[184:187], v[200:203], v[88:91]
	v_mfma_f32_16x16x32_bf16 v[80:83], v[168:171], v[204:207], v[80:83]
	v_mfma_f32_16x16x32_bf16 v[80:83], v[172:175], v[208:211], v[80:83]
	v_mfma_f32_16x16x32_bf16 v[72:75], v[176:179], v[204:207], v[72:75]
	v_mfma_f32_16x16x32_bf16 v[72:75], v[184:187], v[208:211], v[72:75]
	v_mfma_f32_16x16x32_bf16 v[68:71], v[168:171], v[212:215], v[68:71]
	v_mfma_f32_16x16x32_bf16 v[68:71], v[172:175], v[216:219], v[68:71]
	s_barrier
	v_mfma_f32_16x16x32_bf16 v[64:67], v[176:179], v[212:215], v[64:67]
	v_mfma_f32_16x16x32_bf16 v[64:67], v[184:187], v[216:219], v[64:67]
	s_setprio 0
	s_add_i32 s18, s70, s62
	v_lshl_add_u64 v[144:145], s[56:57], 0, v[130:131]
	s_mov_b32 m0, s18
	ds_read_b128 v[188:191], v151 offset:16384
	ds_read_b128 v[192:195], v151 offset:17408
	ds_read_b128 v[196:199], v151 offset:18432
	ds_read_b128 v[200:203], v151 offset:19456
	ds_read_b128 v[204:207], v151 offset:20480
	ds_read_b128 v[208:211], v151 offset:21504
	ds_read_b128 v[212:215], v151 offset:22528
	ds_read_b128 v[216:219], v151 offset:23552
	global_load_lds_dwordx4 v[144:145], off
	s_add_i32 m0, s18, 0x2000
	s_add_u32 s52, s56, 0xb0000
	v_lshl_add_u64 v[220:221], s[56:57], 0, v[134:135]
	s_addc_u32 s53, s57, 0
	s_add_i32 s18, s71, s62
	global_load_lds_dwordx4 v[220:221], off
	v_lshl_add_u64 v[222:223], s[52:53], 0, v[130:131]
	s_mov_b32 m0, s18
	v_lshl_add_u64 v[224:225], s[58:59], 0, v[132:133]
	global_load_lds_dwordx4 v[222:223], off
	v_lshl_add_u64 v[222:223], s[52:53], 0, v[134:135]
	s_add_i32 m0, s18, 0x2000
	s_nop 0
	global_load_lds_dwordx4 v[222:223], off
	v_lshl_add_u64 v[222:223], s[58:59], 0, v[128:129]
	s_mov_b32 m0, s63
	s_nop 0
	global_load_lds_dwordx4 v[222:223], off
	s_mov_b32 m0, s64
	s_nop 0
	global_load_lds_dwordx4 v[224:225], off
	s_waitcnt vmcnt(8)
	s_waitcnt lgkmcnt(0)
	s_barrier
	s_waitcnt lgkmcnt(0)
	v_mfma_f32_16x16x32_bf16 v[60:63], v[152:155], v[188:191], v[60:63]
	v_mfma_f32_16x16x32_bf16 v[60:63], v[156:159], v[192:195], v[60:63]
	s_setprio 1
	v_mfma_f32_16x16x32_bf16 v[56:59], v[160:163], v[188:191], v[56:59]
	v_mfma_f32_16x16x32_bf16 v[56:59], v[164:167], v[192:195], v[56:59]
	v_mfma_f32_16x16x32_bf16 v[52:55], v[152:155], v[196:199], v[52:55]
	v_mfma_f32_16x16x32_bf16 v[52:55], v[156:159], v[200:203], v[52:55]
	v_mfma_f32_16x16x32_bf16 v[44:47], v[160:163], v[196:199], v[44:47]
	v_mfma_f32_16x16x32_bf16 v[44:47], v[164:167], v[200:203], v[44:47]
	v_mfma_f32_16x16x32_bf16 v[36:39], v[152:155], v[204:207], v[36:39]
	v_mfma_f32_16x16x32_bf16 v[36:39], v[156:159], v[208:211], v[36:39]
	v_mfma_f32_16x16x32_bf16 v[28:31], v[160:163], v[204:207], v[28:31]
	v_mfma_f32_16x16x32_bf16 v[28:31], v[164:167], v[208:211], v[28:31]
	v_mfma_f32_16x16x32_bf16 v[20:23], v[152:155], v[212:215], v[20:23]
	v_mfma_f32_16x16x32_bf16 v[20:23], v[156:159], v[216:219], v[20:23]
	v_mfma_f32_16x16x32_bf16 v[12:15], v[160:163], v[212:215], v[12:15]
	v_mfma_f32_16x16x32_bf16 v[12:15], v[164:167], v[216:219], v[12:15]
	v_mfma_f32_16x16x32_bf16 v[48:51], v[168:171], v[188:191], v[48:51]
	v_mfma_f32_16x16x32_bf16 v[48:51], v[172:175], v[192:195], v[48:51]
	v_mfma_f32_16x16x32_bf16 v[40:43], v[176:179], v[188:191], v[40:43]
	v_mfma_f32_16x16x32_bf16 v[40:43], v[184:187], v[192:195], v[40:43]
	v_mfma_f32_16x16x32_bf16 v[32:35], v[168:171], v[196:199], v[32:35]
	v_mfma_f32_16x16x32_bf16 v[32:35], v[172:175], v[200:203], v[32:35]
	v_mfma_f32_16x16x32_bf16 v[24:27], v[176:179], v[196:199], v[24:27]
	v_mfma_f32_16x16x32_bf16 v[24:27], v[184:187], v[200:203], v[24:27]
	v_mfma_f32_16x16x32_bf16 v[16:19], v[168:171], v[204:207], v[16:19]
	v_mfma_f32_16x16x32_bf16 v[16:19], v[172:175], v[208:211], v[16:19]
	v_mfma_f32_16x16x32_bf16 v[8:11], v[176:179], v[204:207], v[8:11]
	v_mfma_f32_16x16x32_bf16 v[8:11], v[184:187], v[208:211], v[8:11]
	v_mfma_f32_16x16x32_bf16 v[4:7], v[168:171], v[212:215], v[4:7]
	v_mfma_f32_16x16x32_bf16 v[4:7], v[172:175], v[216:219], v[4:7]
	s_barrier
	v_mfma_f32_16x16x32_bf16 v[0:3], v[176:179], v[212:215], v[0:3]
	v_mfma_f32_16x16x32_bf16 v[0:3], v[184:187], v[216:219], v[0:3]
	s_setprio 0
.Lmid_gemm1:
	s_add_i32 s18, 0, 0x18000
	s_add_i32 s19, 0, 0x1c000
	v_add_u32_e32 v164, s18, v147
	v_add_u32_e32 v181, s19, v147
	ds_read_b128 v[152:155], v164
	ds_read_b128 v[156:159], v164 offset:1024
	ds_read_b128 v[160:163], v164 offset:2048
	ds_read_b128 v[164:167], v164 offset:3072
	ds_read_b128 v[168:171], v181
	ds_read_b128 v[172:175], v181 offset:1024
	ds_read_b128 v[176:179], v181 offset:2048
	ds_read_b128 v[184:187], v181 offset:3072
	s_add_u32 s52, s58, 0xb0000
	s_addc_u32 s53, s59, 0
	s_mov_b32 m0, s65
	v_lshl_add_u64 v[226:227], s[52:53], 0, v[128:129]
	ds_read_b128 v[188:191], v151 offset:32768
	ds_read_b128 v[192:195], v151 offset:33792
	ds_read_b128 v[196:199], v151 offset:34816
	ds_read_b128 v[200:203], v151 offset:35840
	ds_read_b128 v[204:207], v151 offset:36864
	ds_read_b128 v[208:211], v151 offset:37888
	ds_read_b128 v[212:215], v151 offset:38912
	ds_read_b128 v[216:219], v151 offset:39936
	global_load_lds_dwordx4 v[226:227], off
	v_lshl_add_u64 v[226:227], s[52:53], 0, v[132:133]
	s_mov_b32 m0, s66
	s_nop 0
	global_load_lds_dwordx4 v[226:227], off
	s_waitcnt vmcnt(8)
	s_waitcnt lgkmcnt(0)
	s_barrier
	s_waitcnt lgkmcnt(0)
	v_mfma_f32_16x16x32_bf16 v[124:127], v[152:155], v[188:191], v[124:127]
	v_mfma_f32_16x16x32_bf16 v[124:127], v[156:159], v[192:195], v[124:127]
	s_setprio 1
	v_mfma_f32_16x16x32_bf16 v[120:123], v[160:163], v[188:191], v[120:123]
	v_mfma_f32_16x16x32_bf16 v[120:123], v[164:167], v[192:195], v[120:123]
	v_mfma_f32_16x16x32_bf16 v[116:119], v[152:155], v[196:199], v[116:119]
	v_mfma_f32_16x16x32_bf16 v[116:119], v[156:159], v[200:203], v[116:119]
	v_mfma_f32_16x16x32_bf16 v[108:111], v[160:163], v[196:199], v[108:111]
	v_mfma_f32_16x16x32_bf16 v[108:111], v[164:167], v[200:203], v[108:111]
	v_mfma_f32_16x16x32_bf16 v[100:103], v[152:155], v[204:207], v[100:103]
	v_mfma_f32_16x16x32_bf16 v[100:103], v[156:159], v[208:211], v[100:103]
	v_mfma_f32_16x16x32_bf16 v[92:95], v[160:163], v[204:207], v[92:95]
	v_mfma_f32_16x16x32_bf16 v[92:95], v[164:167], v[208:211], v[92:95]
	v_mfma_f32_16x16x32_bf16 v[84:87], v[152:155], v[212:215], v[84:87]
	v_mfma_f32_16x16x32_bf16 v[84:87], v[156:159], v[216:219], v[84:87]
	v_mfma_f32_16x16x32_bf16 v[76:79], v[160:163], v[212:215], v[76:79]
	v_mfma_f32_16x16x32_bf16 v[76:79], v[164:167], v[216:219], v[76:79]
	v_mfma_f32_16x16x32_bf16 v[112:115], v[168:171], v[188:191], v[112:115]
	v_mfma_f32_16x16x32_bf16 v[112:115], v[172:175], v[192:195], v[112:115]
	v_mfma_f32_16x16x32_bf16 v[104:107], v[176:179], v[188:191], v[104:107]
	v_mfma_f32_16x16x32_bf16 v[104:107], v[184:187], v[192:195], v[104:107]
	v_mfma_f32_16x16x32_bf16 v[96:99], v[168:171], v[196:199], v[96:99]
	v_mfma_f32_16x16x32_bf16 v[96:99], v[172:175], v[200:203], v[96:99]
	v_mfma_f32_16x16x32_bf16 v[88:91], v[176:179], v[196:199], v[88:91]
	v_mfma_f32_16x16x32_bf16 v[88:91], v[184:187], v[200:203], v[88:91]
	v_mfma_f32_16x16x32_bf16 v[80:83], v[168:171], v[204:207], v[80:83]
	v_mfma_f32_16x16x32_bf16 v[80:83], v[172:175], v[208:211], v[80:83]
	v_mfma_f32_16x16x32_bf16 v[72:75], v[176:179], v[204:207], v[72:75]
	v_mfma_f32_16x16x32_bf16 v[72:75], v[184:187], v[208:211], v[72:75]
	v_mfma_f32_16x16x32_bf16 v[68:71], v[168:171], v[212:215], v[68:71]
	v_mfma_f32_16x16x32_bf16 v[68:71], v[172:175], v[216:219], v[68:71]
	s_barrier
	v_mfma_f32_16x16x32_bf16 v[64:67], v[176:179], v[212:215], v[64:67]
	v_mfma_f32_16x16x32_bf16 v[64:67], v[184:187], v[216:219], v[64:67]
	s_setprio 0
	s_add_i32 s18, s18, s62
	v_lshl_add_u64 v[144:145], v[144:145], 0, s[8:9]
	s_mov_b32 m0, s18
	ds_read_b128 v[188:191], v151 offset:49152
	ds_read_b128 v[192:195], v151 offset:50176
	ds_read_b128 v[196:199], v151 offset:51200
	ds_read_b128 v[200:203], v151 offset:52224
	ds_read_b128 v[204:207], v151 offset:53248
	ds_read_b128 v[208:211], v151 offset:54272
	ds_read_b128 v[212:215], v151 offset:55296
	ds_read_b128 v[216:219], v151 offset:56320
	global_load_lds_dwordx4 v[144:145], off
	s_add_i32 m0, s18, 0x2000
	s_add_u32 s52, s56, 0xb0080
	v_lshl_add_u64 v[144:145], v[220:221], 0, s[8:9]
	s_addc_u32 s53, s57, 0
	s_add_i32 s18, s19, s62
	global_load_lds_dwordx4 v[144:145], off
	v_lshl_add_u64 v[144:145], s[52:53], 0, v[130:131]
	s_mov_b32 m0, s18
	s_nop 0
	global_load_lds_dwordx4 v[144:145], off
	v_lshl_add_u64 v[144:145], s[52:53], 0, v[134:135]
	s_add_i32 m0, s18, 0x2000
	s_nop 0
	global_load_lds_dwordx4 v[144:145], off
	v_lshl_add_u64 v[144:145], v[222:223], 0, s[8:9]
	s_mov_b32 m0, s68
	s_nop 0
	global_load_lds_dwordx4 v[144:145], off
	v_lshl_add_u64 v[144:145], v[224:225], 0, s[8:9]
	s_mov_b32 m0, s69
	s_nop 0
	global_load_lds_dwordx4 v[144:145], off
	s_waitcnt vmcnt(8)
	s_waitcnt lgkmcnt(0)
	s_barrier
	s_waitcnt lgkmcnt(0)
	v_mfma_f32_16x16x32_bf16 v[60:63], v[152:155], v[188:191], v[60:63]
	v_mfma_f32_16x16x32_bf16 v[60:63], v[156:159], v[192:195], v[60:63]
	s_setprio 1
	v_mfma_f32_16x16x32_bf16 v[56:59], v[160:163], v[188:191], v[56:59]
	v_mfma_f32_16x16x32_bf16 v[56:59], v[164:167], v[192:195], v[56:59]
	v_mfma_f32_16x16x32_bf16 v[52:55], v[152:155], v[196:199], v[52:55]
	v_mfma_f32_16x16x32_bf16 v[52:55], v[156:159], v[200:203], v[52:55]
	v_mfma_f32_16x16x32_bf16 v[44:47], v[160:163], v[196:199], v[44:47]
	v_mfma_f32_16x16x32_bf16 v[44:47], v[164:167], v[200:203], v[44:47]
	v_mfma_f32_16x16x32_bf16 v[36:39], v[152:155], v[204:207], v[36:39]
	v_mfma_f32_16x16x32_bf16 v[36:39], v[156:159], v[208:211], v[36:39]
	v_mfma_f32_16x16x32_bf16 v[28:31], v[160:163], v[204:207], v[28:31]
	v_mfma_f32_16x16x32_bf16 v[28:31], v[164:167], v[208:211], v[28:31]
	v_mfma_f32_16x16x32_bf16 v[20:23], v[152:155], v[212:215], v[20:23]
	v_mfma_f32_16x16x32_bf16 v[20:23], v[156:159], v[216:219], v[20:23]
	v_mfma_f32_16x16x32_bf16 v[12:15], v[160:163], v[212:215], v[12:15]
	v_mfma_f32_16x16x32_bf16 v[12:15], v[164:167], v[216:219], v[12:15]
	v_mfma_f32_16x16x32_bf16 v[48:51], v[168:171], v[188:191], v[48:51]
	v_mfma_f32_16x16x32_bf16 v[48:51], v[172:175], v[192:195], v[48:51]
	v_mfma_f32_16x16x32_bf16 v[40:43], v[176:179], v[188:191], v[40:43]
	v_mfma_f32_16x16x32_bf16 v[40:43], v[184:187], v[192:195], v[40:43]
	v_mfma_f32_16x16x32_bf16 v[32:35], v[168:171], v[196:199], v[32:35]
	v_mfma_f32_16x16x32_bf16 v[32:35], v[172:175], v[200:203], v[32:35]
	v_mfma_f32_16x16x32_bf16 v[24:27], v[176:179], v[196:199], v[24:27]
	v_mfma_f32_16x16x32_bf16 v[24:27], v[184:187], v[200:203], v[24:27]
	v_mfma_f32_16x16x32_bf16 v[16:19], v[168:171], v[204:207], v[16:19]
	v_mfma_f32_16x16x32_bf16 v[16:19], v[172:175], v[208:211], v[16:19]
	v_mfma_f32_16x16x32_bf16 v[8:11], v[176:179], v[204:207], v[8:11]
	v_mfma_f32_16x16x32_bf16 v[8:11], v[184:187], v[208:211], v[8:11]
	v_mfma_f32_16x16x32_bf16 v[4:7], v[168:171], v[212:215], v[4:7]
	v_mfma_f32_16x16x32_bf16 v[4:7], v[172:175], v[216:219], v[4:7]
	s_barrier
	v_mfma_f32_16x16x32_bf16 v[0:3], v[176:179], v[212:215], v[0:3]
	v_mfma_f32_16x16x32_bf16 v[0:3], v[184:187], v[216:219], v[0:3]
	s_setprio 0
	s_add_i32 s86, s86, 2
	s_add_u32 s84, s84, 0x100
	s_addc_u32 s85, s85, 0
	s_cmp_gt_u32 s86, 41
	s_mov_b64 s[52:53], s[54:55]
	s_cbranch_scc0 .LBB0_264
	s_and_b64 vcc, exec, s[10:11]
	s_cbranch_vccz .LBB0_267
	s_barrier

.LBB0_386:
	s_ashr_i32 s49, s48, 31
	s_lshl_b64 s[52:53], s[48:49], 19
	s_add_u32 s52, s80, s52
	s_addc_u32 s53, s81, s53
	s_and_b64 s[54:55], s[4:5], exec
	s_cselect_b32 s49, s53, s59
	s_cselect_b32 s82, s52, s58
	s_ashr_i32 s47, s46, 31
	s_lshl_b64 s[54:55], s[46:47], 19
	s_add_u32 s54, s64, s54
	s_addc_u32 s55, s65, s55
	s_and_b64 s[62:63], s[4:5], exec
	s_cselect_b32 s47, s55, s61
	s_cselect_b32 s83, s54, s60
	s_add_u32 s58, s58, 0x40080
	s_addc_u32 s59, s59, 0
	s_add_u32 s84, s60, 0x100
	s_addc_u32 s85, s61, 0
	s_mov_b32 s86, -2
	ds_read_b128 v[152:155], v148
	ds_read_b128 v[156:159], v148 offset:1024
	ds_read_b128 v[160:163], v148 offset:2048
	ds_read_b128 v[164:167], v148 offset:3072
	ds_read_b128 v[168:171], v149
	ds_read_b128 v[172:175], v149 offset:1024
	ds_read_b128 v[176:179], v149 offset:2048
	ds_read_b128 v[184:187], v149 offset:3072
	s_add_u32 s18, s58, 0xfffc0080
	s_addc_u32 s19, s59, -1
	s_cmp_eq_u32 s86, 12
	s_cselect_b32 s63, s49, s19
	s_cselect_b32 s62, s82, s18
	s_cselect_b32 s61, s47, s85
	s_cselect_b32 s60, s83, s84
	v_lshl_add_u64 v[220:221], s[58:59], 0, v[138:139]
	s_add_i32 m0, s68, 0xc000
	ds_read_b128 v[188:191], v150
	ds_read_b128 v[192:195], v150 offset:1024
	ds_read_b128 v[196:199], v150 offset:2048
	ds_read_b128 v[200:203], v150 offset:3072
	ds_read_b128 v[204:207], v150 offset:4096
	ds_read_b128 v[208:211], v150 offset:5120
	ds_read_b128 v[212:215], v150 offset:6144
	ds_read_b128 v[216:219], v150 offset:7168
	global_load_lds_dwordx4 v[220:221], off
	v_lshl_add_u64 v[220:221], s[58:59], 0, v[140:141]
	s_add_i32 m0, s68, 0xe000
	s_nop 0
	global_load_lds_dwordx4 v[220:221], off
	s_waitcnt vmcnt(8)
	s_waitcnt lgkmcnt(0)
	s_barrier
	s_waitcnt lgkmcnt(0)
	v_mfma_f32_16x16x32_bf16 v[124:127], v[152:155], v[188:191], 0
	v_mfma_f32_16x16x32_bf16 v[124:127], v[156:159], v[192:195], v[124:127]
	s_setprio 1
	v_mfma_f32_16x16x32_bf16 v[120:123], v[160:163], v[188:191], 0
	v_mfma_f32_16x16x32_bf16 v[120:123], v[164:167], v[192:195], v[120:123]
	v_mfma_f32_16x16x32_bf16 v[116:119], v[152:155], v[196:199], 0
	v_mfma_f32_16x16x32_bf16 v[116:119], v[156:159], v[200:203], v[116:119]
	v_mfma_f32_16x16x32_bf16 v[112:115], v[160:163], v[196:199], 0
	v_mfma_f32_16x16x32_bf16 v[112:115], v[164:167], v[200:203], v[112:115]
	v_mfma_f32_16x16x32_bf16 v[108:111], v[152:155], v[204:207], 0
	v_mfma_f32_16x16x32_bf16 v[108:111], v[156:159], v[208:211], v[108:111]
	v_mfma_f32_16x16x32_bf16 v[104:107], v[160:163], v[204:207], 0
	v_mfma_f32_16x16x32_bf16 v[104:107], v[164:167], v[208:211], v[104:107]
	v_mfma_f32_16x16x32_bf16 v[100:103], v[152:155], v[212:215], 0
	v_mfma_f32_16x16x32_bf16 v[100:103], v[156:159], v[216:219], v[100:103]
	v_mfma_f32_16x16x32_bf16 v[96:99], v[160:163], v[212:215], 0
	v_mfma_f32_16x16x32_bf16 v[96:99], v[164:167], v[216:219], v[96:99]
	v_mfma_f32_16x16x32_bf16 v[68:71], v[168:171], v[188:191], 0
	v_mfma_f32_16x16x32_bf16 v[68:71], v[172:175], v[192:195], v[68:71]
	v_mfma_f32_16x16x32_bf16 v[64:67], v[176:179], v[188:191], 0
	v_mfma_f32_16x16x32_bf16 v[64:67], v[184:187], v[192:195], v[64:67]
	v_mfma_f32_16x16x32_bf16 v[52:55], v[168:171], v[196:199], 0
	v_mfma_f32_16x16x32_bf16 v[52:55], v[172:175], v[200:203], v[52:55]
	v_mfma_f32_16x16x32_bf16 v[48:51], v[176:179], v[196:199], 0
	v_mfma_f32_16x16x32_bf16 v[48:51], v[184:187], v[200:203], v[48:51]
	v_mfma_f32_16x16x32_bf16 v[44:47], v[168:171], v[204:207], 0
	v_mfma_f32_16x16x32_bf16 v[44:47], v[172:175], v[208:211], v[44:47]
	v_mfma_f32_16x16x32_bf16 v[40:43], v[176:179], v[204:207], 0
	v_mfma_f32_16x16x32_bf16 v[40:43], v[184:187], v[208:211], v[40:43]
	v_mfma_f32_16x16x32_bf16 v[36:39], v[168:171], v[212:215], 0
	v_mfma_f32_16x16x32_bf16 v[36:39], v[172:175], v[216:219], v[36:39]
	s_barrier
	v_mfma_f32_16x16x32_bf16 v[32:35], v[176:179], v[212:215], 0
	v_mfma_f32_16x16x32_bf16 v[32:35], v[184:187], v[216:219], v[32:35]
	s_setprio 0
	s_add_i32 s18, s76, s66
	v_lshl_add_u64 v[220:221], s[60:61], 0, v[132:133]
	s_mov_b32 m0, s18
	ds_read_b128 v[188:191], v150 offset:16384
	ds_read_b128 v[192:195], v150 offset:17408
	ds_read_b128 v[196:199], v150 offset:18432
	ds_read_b128 v[200:203], v150 offset:19456
	ds_read_b128 v[204:207], v150 offset:20480
	ds_read_b128 v[208:211], v150 offset:21504
	ds_read_b128 v[212:215], v150 offset:22528
	ds_read_b128 v[216:219], v150 offset:23552
	global_load_lds_dwordx4 v[220:221], off
	s_add_i32 m0, s18, 0x2000
	s_add_u32 s88, s60, 0x40000
	v_lshl_add_u64 v[222:223], s[60:61], 0, v[128:129]
	s_addc_u32 s89, s61, 0
	s_add_i32 s18, s77, s66
	global_load_lds_dwordx4 v[222:223], off
	v_lshl_add_u64 v[224:225], s[88:89], 0, v[132:133]
	s_mov_b32 m0, s18
	v_lshl_add_u64 v[226:227], s[62:63], 0, v[130:131]
	global_load_lds_dwordx4 v[224:225], off
	v_lshl_add_u64 v[224:225], s[88:89], 0, v[128:129]
	s_add_i32 m0, s18, 0x2000
	s_nop 0
	global_load_lds_dwordx4 v[224:225], off
	v_lshl_add_u64 v[224:225], s[62:63], 0, v[134:135]
	s_mov_b32 m0, s68
	s_nop 0
	global_load_lds_dwordx4 v[224:225], off
	s_mov_b32 m0, s69
	s_nop 0
	global_load_lds_dwordx4 v[226:227], off
	s_waitcnt vmcnt(8)
	s_waitcnt lgkmcnt(0)
	s_barrier
	s_waitcnt lgkmcnt(0)
	v_mfma_f32_16x16x32_bf16 v[92:95], v[152:155], v[188:191], 0
	v_mfma_f32_16x16x32_bf16 v[92:95], v[156:159], v[192:195], v[92:95]
	s_setprio 1
	v_mfma_f32_16x16x32_bf16 v[88:91], v[160:163], v[188:191], 0
	v_mfma_f32_16x16x32_bf16 v[88:91], v[164:167], v[192:195], v[88:91]
	v_mfma_f32_16x16x32_bf16 v[84:87], v[152:155], v[196:199], 0
	v_mfma_f32_16x16x32_bf16 v[84:87], v[156:159], v[200:203], v[84:87]
	v_mfma_f32_16x16x32_bf16 v[80:83], v[160:163], v[196:199], 0
	v_mfma_f32_16x16x32_bf16 v[80:83], v[164:167], v[200:203], v[80:83]
	v_mfma_f32_16x16x32_bf16 v[76:79], v[152:155], v[204:207], 0
	v_mfma_f32_16x16x32_bf16 v[76:79], v[156:159], v[208:211], v[76:79]
	v_mfma_f32_16x16x32_bf16 v[72:75], v[160:163], v[204:207], 0
	v_mfma_f32_16x16x32_bf16 v[72:75], v[164:167], v[208:211], v[72:75]
	v_mfma_f32_16x16x32_bf16 v[60:63], v[152:155], v[212:215], 0
	v_mfma_f32_16x16x32_bf16 v[60:63], v[156:159], v[216:219], v[60:63]
	v_mfma_f32_16x16x32_bf16 v[56:59], v[160:163], v[212:215], 0
	v_mfma_f32_16x16x32_bf16 v[56:59], v[164:167], v[216:219], v[56:59]
	v_mfma_f32_16x16x32_bf16 v[28:31], v[168:171], v[188:191], 0
	v_mfma_f32_16x16x32_bf16 v[28:31], v[172:175], v[192:195], v[28:31]
	v_mfma_f32_16x16x32_bf16 v[24:27], v[176:179], v[188:191], 0
	v_mfma_f32_16x16x32_bf16 v[24:27], v[184:187], v[192:195], v[24:27]
	v_mfma_f32_16x16x32_bf16 v[20:23], v[168:171], v[196:199], 0
	v_mfma_f32_16x16x32_bf16 v[20:23], v[172:175], v[200:203], v[20:23]
	v_mfma_f32_16x16x32_bf16 v[16:19], v[176:179], v[196:199], 0
	v_mfma_f32_16x16x32_bf16 v[16:19], v[184:187], v[200:203], v[16:19]
	v_mfma_f32_16x16x32_bf16 v[12:15], v[168:171], v[204:207], 0
	v_mfma_f32_16x16x32_bf16 v[12:15], v[172:175], v[208:211], v[12:15]
	v_mfma_f32_16x16x32_bf16 v[8:11], v[176:179], v[204:207], 0
	v_mfma_f32_16x16x32_bf16 v[8:11], v[184:187], v[208:211], v[8:11]
	v_mfma_f32_16x16x32_bf16 v[4:7], v[168:171], v[212:215], 0
	v_mfma_f32_16x16x32_bf16 v[4:7], v[172:175], v[216:219], v[4:7]
	s_barrier
	v_mfma_f32_16x16x32_bf16 v[0:3], v[176:179], v[212:215], 0
	v_mfma_f32_16x16x32_bf16 v[0:3], v[184:187], v[216:219], v[0:3]
	s_setprio 0
	s_branch .Lmid_gemm2
.LBB0_387:
	ds_read_b128 v[152:155], v148
	ds_read_b128 v[156:159], v148 offset:1024
	ds_read_b128 v[160:163], v148 offset:2048
	ds_read_b128 v[164:167], v148 offset:3072
	ds_read_b128 v[168:171], v149
	ds_read_b128 v[172:175], v149 offset:1024
	ds_read_b128 v[176:179], v149 offset:2048
	ds_read_b128 v[184:187], v149 offset:3072
	s_add_u32 s18, s58, 0xfffc0080
	s_addc_u32 s19, s59, -1
	s_cmp_eq_u32 s86, 12
	s_cselect_b32 s63, s49, s19
	s_cselect_b32 s62, s82, s18
	s_cselect_b32 s61, s47, s85
	s_cselect_b32 s60, s83, s84
	v_lshl_add_u64 v[220:221], s[58:59], 0, v[138:139]
	s_add_i32 m0, s68, 0xc000
	ds_read_b128 v[188:191], v150
	ds_read_b128 v[192:195], v150 offset:1024
	ds_read_b128 v[196:199], v150 offset:2048
	ds_read_b128 v[200:203], v150 offset:3072
	ds_read_b128 v[204:207], v150 offset:4096
	ds_read_b128 v[208:211], v150 offset:5120
	ds_read_b128 v[212:215], v150 offset:6144
	ds_read_b128 v[216:219], v150 offset:7168
	global_load_lds_dwordx4 v[220:221], off
	v_lshl_add_u64 v[220:221], s[58:59], 0, v[140:141]
	s_add_i32 m0, s68, 0xe000
	s_nop 0
	global_load_lds_dwordx4 v[220:221], off
	s_waitcnt vmcnt(8)
	s_waitcnt lgkmcnt(0)
	s_barrier
	s_waitcnt lgkmcnt(0)
	v_mfma_f32_16x16x32_bf16 v[124:127], v[152:155], v[188:191], v[124:127]
	v_mfma_f32_16x16x32_bf16 v[124:127], v[156:159], v[192:195], v[124:127]
	s_setprio 1
	v_mfma_f32_16x16x32_bf16 v[120:123], v[160:163], v[188:191], v[120:123]
	v_mfma_f32_16x16x32_bf16 v[120:123], v[164:167], v[192:195], v[120:123]
	v_mfma_f32_16x16x32_bf16 v[116:119], v[152:155], v[196:199], v[116:119]
	v_mfma_f32_16x16x32_bf16 v[116:119], v[156:159], v[200:203], v[116:119]
	v_mfma_f32_16x16x32_bf16 v[112:115], v[160:163], v[196:199], v[112:115]
	v_mfma_f32_16x16x32_bf16 v[112:115], v[164:167], v[200:203], v[112:115]
	v_mfma_f32_16x16x32_bf16 v[108:111], v[152:155], v[204:207], v[108:111]
	v_mfma_f32_16x16x32_bf16 v[108:111], v[156:159], v[208:211], v[108:111]
	v_mfma_f32_16x16x32_bf16 v[104:107], v[160:163], v[204:207], v[104:107]
	v_mfma_f32_16x16x32_bf16 v[104:107], v[164:167], v[208:211], v[104:107]
	v_mfma_f32_16x16x32_bf16 v[100:103], v[152:155], v[212:215], v[100:103]
	v_mfma_f32_16x16x32_bf16 v[100:103], v[156:159], v[216:219], v[100:103]
	v_mfma_f32_16x16x32_bf16 v[96:99], v[160:163], v[212:215], v[96:99]
	v_mfma_f32_16x16x32_bf16 v[96:99], v[164:167], v[216:219], v[96:99]
	v_mfma_f32_16x16x32_bf16 v[68:71], v[168:171], v[188:191], v[68:71]
	v_mfma_f32_16x16x32_bf16 v[68:71], v[172:175], v[192:195], v[68:71]
	v_mfma_f32_16x16x32_bf16 v[64:67], v[176:179], v[188:191], v[64:67]
	v_mfma_f32_16x16x32_bf16 v[64:67], v[184:187], v[192:195], v[64:67]
	v_mfma_f32_16x16x32_bf16 v[52:55], v[168:171], v[196:199], v[52:55]
	v_mfma_f32_16x16x32_bf16 v[52:55], v[172:175], v[200:203], v[52:55]
	v_mfma_f32_16x16x32_bf16 v[48:51], v[176:179], v[196:199], v[48:51]
	v_mfma_f32_16x16x32_bf16 v[48:51], v[184:187], v[200:203], v[48:51]
	v_mfma_f32_16x16x32_bf16 v[44:47], v[168:171], v[204:207], v[44:47]
	v_mfma_f32_16x16x32_bf16 v[44:47], v[172:175], v[208:211], v[44:47]
	v_mfma_f32_16x16x32_bf16 v[40:43], v[176:179], v[204:207], v[40:43]
	v_mfma_f32_16x16x32_bf16 v[40:43], v[184:187], v[208:211], v[40:43]
	v_mfma_f32_16x16x32_bf16 v[36:39], v[168:171], v[212:215], v[36:39]
	v_mfma_f32_16x16x32_bf16 v[36:39], v[172:175], v[216:219], v[36:39]
	s_barrier
	v_mfma_f32_16x16x32_bf16 v[32:35], v[176:179], v[212:215], v[32:35]
	v_mfma_f32_16x16x32_bf16 v[32:35], v[184:187], v[216:219], v[32:35]
	s_setprio 0
	s_add_i32 s18, s76, s66
	v_lshl_add_u64 v[220:221], s[60:61], 0, v[132:133]
	s_mov_b32 m0, s18
	ds_read_b128 v[188:191], v150 offset:16384
	ds_read_b128 v[192:195], v150 offset:17408
	ds_read_b128 v[196:199], v150 offset:18432
	ds_read_b128 v[200:203], v150 offset:19456
	ds_read_b128 v[204:207], v150 offset:20480
	ds_read_b128 v[208:211], v150 offset:21504
	ds_read_b128 v[212:215], v150 offset:22528
	ds_read_b128 v[216:219], v150 offset:23552
	global_load_lds_dwordx4 v[220:221], off
	s_add_i32 m0, s18, 0x2000
	s_add_u32 s88, s60, 0x40000
	v_lshl_add_u64 v[222:223], s[60:61], 0, v[128:129]
	s_addc_u32 s89, s61, 0
	s_add_i32 s18, s77, s66
	global_load_lds_dwordx4 v[222:223], off
	v_lshl_add_u64 v[224:225], s[88:89], 0, v[132:133]
	s_mov_b32 m0, s18
	v_lshl_add_u64 v[226:227], s[62:63], 0, v[130:131]
	global_load_lds_dwordx4 v[224:225], off
	v_lshl_add_u64 v[224:225], s[88:89], 0, v[128:129]
	s_add_i32 m0, s18, 0x2000
	s_nop 0
	global_load_lds_dwordx4 v[224:225], off
	v_lshl_add_u64 v[224:225], s[62:63], 0, v[134:135]
	s_mov_b32 m0, s68
	s_nop 0
	global_load_lds_dwordx4 v[224:225], off
	s_mov_b32 m0, s69
	s_nop 0
	global_load_lds_dwordx4 v[226:227], off
	s_waitcnt vmcnt(8)
	s_waitcnt lgkmcnt(0)
	s_barrier
	s_waitcnt lgkmcnt(0)
	v_mfma_f32_16x16x32_bf16 v[92:95], v[152:155], v[188:191], v[92:95]
	v_mfma_f32_16x16x32_bf16 v[92:95], v[156:159], v[192:195], v[92:95]
	s_setprio 1
	v_mfma_f32_16x16x32_bf16 v[88:91], v[160:163], v[188:191], v[88:91]
	v_mfma_f32_16x16x32_bf16 v[88:91], v[164:167], v[192:195], v[88:91]
	v_mfma_f32_16x16x32_bf16 v[84:87], v[152:155], v[196:199], v[84:87]
	v_mfma_f32_16x16x32_bf16 v[84:87], v[156:159], v[200:203], v[84:87]
	v_mfma_f32_16x16x32_bf16 v[80:83], v[160:163], v[196:199], v[80:83]
	v_mfma_f32_16x16x32_bf16 v[80:83], v[164:167], v[200:203], v[80:83]
	v_mfma_f32_16x16x32_bf16 v[76:79], v[152:155], v[204:207], v[76:79]
	v_mfma_f32_16x16x32_bf16 v[76:79], v[156:159], v[208:211], v[76:79]
	v_mfma_f32_16x16x32_bf16 v[72:75], v[160:163], v[204:207], v[72:75]
	v_mfma_f32_16x16x32_bf16 v[72:75], v[164:167], v[208:211], v[72:75]
	v_mfma_f32_16x16x32_bf16 v[60:63], v[152:155], v[212:215], v[60:63]
	v_mfma_f32_16x16x32_bf16 v[60:63], v[156:159], v[216:219], v[60:63]
	v_mfma_f32_16x16x32_bf16 v[56:59], v[160:163], v[212:215], v[56:59]
	v_mfma_f32_16x16x32_bf16 v[56:59], v[164:167], v[216:219], v[56:59]
	v_mfma_f32_16x16x32_bf16 v[28:31], v[168:171], v[188:191], v[28:31]
	v_mfma_f32_16x16x32_bf16 v[28:31], v[172:175], v[192:195], v[28:31]
	v_mfma_f32_16x16x32_bf16 v[24:27], v[176:179], v[188:191], v[24:27]
	v_mfma_f32_16x16x32_bf16 v[24:27], v[184:187], v[192:195], v[24:27]
	v_mfma_f32_16x16x32_bf16 v[20:23], v[168:171], v[196:199], v[20:23]
	v_mfma_f32_16x16x32_bf16 v[20:23], v[172:175], v[200:203], v[20:23]
	v_mfma_f32_16x16x32_bf16 v[16:19], v[176:179], v[196:199], v[16:19]
	v_mfma_f32_16x16x32_bf16 v[16:19], v[184:187], v[200:203], v[16:19]
	v_mfma_f32_16x16x32_bf16 v[12:15], v[168:171], v[204:207], v[12:15]
	v_mfma_f32_16x16x32_bf16 v[12:15], v[172:175], v[208:211], v[12:15]
	v_mfma_f32_16x16x32_bf16 v[8:11], v[176:179], v[204:207], v[8:11]
	v_mfma_f32_16x16x32_bf16 v[8:11], v[184:187], v[208:211], v[8:11]
	v_mfma_f32_16x16x32_bf16 v[4:7], v[168:171], v[212:215], v[4:7]
	v_mfma_f32_16x16x32_bf16 v[4:7], v[172:175], v[216:219], v[4:7]
	s_barrier
	v_mfma_f32_16x16x32_bf16 v[0:3], v[176:179], v[212:215], v[0:3]
	v_mfma_f32_16x16x32_bf16 v[0:3], v[184:187], v[216:219], v[0:3]
	s_setprio 0
.Lmid_gemm2:
	s_add_i32 s18, 0, 0x18000
	s_add_i32 s19, 0, 0x1c000
	v_add_u32_e32 v164, s18, v147
	v_add_u32_e32 v181, s19, v147
	ds_read_b128 v[152:155], v164
	ds_read_b128 v[156:159], v164 offset:1024
	ds_read_b128 v[160:163], v164 offset:2048
	ds_read_b128 v[164:167], v164 offset:3072
	ds_read_b128 v[168:171], v181
	ds_read_b128 v[172:175], v181 offset:1024
	ds_read_b128 v[176:179], v181 offset:2048
	ds_read_b128 v[184:187], v181 offset:3072
	s_add_u32 s62, s62, 0x40000
	s_addc_u32 s63, s63, 0
	s_mov_b32 m0, s70
	v_lshl_add_u64 v[228:229], s[62:63], 0, v[134:135]
	ds_read_b128 v[188:191], v150 offset:32768
	ds_read_b128 v[192:195], v150 offset:33792
	ds_read_b128 v[196:199], v150 offset:34816
	ds_read_b128 v[200:203], v150 offset:35840
	ds_read_b128 v[204:207], v150 offset:36864
	ds_read_b128 v[208:211], v150 offset:37888
	ds_read_b128 v[212:215], v150 offset:38912
	ds_read_b128 v[216:219], v150 offset:39936
	global_load_lds_dwordx4 v[228:229], off
	v_lshl_add_u64 v[228:229], s[62:63], 0, v[130:131]
	s_mov_b32 m0, s71
	s_nop 0
	global_load_lds_dwordx4 v[228:229], off
	s_waitcnt vmcnt(8)
	s_waitcnt lgkmcnt(0)
	s_barrier
	s_waitcnt lgkmcnt(0)
	v_mfma_f32_16x16x32_bf16 v[124:127], v[152:155], v[188:191], v[124:127]
	v_mfma_f32_16x16x32_bf16 v[124:127], v[156:159], v[192:195], v[124:127]
	s_setprio 1
	v_mfma_f32_16x16x32_bf16 v[120:123], v[160:163], v[188:191], v[120:123]
	v_mfma_f32_16x16x32_bf16 v[120:123], v[164:167], v[192:195], v[120:123]
	v_mfma_f32_16x16x32_bf16 v[116:119], v[152:155], v[196:199], v[116:119]
	v_mfma_f32_16x16x32_bf16 v[116:119], v[156:159], v[200:203], v[116:119]
	v_mfma_f32_16x16x32_bf16 v[112:115], v[160:163], v[196:199], v[112:115]
	v_mfma_f32_16x16x32_bf16 v[112:115], v[164:167], v[200:203], v[112:115]
	v_mfma_f32_16x16x32_bf16 v[108:111], v[152:155], v[204:207], v[108:111]
	v_mfma_f32_16x16x32_bf16 v[108:111], v[156:159], v[208:211], v[108:111]
	v_mfma_f32_16x16x32_bf16 v[104:107], v[160:163], v[204:207], v[104:107]
	v_mfma_f32_16x16x32_bf16 v[104:107], v[164:167], v[208:211], v[104:107]
	v_mfma_f32_16x16x32_bf16 v[100:103], v[152:155], v[212:215], v[100:103]
	v_mfma_f32_16x16x32_bf16 v[100:103], v[156:159], v[216:219], v[100:103]
	v_mfma_f32_16x16x32_bf16 v[96:99], v[160:163], v[212:215], v[96:99]
	v_mfma_f32_16x16x32_bf16 v[96:99], v[164:167], v[216:219], v[96:99]
	v_mfma_f32_16x16x32_bf16 v[68:71], v[168:171], v[188:191], v[68:71]
	v_mfma_f32_16x16x32_bf16 v[68:71], v[172:175], v[192:195], v[68:71]
	v_mfma_f32_16x16x32_bf16 v[64:67], v[176:179], v[188:191], v[64:67]
	v_mfma_f32_16x16x32_bf16 v[64:67], v[184:187], v[192:195], v[64:67]
	v_mfma_f32_16x16x32_bf16 v[52:55], v[168:171], v[196:199], v[52:55]
	v_mfma_f32_16x16x32_bf16 v[52:55], v[172:175], v[200:203], v[52:55]
	v_mfma_f32_16x16x32_bf16 v[48:51], v[176:179], v[196:199], v[48:51]
	v_mfma_f32_16x16x32_bf16 v[48:51], v[184:187], v[200:203], v[48:51]
	v_mfma_f32_16x16x32_bf16 v[44:47], v[168:171], v[204:207], v[44:47]
	v_mfma_f32_16x16x32_bf16 v[44:47], v[172:175], v[208:211], v[44:47]
	v_mfma_f32_16x16x32_bf16 v[40:43], v[176:179], v[204:207], v[40:43]
	v_mfma_f32_16x16x32_bf16 v[40:43], v[184:187], v[208:211], v[40:43]
	v_mfma_f32_16x16x32_bf16 v[36:39], v[168:171], v[212:215], v[36:39]
	v_mfma_f32_16x16x32_bf16 v[36:39], v[172:175], v[216:219], v[36:39]
	s_barrier
	v_mfma_f32_16x16x32_bf16 v[32:35], v[176:179], v[212:215], v[32:35]
	v_mfma_f32_16x16x32_bf16 v[32:35], v[184:187], v[216:219], v[32:35]
	s_setprio 0
	s_add_i32 s18, s18, s66
	v_lshl_add_u64 v[220:221], v[220:221], 0, s[6:7]
	s_mov_b32 m0, s18
	ds_read_b128 v[188:191], v150 offset:49152
	ds_read_b128 v[192:195], v150 offset:50176
	ds_read_b128 v[196:199], v150 offset:51200
	ds_read_b128 v[200:203], v150 offset:52224
	ds_read_b128 v[204:207], v150 offset:53248
	ds_read_b128 v[208:211], v150 offset:54272
	ds_read_b128 v[212:215], v150 offset:55296
	ds_read_b128 v[216:219], v150 offset:56320
	global_load_lds_dwordx4 v[220:221], off
	s_add_i32 m0, s18, 0x2000
	s_add_u32 s60, s60, 0x40080
	v_lshl_add_u64 v[220:221], v[222:223], 0, s[6:7]
	s_addc_u32 s61, s61, 0
	s_add_i32 s18, s19, s66
	global_load_lds_dwordx4 v[220:221], off
	v_lshl_add_u64 v[220:221], s[60:61], 0, v[132:133]
	s_mov_b32 m0, s18
	s_nop 0
	global_load_lds_dwordx4 v[220:221], off
	v_lshl_add_u64 v[220:221], s[60:61], 0, v[128:129]
	s_add_i32 m0, s18, 0x2000
	s_nop 0
	global_load_lds_dwordx4 v[220:221], off
	v_lshl_add_u64 v[220:221], v[224:225], 0, s[6:7]
	s_mov_b32 m0, s74
	s_nop 0
	global_load_lds_dwordx4 v[220:221], off
	v_lshl_add_u64 v[220:221], v[226:227], 0, s[6:7]
	s_mov_b32 m0, s75
	s_nop 0
	global_load_lds_dwordx4 v[220:221], off
	s_waitcnt vmcnt(8)
	s_waitcnt lgkmcnt(0)
	s_barrier
	s_waitcnt lgkmcnt(0)
	v_mfma_f32_16x16x32_bf16 v[92:95], v[152:155], v[188:191], v[92:95]
	v_mfma_f32_16x16x32_bf16 v[92:95], v[156:159], v[192:195], v[92:95]
	s_setprio 1
	v_mfma_f32_16x16x32_bf16 v[88:91], v[160:163], v[188:191], v[88:91]
	v_mfma_f32_16x16x32_bf16 v[88:91], v[164:167], v[192:195], v[88:91]
	v_mfma_f32_16x16x32_bf16 v[84:87], v[152:155], v[196:199], v[84:87]
	v_mfma_f32_16x16x32_bf16 v[84:87], v[156:159], v[200:203], v[84:87]
	v_mfma_f32_16x16x32_bf16 v[80:83], v[160:163], v[196:199], v[80:83]
	v_mfma_f32_16x16x32_bf16 v[80:83], v[164:167], v[200:203], v[80:83]
	v_mfma_f32_16x16x32_bf16 v[76:79], v[152:155], v[204:207], v[76:79]
	v_mfma_f32_16x16x32_bf16 v[76:79], v[156:159], v[208:211], v[76:79]
	v_mfma_f32_16x16x32_bf16 v[72:75], v[160:163], v[204:207], v[72:75]
	v_mfma_f32_16x16x32_bf16 v[72:75], v[164:167], v[208:211], v[72:75]
	v_mfma_f32_16x16x32_bf16 v[60:63], v[152:155], v[212:215], v[60:63]
	v_mfma_f32_16x16x32_bf16 v[60:63], v[156:159], v[216:219], v[60:63]
	v_mfma_f32_16x16x32_bf16 v[56:59], v[160:163], v[212:215], v[56:59]
	v_mfma_f32_16x16x32_bf16 v[56:59], v[164:167], v[216:219], v[56:59]
	v_mfma_f32_16x16x32_bf16 v[28:31], v[168:171], v[188:191], v[28:31]
	v_mfma_f32_16x16x32_bf16 v[28:31], v[172:175], v[192:195], v[28:31]
	v_mfma_f32_16x16x32_bf16 v[24:27], v[176:179], v[188:191], v[24:27]
	v_mfma_f32_16x16x32_bf16 v[24:27], v[184:187], v[192:195], v[24:27]
	v_mfma_f32_16x16x32_bf16 v[20:23], v[168:171], v[196:199], v[20:23]
	v_mfma_f32_16x16x32_bf16 v[20:23], v[172:175], v[200:203], v[20:23]
	v_mfma_f32_16x16x32_bf16 v[16:19], v[176:179], v[196:199], v[16:19]
	v_mfma_f32_16x16x32_bf16 v[16:19], v[184:187], v[200:203], v[16:19]
	v_mfma_f32_16x16x32_bf16 v[12:15], v[168:171], v[204:207], v[12:15]
	v_mfma_f32_16x16x32_bf16 v[12:15], v[172:175], v[208:211], v[12:15]
	v_mfma_f32_16x16x32_bf16 v[8:11], v[176:179], v[204:207], v[8:11]
	v_mfma_f32_16x16x32_bf16 v[8:11], v[184:187], v[208:211], v[8:11]
	v_mfma_f32_16x16x32_bf16 v[4:7], v[168:171], v[212:215], v[4:7]
	v_mfma_f32_16x16x32_bf16 v[4:7], v[172:175], v[216:219], v[4:7]
	s_barrier
	v_mfma_f32_16x16x32_bf16 v[0:3], v[176:179], v[212:215], v[0:3]
	v_mfma_f32_16x16x32_bf16 v[0:3], v[184:187], v[216:219], v[0:3]
	s_setprio 0
	s_add_i32 s86, s86, 2
	s_add_u32 s58, s58, 0x100
	s_addc_u32 s59, s59, 0
	s_add_u32 s84, s84, 0x100
	s_addc_u32 s85, s85, 0
	s_cmp_gt_u32 s86, 13
	s_cbranch_scc0 .LBB0_387
	s_and_b64 vcc, exec, s[8:9]
	s_cbranch_vccz .LBB0_390
	s_barrier

.LBB0_600:
	s_ashr_i32 s49, s48, 31
	s_lshl_b64 s[18:19], s[48:49], 19
	s_add_u32 s52, s38, s18
	s_addc_u32 s53, s39, s19
	s_and_b64 s[18:19], s[4:5], exec
	s_cselect_b32 s49, s53, s59
	s_cselect_b32 s84, s52, s58
	s_ashr_i32 s47, s46, 31
	s_lshl_b64 s[18:19], s[46:47], 19
	s_add_u32 s54, s64, s18
	s_addc_u32 s55, s65, s19
	s_and_b64 s[18:19], s[4:5], exec
	s_cselect_b32 s47, s55, s61
	s_cselect_b32 s85, s54, s60
	s_add_u32 s58, s58, 0x40080
	s_addc_u32 s59, s59, 0
	s_add_u32 s86, s60, 0x100
	s_addc_u32 s87, s61, 0
	s_mov_b32 s88, -2
	ds_read_b128 v[152:155], v149
	ds_read_b128 v[156:159], v149 offset:1024
	ds_read_b128 v[160:163], v149 offset:2048
	ds_read_b128 v[164:167], v149 offset:3072
	ds_read_b128 v[168:171], v150
	ds_read_b128 v[172:175], v150 offset:1024
	ds_read_b128 v[176:179], v150 offset:2048
	ds_read_b128 v[184:187], v150 offset:3072
	s_add_u32 s18, s58, 0xfffc0080
	s_addc_u32 s19, s59, -1
	s_cmp_eq_u32 s88, 12
	s_cselect_b32 s63, s49, s19
	s_cselect_b32 s62, s84, s18
	s_cselect_b32 s61, s47, s87
	s_cselect_b32 s60, s85, s86
	v_lshl_add_u64 v[144:145], s[58:59], 0, v[136:137]
	s_add_i32 m0, s57, 0xc000
	ds_read_b128 v[188:191], v151
	ds_read_b128 v[192:195], v151 offset:1024
	ds_read_b128 v[196:199], v151 offset:2048
	ds_read_b128 v[200:203], v151 offset:3072
	ds_read_b128 v[204:207], v151 offset:4096
	ds_read_b128 v[208:211], v151 offset:5120
	ds_read_b128 v[212:215], v151 offset:6144
	ds_read_b128 v[216:219], v151 offset:7168
	global_load_lds_dwordx4 v[144:145], off
	v_lshl_add_u64 v[144:145], s[58:59], 0, v[138:139]
	s_add_i32 m0, s57, 0xe000
	s_nop 0
	global_load_lds_dwordx4 v[144:145], off
	s_waitcnt vmcnt(8)
	s_waitcnt lgkmcnt(0)
	s_barrier
	s_waitcnt lgkmcnt(0)
	v_mfma_f32_16x16x32_bf16 v[124:127], v[152:155], v[188:191], 0
	v_mfma_f32_16x16x32_bf16 v[124:127], v[156:159], v[192:195], v[124:127]
	s_setprio 1
	v_mfma_f32_16x16x32_bf16 v[120:123], v[160:163], v[188:191], 0
	v_mfma_f32_16x16x32_bf16 v[120:123], v[164:167], v[192:195], v[120:123]
	v_mfma_f32_16x16x32_bf16 v[116:119], v[152:155], v[196:199], 0
	v_mfma_f32_16x16x32_bf16 v[116:119], v[156:159], v[200:203], v[116:119]
	v_mfma_f32_16x16x32_bf16 v[108:111], v[160:163], v[196:199], 0
	v_mfma_f32_16x16x32_bf16 v[108:111], v[164:167], v[200:203], v[108:111]
	v_mfma_f32_16x16x32_bf16 v[100:103], v[152:155], v[204:207], 0
	v_mfma_f32_16x16x32_bf16 v[100:103], v[156:159], v[208:211], v[100:103]
	v_mfma_f32_16x16x32_bf16 v[92:95], v[160:163], v[204:207], 0
	v_mfma_f32_16x16x32_bf16 v[92:95], v[164:167], v[208:211], v[92:95]
	v_mfma_f32_16x16x32_bf16 v[84:87], v[152:155], v[212:215], 0
	v_mfma_f32_16x16x32_bf16 v[84:87], v[156:159], v[216:219], v[84:87]
	v_mfma_f32_16x16x32_bf16 v[76:79], v[160:163], v[212:215], 0
	v_mfma_f32_16x16x32_bf16 v[76:79], v[164:167], v[216:219], v[76:79]
	v_mfma_f32_16x16x32_bf16 v[112:115], v[168:171], v[188:191], 0
	v_mfma_f32_16x16x32_bf16 v[112:115], v[172:175], v[192:195], v[112:115]
	v_mfma_f32_16x16x32_bf16 v[104:107], v[176:179], v[188:191], 0
	v_mfma_f32_16x16x32_bf16 v[104:107], v[184:187], v[192:195], v[104:107]
	v_mfma_f32_16x16x32_bf16 v[96:99], v[168:171], v[196:199], 0
	v_mfma_f32_16x16x32_bf16 v[96:99], v[172:175], v[200:203], v[96:99]
	v_mfma_f32_16x16x32_bf16 v[88:91], v[176:179], v[196:199], 0
	v_mfma_f32_16x16x32_bf16 v[88:91], v[184:187], v[200:203], v[88:91]
	v_mfma_f32_16x16x32_bf16 v[80:83], v[168:171], v[204:207], 0
	v_mfma_f32_16x16x32_bf16 v[80:83], v[172:175], v[208:211], v[80:83]
	v_mfma_f32_16x16x32_bf16 v[72:75], v[176:179], v[204:207], 0
	v_mfma_f32_16x16x32_bf16 v[72:75], v[184:187], v[208:211], v[72:75]
	v_mfma_f32_16x16x32_bf16 v[68:71], v[168:171], v[212:215], 0
	v_mfma_f32_16x16x32_bf16 v[68:71], v[172:175], v[216:219], v[68:71]
	s_barrier
	v_mfma_f32_16x16x32_bf16 v[64:67], v[176:179], v[212:215], 0
	v_mfma_f32_16x16x32_bf16 v[64:67], v[184:187], v[216:219], v[64:67]
	s_setprio 0
	s_add_i32 s18, s73, s66
	v_lshl_add_u64 v[144:145], s[60:61], 0, v[130:131]
	s_mov_b32 m0, s18
	ds_read_b128 v[188:191], v151 offset:16384
	ds_read_b128 v[192:195], v151 offset:17408
	ds_read_b128 v[196:199], v151 offset:18432
	ds_read_b128 v[200:203], v151 offset:19456
	ds_read_b128 v[204:207], v151 offset:20480
	ds_read_b128 v[208:211], v151 offset:21504
	ds_read_b128 v[212:215], v151 offset:22528
	ds_read_b128 v[216:219], v151 offset:23552
	global_load_lds_dwordx4 v[144:145], off
	s_add_i32 m0, s18, 0x2000
	s_add_u32 s18, s60, 0x40000
	v_lshl_add_u64 v[220:221], s[60:61], 0, v[134:135]
	s_addc_u32 s19, s61, 0
	s_add_i32 s79, s74, s66
	global_load_lds_dwordx4 v[220:221], off
	v_lshl_add_u64 v[222:223], s[18:19], 0, v[130:131]
	s_mov_b32 m0, s79
	v_lshl_add_u64 v[224:225], s[62:63], 0, v[132:133]
	global_load_lds_dwordx4 v[222:223], off
	v_lshl_add_u64 v[222:223], s[18:19], 0, v[134:135]
	s_add_i32 m0, s79, 0x2000
	s_nop 0
	global_load_lds_dwordx4 v[222:223], off
	v_lshl_add_u64 v[222:223], s[62:63], 0, v[128:129]
	s_mov_b32 m0, s57
	s_nop 0
	global_load_lds_dwordx4 v[222:223], off
	s_mov_b32 m0, s67
	s_nop 0
	global_load_lds_dwordx4 v[224:225], off
	s_waitcnt vmcnt(8)
	s_waitcnt lgkmcnt(0)
	s_barrier
	s_waitcnt lgkmcnt(0)
	v_mfma_f32_16x16x32_bf16 v[60:63], v[152:155], v[188:191], 0
	v_mfma_f32_16x16x32_bf16 v[60:63], v[156:159], v[192:195], v[60:63]
	s_setprio 1
	v_mfma_f32_16x16x32_bf16 v[56:59], v[160:163], v[188:191], 0
	v_mfma_f32_16x16x32_bf16 v[56:59], v[164:167], v[192:195], v[56:59]
	v_mfma_f32_16x16x32_bf16 v[52:55], v[152:155], v[196:199], 0
	v_mfma_f32_16x16x32_bf16 v[52:55], v[156:159], v[200:203], v[52:55]
	v_mfma_f32_16x16x32_bf16 v[44:47], v[160:163], v[196:199], 0
	v_mfma_f32_16x16x32_bf16 v[44:47], v[164:167], v[200:203], v[44:47]
	v_mfma_f32_16x16x32_bf16 v[36:39], v[152:155], v[204:207], 0
	v_mfma_f32_16x16x32_bf16 v[36:39], v[156:159], v[208:211], v[36:39]
	v_mfma_f32_16x16x32_bf16 v[28:31], v[160:163], v[204:207], 0
	v_mfma_f32_16x16x32_bf16 v[28:31], v[164:167], v[208:211], v[28:31]
	v_mfma_f32_16x16x32_bf16 v[20:23], v[152:155], v[212:215], 0
	v_mfma_f32_16x16x32_bf16 v[20:23], v[156:159], v[216:219], v[20:23]
	v_mfma_f32_16x16x32_bf16 v[12:15], v[160:163], v[212:215], 0
	v_mfma_f32_16x16x32_bf16 v[12:15], v[164:167], v[216:219], v[12:15]
	v_mfma_f32_16x16x32_bf16 v[48:51], v[168:171], v[188:191], 0
	v_mfma_f32_16x16x32_bf16 v[48:51], v[172:175], v[192:195], v[48:51]
	v_mfma_f32_16x16x32_bf16 v[40:43], v[176:179], v[188:191], 0
	v_mfma_f32_16x16x32_bf16 v[40:43], v[184:187], v[192:195], v[40:43]
	v_mfma_f32_16x16x32_bf16 v[32:35], v[168:171], v[196:199], 0
	v_mfma_f32_16x16x32_bf16 v[32:35], v[172:175], v[200:203], v[32:35]
	v_mfma_f32_16x16x32_bf16 v[24:27], v[176:179], v[196:199], 0
	v_mfma_f32_16x16x32_bf16 v[24:27], v[184:187], v[200:203], v[24:27]
	v_mfma_f32_16x16x32_bf16 v[16:19], v[168:171], v[204:207], 0
	v_mfma_f32_16x16x32_bf16 v[16:19], v[172:175], v[208:211], v[16:19]
	v_mfma_f32_16x16x32_bf16 v[8:11], v[176:179], v[204:207], 0
	v_mfma_f32_16x16x32_bf16 v[8:11], v[184:187], v[208:211], v[8:11]
	v_mfma_f32_16x16x32_bf16 v[4:7], v[168:171], v[212:215], 0
	v_mfma_f32_16x16x32_bf16 v[4:7], v[172:175], v[216:219], v[4:7]
	s_barrier
	v_mfma_f32_16x16x32_bf16 v[0:3], v[176:179], v[212:215], 0
	v_mfma_f32_16x16x32_bf16 v[0:3], v[184:187], v[216:219], v[0:3]
	s_setprio 0
	s_branch .Lmid_gemm3
.LBB0_601:
	ds_read_b128 v[152:155], v149
	ds_read_b128 v[156:159], v149 offset:1024
	ds_read_b128 v[160:163], v149 offset:2048
	ds_read_b128 v[164:167], v149 offset:3072
	ds_read_b128 v[168:171], v150
	ds_read_b128 v[172:175], v150 offset:1024
	ds_read_b128 v[176:179], v150 offset:2048
	ds_read_b128 v[184:187], v150 offset:3072
	s_add_u32 s18, s58, 0xfffc0080
	s_addc_u32 s19, s59, -1
	s_cmp_eq_u32 s88, 12
	s_cselect_b32 s63, s49, s19
	s_cselect_b32 s62, s84, s18
	s_cselect_b32 s61, s47, s87
	s_cselect_b32 s60, s85, s86
	v_lshl_add_u64 v[144:145], s[58:59], 0, v[136:137]
	s_add_i32 m0, s57, 0xc000
	ds_read_b128 v[188:191], v151
	ds_read_b128 v[192:195], v151 offset:1024
	ds_read_b128 v[196:199], v151 offset:2048
	ds_read_b128 v[200:203], v151 offset:3072
	ds_read_b128 v[204:207], v151 offset:4096
	ds_read_b128 v[208:211], v151 offset:5120
	ds_read_b128 v[212:215], v151 offset:6144
	ds_read_b128 v[216:219], v151 offset:7168
	global_load_lds_dwordx4 v[144:145], off
	v_lshl_add_u64 v[144:145], s[58:59], 0, v[138:139]
	s_add_i32 m0, s57, 0xe000
	s_nop 0
	global_load_lds_dwordx4 v[144:145], off
	s_waitcnt vmcnt(8)
	s_waitcnt lgkmcnt(0)
	s_barrier
	s_waitcnt lgkmcnt(0)
	v_mfma_f32_16x16x32_bf16 v[124:127], v[152:155], v[188:191], v[124:127]
	v_mfma_f32_16x16x32_bf16 v[124:127], v[156:159], v[192:195], v[124:127]
	s_setprio 1
	v_mfma_f32_16x16x32_bf16 v[120:123], v[160:163], v[188:191], v[120:123]
	v_mfma_f32_16x16x32_bf16 v[120:123], v[164:167], v[192:195], v[120:123]
	v_mfma_f32_16x16x32_bf16 v[116:119], v[152:155], v[196:199], v[116:119]
	v_mfma_f32_16x16x32_bf16 v[116:119], v[156:159], v[200:203], v[116:119]
	v_mfma_f32_16x16x32_bf16 v[108:111], v[160:163], v[196:199], v[108:111]
	v_mfma_f32_16x16x32_bf16 v[108:111], v[164:167], v[200:203], v[108:111]
	v_mfma_f32_16x16x32_bf16 v[100:103], v[152:155], v[204:207], v[100:103]
	v_mfma_f32_16x16x32_bf16 v[100:103], v[156:159], v[208:211], v[100:103]
	v_mfma_f32_16x16x32_bf16 v[92:95], v[160:163], v[204:207], v[92:95]
	v_mfma_f32_16x16x32_bf16 v[92:95], v[164:167], v[208:211], v[92:95]
	v_mfma_f32_16x16x32_bf16 v[84:87], v[152:155], v[212:215], v[84:87]
	v_mfma_f32_16x16x32_bf16 v[84:87], v[156:159], v[216:219], v[84:87]
	v_mfma_f32_16x16x32_bf16 v[76:79], v[160:163], v[212:215], v[76:79]
	v_mfma_f32_16x16x32_bf16 v[76:79], v[164:167], v[216:219], v[76:79]
	v_mfma_f32_16x16x32_bf16 v[112:115], v[168:171], v[188:191], v[112:115]
	v_mfma_f32_16x16x32_bf16 v[112:115], v[172:175], v[192:195], v[112:115]
	v_mfma_f32_16x16x32_bf16 v[104:107], v[176:179], v[188:191], v[104:107]
	v_mfma_f32_16x16x32_bf16 v[104:107], v[184:187], v[192:195], v[104:107]
	v_mfma_f32_16x16x32_bf16 v[96:99], v[168:171], v[196:199], v[96:99]
	v_mfma_f32_16x16x32_bf16 v[96:99], v[172:175], v[200:203], v[96:99]
	v_mfma_f32_16x16x32_bf16 v[88:91], v[176:179], v[196:199], v[88:91]
	v_mfma_f32_16x16x32_bf16 v[88:91], v[184:187], v[200:203], v[88:91]
	v_mfma_f32_16x16x32_bf16 v[80:83], v[168:171], v[204:207], v[80:83]
	v_mfma_f32_16x16x32_bf16 v[80:83], v[172:175], v[208:211], v[80:83]
	v_mfma_f32_16x16x32_bf16 v[72:75], v[176:179], v[204:207], v[72:75]
	v_mfma_f32_16x16x32_bf16 v[72:75], v[184:187], v[208:211], v[72:75]
	v_mfma_f32_16x16x32_bf16 v[68:71], v[168:171], v[212:215], v[68:71]
	v_mfma_f32_16x16x32_bf16 v[68:71], v[172:175], v[216:219], v[68:71]
	s_barrier
	v_mfma_f32_16x16x32_bf16 v[64:67], v[176:179], v[212:215], v[64:67]
	v_mfma_f32_16x16x32_bf16 v[64:67], v[184:187], v[216:219], v[64:67]
	s_setprio 0
	s_add_i32 s18, s73, s66
	v_lshl_add_u64 v[144:145], s[60:61], 0, v[130:131]
	s_mov_b32 m0, s18
	ds_read_b128 v[188:191], v151 offset:16384
	ds_read_b128 v[192:195], v151 offset:17408
	ds_read_b128 v[196:199], v151 offset:18432
	ds_read_b128 v[200:203], v151 offset:19456
	ds_read_b128 v[204:207], v151 offset:20480
	ds_read_b128 v[208:211], v151 offset:21504
	ds_read_b128 v[212:215], v151 offset:22528
	ds_read_b128 v[216:219], v151 offset:23552
	global_load_lds_dwordx4 v[144:145], off
	s_add_i32 m0, s18, 0x2000
	s_add_u32 s18, s60, 0x40000
	v_lshl_add_u64 v[220:221], s[60:61], 0, v[134:135]
	s_addc_u32 s19, s61, 0
	s_add_i32 s79, s74, s66
	global_load_lds_dwordx4 v[220:221], off
	v_lshl_add_u64 v[222:223], s[18:19], 0, v[130:131]
	s_mov_b32 m0, s79
	v_lshl_add_u64 v[224:225], s[62:63], 0, v[132:133]
	global_load_lds_dwordx4 v[222:223], off
	v_lshl_add_u64 v[222:223], s[18:19], 0, v[134:135]
	s_add_i32 m0, s79, 0x2000
	s_nop 0
	global_load_lds_dwordx4 v[222:223], off
	v_lshl_add_u64 v[222:223], s[62:63], 0, v[128:129]
	s_mov_b32 m0, s57
	s_nop 0
	global_load_lds_dwordx4 v[222:223], off
	s_mov_b32 m0, s67
	s_nop 0
	global_load_lds_dwordx4 v[224:225], off
	s_waitcnt vmcnt(8)
	s_waitcnt lgkmcnt(0)
	s_barrier
	s_waitcnt lgkmcnt(0)
	v_mfma_f32_16x16x32_bf16 v[60:63], v[152:155], v[188:191], v[60:63]
	v_mfma_f32_16x16x32_bf16 v[60:63], v[156:159], v[192:195], v[60:63]
	s_setprio 1
	v_mfma_f32_16x16x32_bf16 v[56:59], v[160:163], v[188:191], v[56:59]
	v_mfma_f32_16x16x32_bf16 v[56:59], v[164:167], v[192:195], v[56:59]
	v_mfma_f32_16x16x32_bf16 v[52:55], v[152:155], v[196:199], v[52:55]
	v_mfma_f32_16x16x32_bf16 v[52:55], v[156:159], v[200:203], v[52:55]
	v_mfma_f32_16x16x32_bf16 v[44:47], v[160:163], v[196:199], v[44:47]
	v_mfma_f32_16x16x32_bf16 v[44:47], v[164:167], v[200:203], v[44:47]
	v_mfma_f32_16x16x32_bf16 v[36:39], v[152:155], v[204:207], v[36:39]
	v_mfma_f32_16x16x32_bf16 v[36:39], v[156:159], v[208:211], v[36:39]
	v_mfma_f32_16x16x32_bf16 v[28:31], v[160:163], v[204:207], v[28:31]
	v_mfma_f32_16x16x32_bf16 v[28:31], v[164:167], v[208:211], v[28:31]
	v_mfma_f32_16x16x32_bf16 v[20:23], v[152:155], v[212:215], v[20:23]
	v_mfma_f32_16x16x32_bf16 v[20:23], v[156:159], v[216:219], v[20:23]
	v_mfma_f32_16x16x32_bf16 v[12:15], v[160:163], v[212:215], v[12:15]
	v_mfma_f32_16x16x32_bf16 v[12:15], v[164:167], v[216:219], v[12:15]
	v_mfma_f32_16x16x32_bf16 v[48:51], v[168:171], v[188:191], v[48:51]
	v_mfma_f32_16x16x32_bf16 v[48:51], v[172:175], v[192:195], v[48:51]
	v_mfma_f32_16x16x32_bf16 v[40:43], v[176:179], v[188:191], v[40:43]
	v_mfma_f32_16x16x32_bf16 v[40:43], v[184:187], v[192:195], v[40:43]
	v_mfma_f32_16x16x32_bf16 v[32:35], v[168:171], v[196:199], v[32:35]
	v_mfma_f32_16x16x32_bf16 v[32:35], v[172:175], v[200:203], v[32:35]
	v_mfma_f32_16x16x32_bf16 v[24:27], v[176:179], v[196:199], v[24:27]
	v_mfma_f32_16x16x32_bf16 v[24:27], v[184:187], v[200:203], v[24:27]
	v_mfma_f32_16x16x32_bf16 v[16:19], v[168:171], v[204:207], v[16:19]
	v_mfma_f32_16x16x32_bf16 v[16:19], v[172:175], v[208:211], v[16:19]
	v_mfma_f32_16x16x32_bf16 v[8:11], v[176:179], v[204:207], v[8:11]
	v_mfma_f32_16x16x32_bf16 v[8:11], v[184:187], v[208:211], v[8:11]
	v_mfma_f32_16x16x32_bf16 v[4:7], v[168:171], v[212:215], v[4:7]
	v_mfma_f32_16x16x32_bf16 v[4:7], v[172:175], v[216:219], v[4:7]
	s_barrier
	v_mfma_f32_16x16x32_bf16 v[0:3], v[176:179], v[212:215], v[0:3]
	v_mfma_f32_16x16x32_bf16 v[0:3], v[184:187], v[216:219], v[0:3]
	s_setprio 0
.Lmid_gemm3:
	s_add_i32 s79, 0, 0x18000
	s_add_i32 s89, 0, 0x1c000
	v_add_u32_e32 v164, s79, v147
	v_add_u32_e32 v181, s89, v147
	ds_read_b128 v[152:155], v164
	ds_read_b128 v[156:159], v164 offset:1024
	ds_read_b128 v[160:163], v164 offset:2048
	ds_read_b128 v[164:167], v164 offset:3072
	ds_read_b128 v[168:171], v181
	ds_read_b128 v[172:175], v181 offset:1024
	ds_read_b128 v[176:179], v181 offset:2048
	ds_read_b128 v[184:187], v181 offset:3072
	s_add_u32 s18, s62, 0x40000
	s_addc_u32 s19, s63, 0
	s_mov_b32 m0, s68
	v_lshl_add_u64 v[226:227], s[18:19], 0, v[128:129]
	ds_read_b128 v[188:191], v151 offset:32768
	ds_read_b128 v[192:195], v151 offset:33792
	ds_read_b128 v[196:199], v151 offset:34816
	ds_read_b128 v[200:203], v151 offset:35840
	ds_read_b128 v[204:207], v151 offset:36864
	ds_read_b128 v[208:211], v151 offset:37888
	ds_read_b128 v[212:215], v151 offset:38912
	ds_read_b128 v[216:219], v151 offset:39936
	global_load_lds_dwordx4 v[226:227], off
	v_lshl_add_u64 v[226:227], s[18:19], 0, v[132:133]
	s_mov_b32 m0, s69
	s_nop 0
	global_load_lds_dwordx4 v[226:227], off
	s_waitcnt vmcnt(8)
	s_waitcnt lgkmcnt(0)
	s_barrier
	s_waitcnt lgkmcnt(0)
	v_mfma_f32_16x16x32_bf16 v[124:127], v[152:155], v[188:191], v[124:127]
	v_mfma_f32_16x16x32_bf16 v[124:127], v[156:159], v[192:195], v[124:127]
	s_setprio 1
	v_mfma_f32_16x16x32_bf16 v[120:123], v[160:163], v[188:191], v[120:123]
	v_mfma_f32_16x16x32_bf16 v[120:123], v[164:167], v[192:195], v[120:123]
	v_mfma_f32_16x16x32_bf16 v[116:119], v[152:155], v[196:199], v[116:119]
	v_mfma_f32_16x16x32_bf16 v[116:119], v[156:159], v[200:203], v[116:119]
	v_mfma_f32_16x16x32_bf16 v[108:111], v[160:163], v[196:199], v[108:111]
	v_mfma_f32_16x16x32_bf16 v[108:111], v[164:167], v[200:203], v[108:111]
	v_mfma_f32_16x16x32_bf16 v[100:103], v[152:155], v[204:207], v[100:103]
	v_mfma_f32_16x16x32_bf16 v[100:103], v[156:159], v[208:211], v[100:103]
	v_mfma_f32_16x16x32_bf16 v[92:95], v[160:163], v[204:207], v[92:95]
	v_mfma_f32_16x16x32_bf16 v[92:95], v[164:167], v[208:211], v[92:95]
	v_mfma_f32_16x16x32_bf16 v[84:87], v[152:155], v[212:215], v[84:87]
	v_mfma_f32_16x16x32_bf16 v[84:87], v[156:159], v[216:219], v[84:87]
	v_mfma_f32_16x16x32_bf16 v[76:79], v[160:163], v[212:215], v[76:79]
	v_mfma_f32_16x16x32_bf16 v[76:79], v[164:167], v[216:219], v[76:79]
	v_mfma_f32_16x16x32_bf16 v[112:115], v[168:171], v[188:191], v[112:115]
	v_mfma_f32_16x16x32_bf16 v[112:115], v[172:175], v[192:195], v[112:115]
	v_mfma_f32_16x16x32_bf16 v[104:107], v[176:179], v[188:191], v[104:107]
	v_mfma_f32_16x16x32_bf16 v[104:107], v[184:187], v[192:195], v[104:107]
	v_mfma_f32_16x16x32_bf16 v[96:99], v[168:171], v[196:199], v[96:99]
	v_mfma_f32_16x16x32_bf16 v[96:99], v[172:175], v[200:203], v[96:99]
	v_mfma_f32_16x16x32_bf16 v[88:91], v[176:179], v[196:199], v[88:91]
	v_mfma_f32_16x16x32_bf16 v[88:91], v[184:187], v[200:203], v[88:91]
	v_mfma_f32_16x16x32_bf16 v[80:83], v[168:171], v[204:207], v[80:83]
	v_mfma_f32_16x16x32_bf16 v[80:83], v[172:175], v[208:211], v[80:83]
	v_mfma_f32_16x16x32_bf16 v[72:75], v[176:179], v[204:207], v[72:75]
	v_mfma_f32_16x16x32_bf16 v[72:75], v[184:187], v[208:211], v[72:75]
	v_mfma_f32_16x16x32_bf16 v[68:71], v[168:171], v[212:215], v[68:71]
	v_mfma_f32_16x16x32_bf16 v[68:71], v[172:175], v[216:219], v[68:71]
	s_barrier
	v_mfma_f32_16x16x32_bf16 v[64:67], v[176:179], v[212:215], v[64:67]
	v_mfma_f32_16x16x32_bf16 v[64:67], v[184:187], v[216:219], v[64:67]
	s_setprio 0
	s_add_i32 s18, s79, s66
	v_lshl_add_u64 v[144:145], v[144:145], 0, s[10:11]
	s_mov_b32 m0, s18
	ds_read_b128 v[188:191], v151 offset:49152
	ds_read_b128 v[192:195], v151 offset:50176
	ds_read_b128 v[196:199], v151 offset:51200
	ds_read_b128 v[200:203], v151 offset:52224
	ds_read_b128 v[204:207], v151 offset:53248
	ds_read_b128 v[208:211], v151 offset:54272
	ds_read_b128 v[212:215], v151 offset:55296
	ds_read_b128 v[216:219], v151 offset:56320
	global_load_lds_dwordx4 v[144:145], off
	s_add_i32 m0, s18, 0x2000
	s_add_u32 s18, s60, 0x40080
	v_lshl_add_u64 v[144:145], v[220:221], 0, s[10:11]
	s_addc_u32 s19, s61, 0
	s_add_i32 s60, s89, s66
	global_load_lds_dwordx4 v[144:145], off
	v_lshl_add_u64 v[144:145], s[18:19], 0, v[130:131]
	s_mov_b32 m0, s60
	s_nop 0
	global_load_lds_dwordx4 v[144:145], off
	v_lshl_add_u64 v[144:145], s[18:19], 0, v[134:135]
	s_add_i32 m0, s60, 0x2000
	s_nop 0
	global_load_lds_dwordx4 v[144:145], off
	v_lshl_add_u64 v[144:145], v[222:223], 0, s[10:11]
	s_mov_b32 m0, s71
	s_nop 0
	global_load_lds_dwordx4 v[144:145], off
	v_lshl_add_u64 v[144:145], v[224:225], 0, s[10:11]
	s_mov_b32 m0, s72
	s_nop 0
	global_load_lds_dwordx4 v[144:145], off
	s_waitcnt vmcnt(8)
	s_waitcnt lgkmcnt(0)
	s_barrier
	s_waitcnt lgkmcnt(0)
	v_mfma_f32_16x16x32_bf16 v[60:63], v[152:155], v[188:191], v[60:63]
	v_mfma_f32_16x16x32_bf16 v[60:63], v[156:159], v[192:195], v[60:63]
	s_setprio 1
	v_mfma_f32_16x16x32_bf16 v[56:59], v[160:163], v[188:191], v[56:59]
	v_mfma_f32_16x16x32_bf16 v[56:59], v[164:167], v[192:195], v[56:59]
	v_mfma_f32_16x16x32_bf16 v[52:55], v[152:155], v[196:199], v[52:55]
	v_mfma_f32_16x16x32_bf16 v[52:55], v[156:159], v[200:203], v[52:55]
	v_mfma_f32_16x16x32_bf16 v[44:47], v[160:163], v[196:199], v[44:47]
	v_mfma_f32_16x16x32_bf16 v[44:47], v[164:167], v[200:203], v[44:47]
	v_mfma_f32_16x16x32_bf16 v[36:39], v[152:155], v[204:207], v[36:39]
	v_mfma_f32_16x16x32_bf16 v[36:39], v[156:159], v[208:211], v[36:39]
	v_mfma_f32_16x16x32_bf16 v[28:31], v[160:163], v[204:207], v[28:31]
	v_mfma_f32_16x16x32_bf16 v[28:31], v[164:167], v[208:211], v[28:31]
	v_mfma_f32_16x16x32_bf16 v[20:23], v[152:155], v[212:215], v[20:23]
	v_mfma_f32_16x16x32_bf16 v[20:23], v[156:159], v[216:219], v[20:23]
	v_mfma_f32_16x16x32_bf16 v[12:15], v[160:163], v[212:215], v[12:15]
	v_mfma_f32_16x16x32_bf16 v[12:15], v[164:167], v[216:219], v[12:15]
	v_mfma_f32_16x16x32_bf16 v[48:51], v[168:171], v[188:191], v[48:51]
	v_mfma_f32_16x16x32_bf16 v[48:51], v[172:175], v[192:195], v[48:51]
	v_mfma_f32_16x16x32_bf16 v[40:43], v[176:179], v[188:191], v[40:43]
	v_mfma_f32_16x16x32_bf16 v[40:43], v[184:187], v[192:195], v[40:43]
	v_mfma_f32_16x16x32_bf16 v[32:35], v[168:171], v[196:199], v[32:35]
	v_mfma_f32_16x16x32_bf16 v[32:35], v[172:175], v[200:203], v[32:35]
	v_mfma_f32_16x16x32_bf16 v[24:27], v[176:179], v[196:199], v[24:27]
	v_mfma_f32_16x16x32_bf16 v[24:27], v[184:187], v[200:203], v[24:27]
	v_mfma_f32_16x16x32_bf16 v[16:19], v[168:171], v[204:207], v[16:19]
	v_mfma_f32_16x16x32_bf16 v[16:19], v[172:175], v[208:211], v[16:19]
	v_mfma_f32_16x16x32_bf16 v[8:11], v[176:179], v[204:207], v[8:11]
	v_mfma_f32_16x16x32_bf16 v[8:11], v[184:187], v[208:211], v[8:11]
	v_mfma_f32_16x16x32_bf16 v[4:7], v[168:171], v[212:215], v[4:7]
	v_mfma_f32_16x16x32_bf16 v[4:7], v[172:175], v[216:219], v[4:7]
	s_barrier
	v_mfma_f32_16x16x32_bf16 v[0:3], v[176:179], v[212:215], v[0:3]
	v_mfma_f32_16x16x32_bf16 v[0:3], v[184:187], v[216:219], v[0:3]
	s_setprio 0
	s_add_i32 s88, s88, 2
	s_add_u32 s58, s58, 0x100
	s_addc_u32 s59, s59, 0
	s_add_u32 s86, s86, 0x100
	s_addc_u32 s87, s87, 0
	s_cmp_gt_u32 s88, 13
	s_cbranch_scc0 .LBB0_601
	s_and_b64 vcc, exec, s[12:13]
	s_cbranch_vccz .LBB0_604
	s_barrier

.LBB0_723:
	s_ashr_i32 s31, s30, 31
	s_lshl_b64 s[36:37], s[30:31], 19
	s_add_u32 s36, s80, s36
	s_addc_u32 s37, s81, s37
	s_and_b64 s[44:45], s[10:11], exec
	s_cselect_b32 s31, s37, s49
	s_cselect_b32 s70, s36, s48
	s_ashr_i32 s19, s18, 31
	s_lshl_b64 s[44:45], s[18:19], 19
	s_add_u32 s44, s56, s44
	s_addc_u32 s45, s57, s45
	s_and_b64 s[54:55], s[10:11], exec
	s_cselect_b32 s19, s45, s53
	s_cselect_b32 s71, s44, s52
	s_add_u32 s48, s48, 0x40080
	s_addc_u32 s49, s49, 0
	s_add_u32 s72, s52, 0x100
	s_addc_u32 s73, s53, 0
	s_mov_b32 s74, -2
	ds_read_b128 v[140:143], v147
	ds_read_b128 v[150:153], v147 offset:1024
	ds_read_b128 v[154:157], v147 offset:2048
	ds_read_b128 v[158:161], v147 offset:3072
	ds_read_b128 v[162:165], v148
	ds_read_b128 v[166:169], v148 offset:1024
	ds_read_b128 v[170:173], v148 offset:2048
	ds_read_b128 v[174:177], v148 offset:3072
	s_add_u32 s52, s48, 0xfffc0080
	s_addc_u32 s53, s49, -1
	s_cmp_eq_u32 s74, 12
	s_cselect_b32 s55, s31, s53
	s_cselect_b32 s54, s70, s52
	s_cselect_b32 s53, s19, s73
	s_cselect_b32 s52, s71, s72
	v_lshl_add_u64 v[178:179], s[48:49], 0, v[132:133]
	s_add_i32 m0, s47, 0xc000
	ds_read_b128 v[184:187], v149
	ds_read_b128 v[188:191], v149 offset:1024
	ds_read_b128 v[192:195], v149 offset:2048
	ds_read_b128 v[196:199], v149 offset:3072
	ds_read_b128 v[200:203], v149 offset:4096
	ds_read_b128 v[204:207], v149 offset:5120
	ds_read_b128 v[208:211], v149 offset:6144
	ds_read_b128 v[212:215], v149 offset:7168
	global_load_lds_dwordx4 v[178:179], off
	v_lshl_add_u64 v[178:179], s[48:49], 0, v[134:135]
	s_add_i32 m0, s47, 0xe000
	s_nop 0
	global_load_lds_dwordx4 v[178:179], off
	s_waitcnt vmcnt(8)
	s_waitcnt lgkmcnt(0)
	s_barrier
	s_waitcnt lgkmcnt(0)
	v_mfma_f32_16x16x32_bf16 v[124:127], v[140:143], v[184:187], 0
	v_mfma_f32_16x16x32_bf16 v[124:127], v[150:153], v[188:191], v[124:127]
	s_setprio 1
	v_mfma_f32_16x16x32_bf16 v[120:123], v[154:157], v[184:187], 0
	v_mfma_f32_16x16x32_bf16 v[120:123], v[158:161], v[188:191], v[120:123]
	v_mfma_f32_16x16x32_bf16 v[108:111], v[140:143], v[192:195], 0
	v_mfma_f32_16x16x32_bf16 v[108:111], v[150:153], v[196:199], v[108:111]
	v_mfma_f32_16x16x32_bf16 v[104:107], v[154:157], v[192:195], 0
	v_mfma_f32_16x16x32_bf16 v[104:107], v[158:161], v[196:199], v[104:107]
	v_mfma_f32_16x16x32_bf16 v[92:95], v[140:143], v[200:203], 0
	v_mfma_f32_16x16x32_bf16 v[92:95], v[150:153], v[204:207], v[92:95]
	v_mfma_f32_16x16x32_bf16 v[88:91], v[154:157], v[200:203], 0
	v_mfma_f32_16x16x32_bf16 v[88:91], v[158:161], v[204:207], v[88:91]
	v_mfma_f32_16x16x32_bf16 v[76:79], v[140:143], v[208:211], 0
	v_mfma_f32_16x16x32_bf16 v[76:79], v[150:153], v[212:215], v[76:79]
	v_mfma_f32_16x16x32_bf16 v[72:75], v[154:157], v[208:211], 0
	v_mfma_f32_16x16x32_bf16 v[72:75], v[158:161], v[212:215], v[72:75]
	v_mfma_f32_16x16x32_bf16 v[116:119], v[162:165], v[184:187], 0
	v_mfma_f32_16x16x32_bf16 v[116:119], v[166:169], v[188:191], v[116:119]
	v_mfma_f32_16x16x32_bf16 v[112:115], v[170:173], v[184:187], 0
	v_mfma_f32_16x16x32_bf16 v[112:115], v[174:177], v[188:191], v[112:115]
	v_mfma_f32_16x16x32_bf16 v[100:103], v[162:165], v[192:195], 0
	v_mfma_f32_16x16x32_bf16 v[100:103], v[166:169], v[196:199], v[100:103]
	v_mfma_f32_16x16x32_bf16 v[96:99], v[170:173], v[192:195], 0
	v_mfma_f32_16x16x32_bf16 v[96:99], v[174:177], v[196:199], v[96:99]
	v_mfma_f32_16x16x32_bf16 v[84:87], v[162:165], v[200:203], 0
	v_mfma_f32_16x16x32_bf16 v[84:87], v[166:169], v[204:207], v[84:87]
	v_mfma_f32_16x16x32_bf16 v[80:83], v[170:173], v[200:203], 0
	v_mfma_f32_16x16x32_bf16 v[80:83], v[174:177], v[204:207], v[80:83]
	v_mfma_f32_16x16x32_bf16 v[68:71], v[162:165], v[208:211], 0
	v_mfma_f32_16x16x32_bf16 v[68:71], v[166:169], v[212:215], v[68:71]
	s_barrier
	v_mfma_f32_16x16x32_bf16 v[64:67], v[170:173], v[208:211], 0
	v_mfma_f32_16x16x32_bf16 v[64:67], v[174:177], v[212:215], v[64:67]
	s_setprio 0
	s_add_i32 s75, s66, s58
	v_lshl_add_u64 v[178:179], s[52:53], 0, v[130:131]
	s_mov_b32 m0, s75
	ds_read_b128 v[184:187], v149 offset:16384
	ds_read_b128 v[188:191], v149 offset:17408
	ds_read_b128 v[192:195], v149 offset:18432
	ds_read_b128 v[196:199], v149 offset:19456
	ds_read_b128 v[200:203], v149 offset:20480
	ds_read_b128 v[204:207], v149 offset:21504
	ds_read_b128 v[208:211], v149 offset:22528
	ds_read_b128 v[212:215], v149 offset:23552
	global_load_lds_dwordx4 v[178:179], off
	s_add_i32 m0, s75, 0x2000
	s_add_u32 s76, s52, 0x40000
	v_lshl_add_u64 v[216:217], s[52:53], 0, v[128:129]
	s_addc_u32 s77, s53, 0
	s_add_i32 s75, s67, s58
	global_load_lds_dwordx4 v[216:217], off
	v_lshl_add_u64 v[218:219], s[76:77], 0, v[130:131]
	s_mov_b32 m0, s75
	v_lshl_add_u64 v[220:221], s[54:55], 0, v[128:129]
	global_load_lds_dwordx4 v[218:219], off
	v_lshl_add_u64 v[218:219], s[76:77], 0, v[128:129]
	s_add_i32 m0, s75, 0x2000
	s_nop 0
	global_load_lds_dwordx4 v[218:219], off
	v_lshl_add_u64 v[218:219], s[54:55], 0, v[130:131]
	s_mov_b32 m0, s47
	s_nop 0
	global_load_lds_dwordx4 v[218:219], off
	s_mov_b32 m0, s60
	s_nop 0
	global_load_lds_dwordx4 v[220:221], off
	s_waitcnt vmcnt(8)
	s_waitcnt lgkmcnt(0)
	s_barrier
	s_waitcnt lgkmcnt(0)
	v_mfma_f32_16x16x32_bf16 v[60:63], v[140:143], v[184:187], 0
	v_mfma_f32_16x16x32_bf16 v[60:63], v[150:153], v[188:191], v[60:63]
	s_setprio 1
	v_mfma_f32_16x16x32_bf16 v[56:59], v[154:157], v[184:187], 0
	v_mfma_f32_16x16x32_bf16 v[56:59], v[158:161], v[188:191], v[56:59]
	v_mfma_f32_16x16x32_bf16 v[44:47], v[140:143], v[192:195], 0
	v_mfma_f32_16x16x32_bf16 v[44:47], v[150:153], v[196:199], v[44:47]
	v_mfma_f32_16x16x32_bf16 v[40:43], v[154:157], v[192:195], 0
	v_mfma_f32_16x16x32_bf16 v[40:43], v[158:161], v[196:199], v[40:43]
	v_mfma_f32_16x16x32_bf16 v[28:31], v[140:143], v[200:203], 0
	v_mfma_f32_16x16x32_bf16 v[28:31], v[150:153], v[204:207], v[28:31]
	v_mfma_f32_16x16x32_bf16 v[24:27], v[154:157], v[200:203], 0
	v_mfma_f32_16x16x32_bf16 v[24:27], v[158:161], v[204:207], v[24:27]
	v_mfma_f32_16x16x32_bf16 v[12:15], v[140:143], v[208:211], 0
	v_mfma_f32_16x16x32_bf16 v[12:15], v[150:153], v[212:215], v[12:15]
	v_mfma_f32_16x16x32_bf16 v[8:11], v[154:157], v[208:211], 0
	v_mfma_f32_16x16x32_bf16 v[8:11], v[158:161], v[212:215], v[8:11]
	v_mfma_f32_16x16x32_bf16 v[52:55], v[162:165], v[184:187], 0
	v_mfma_f32_16x16x32_bf16 v[52:55], v[166:169], v[188:191], v[52:55]
	v_mfma_f32_16x16x32_bf16 v[48:51], v[170:173], v[184:187], 0
	v_mfma_f32_16x16x32_bf16 v[48:51], v[174:177], v[188:191], v[48:51]
	v_mfma_f32_16x16x32_bf16 v[36:39], v[162:165], v[192:195], 0
	v_mfma_f32_16x16x32_bf16 v[36:39], v[166:169], v[196:199], v[36:39]
	v_mfma_f32_16x16x32_bf16 v[32:35], v[170:173], v[192:195], 0
	v_mfma_f32_16x16x32_bf16 v[32:35], v[174:177], v[196:199], v[32:35]
	v_mfma_f32_16x16x32_bf16 v[20:23], v[162:165], v[200:203], 0
	v_mfma_f32_16x16x32_bf16 v[20:23], v[166:169], v[204:207], v[20:23]
	v_mfma_f32_16x16x32_bf16 v[16:19], v[170:173], v[200:203], 0
	v_mfma_f32_16x16x32_bf16 v[16:19], v[174:177], v[204:207], v[16:19]
	v_mfma_f32_16x16x32_bf16 v[4:7], v[162:165], v[208:211], 0
	v_mfma_f32_16x16x32_bf16 v[4:7], v[166:169], v[212:215], v[4:7]
	s_barrier
	v_mfma_f32_16x16x32_bf16 v[0:3], v[170:173], v[208:211], 0
	v_mfma_f32_16x16x32_bf16 v[0:3], v[174:177], v[212:215], v[0:3]
	s_setprio 0
	s_branch .Lmid_gemm4
.LBB0_724:
	ds_read_b128 v[140:143], v147
	ds_read_b128 v[150:153], v147 offset:1024
	ds_read_b128 v[154:157], v147 offset:2048
	ds_read_b128 v[158:161], v147 offset:3072
	ds_read_b128 v[162:165], v148
	ds_read_b128 v[166:169], v148 offset:1024
	ds_read_b128 v[170:173], v148 offset:2048
	ds_read_b128 v[174:177], v148 offset:3072
	s_add_u32 s52, s48, 0xfffc0080
	s_addc_u32 s53, s49, -1
	s_cmp_eq_u32 s74, 12
	s_cselect_b32 s55, s31, s53
	s_cselect_b32 s54, s70, s52
	s_cselect_b32 s53, s19, s73
	s_cselect_b32 s52, s71, s72
	v_lshl_add_u64 v[178:179], s[48:49], 0, v[132:133]
	s_add_i32 m0, s47, 0xc000
	ds_read_b128 v[184:187], v149
	ds_read_b128 v[188:191], v149 offset:1024
	ds_read_b128 v[192:195], v149 offset:2048
	ds_read_b128 v[196:199], v149 offset:3072
	ds_read_b128 v[200:203], v149 offset:4096
	ds_read_b128 v[204:207], v149 offset:5120
	ds_read_b128 v[208:211], v149 offset:6144
	ds_read_b128 v[212:215], v149 offset:7168
	global_load_lds_dwordx4 v[178:179], off
	v_lshl_add_u64 v[178:179], s[48:49], 0, v[134:135]
	s_add_i32 m0, s47, 0xe000
	s_nop 0
	global_load_lds_dwordx4 v[178:179], off
	s_waitcnt vmcnt(8)
	s_waitcnt lgkmcnt(0)
	s_barrier
	s_waitcnt lgkmcnt(0)
	v_mfma_f32_16x16x32_bf16 v[124:127], v[140:143], v[184:187], v[124:127]
	v_mfma_f32_16x16x32_bf16 v[124:127], v[150:153], v[188:191], v[124:127]
	s_setprio 1
	v_mfma_f32_16x16x32_bf16 v[120:123], v[154:157], v[184:187], v[120:123]
	v_mfma_f32_16x16x32_bf16 v[120:123], v[158:161], v[188:191], v[120:123]
	v_mfma_f32_16x16x32_bf16 v[108:111], v[140:143], v[192:195], v[108:111]
	v_mfma_f32_16x16x32_bf16 v[108:111], v[150:153], v[196:199], v[108:111]
	v_mfma_f32_16x16x32_bf16 v[104:107], v[154:157], v[192:195], v[104:107]
	v_mfma_f32_16x16x32_bf16 v[104:107], v[158:161], v[196:199], v[104:107]
	v_mfma_f32_16x16x32_bf16 v[92:95], v[140:143], v[200:203], v[92:95]
	v_mfma_f32_16x16x32_bf16 v[92:95], v[150:153], v[204:207], v[92:95]
	v_mfma_f32_16x16x32_bf16 v[88:91], v[154:157], v[200:203], v[88:91]
	v_mfma_f32_16x16x32_bf16 v[88:91], v[158:161], v[204:207], v[88:91]
	v_mfma_f32_16x16x32_bf16 v[76:79], v[140:143], v[208:211], v[76:79]
	v_mfma_f32_16x16x32_bf16 v[76:79], v[150:153], v[212:215], v[76:79]
	v_mfma_f32_16x16x32_bf16 v[72:75], v[154:157], v[208:211], v[72:75]
	v_mfma_f32_16x16x32_bf16 v[72:75], v[158:161], v[212:215], v[72:75]
	v_mfma_f32_16x16x32_bf16 v[116:119], v[162:165], v[184:187], v[116:119]
	v_mfma_f32_16x16x32_bf16 v[116:119], v[166:169], v[188:191], v[116:119]
	v_mfma_f32_16x16x32_bf16 v[112:115], v[170:173], v[184:187], v[112:115]
	v_mfma_f32_16x16x32_bf16 v[112:115], v[174:177], v[188:191], v[112:115]
	v_mfma_f32_16x16x32_bf16 v[100:103], v[162:165], v[192:195], v[100:103]
	v_mfma_f32_16x16x32_bf16 v[100:103], v[166:169], v[196:199], v[100:103]
	v_mfma_f32_16x16x32_bf16 v[96:99], v[170:173], v[192:195], v[96:99]
	v_mfma_f32_16x16x32_bf16 v[96:99], v[174:177], v[196:199], v[96:99]
	v_mfma_f32_16x16x32_bf16 v[84:87], v[162:165], v[200:203], v[84:87]
	v_mfma_f32_16x16x32_bf16 v[84:87], v[166:169], v[204:207], v[84:87]
	v_mfma_f32_16x16x32_bf16 v[80:83], v[170:173], v[200:203], v[80:83]
	v_mfma_f32_16x16x32_bf16 v[80:83], v[174:177], v[204:207], v[80:83]
	v_mfma_f32_16x16x32_bf16 v[68:71], v[162:165], v[208:211], v[68:71]
	v_mfma_f32_16x16x32_bf16 v[68:71], v[166:169], v[212:215], v[68:71]
	s_barrier
	v_mfma_f32_16x16x32_bf16 v[64:67], v[170:173], v[208:211], v[64:67]
	v_mfma_f32_16x16x32_bf16 v[64:67], v[174:177], v[212:215], v[64:67]
	s_setprio 0
	s_add_i32 s75, s66, s58
	v_lshl_add_u64 v[178:179], s[52:53], 0, v[130:131]
	s_mov_b32 m0, s75
	ds_read_b128 v[184:187], v149 offset:16384
	ds_read_b128 v[188:191], v149 offset:17408
	ds_read_b128 v[192:195], v149 offset:18432
	ds_read_b128 v[196:199], v149 offset:19456
	ds_read_b128 v[200:203], v149 offset:20480
	ds_read_b128 v[204:207], v149 offset:21504
	ds_read_b128 v[208:211], v149 offset:22528
	ds_read_b128 v[212:215], v149 offset:23552
	global_load_lds_dwordx4 v[178:179], off
	s_add_i32 m0, s75, 0x2000
	s_add_u32 s76, s52, 0x40000
	v_lshl_add_u64 v[216:217], s[52:53], 0, v[128:129]
	s_addc_u32 s77, s53, 0
	s_add_i32 s75, s67, s58
	global_load_lds_dwordx4 v[216:217], off
	v_lshl_add_u64 v[218:219], s[76:77], 0, v[130:131]
	s_mov_b32 m0, s75
	v_lshl_add_u64 v[220:221], s[54:55], 0, v[128:129]
	global_load_lds_dwordx4 v[218:219], off
	v_lshl_add_u64 v[218:219], s[76:77], 0, v[128:129]
	s_add_i32 m0, s75, 0x2000
	s_nop 0
	global_load_lds_dwordx4 v[218:219], off
	v_lshl_add_u64 v[218:219], s[54:55], 0, v[130:131]
	s_mov_b32 m0, s47
	s_nop 0
	global_load_lds_dwordx4 v[218:219], off
	s_mov_b32 m0, s60
	s_nop 0
	global_load_lds_dwordx4 v[220:221], off
	s_waitcnt vmcnt(8)
	s_waitcnt lgkmcnt(0)
	s_barrier
	s_waitcnt lgkmcnt(0)
	v_mfma_f32_16x16x32_bf16 v[60:63], v[140:143], v[184:187], v[60:63]
	v_mfma_f32_16x16x32_bf16 v[60:63], v[150:153], v[188:191], v[60:63]
	s_setprio 1
	v_mfma_f32_16x16x32_bf16 v[56:59], v[154:157], v[184:187], v[56:59]
	v_mfma_f32_16x16x32_bf16 v[56:59], v[158:161], v[188:191], v[56:59]
	v_mfma_f32_16x16x32_bf16 v[44:47], v[140:143], v[192:195], v[44:47]
	v_mfma_f32_16x16x32_bf16 v[44:47], v[150:153], v[196:199], v[44:47]
	v_mfma_f32_16x16x32_bf16 v[40:43], v[154:157], v[192:195], v[40:43]
	v_mfma_f32_16x16x32_bf16 v[40:43], v[158:161], v[196:199], v[40:43]
	v_mfma_f32_16x16x32_bf16 v[28:31], v[140:143], v[200:203], v[28:31]
	v_mfma_f32_16x16x32_bf16 v[28:31], v[150:153], v[204:207], v[28:31]
	v_mfma_f32_16x16x32_bf16 v[24:27], v[154:157], v[200:203], v[24:27]
	v_mfma_f32_16x16x32_bf16 v[24:27], v[158:161], v[204:207], v[24:27]
	v_mfma_f32_16x16x32_bf16 v[12:15], v[140:143], v[208:211], v[12:15]
	v_mfma_f32_16x16x32_bf16 v[12:15], v[150:153], v[212:215], v[12:15]
	v_mfma_f32_16x16x32_bf16 v[8:11], v[154:157], v[208:211], v[8:11]
	v_mfma_f32_16x16x32_bf16 v[8:11], v[158:161], v[212:215], v[8:11]
	v_mfma_f32_16x16x32_bf16 v[52:55], v[162:165], v[184:187], v[52:55]
	v_mfma_f32_16x16x32_bf16 v[52:55], v[166:169], v[188:191], v[52:55]
	v_mfma_f32_16x16x32_bf16 v[48:51], v[170:173], v[184:187], v[48:51]
	v_mfma_f32_16x16x32_bf16 v[48:51], v[174:177], v[188:191], v[48:51]
	v_mfma_f32_16x16x32_bf16 v[36:39], v[162:165], v[192:195], v[36:39]
	v_mfma_f32_16x16x32_bf16 v[36:39], v[166:169], v[196:199], v[36:39]
	v_mfma_f32_16x16x32_bf16 v[32:35], v[170:173], v[192:195], v[32:35]
	v_mfma_f32_16x16x32_bf16 v[32:35], v[174:177], v[196:199], v[32:35]
	v_mfma_f32_16x16x32_bf16 v[20:23], v[162:165], v[200:203], v[20:23]
	v_mfma_f32_16x16x32_bf16 v[20:23], v[166:169], v[204:207], v[20:23]
	v_mfma_f32_16x16x32_bf16 v[16:19], v[170:173], v[200:203], v[16:19]
	v_mfma_f32_16x16x32_bf16 v[16:19], v[174:177], v[204:207], v[16:19]
	v_mfma_f32_16x16x32_bf16 v[4:7], v[162:165], v[208:211], v[4:7]
	v_mfma_f32_16x16x32_bf16 v[4:7], v[166:169], v[212:215], v[4:7]
	s_barrier
	v_mfma_f32_16x16x32_bf16 v[0:3], v[170:173], v[208:211], v[0:3]
	v_mfma_f32_16x16x32_bf16 v[0:3], v[174:177], v[212:215], v[0:3]
	s_setprio 0
.Lmid_gemm4:
	s_add_i32 s75, 0, 0x18000
	s_add_i32 s76, 0, 0x1c000
	v_add_u32_e32 v158, s75, v145
	v_add_u32_e32 v174, s76, v145
	ds_read_b128 v[140:143], v158
	ds_read_b128 v[150:153], v158 offset:1024
	ds_read_b128 v[154:157], v158 offset:2048
	ds_read_b128 v[158:161], v158 offset:3072
	ds_read_b128 v[162:165], v174
	ds_read_b128 v[166:169], v174 offset:1024
	ds_read_b128 v[170:173], v174 offset:2048
	ds_read_b128 v[174:177], v174 offset:3072
	s_add_u32 s54, s54, 0x40000
	s_addc_u32 s55, s55, 0
	s_mov_b32 m0, s61
	v_lshl_add_u64 v[222:223], s[54:55], 0, v[130:131]
	ds_read_b128 v[184:187], v149 offset:32768
	ds_read_b128 v[188:191], v149 offset:33792
	ds_read_b128 v[192:195], v149 offset:34816
	ds_read_b128 v[196:199], v149 offset:35840
	ds_read_b128 v[200:203], v149 offset:36864
	ds_read_b128 v[204:207], v149 offset:37888
	ds_read_b128 v[208:211], v149 offset:38912
	ds_read_b128 v[212:215], v149 offset:39936
	global_load_lds_dwordx4 v[222:223], off
	v_lshl_add_u64 v[222:223], s[54:55], 0, v[128:129]
	s_mov_b32 m0, s62
	s_nop 0
	global_load_lds_dwordx4 v[222:223], off
	s_waitcnt vmcnt(8)
	s_waitcnt lgkmcnt(0)
	s_barrier
	s_waitcnt lgkmcnt(0)
	v_mfma_f32_16x16x32_bf16 v[124:127], v[140:143], v[184:187], v[124:127]
	v_mfma_f32_16x16x32_bf16 v[124:127], v[150:153], v[188:191], v[124:127]
	s_setprio 1
	v_mfma_f32_16x16x32_bf16 v[120:123], v[154:157], v[184:187], v[120:123]
	v_mfma_f32_16x16x32_bf16 v[120:123], v[158:161], v[188:191], v[120:123]
	v_mfma_f32_16x16x32_bf16 v[108:111], v[140:143], v[192:195], v[108:111]
	v_mfma_f32_16x16x32_bf16 v[108:111], v[150:153], v[196:199], v[108:111]
	v_mfma_f32_16x16x32_bf16 v[104:107], v[154:157], v[192:195], v[104:107]
	v_mfma_f32_16x16x32_bf16 v[104:107], v[158:161], v[196:199], v[104:107]
	v_mfma_f32_16x16x32_bf16 v[92:95], v[140:143], v[200:203], v[92:95]
	v_mfma_f32_16x16x32_bf16 v[92:95], v[150:153], v[204:207], v[92:95]
	v_mfma_f32_16x16x32_bf16 v[88:91], v[154:157], v[200:203], v[88:91]
	v_mfma_f32_16x16x32_bf16 v[88:91], v[158:161], v[204:207], v[88:91]
	v_mfma_f32_16x16x32_bf16 v[76:79], v[140:143], v[208:211], v[76:79]
	v_mfma_f32_16x16x32_bf16 v[76:79], v[150:153], v[212:215], v[76:79]
	v_mfma_f32_16x16x32_bf16 v[72:75], v[154:157], v[208:211], v[72:75]
	v_mfma_f32_16x16x32_bf16 v[72:75], v[158:161], v[212:215], v[72:75]
	v_mfma_f32_16x16x32_bf16 v[116:119], v[162:165], v[184:187], v[116:119]
	v_mfma_f32_16x16x32_bf16 v[116:119], v[166:169], v[188:191], v[116:119]
	v_mfma_f32_16x16x32_bf16 v[112:115], v[170:173], v[184:187], v[112:115]
	v_mfma_f32_16x16x32_bf16 v[112:115], v[174:177], v[188:191], v[112:115]
	v_mfma_f32_16x16x32_bf16 v[100:103], v[162:165], v[192:195], v[100:103]
	v_mfma_f32_16x16x32_bf16 v[100:103], v[166:169], v[196:199], v[100:103]
	v_mfma_f32_16x16x32_bf16 v[96:99], v[170:173], v[192:195], v[96:99]
	v_mfma_f32_16x16x32_bf16 v[96:99], v[174:177], v[196:199], v[96:99]
	v_mfma_f32_16x16x32_bf16 v[84:87], v[162:165], v[200:203], v[84:87]
	v_mfma_f32_16x16x32_bf16 v[84:87], v[166:169], v[204:207], v[84:87]
	v_mfma_f32_16x16x32_bf16 v[80:83], v[170:173], v[200:203], v[80:83]
	v_mfma_f32_16x16x32_bf16 v[80:83], v[174:177], v[204:207], v[80:83]
	v_mfma_f32_16x16x32_bf16 v[68:71], v[162:165], v[208:211], v[68:71]
	v_mfma_f32_16x16x32_bf16 v[68:71], v[166:169], v[212:215], v[68:71]
	s_barrier
	v_mfma_f32_16x16x32_bf16 v[64:67], v[170:173], v[208:211], v[64:67]
	v_mfma_f32_16x16x32_bf16 v[64:67], v[174:177], v[212:215], v[64:67]
	s_setprio 0
	s_add_i32 s54, s75, s58
	v_lshl_add_u64 v[178:179], v[178:179], 0, s[12:13]
	s_mov_b32 m0, s54
	ds_read_b128 v[184:187], v149 offset:49152
	ds_read_b128 v[188:191], v149 offset:50176
	ds_read_b128 v[192:195], v149 offset:51200
	ds_read_b128 v[196:199], v149 offset:52224
	ds_read_b128 v[200:203], v149 offset:53248
	ds_read_b128 v[204:207], v149 offset:54272
	ds_read_b128 v[208:211], v149 offset:55296
	ds_read_b128 v[212:215], v149 offset:56320
	global_load_lds_dwordx4 v[178:179], off
	s_add_i32 m0, s54, 0x2000
	s_add_u32 s52, s52, 0x40080
	v_lshl_add_u64 v[178:179], v[216:217], 0, s[12:13]
	s_addc_u32 s53, s53, 0
	s_add_i32 s54, s76, s58
	global_load_lds_dwordx4 v[178:179], off
	v_lshl_add_u64 v[178:179], s[52:53], 0, v[130:131]
	s_mov_b32 m0, s54
	s_nop 0
	global_load_lds_dwordx4 v[178:179], off
	v_lshl_add_u64 v[178:179], s[52:53], 0, v[128:129]
	s_add_i32 m0, s54, 0x2000
	s_nop 0
	global_load_lds_dwordx4 v[178:179], off
	v_lshl_add_u64 v[178:179], v[218:219], 0, s[12:13]
	s_mov_b32 m0, s64
	s_nop 0
	global_load_lds_dwordx4 v[178:179], off
	v_lshl_add_u64 v[178:179], v[220:221], 0, s[12:13]
	s_mov_b32 m0, s65
	s_nop 0
	global_load_lds_dwordx4 v[178:179], off
	s_waitcnt vmcnt(8)
	s_waitcnt lgkmcnt(0)
	s_barrier
	s_waitcnt lgkmcnt(0)
	v_mfma_f32_16x16x32_bf16 v[60:63], v[140:143], v[184:187], v[60:63]
	v_mfma_f32_16x16x32_bf16 v[60:63], v[150:153], v[188:191], v[60:63]
	s_setprio 1
	v_mfma_f32_16x16x32_bf16 v[56:59], v[154:157], v[184:187], v[56:59]
	v_mfma_f32_16x16x32_bf16 v[56:59], v[158:161], v[188:191], v[56:59]
	v_mfma_f32_16x16x32_bf16 v[44:47], v[140:143], v[192:195], v[44:47]
	v_mfma_f32_16x16x32_bf16 v[44:47], v[150:153], v[196:199], v[44:47]
	v_mfma_f32_16x16x32_bf16 v[40:43], v[154:157], v[192:195], v[40:43]
	v_mfma_f32_16x16x32_bf16 v[40:43], v[158:161], v[196:199], v[40:43]
	v_mfma_f32_16x16x32_bf16 v[28:31], v[140:143], v[200:203], v[28:31]
	v_mfma_f32_16x16x32_bf16 v[28:31], v[150:153], v[204:207], v[28:31]
	v_mfma_f32_16x16x32_bf16 v[24:27], v[154:157], v[200:203], v[24:27]
	v_mfma_f32_16x16x32_bf16 v[24:27], v[158:161], v[204:207], v[24:27]
	v_mfma_f32_16x16x32_bf16 v[12:15], v[140:143], v[208:211], v[12:15]
	v_mfma_f32_16x16x32_bf16 v[12:15], v[150:153], v[212:215], v[12:15]
	v_mfma_f32_16x16x32_bf16 v[8:11], v[154:157], v[208:211], v[8:11]
	v_mfma_f32_16x16x32_bf16 v[8:11], v[158:161], v[212:215], v[8:11]
	v_mfma_f32_16x16x32_bf16 v[52:55], v[162:165], v[184:187], v[52:55]
	v_mfma_f32_16x16x32_bf16 v[52:55], v[166:169], v[188:191], v[52:55]
	v_mfma_f32_16x16x32_bf16 v[48:51], v[170:173], v[184:187], v[48:51]
	v_mfma_f32_16x16x32_bf16 v[48:51], v[174:177], v[188:191], v[48:51]
	v_mfma_f32_16x16x32_bf16 v[36:39], v[162:165], v[192:195], v[36:39]
	v_mfma_f32_16x16x32_bf16 v[36:39], v[166:169], v[196:199], v[36:39]
	v_mfma_f32_16x16x32_bf16 v[32:35], v[170:173], v[192:195], v[32:35]
	v_mfma_f32_16x16x32_bf16 v[32:35], v[174:177], v[196:199], v[32:35]
	v_mfma_f32_16x16x32_bf16 v[20:23], v[162:165], v[200:203], v[20:23]
	v_mfma_f32_16x16x32_bf16 v[20:23], v[166:169], v[204:207], v[20:23]
	v_mfma_f32_16x16x32_bf16 v[16:19], v[170:173], v[200:203], v[16:19]
	v_mfma_f32_16x16x32_bf16 v[16:19], v[174:177], v[204:207], v[16:19]
	v_mfma_f32_16x16x32_bf16 v[4:7], v[162:165], v[208:211], v[4:7]
	v_mfma_f32_16x16x32_bf16 v[4:7], v[166:169], v[212:215], v[4:7]
	s_barrier
	v_mfma_f32_16x16x32_bf16 v[0:3], v[170:173], v[208:211], v[0:3]
	v_mfma_f32_16x16x32_bf16 v[0:3], v[174:177], v[212:215], v[0:3]
	s_setprio 0
	s_add_i32 s74, s74, 2
	s_add_u32 s48, s48, 0x100
	s_addc_u32 s49, s49, 0
	s_add_u32 s72, s72, 0x100
	s_addc_u32 s73, s73, 0
	s_cmp_gt_u32 s74, 13
	s_cbranch_scc0 .LBB0_724
	s_and_b64 vcc, exec, s[16:17]
	s_cbranch_vccz .LBB0_727
	s_barrier

.LBB0_803:
	s_add_u32 s84, s54, 0x100
	s_addc_u32 s85, s55, 0
	s_mov_b32 s86, -2
	ds_read_b128 v[152:155], v149
	ds_read_b128 v[156:159], v149 offset:1024
	ds_read_b128 v[160:163], v149 offset:2048
	ds_read_b128 v[164:167], v149 offset:3072
	ds_read_b128 v[168:171], v150
	ds_read_b128 v[172:175], v150 offset:1024
	ds_read_b128 v[176:179], v150 offset:2048
	ds_read_b128 v[184:187], v150 offset:3072
	s_add_u32 s54, s52, 0x100
	s_addc_u32 s55, s53, 0
	s_cmp_eq_u32 s86, 40
	s_cselect_b32 s59, s13, s55
	s_cselect_b32 s58, s12, s54
	s_cselect_b32 s57, s49, s85
	s_cselect_b32 s56, s48, s84
	v_lshl_add_u64 v[144:145], s[52:53], 0, v[136:137]
	s_add_i32 m0, s63, 0xc000
	ds_read_b128 v[188:191], v151
	ds_read_b128 v[192:195], v151 offset:1024
	ds_read_b128 v[196:199], v151 offset:2048
	ds_read_b128 v[200:203], v151 offset:3072
	ds_read_b128 v[204:207], v151 offset:4096
	ds_read_b128 v[208:211], v151 offset:5120
	ds_read_b128 v[212:215], v151 offset:6144
	ds_read_b128 v[216:219], v151 offset:7168
	global_load_lds_dwordx4 v[144:145], off
	v_lshl_add_u64 v[144:145], s[52:53], 0, v[138:139]
	s_add_i32 m0, s63, 0xe000
	s_nop 0
	global_load_lds_dwordx4 v[144:145], off
	s_waitcnt vmcnt(8)
	s_waitcnt lgkmcnt(0)
	s_barrier
	s_waitcnt lgkmcnt(0)
	v_mfma_f32_16x16x32_bf16 v[124:127], v[152:155], v[188:191], 0
	v_mfma_f32_16x16x32_bf16 v[124:127], v[156:159], v[192:195], v[124:127]
	s_setprio 1
	v_mfma_f32_16x16x32_bf16 v[120:123], v[160:163], v[188:191], 0
	v_mfma_f32_16x16x32_bf16 v[120:123], v[164:167], v[192:195], v[120:123]
	v_mfma_f32_16x16x32_bf16 v[116:119], v[152:155], v[196:199], 0
	v_mfma_f32_16x16x32_bf16 v[116:119], v[156:159], v[200:203], v[116:119]
	v_mfma_f32_16x16x32_bf16 v[108:111], v[160:163], v[196:199], 0
	v_mfma_f32_16x16x32_bf16 v[108:111], v[164:167], v[200:203], v[108:111]
	v_mfma_f32_16x16x32_bf16 v[100:103], v[152:155], v[204:207], 0
	v_mfma_f32_16x16x32_bf16 v[100:103], v[156:159], v[208:211], v[100:103]
	v_mfma_f32_16x16x32_bf16 v[92:95], v[160:163], v[204:207], 0
	v_mfma_f32_16x16x32_bf16 v[92:95], v[164:167], v[208:211], v[92:95]
	v_mfma_f32_16x16x32_bf16 v[84:87], v[152:155], v[212:215], 0
	v_mfma_f32_16x16x32_bf16 v[84:87], v[156:159], v[216:219], v[84:87]
	v_mfma_f32_16x16x32_bf16 v[76:79], v[160:163], v[212:215], 0
	v_mfma_f32_16x16x32_bf16 v[76:79], v[164:167], v[216:219], v[76:79]
	v_mfma_f32_16x16x32_bf16 v[112:115], v[168:171], v[188:191], 0
	v_mfma_f32_16x16x32_bf16 v[112:115], v[172:175], v[192:195], v[112:115]
	v_mfma_f32_16x16x32_bf16 v[104:107], v[176:179], v[188:191], 0
	v_mfma_f32_16x16x32_bf16 v[104:107], v[184:187], v[192:195], v[104:107]
	v_mfma_f32_16x16x32_bf16 v[96:99], v[168:171], v[196:199], 0
	v_mfma_f32_16x16x32_bf16 v[96:99], v[172:175], v[200:203], v[96:99]
	v_mfma_f32_16x16x32_bf16 v[88:91], v[176:179], v[196:199], 0
	v_mfma_f32_16x16x32_bf16 v[88:91], v[184:187], v[200:203], v[88:91]
	v_mfma_f32_16x16x32_bf16 v[80:83], v[168:171], v[204:207], 0
	v_mfma_f32_16x16x32_bf16 v[80:83], v[172:175], v[208:211], v[80:83]
	v_mfma_f32_16x16x32_bf16 v[72:75], v[176:179], v[204:207], 0
	v_mfma_f32_16x16x32_bf16 v[72:75], v[184:187], v[208:211], v[72:75]
	v_mfma_f32_16x16x32_bf16 v[68:71], v[168:171], v[212:215], 0
	v_mfma_f32_16x16x32_bf16 v[68:71], v[172:175], v[216:219], v[68:71]
	s_barrier
	v_mfma_f32_16x16x32_bf16 v[64:67], v[176:179], v[212:215], 0
	v_mfma_f32_16x16x32_bf16 v[64:67], v[184:187], v[216:219], v[64:67]
	s_setprio 0
	s_add_i32 s52, s70, s62
	v_lshl_add_u64 v[144:145], s[56:57], 0, v[130:131]
	s_mov_b32 m0, s52
	ds_read_b128 v[188:191], v151 offset:16384
	ds_read_b128 v[192:195], v151 offset:17408
	ds_read_b128 v[196:199], v151 offset:18432
	ds_read_b128 v[200:203], v151 offset:19456
	ds_read_b128 v[204:207], v151 offset:20480
	ds_read_b128 v[208:211], v151 offset:21504
	ds_read_b128 v[212:215], v151 offset:22528
	ds_read_b128 v[216:219], v151 offset:23552
	global_load_lds_dwordx4 v[144:145], off
	s_add_i32 m0, s52, 0x2000
	s_add_u32 s52, s56, 0xb0000
	v_lshl_add_u64 v[220:221], s[56:57], 0, v[134:135]
	s_addc_u32 s53, s57, 0
	s_add_i32 s79, s71, s62
	global_load_lds_dwordx4 v[220:221], off
	v_lshl_add_u64 v[222:223], s[52:53], 0, v[130:131]
	s_mov_b32 m0, s79
	v_lshl_add_u64 v[224:225], s[58:59], 0, v[132:133]
	global_load_lds_dwordx4 v[222:223], off
	v_lshl_add_u64 v[222:223], s[52:53], 0, v[134:135]
	s_add_i32 m0, s79, 0x2000
	s_nop 0
	global_load_lds_dwordx4 v[222:223], off
	v_lshl_add_u64 v[222:223], s[58:59], 0, v[128:129]
	s_mov_b32 m0, s63
	s_nop 0
	global_load_lds_dwordx4 v[222:223], off
	s_mov_b32 m0, s64
	s_nop 0
	global_load_lds_dwordx4 v[224:225], off
	s_waitcnt vmcnt(8)
	s_waitcnt lgkmcnt(0)
	s_barrier
	s_waitcnt lgkmcnt(0)
	v_mfma_f32_16x16x32_bf16 v[60:63], v[152:155], v[188:191], 0
	v_mfma_f32_16x16x32_bf16 v[60:63], v[156:159], v[192:195], v[60:63]
	s_setprio 1
	v_mfma_f32_16x16x32_bf16 v[56:59], v[160:163], v[188:191], 0
	v_mfma_f32_16x16x32_bf16 v[56:59], v[164:167], v[192:195], v[56:59]
	v_mfma_f32_16x16x32_bf16 v[52:55], v[152:155], v[196:199], 0
	v_mfma_f32_16x16x32_bf16 v[52:55], v[156:159], v[200:203], v[52:55]
	v_mfma_f32_16x16x32_bf16 v[44:47], v[160:163], v[196:199], 0
	v_mfma_f32_16x16x32_bf16 v[44:47], v[164:167], v[200:203], v[44:47]
	v_mfma_f32_16x16x32_bf16 v[36:39], v[152:155], v[204:207], 0
	v_mfma_f32_16x16x32_bf16 v[36:39], v[156:159], v[208:211], v[36:39]
	v_mfma_f32_16x16x32_bf16 v[28:31], v[160:163], v[204:207], 0
	v_mfma_f32_16x16x32_bf16 v[28:31], v[164:167], v[208:211], v[28:31]
	v_mfma_f32_16x16x32_bf16 v[20:23], v[152:155], v[212:215], 0
	v_mfma_f32_16x16x32_bf16 v[20:23], v[156:159], v[216:219], v[20:23]
	v_mfma_f32_16x16x32_bf16 v[12:15], v[160:163], v[212:215], 0
	v_mfma_f32_16x16x32_bf16 v[12:15], v[164:167], v[216:219], v[12:15]
	v_mfma_f32_16x16x32_bf16 v[48:51], v[168:171], v[188:191], 0
	v_mfma_f32_16x16x32_bf16 v[48:51], v[172:175], v[192:195], v[48:51]
	v_mfma_f32_16x16x32_bf16 v[40:43], v[176:179], v[188:191], 0
	v_mfma_f32_16x16x32_bf16 v[40:43], v[184:187], v[192:195], v[40:43]
	v_mfma_f32_16x16x32_bf16 v[32:35], v[168:171], v[196:199], 0
	v_mfma_f32_16x16x32_bf16 v[32:35], v[172:175], v[200:203], v[32:35]
	v_mfma_f32_16x16x32_bf16 v[24:27], v[176:179], v[196:199], 0
	v_mfma_f32_16x16x32_bf16 v[24:27], v[184:187], v[200:203], v[24:27]
	v_mfma_f32_16x16x32_bf16 v[16:19], v[168:171], v[204:207], 0
	v_mfma_f32_16x16x32_bf16 v[16:19], v[172:175], v[208:211], v[16:19]
	v_mfma_f32_16x16x32_bf16 v[8:11], v[176:179], v[204:207], 0
	v_mfma_f32_16x16x32_bf16 v[8:11], v[184:187], v[208:211], v[8:11]
	v_mfma_f32_16x16x32_bf16 v[4:7], v[168:171], v[212:215], 0
	v_mfma_f32_16x16x32_bf16 v[4:7], v[172:175], v[216:219], v[4:7]
	s_barrier
	v_mfma_f32_16x16x32_bf16 v[0:3], v[176:179], v[212:215], 0
	v_mfma_f32_16x16x32_bf16 v[0:3], v[184:187], v[216:219], v[0:3]
	s_setprio 0
	s_branch .Lmid_gemm5
.LBB0_804:
	ds_read_b128 v[152:155], v149
	ds_read_b128 v[156:159], v149 offset:1024
	ds_read_b128 v[160:163], v149 offset:2048
	ds_read_b128 v[164:167], v149 offset:3072
	ds_read_b128 v[168:171], v150
	ds_read_b128 v[172:175], v150 offset:1024
	ds_read_b128 v[176:179], v150 offset:2048
	ds_read_b128 v[184:187], v150 offset:3072
	s_add_u32 s54, s52, 0x100
	s_addc_u32 s55, s53, 0
	s_cmp_eq_u32 s86, 40
	s_cselect_b32 s59, s13, s55
	s_cselect_b32 s58, s12, s54
	s_cselect_b32 s57, s49, s85
	s_cselect_b32 s56, s48, s84
	v_lshl_add_u64 v[144:145], s[52:53], 0, v[136:137]
	s_add_i32 m0, s63, 0xc000
	ds_read_b128 v[188:191], v151
	ds_read_b128 v[192:195], v151 offset:1024
	ds_read_b128 v[196:199], v151 offset:2048
	ds_read_b128 v[200:203], v151 offset:3072
	ds_read_b128 v[204:207], v151 offset:4096
	ds_read_b128 v[208:211], v151 offset:5120
	ds_read_b128 v[212:215], v151 offset:6144
	ds_read_b128 v[216:219], v151 offset:7168
	global_load_lds_dwordx4 v[144:145], off
	v_lshl_add_u64 v[144:145], s[52:53], 0, v[138:139]
	s_add_i32 m0, s63, 0xe000
	s_nop 0
	global_load_lds_dwordx4 v[144:145], off
	s_waitcnt vmcnt(8)
	s_waitcnt lgkmcnt(0)
	s_barrier
	s_waitcnt lgkmcnt(0)
	v_mfma_f32_16x16x32_bf16 v[124:127], v[152:155], v[188:191], v[124:127]
	v_mfma_f32_16x16x32_bf16 v[124:127], v[156:159], v[192:195], v[124:127]
	s_setprio 1
	v_mfma_f32_16x16x32_bf16 v[120:123], v[160:163], v[188:191], v[120:123]
	v_mfma_f32_16x16x32_bf16 v[120:123], v[164:167], v[192:195], v[120:123]
	v_mfma_f32_16x16x32_bf16 v[116:119], v[152:155], v[196:199], v[116:119]
	v_mfma_f32_16x16x32_bf16 v[116:119], v[156:159], v[200:203], v[116:119]
	v_mfma_f32_16x16x32_bf16 v[108:111], v[160:163], v[196:199], v[108:111]
	v_mfma_f32_16x16x32_bf16 v[108:111], v[164:167], v[200:203], v[108:111]
	v_mfma_f32_16x16x32_bf16 v[100:103], v[152:155], v[204:207], v[100:103]
	v_mfma_f32_16x16x32_bf16 v[100:103], v[156:159], v[208:211], v[100:103]
	v_mfma_f32_16x16x32_bf16 v[92:95], v[160:163], v[204:207], v[92:95]
	v_mfma_f32_16x16x32_bf16 v[92:95], v[164:167], v[208:211], v[92:95]
	v_mfma_f32_16x16x32_bf16 v[84:87], v[152:155], v[212:215], v[84:87]
	v_mfma_f32_16x16x32_bf16 v[84:87], v[156:159], v[216:219], v[84:87]
	v_mfma_f32_16x16x32_bf16 v[76:79], v[160:163], v[212:215], v[76:79]
	v_mfma_f32_16x16x32_bf16 v[76:79], v[164:167], v[216:219], v[76:79]
	v_mfma_f32_16x16x32_bf16 v[112:115], v[168:171], v[188:191], v[112:115]
	v_mfma_f32_16x16x32_bf16 v[112:115], v[172:175], v[192:195], v[112:115]
	v_mfma_f32_16x16x32_bf16 v[104:107], v[176:179], v[188:191], v[104:107]
	v_mfma_f32_16x16x32_bf16 v[104:107], v[184:187], v[192:195], v[104:107]
	v_mfma_f32_16x16x32_bf16 v[96:99], v[168:171], v[196:199], v[96:99]
	v_mfma_f32_16x16x32_bf16 v[96:99], v[172:175], v[200:203], v[96:99]
	v_mfma_f32_16x16x32_bf16 v[88:91], v[176:179], v[196:199], v[88:91]
	v_mfma_f32_16x16x32_bf16 v[88:91], v[184:187], v[200:203], v[88:91]
	v_mfma_f32_16x16x32_bf16 v[80:83], v[168:171], v[204:207], v[80:83]
	v_mfma_f32_16x16x32_bf16 v[80:83], v[172:175], v[208:211], v[80:83]
	v_mfma_f32_16x16x32_bf16 v[72:75], v[176:179], v[204:207], v[72:75]
	v_mfma_f32_16x16x32_bf16 v[72:75], v[184:187], v[208:211], v[72:75]
	v_mfma_f32_16x16x32_bf16 v[68:71], v[168:171], v[212:215], v[68:71]
	v_mfma_f32_16x16x32_bf16 v[68:71], v[172:175], v[216:219], v[68:71]
	s_barrier
	v_mfma_f32_16x16x32_bf16 v[64:67], v[176:179], v[212:215], v[64:67]
	v_mfma_f32_16x16x32_bf16 v[64:67], v[184:187], v[216:219], v[64:67]
	s_setprio 0
	s_add_i32 s52, s70, s62
	v_lshl_add_u64 v[144:145], s[56:57], 0, v[130:131]
	s_mov_b32 m0, s52
	ds_read_b128 v[188:191], v151 offset:16384
	ds_read_b128 v[192:195], v151 offset:17408
	ds_read_b128 v[196:199], v151 offset:18432
	ds_read_b128 v[200:203], v151 offset:19456
	ds_read_b128 v[204:207], v151 offset:20480
	ds_read_b128 v[208:211], v151 offset:21504
	ds_read_b128 v[212:215], v151 offset:22528
	ds_read_b128 v[216:219], v151 offset:23552
	global_load_lds_dwordx4 v[144:145], off
	s_add_i32 m0, s52, 0x2000
	s_add_u32 s52, s56, 0xb0000
	v_lshl_add_u64 v[220:221], s[56:57], 0, v[134:135]
	s_addc_u32 s53, s57, 0
	s_add_i32 s79, s71, s62
	global_load_lds_dwordx4 v[220:221], off
	v_lshl_add_u64 v[222:223], s[52:53], 0, v[130:131]
	s_mov_b32 m0, s79
	v_lshl_add_u64 v[224:225], s[58:59], 0, v[132:133]
	global_load_lds_dwordx4 v[222:223], off
	v_lshl_add_u64 v[222:223], s[52:53], 0, v[134:135]
	s_add_i32 m0, s79, 0x2000
	s_nop 0
	global_load_lds_dwordx4 v[222:223], off
	v_lshl_add_u64 v[222:223], s[58:59], 0, v[128:129]
	s_mov_b32 m0, s63
	s_nop 0
	global_load_lds_dwordx4 v[222:223], off
	s_mov_b32 m0, s64
	s_nop 0
	global_load_lds_dwordx4 v[224:225], off
	s_waitcnt vmcnt(8)
	s_waitcnt lgkmcnt(0)
	s_barrier
	s_waitcnt lgkmcnt(0)
	v_mfma_f32_16x16x32_bf16 v[60:63], v[152:155], v[188:191], v[60:63]
	v_mfma_f32_16x16x32_bf16 v[60:63], v[156:159], v[192:195], v[60:63]
	s_setprio 1
	v_mfma_f32_16x16x32_bf16 v[56:59], v[160:163], v[188:191], v[56:59]
	v_mfma_f32_16x16x32_bf16 v[56:59], v[164:167], v[192:195], v[56:59]
	v_mfma_f32_16x16x32_bf16 v[52:55], v[152:155], v[196:199], v[52:55]
	v_mfma_f32_16x16x32_bf16 v[52:55], v[156:159], v[200:203], v[52:55]
	v_mfma_f32_16x16x32_bf16 v[44:47], v[160:163], v[196:199], v[44:47]
	v_mfma_f32_16x16x32_bf16 v[44:47], v[164:167], v[200:203], v[44:47]
	v_mfma_f32_16x16x32_bf16 v[36:39], v[152:155], v[204:207], v[36:39]
	v_mfma_f32_16x16x32_bf16 v[36:39], v[156:159], v[208:211], v[36:39]
	v_mfma_f32_16x16x32_bf16 v[28:31], v[160:163], v[204:207], v[28:31]
	v_mfma_f32_16x16x32_bf16 v[28:31], v[164:167], v[208:211], v[28:31]
	v_mfma_f32_16x16x32_bf16 v[20:23], v[152:155], v[212:215], v[20:23]
	v_mfma_f32_16x16x32_bf16 v[20:23], v[156:159], v[216:219], v[20:23]
	v_mfma_f32_16x16x32_bf16 v[12:15], v[160:163], v[212:215], v[12:15]
	v_mfma_f32_16x16x32_bf16 v[12:15], v[164:167], v[216:219], v[12:15]
	v_mfma_f32_16x16x32_bf16 v[48:51], v[168:171], v[188:191], v[48:51]
	v_mfma_f32_16x16x32_bf16 v[48:51], v[172:175], v[192:195], v[48:51]
	v_mfma_f32_16x16x32_bf16 v[40:43], v[176:179], v[188:191], v[40:43]
	v_mfma_f32_16x16x32_bf16 v[40:43], v[184:187], v[192:195], v[40:43]
	v_mfma_f32_16x16x32_bf16 v[32:35], v[168:171], v[196:199], v[32:35]
	v_mfma_f32_16x16x32_bf16 v[32:35], v[172:175], v[200:203], v[32:35]
	v_mfma_f32_16x16x32_bf16 v[24:27], v[176:179], v[196:199], v[24:27]
	v_mfma_f32_16x16x32_bf16 v[24:27], v[184:187], v[200:203], v[24:27]
	v_mfma_f32_16x16x32_bf16 v[16:19], v[168:171], v[204:207], v[16:19]
	v_mfma_f32_16x16x32_bf16 v[16:19], v[172:175], v[208:211], v[16:19]
	v_mfma_f32_16x16x32_bf16 v[8:11], v[176:179], v[204:207], v[8:11]
	v_mfma_f32_16x16x32_bf16 v[8:11], v[184:187], v[208:211], v[8:11]
	v_mfma_f32_16x16x32_bf16 v[4:7], v[168:171], v[212:215], v[4:7]
	v_mfma_f32_16x16x32_bf16 v[4:7], v[172:175], v[216:219], v[4:7]
	s_barrier
	v_mfma_f32_16x16x32_bf16 v[0:3], v[176:179], v[212:215], v[0:3]
	v_mfma_f32_16x16x32_bf16 v[0:3], v[184:187], v[216:219], v[0:3]
	s_setprio 0
.Lmid_gemm5:
	s_add_i32 s79, 0, 0x18000
	s_add_i32 s87, 0, 0x1c000
	v_add_u32_e32 v164, s79, v147
	v_add_u32_e32 v181, s87, v147
	ds_read_b128 v[152:155], v164
	ds_read_b128 v[156:159], v164 offset:1024
	ds_read_b128 v[160:163], v164 offset:2048
	ds_read_b128 v[164:167], v164 offset:3072
	ds_read_b128 v[168:171], v181
	ds_read_b128 v[172:175], v181 offset:1024
	ds_read_b128 v[176:179], v181 offset:2048
	ds_read_b128 v[184:187], v181 offset:3072
	s_add_u32 s52, s58, 0xb0000
	s_addc_u32 s53, s59, 0
	s_mov_b32 m0, s65
	v_lshl_add_u64 v[226:227], s[52:53], 0, v[128:129]
	ds_read_b128 v[188:191], v151 offset:32768
	ds_read_b128 v[192:195], v151 offset:33792
	ds_read_b128 v[196:199], v151 offset:34816
	ds_read_b128 v[200:203], v151 offset:35840
	ds_read_b128 v[204:207], v151 offset:36864
	ds_read_b128 v[208:211], v151 offset:37888
	ds_read_b128 v[212:215], v151 offset:38912
	ds_read_b128 v[216:219], v151 offset:39936
	global_load_lds_dwordx4 v[226:227], off
	v_lshl_add_u64 v[226:227], s[52:53], 0, v[132:133]
	s_mov_b32 m0, s66
	s_nop 0
	global_load_lds_dwordx4 v[226:227], off
	s_waitcnt vmcnt(8)
	s_waitcnt lgkmcnt(0)
	s_barrier
	s_waitcnt lgkmcnt(0)
	v_mfma_f32_16x16x32_bf16 v[124:127], v[152:155], v[188:191], v[124:127]
	v_mfma_f32_16x16x32_bf16 v[124:127], v[156:159], v[192:195], v[124:127]
	s_setprio 1
	v_mfma_f32_16x16x32_bf16 v[120:123], v[160:163], v[188:191], v[120:123]
	v_mfma_f32_16x16x32_bf16 v[120:123], v[164:167], v[192:195], v[120:123]
	v_mfma_f32_16x16x32_bf16 v[116:119], v[152:155], v[196:199], v[116:119]
	v_mfma_f32_16x16x32_bf16 v[116:119], v[156:159], v[200:203], v[116:119]
	v_mfma_f32_16x16x32_bf16 v[108:111], v[160:163], v[196:199], v[108:111]
	v_mfma_f32_16x16x32_bf16 v[108:111], v[164:167], v[200:203], v[108:111]
	v_mfma_f32_16x16x32_bf16 v[100:103], v[152:155], v[204:207], v[100:103]
	v_mfma_f32_16x16x32_bf16 v[100:103], v[156:159], v[208:211], v[100:103]
	v_mfma_f32_16x16x32_bf16 v[92:95], v[160:163], v[204:207], v[92:95]
	v_mfma_f32_16x16x32_bf16 v[92:95], v[164:167], v[208:211], v[92:95]
	v_mfma_f32_16x16x32_bf16 v[84:87], v[152:155], v[212:215], v[84:87]
	v_mfma_f32_16x16x32_bf16 v[84:87], v[156:159], v[216:219], v[84:87]
	v_mfma_f32_16x16x32_bf16 v[76:79], v[160:163], v[212:215], v[76:79]
	v_mfma_f32_16x16x32_bf16 v[76:79], v[164:167], v[216:219], v[76:79]
	v_mfma_f32_16x16x32_bf16 v[112:115], v[168:171], v[188:191], v[112:115]
	v_mfma_f32_16x16x32_bf16 v[112:115], v[172:175], v[192:195], v[112:115]
	v_mfma_f32_16x16x32_bf16 v[104:107], v[176:179], v[188:191], v[104:107]
	v_mfma_f32_16x16x32_bf16 v[104:107], v[184:187], v[192:195], v[104:107]
	v_mfma_f32_16x16x32_bf16 v[96:99], v[168:171], v[196:199], v[96:99]
	v_mfma_f32_16x16x32_bf16 v[96:99], v[172:175], v[200:203], v[96:99]
	v_mfma_f32_16x16x32_bf16 v[88:91], v[176:179], v[196:199], v[88:91]
	v_mfma_f32_16x16x32_bf16 v[88:91], v[184:187], v[200:203], v[88:91]
	v_mfma_f32_16x16x32_bf16 v[80:83], v[168:171], v[204:207], v[80:83]
	v_mfma_f32_16x16x32_bf16 v[80:83], v[172:175], v[208:211], v[80:83]
	v_mfma_f32_16x16x32_bf16 v[72:75], v[176:179], v[204:207], v[72:75]
	v_mfma_f32_16x16x32_bf16 v[72:75], v[184:187], v[208:211], v[72:75]
	v_mfma_f32_16x16x32_bf16 v[68:71], v[168:171], v[212:215], v[68:71]
	v_mfma_f32_16x16x32_bf16 v[68:71], v[172:175], v[216:219], v[68:71]
	s_barrier
	v_mfma_f32_16x16x32_bf16 v[64:67], v[176:179], v[212:215], v[64:67]
	v_mfma_f32_16x16x32_bf16 v[64:67], v[184:187], v[216:219], v[64:67]
	s_setprio 0
	s_add_i32 s52, s79, s62
	v_lshl_add_u64 v[144:145], v[144:145], 0, s[16:17]
	s_mov_b32 m0, s52
	ds_read_b128 v[188:191], v151 offset:49152
	ds_read_b128 v[192:195], v151 offset:50176
	ds_read_b128 v[196:199], v151 offset:51200
	ds_read_b128 v[200:203], v151 offset:52224
	ds_read_b128 v[204:207], v151 offset:53248
	ds_read_b128 v[208:211], v151 offset:54272
	ds_read_b128 v[212:215], v151 offset:55296
	ds_read_b128 v[216:219], v151 offset:56320
	global_load_lds_dwordx4 v[144:145], off
	s_add_i32 m0, s52, 0x2000
	s_add_u32 s52, s56, 0xb0080
	v_lshl_add_u64 v[144:145], v[220:221], 0, s[16:17]
	s_addc_u32 s53, s57, 0
	s_add_i32 s56, s87, s62
	global_load_lds_dwordx4 v[144:145], off
	v_lshl_add_u64 v[144:145], s[52:53], 0, v[130:131]
	s_mov_b32 m0, s56
	s_nop 0
	global_load_lds_dwordx4 v[144:145], off
	v_lshl_add_u64 v[144:145], s[52:53], 0, v[134:135]
	s_add_i32 m0, s56, 0x2000
	s_nop 0
	global_load_lds_dwordx4 v[144:145], off
	v_lshl_add_u64 v[144:145], v[222:223], 0, s[16:17]
	s_mov_b32 m0, s68
	s_nop 0
	global_load_lds_dwordx4 v[144:145], off
	v_lshl_add_u64 v[144:145], v[224:225], 0, s[16:17]
	s_mov_b32 m0, s69
	s_nop 0
	global_load_lds_dwordx4 v[144:145], off
	s_waitcnt vmcnt(8)
	s_waitcnt lgkmcnt(0)
	s_barrier
	s_waitcnt lgkmcnt(0)
	v_mfma_f32_16x16x32_bf16 v[60:63], v[152:155], v[188:191], v[60:63]
	v_mfma_f32_16x16x32_bf16 v[60:63], v[156:159], v[192:195], v[60:63]
	s_setprio 1
	v_mfma_f32_16x16x32_bf16 v[56:59], v[160:163], v[188:191], v[56:59]
	v_mfma_f32_16x16x32_bf16 v[56:59], v[164:167], v[192:195], v[56:59]
	v_mfma_f32_16x16x32_bf16 v[52:55], v[152:155], v[196:199], v[52:55]
	v_mfma_f32_16x16x32_bf16 v[52:55], v[156:159], v[200:203], v[52:55]
	v_mfma_f32_16x16x32_bf16 v[44:47], v[160:163], v[196:199], v[44:47]
	v_mfma_f32_16x16x32_bf16 v[44:47], v[164:167], v[200:203], v[44:47]
	v_mfma_f32_16x16x32_bf16 v[36:39], v[152:155], v[204:207], v[36:39]
	v_mfma_f32_16x16x32_bf16 v[36:39], v[156:159], v[208:211], v[36:39]
	v_mfma_f32_16x16x32_bf16 v[28:31], v[160:163], v[204:207], v[28:31]
	v_mfma_f32_16x16x32_bf16 v[28:31], v[164:167], v[208:211], v[28:31]
	v_mfma_f32_16x16x32_bf16 v[20:23], v[152:155], v[212:215], v[20:23]
	v_mfma_f32_16x16x32_bf16 v[20:23], v[156:159], v[216:219], v[20:23]
	v_mfma_f32_16x16x32_bf16 v[12:15], v[160:163], v[212:215], v[12:15]
	v_mfma_f32_16x16x32_bf16 v[12:15], v[164:167], v[216:219], v[12:15]
	v_mfma_f32_16x16x32_bf16 v[48:51], v[168:171], v[188:191], v[48:51]
	v_mfma_f32_16x16x32_bf16 v[48:51], v[172:175], v[192:195], v[48:51]
	v_mfma_f32_16x16x32_bf16 v[40:43], v[176:179], v[188:191], v[40:43]
	v_mfma_f32_16x16x32_bf16 v[40:43], v[184:187], v[192:195], v[40:43]
	v_mfma_f32_16x16x32_bf16 v[32:35], v[168:171], v[196:199], v[32:35]
	v_mfma_f32_16x16x32_bf16 v[32:35], v[172:175], v[200:203], v[32:35]
	v_mfma_f32_16x16x32_bf16 v[24:27], v[176:179], v[196:199], v[24:27]
	v_mfma_f32_16x16x32_bf16 v[24:27], v[184:187], v[200:203], v[24:27]
	v_mfma_f32_16x16x32_bf16 v[16:19], v[168:171], v[204:207], v[16:19]
	v_mfma_f32_16x16x32_bf16 v[16:19], v[172:175], v[208:211], v[16:19]
	v_mfma_f32_16x16x32_bf16 v[8:11], v[176:179], v[204:207], v[8:11]
	v_mfma_f32_16x16x32_bf16 v[8:11], v[184:187], v[208:211], v[8:11]
	v_mfma_f32_16x16x32_bf16 v[4:7], v[168:171], v[212:215], v[4:7]
	v_mfma_f32_16x16x32_bf16 v[4:7], v[172:175], v[216:219], v[4:7]
	s_barrier
	v_mfma_f32_16x16x32_bf16 v[0:3], v[176:179], v[212:215], v[0:3]
	v_mfma_f32_16x16x32_bf16 v[0:3], v[184:187], v[216:219], v[0:3]
	s_setprio 0
	s_add_i32 s86, s86, 2
	s_add_u32 s84, s84, 0x100
	s_addc_u32 s85, s85, 0
	s_cmp_gt_u32 s86, 41
	s_mov_b64 s[52:53], s[54:55]
	s_cbranch_scc0 .LBB0_804
	s_and_b64 vcc, exec, s[18:19]
	s_cbranch_vccz .LBB0_807
	s_barrier

.LBB0_934:
	s_ashr_i32 s53, s52, 31
	s_lshl_b64 s[54:55], s[52:53], 19
	s_add_u32 s54, s80, s54
	s_addc_u32 s55, s81, s55
	s_and_b64 s[56:57], s[10:11], exec
	s_cselect_b32 s53, s55, s61
	s_cselect_b32 s83, s54, s60
	s_ashr_i32 s49, s48, 31
	s_lshl_b64 s[56:57], s[48:49], 19
	s_add_u32 s56, s66, s56
	s_addc_u32 s57, s67, s57
	s_and_b64 s[64:65], s[10:11], exec
	s_cselect_b32 s49, s57, s63
	s_cselect_b32 s84, s56, s62
	s_add_u32 s60, s60, 0x40080
	s_addc_u32 s61, s61, 0
	s_add_u32 s85, s62, 0x100
	s_addc_u32 s86, s63, 0
	s_mov_b32 s87, -2
	ds_read_b128 v[152:155], v148
	ds_read_b128 v[156:159], v148 offset:1024
	ds_read_b128 v[160:163], v148 offset:2048
	ds_read_b128 v[164:167], v148 offset:3072
	ds_read_b128 v[168:171], v149
	ds_read_b128 v[172:175], v149 offset:1024
	ds_read_b128 v[176:179], v149 offset:2048
	ds_read_b128 v[184:187], v149 offset:3072
	s_add_u32 s62, s60, 0xfffc0080
	s_addc_u32 s63, s61, -1
	s_cmp_eq_u32 s87, 12
	s_cselect_b32 s65, s53, s63
	s_cselect_b32 s64, s83, s62
	s_cselect_b32 s63, s49, s86
	s_cselect_b32 s62, s84, s85
	v_lshl_add_u64 v[220:221], s[60:61], 0, v[138:139]
	s_add_i32 m0, s69, 0xc000
	ds_read_b128 v[188:191], v150
	ds_read_b128 v[192:195], v150 offset:1024
	ds_read_b128 v[196:199], v150 offset:2048
	ds_read_b128 v[200:203], v150 offset:3072
	ds_read_b128 v[204:207], v150 offset:4096
	ds_read_b128 v[208:211], v150 offset:5120
	ds_read_b128 v[212:215], v150 offset:6144
	ds_read_b128 v[216:219], v150 offset:7168
	global_load_lds_dwordx4 v[220:221], off
	v_lshl_add_u64 v[220:221], s[60:61], 0, v[140:141]
	s_add_i32 m0, s69, 0xe000
	s_nop 0
	global_load_lds_dwordx4 v[220:221], off
	s_waitcnt vmcnt(8)
	s_waitcnt lgkmcnt(0)
	s_barrier
	s_waitcnt lgkmcnt(0)
	v_mfma_f32_16x16x32_bf16 v[124:127], v[152:155], v[188:191], 0
	v_mfma_f32_16x16x32_bf16 v[124:127], v[156:159], v[192:195], v[124:127]
	s_setprio 1
	v_mfma_f32_16x16x32_bf16 v[120:123], v[160:163], v[188:191], 0
	v_mfma_f32_16x16x32_bf16 v[120:123], v[164:167], v[192:195], v[120:123]
	v_mfma_f32_16x16x32_bf16 v[116:119], v[152:155], v[196:199], 0
	v_mfma_f32_16x16x32_bf16 v[116:119], v[156:159], v[200:203], v[116:119]
	v_mfma_f32_16x16x32_bf16 v[112:115], v[160:163], v[196:199], 0
	v_mfma_f32_16x16x32_bf16 v[112:115], v[164:167], v[200:203], v[112:115]
	v_mfma_f32_16x16x32_bf16 v[108:111], v[152:155], v[204:207], 0
	v_mfma_f32_16x16x32_bf16 v[108:111], v[156:159], v[208:211], v[108:111]
	v_mfma_f32_16x16x32_bf16 v[104:107], v[160:163], v[204:207], 0
	v_mfma_f32_16x16x32_bf16 v[104:107], v[164:167], v[208:211], v[104:107]
	v_mfma_f32_16x16x32_bf16 v[100:103], v[152:155], v[212:215], 0
	v_mfma_f32_16x16x32_bf16 v[100:103], v[156:159], v[216:219], v[100:103]
	v_mfma_f32_16x16x32_bf16 v[96:99], v[160:163], v[212:215], 0
	v_mfma_f32_16x16x32_bf16 v[96:99], v[164:167], v[216:219], v[96:99]
	v_mfma_f32_16x16x32_bf16 v[76:79], v[168:171], v[188:191], 0
	v_mfma_f32_16x16x32_bf16 v[76:79], v[172:175], v[192:195], v[76:79]
	v_mfma_f32_16x16x32_bf16 v[68:71], v[176:179], v[188:191], 0
	v_mfma_f32_16x16x32_bf16 v[68:71], v[184:187], v[192:195], v[68:71]
	v_mfma_f32_16x16x32_bf16 v[60:63], v[168:171], v[196:199], 0
	v_mfma_f32_16x16x32_bf16 v[60:63], v[172:175], v[200:203], v[60:63]
	v_mfma_f32_16x16x32_bf16 v[52:55], v[176:179], v[196:199], 0
	v_mfma_f32_16x16x32_bf16 v[52:55], v[184:187], v[200:203], v[52:55]
	v_mfma_f32_16x16x32_bf16 v[44:47], v[168:171], v[204:207], 0
	v_mfma_f32_16x16x32_bf16 v[44:47], v[172:175], v[208:211], v[44:47]
	v_mfma_f32_16x16x32_bf16 v[40:43], v[176:179], v[204:207], 0
	v_mfma_f32_16x16x32_bf16 v[40:43], v[184:187], v[208:211], v[40:43]
	v_mfma_f32_16x16x32_bf16 v[36:39], v[168:171], v[212:215], 0
	v_mfma_f32_16x16x32_bf16 v[36:39], v[172:175], v[216:219], v[36:39]
	s_barrier
	v_mfma_f32_16x16x32_bf16 v[32:35], v[176:179], v[212:215], 0
	v_mfma_f32_16x16x32_bf16 v[32:35], v[184:187], v[216:219], v[32:35]
	s_setprio 0
	s_add_i32 s79, s77, s68
	v_lshl_add_u64 v[220:221], s[62:63], 0, v[130:131]
	s_mov_b32 m0, s79
	ds_read_b128 v[188:191], v150 offset:16384
	ds_read_b128 v[192:195], v150 offset:17408
	ds_read_b128 v[196:199], v150 offset:18432
	ds_read_b128 v[200:203], v150 offset:19456
	ds_read_b128 v[204:207], v150 offset:20480
	ds_read_b128 v[208:211], v150 offset:21504
	ds_read_b128 v[212:215], v150 offset:22528
	ds_read_b128 v[216:219], v150 offset:23552
	global_load_lds_dwordx4 v[220:221], off
	s_add_i32 m0, s79, 0x2000
	s_add_u32 s88, s62, 0x40000
	v_lshl_add_u64 v[222:223], s[62:63], 0, v[134:135]
	s_addc_u32 s89, s63, 0
	s_add_i32 s79, s82, s68
	global_load_lds_dwordx4 v[222:223], off
	v_lshl_add_u64 v[224:225], s[88:89], 0, v[130:131]
	s_mov_b32 m0, s79
	v_lshl_add_u64 v[226:227], s[64:65], 0, v[132:133]
	global_load_lds_dwordx4 v[224:225], off
	v_lshl_add_u64 v[224:225], s[88:89], 0, v[134:135]
	s_add_i32 m0, s79, 0x2000
	s_nop 0
	global_load_lds_dwordx4 v[224:225], off
	v_lshl_add_u64 v[224:225], s[64:65], 0, v[128:129]
	s_mov_b32 m0, s69
	s_nop 0
	global_load_lds_dwordx4 v[224:225], off
	s_mov_b32 m0, s70
	s_nop 0
	global_load_lds_dwordx4 v[226:227], off
	s_waitcnt vmcnt(8)
	s_waitcnt lgkmcnt(0)
	s_barrier
	s_waitcnt lgkmcnt(0)
	v_mfma_f32_16x16x32_bf16 v[92:95], v[152:155], v[188:191], 0
	v_mfma_f32_16x16x32_bf16 v[92:95], v[156:159], v[192:195], v[92:95]
	s_setprio 1
	v_mfma_f32_16x16x32_bf16 v[88:91], v[160:163], v[188:191], 0
	v_mfma_f32_16x16x32_bf16 v[88:91], v[164:167], v[192:195], v[88:91]
	v_mfma_f32_16x16x32_bf16 v[84:87], v[152:155], v[196:199], 0
	v_mfma_f32_16x16x32_bf16 v[84:87], v[156:159], v[200:203], v[84:87]
	v_mfma_f32_16x16x32_bf16 v[80:83], v[160:163], v[196:199], 0
	v_mfma_f32_16x16x32_bf16 v[80:83], v[164:167], v[200:203], v[80:83]
	v_mfma_f32_16x16x32_bf16 v[72:75], v[152:155], v[204:207], 0
	v_mfma_f32_16x16x32_bf16 v[72:75], v[156:159], v[208:211], v[72:75]
	v_mfma_f32_16x16x32_bf16 v[64:67], v[160:163], v[204:207], 0
	v_mfma_f32_16x16x32_bf16 v[64:67], v[164:167], v[208:211], v[64:67]
	v_mfma_f32_16x16x32_bf16 v[56:59], v[152:155], v[212:215], 0
	v_mfma_f32_16x16x32_bf16 v[56:59], v[156:159], v[216:219], v[56:59]
	v_mfma_f32_16x16x32_bf16 v[48:51], v[160:163], v[212:215], 0
	v_mfma_f32_16x16x32_bf16 v[48:51], v[164:167], v[216:219], v[48:51]
	v_mfma_f32_16x16x32_bf16 v[28:31], v[168:171], v[188:191], 0
	v_mfma_f32_16x16x32_bf16 v[28:31], v[172:175], v[192:195], v[28:31]
	v_mfma_f32_16x16x32_bf16 v[24:27], v[176:179], v[188:191], 0
	v_mfma_f32_16x16x32_bf16 v[24:27], v[184:187], v[192:195], v[24:27]
	v_mfma_f32_16x16x32_bf16 v[20:23], v[168:171], v[196:199], 0
	v_mfma_f32_16x16x32_bf16 v[20:23], v[172:175], v[200:203], v[20:23]
	v_mfma_f32_16x16x32_bf16 v[16:19], v[176:179], v[196:199], 0
	v_mfma_f32_16x16x32_bf16 v[16:19], v[184:187], v[200:203], v[16:19]
	v_mfma_f32_16x16x32_bf16 v[12:15], v[168:171], v[204:207], 0
	v_mfma_f32_16x16x32_bf16 v[12:15], v[172:175], v[208:211], v[12:15]
	v_mfma_f32_16x16x32_bf16 v[8:11], v[176:179], v[204:207], 0
	v_mfma_f32_16x16x32_bf16 v[8:11], v[184:187], v[208:211], v[8:11]
	v_mfma_f32_16x16x32_bf16 v[4:7], v[168:171], v[212:215], 0
	v_mfma_f32_16x16x32_bf16 v[4:7], v[172:175], v[216:219], v[4:7]
	s_barrier
	v_mfma_f32_16x16x32_bf16 v[0:3], v[176:179], v[212:215], 0
	v_mfma_f32_16x16x32_bf16 v[0:3], v[184:187], v[216:219], v[0:3]
	s_setprio 0
	s_branch .Lmid_gemm6
.LBB0_935:
	ds_read_b128 v[152:155], v148
	ds_read_b128 v[156:159], v148 offset:1024
	ds_read_b128 v[160:163], v148 offset:2048
	ds_read_b128 v[164:167], v148 offset:3072
	ds_read_b128 v[168:171], v149
	ds_read_b128 v[172:175], v149 offset:1024
	ds_read_b128 v[176:179], v149 offset:2048
	ds_read_b128 v[184:187], v149 offset:3072
	s_add_u32 s62, s60, 0xfffc0080
	s_addc_u32 s63, s61, -1
	s_cmp_eq_u32 s87, 12
	s_cselect_b32 s65, s53, s63
	s_cselect_b32 s64, s83, s62
	s_cselect_b32 s63, s49, s86
	s_cselect_b32 s62, s84, s85
	v_lshl_add_u64 v[220:221], s[60:61], 0, v[138:139]
	s_add_i32 m0, s69, 0xc000
	ds_read_b128 v[188:191], v150
	ds_read_b128 v[192:195], v150 offset:1024
	ds_read_b128 v[196:199], v150 offset:2048
	ds_read_b128 v[200:203], v150 offset:3072
	ds_read_b128 v[204:207], v150 offset:4096
	ds_read_b128 v[208:211], v150 offset:5120
	ds_read_b128 v[212:215], v150 offset:6144
	ds_read_b128 v[216:219], v150 offset:7168
	global_load_lds_dwordx4 v[220:221], off
	v_lshl_add_u64 v[220:221], s[60:61], 0, v[140:141]
	s_add_i32 m0, s69, 0xe000
	s_nop 0
	global_load_lds_dwordx4 v[220:221], off
	s_waitcnt vmcnt(8)
	s_waitcnt lgkmcnt(0)
	s_barrier
	s_waitcnt lgkmcnt(0)
	v_mfma_f32_16x16x32_bf16 v[124:127], v[152:155], v[188:191], v[124:127]
	v_mfma_f32_16x16x32_bf16 v[124:127], v[156:159], v[192:195], v[124:127]
	s_setprio 1
	v_mfma_f32_16x16x32_bf16 v[120:123], v[160:163], v[188:191], v[120:123]
	v_mfma_f32_16x16x32_bf16 v[120:123], v[164:167], v[192:195], v[120:123]
	v_mfma_f32_16x16x32_bf16 v[116:119], v[152:155], v[196:199], v[116:119]
	v_mfma_f32_16x16x32_bf16 v[116:119], v[156:159], v[200:203], v[116:119]
	v_mfma_f32_16x16x32_bf16 v[112:115], v[160:163], v[196:199], v[112:115]
	v_mfma_f32_16x16x32_bf16 v[112:115], v[164:167], v[200:203], v[112:115]
	v_mfma_f32_16x16x32_bf16 v[108:111], v[152:155], v[204:207], v[108:111]
	v_mfma_f32_16x16x32_bf16 v[108:111], v[156:159], v[208:211], v[108:111]
	v_mfma_f32_16x16x32_bf16 v[104:107], v[160:163], v[204:207], v[104:107]
	v_mfma_f32_16x16x32_bf16 v[104:107], v[164:167], v[208:211], v[104:107]
	v_mfma_f32_16x16x32_bf16 v[100:103], v[152:155], v[212:215], v[100:103]
	v_mfma_f32_16x16x32_bf16 v[100:103], v[156:159], v[216:219], v[100:103]
	v_mfma_f32_16x16x32_bf16 v[96:99], v[160:163], v[212:215], v[96:99]
	v_mfma_f32_16x16x32_bf16 v[96:99], v[164:167], v[216:219], v[96:99]
	v_mfma_f32_16x16x32_bf16 v[76:79], v[168:171], v[188:191], v[76:79]
	v_mfma_f32_16x16x32_bf16 v[76:79], v[172:175], v[192:195], v[76:79]
	v_mfma_f32_16x16x32_bf16 v[68:71], v[176:179], v[188:191], v[68:71]
	v_mfma_f32_16x16x32_bf16 v[68:71], v[184:187], v[192:195], v[68:71]
	v_mfma_f32_16x16x32_bf16 v[60:63], v[168:171], v[196:199], v[60:63]
	v_mfma_f32_16x16x32_bf16 v[60:63], v[172:175], v[200:203], v[60:63]
	v_mfma_f32_16x16x32_bf16 v[52:55], v[176:179], v[196:199], v[52:55]
	v_mfma_f32_16x16x32_bf16 v[52:55], v[184:187], v[200:203], v[52:55]
	v_mfma_f32_16x16x32_bf16 v[44:47], v[168:171], v[204:207], v[44:47]
	v_mfma_f32_16x16x32_bf16 v[44:47], v[172:175], v[208:211], v[44:47]
	v_mfma_f32_16x16x32_bf16 v[40:43], v[176:179], v[204:207], v[40:43]
	v_mfma_f32_16x16x32_bf16 v[40:43], v[184:187], v[208:211], v[40:43]
	v_mfma_f32_16x16x32_bf16 v[36:39], v[168:171], v[212:215], v[36:39]
	v_mfma_f32_16x16x32_bf16 v[36:39], v[172:175], v[216:219], v[36:39]
	s_barrier
	v_mfma_f32_16x16x32_bf16 v[32:35], v[176:179], v[212:215], v[32:35]
	v_mfma_f32_16x16x32_bf16 v[32:35], v[184:187], v[216:219], v[32:35]
	s_setprio 0
	s_add_i32 s79, s77, s68
	v_lshl_add_u64 v[220:221], s[62:63], 0, v[130:131]
	s_mov_b32 m0, s79
	ds_read_b128 v[188:191], v150 offset:16384
	ds_read_b128 v[192:195], v150 offset:17408
	ds_read_b128 v[196:199], v150 offset:18432
	ds_read_b128 v[200:203], v150 offset:19456
	ds_read_b128 v[204:207], v150 offset:20480
	ds_read_b128 v[208:211], v150 offset:21504
	ds_read_b128 v[212:215], v150 offset:22528
	ds_read_b128 v[216:219], v150 offset:23552
	global_load_lds_dwordx4 v[220:221], off
	s_add_i32 m0, s79, 0x2000
	s_add_u32 s88, s62, 0x40000
	v_lshl_add_u64 v[222:223], s[62:63], 0, v[134:135]
	s_addc_u32 s89, s63, 0
	s_add_i32 s79, s82, s68
	global_load_lds_dwordx4 v[222:223], off
	v_lshl_add_u64 v[224:225], s[88:89], 0, v[130:131]
	s_mov_b32 m0, s79
	v_lshl_add_u64 v[226:227], s[64:65], 0, v[132:133]
	global_load_lds_dwordx4 v[224:225], off
	v_lshl_add_u64 v[224:225], s[88:89], 0, v[134:135]
	s_add_i32 m0, s79, 0x2000
	s_nop 0
	global_load_lds_dwordx4 v[224:225], off
	v_lshl_add_u64 v[224:225], s[64:65], 0, v[128:129]
	s_mov_b32 m0, s69
	s_nop 0
	global_load_lds_dwordx4 v[224:225], off
	s_mov_b32 m0, s70
	s_nop 0
	global_load_lds_dwordx4 v[226:227], off
	s_waitcnt vmcnt(8)
	s_waitcnt lgkmcnt(0)
	s_barrier
	s_waitcnt lgkmcnt(0)
	v_mfma_f32_16x16x32_bf16 v[92:95], v[152:155], v[188:191], v[92:95]
	v_mfma_f32_16x16x32_bf16 v[92:95], v[156:159], v[192:195], v[92:95]
	s_setprio 1
	v_mfma_f32_16x16x32_bf16 v[88:91], v[160:163], v[188:191], v[88:91]
	v_mfma_f32_16x16x32_bf16 v[88:91], v[164:167], v[192:195], v[88:91]
	v_mfma_f32_16x16x32_bf16 v[84:87], v[152:155], v[196:199], v[84:87]
	v_mfma_f32_16x16x32_bf16 v[84:87], v[156:159], v[200:203], v[84:87]
	v_mfma_f32_16x16x32_bf16 v[80:83], v[160:163], v[196:199], v[80:83]
	v_mfma_f32_16x16x32_bf16 v[80:83], v[164:167], v[200:203], v[80:83]
	v_mfma_f32_16x16x32_bf16 v[72:75], v[152:155], v[204:207], v[72:75]
	v_mfma_f32_16x16x32_bf16 v[72:75], v[156:159], v[208:211], v[72:75]
	v_mfma_f32_16x16x32_bf16 v[64:67], v[160:163], v[204:207], v[64:67]
	v_mfma_f32_16x16x32_bf16 v[64:67], v[164:167], v[208:211], v[64:67]
	v_mfma_f32_16x16x32_bf16 v[56:59], v[152:155], v[212:215], v[56:59]
	v_mfma_f32_16x16x32_bf16 v[56:59], v[156:159], v[216:219], v[56:59]
	v_mfma_f32_16x16x32_bf16 v[48:51], v[160:163], v[212:215], v[48:51]
	v_mfma_f32_16x16x32_bf16 v[48:51], v[164:167], v[216:219], v[48:51]
	v_mfma_f32_16x16x32_bf16 v[28:31], v[168:171], v[188:191], v[28:31]
	v_mfma_f32_16x16x32_bf16 v[28:31], v[172:175], v[192:195], v[28:31]
	v_mfma_f32_16x16x32_bf16 v[24:27], v[176:179], v[188:191], v[24:27]
	v_mfma_f32_16x16x32_bf16 v[24:27], v[184:187], v[192:195], v[24:27]
	v_mfma_f32_16x16x32_bf16 v[20:23], v[168:171], v[196:199], v[20:23]
	v_mfma_f32_16x16x32_bf16 v[20:23], v[172:175], v[200:203], v[20:23]
	v_mfma_f32_16x16x32_bf16 v[16:19], v[176:179], v[196:199], v[16:19]
	v_mfma_f32_16x16x32_bf16 v[16:19], v[184:187], v[200:203], v[16:19]
	v_mfma_f32_16x16x32_bf16 v[12:15], v[168:171], v[204:207], v[12:15]
	v_mfma_f32_16x16x32_bf16 v[12:15], v[172:175], v[208:211], v[12:15]
	v_mfma_f32_16x16x32_bf16 v[8:11], v[176:179], v[204:207], v[8:11]
	v_mfma_f32_16x16x32_bf16 v[8:11], v[184:187], v[208:211], v[8:11]
	v_mfma_f32_16x16x32_bf16 v[4:7], v[168:171], v[212:215], v[4:7]
	v_mfma_f32_16x16x32_bf16 v[4:7], v[172:175], v[216:219], v[4:7]
	s_barrier
	v_mfma_f32_16x16x32_bf16 v[0:3], v[176:179], v[212:215], v[0:3]
	v_mfma_f32_16x16x32_bf16 v[0:3], v[184:187], v[216:219], v[0:3]
	s_setprio 0
.Lmid_gemm6:
	s_add_i32 s79, 0, 0x18000
	v_add_u32_e32 v151, s79, v147
	s_add_i32 s88, 0, 0x1c000
	ds_read_b128 v[152:155], v151
	ds_read_b128 v[156:159], v151 offset:1024
	ds_read_b128 v[160:163], v151 offset:2048
	ds_read_b128 v[164:167], v151 offset:3072
	v_add_u32_e32 v151, s88, v147
	ds_read_b128 v[168:171], v151
	ds_read_b128 v[172:175], v151 offset:1024
	ds_read_b128 v[176:179], v151 offset:2048
	ds_read_b128 v[184:187], v151 offset:3072
	s_add_u32 s64, s64, 0x40000
	s_addc_u32 s65, s65, 0
	s_mov_b32 m0, s71
	v_lshl_add_u64 v[228:229], s[64:65], 0, v[128:129]
	ds_read_b128 v[188:191], v150 offset:32768
	ds_read_b128 v[192:195], v150 offset:33792
	ds_read_b128 v[196:199], v150 offset:34816
	ds_read_b128 v[200:203], v150 offset:35840
	ds_read_b128 v[204:207], v150 offset:36864
	ds_read_b128 v[208:211], v150 offset:37888
	ds_read_b128 v[212:215], v150 offset:38912
	ds_read_b128 v[216:219], v150 offset:39936
	global_load_lds_dwordx4 v[228:229], off
	v_lshl_add_u64 v[228:229], s[64:65], 0, v[132:133]
	s_mov_b32 m0, s72
	s_nop 0
	global_load_lds_dwordx4 v[228:229], off
	s_waitcnt vmcnt(8)
	s_waitcnt lgkmcnt(0)
	s_barrier
	s_waitcnt lgkmcnt(0)
	v_mfma_f32_16x16x32_bf16 v[124:127], v[152:155], v[188:191], v[124:127]
	v_mfma_f32_16x16x32_bf16 v[124:127], v[156:159], v[192:195], v[124:127]
	s_setprio 1
	v_mfma_f32_16x16x32_bf16 v[120:123], v[160:163], v[188:191], v[120:123]
	v_mfma_f32_16x16x32_bf16 v[120:123], v[164:167], v[192:195], v[120:123]
	v_mfma_f32_16x16x32_bf16 v[116:119], v[152:155], v[196:199], v[116:119]
	v_mfma_f32_16x16x32_bf16 v[116:119], v[156:159], v[200:203], v[116:119]
	v_mfma_f32_16x16x32_bf16 v[112:115], v[160:163], v[196:199], v[112:115]
	v_mfma_f32_16x16x32_bf16 v[112:115], v[164:167], v[200:203], v[112:115]
	v_mfma_f32_16x16x32_bf16 v[108:111], v[152:155], v[204:207], v[108:111]
	v_mfma_f32_16x16x32_bf16 v[108:111], v[156:159], v[208:211], v[108:111]
	v_mfma_f32_16x16x32_bf16 v[104:107], v[160:163], v[204:207], v[104:107]
	v_mfma_f32_16x16x32_bf16 v[104:107], v[164:167], v[208:211], v[104:107]
	v_mfma_f32_16x16x32_bf16 v[100:103], v[152:155], v[212:215], v[100:103]
	v_mfma_f32_16x16x32_bf16 v[100:103], v[156:159], v[216:219], v[100:103]
	v_mfma_f32_16x16x32_bf16 v[96:99], v[160:163], v[212:215], v[96:99]
	v_mfma_f32_16x16x32_bf16 v[96:99], v[164:167], v[216:219], v[96:99]
	v_mfma_f32_16x16x32_bf16 v[76:79], v[168:171], v[188:191], v[76:79]
	v_mfma_f32_16x16x32_bf16 v[76:79], v[172:175], v[192:195], v[76:79]
	v_mfma_f32_16x16x32_bf16 v[68:71], v[176:179], v[188:191], v[68:71]
	v_mfma_f32_16x16x32_bf16 v[68:71], v[184:187], v[192:195], v[68:71]
	v_mfma_f32_16x16x32_bf16 v[60:63], v[168:171], v[196:199], v[60:63]
	v_mfma_f32_16x16x32_bf16 v[60:63], v[172:175], v[200:203], v[60:63]
	v_mfma_f32_16x16x32_bf16 v[52:55], v[176:179], v[196:199], v[52:55]
	v_mfma_f32_16x16x32_bf16 v[52:55], v[184:187], v[200:203], v[52:55]
	v_mfma_f32_16x16x32_bf16 v[44:47], v[168:171], v[204:207], v[44:47]
	v_mfma_f32_16x16x32_bf16 v[44:47], v[172:175], v[208:211], v[44:47]
	v_mfma_f32_16x16x32_bf16 v[40:43], v[176:179], v[204:207], v[40:43]
	v_mfma_f32_16x16x32_bf16 v[40:43], v[184:187], v[208:211], v[40:43]
	v_mfma_f32_16x16x32_bf16 v[36:39], v[168:171], v[212:215], v[36:39]
	v_mfma_f32_16x16x32_bf16 v[36:39], v[172:175], v[216:219], v[36:39]
	s_barrier
	v_mfma_f32_16x16x32_bf16 v[32:35], v[176:179], v[212:215], v[32:35]
	v_mfma_f32_16x16x32_bf16 v[32:35], v[184:187], v[216:219], v[32:35]
	s_setprio 0
	s_add_i32 s64, s79, s68
	v_lshl_add_u64 v[220:221], v[220:221], 0, s[12:13]
	s_mov_b32 m0, s64
	ds_read_b128 v[188:191], v150 offset:49152
	ds_read_b128 v[192:195], v150 offset:50176
	ds_read_b128 v[196:199], v150 offset:51200
	ds_read_b128 v[200:203], v150 offset:52224
	ds_read_b128 v[204:207], v150 offset:53248
	ds_read_b128 v[208:211], v150 offset:54272
	ds_read_b128 v[212:215], v150 offset:55296
	ds_read_b128 v[216:219], v150 offset:56320
	global_load_lds_dwordx4 v[220:221], off
	s_add_i32 m0, s64, 0x2000
	s_add_u32 s62, s62, 0x40080
	v_lshl_add_u64 v[220:221], v[222:223], 0, s[12:13]
	s_addc_u32 s63, s63, 0
	s_add_i32 s64, s88, s68
	global_load_lds_dwordx4 v[220:221], off
	v_lshl_add_u64 v[220:221], s[62:63], 0, v[130:131]
	s_mov_b32 m0, s64
	s_nop 0
	global_load_lds_dwordx4 v[220:221], off
	v_lshl_add_u64 v[220:221], s[62:63], 0, v[134:135]
	s_add_i32 m0, s64, 0x2000
	s_nop 0
	global_load_lds_dwordx4 v[220:221], off
	v_lshl_add_u64 v[220:221], v[224:225], 0, s[12:13]
	s_mov_b32 m0, s75
	s_nop 0
	global_load_lds_dwordx4 v[220:221], off
	v_lshl_add_u64 v[220:221], v[226:227], 0, s[12:13]
	s_mov_b32 m0, s76
	s_nop 0
	global_load_lds_dwordx4 v[220:221], off
	s_waitcnt vmcnt(8)
	s_waitcnt lgkmcnt(0)
	s_barrier
	s_waitcnt lgkmcnt(0)
	v_mfma_f32_16x16x32_bf16 v[92:95], v[152:155], v[188:191], v[92:95]
	v_mfma_f32_16x16x32_bf16 v[92:95], v[156:159], v[192:195], v[92:95]
	s_setprio 1
	v_mfma_f32_16x16x32_bf16 v[88:91], v[160:163], v[188:191], v[88:91]
	v_mfma_f32_16x16x32_bf16 v[88:91], v[164:167], v[192:195], v[88:91]
	v_mfma_f32_16x16x32_bf16 v[84:87], v[152:155], v[196:199], v[84:87]
	v_mfma_f32_16x16x32_bf16 v[84:87], v[156:159], v[200:203], v[84:87]
	v_mfma_f32_16x16x32_bf16 v[80:83], v[160:163], v[196:199], v[80:83]
	v_mfma_f32_16x16x32_bf16 v[80:83], v[164:167], v[200:203], v[80:83]
	v_mfma_f32_16x16x32_bf16 v[72:75], v[152:155], v[204:207], v[72:75]
	v_mfma_f32_16x16x32_bf16 v[72:75], v[156:159], v[208:211], v[72:75]
	v_mfma_f32_16x16x32_bf16 v[64:67], v[160:163], v[204:207], v[64:67]
	v_mfma_f32_16x16x32_bf16 v[64:67], v[164:167], v[208:211], v[64:67]
	v_mfma_f32_16x16x32_bf16 v[56:59], v[152:155], v[212:215], v[56:59]
	v_mfma_f32_16x16x32_bf16 v[56:59], v[156:159], v[216:219], v[56:59]
	v_mfma_f32_16x16x32_bf16 v[48:51], v[160:163], v[212:215], v[48:51]
	v_mfma_f32_16x16x32_bf16 v[48:51], v[164:167], v[216:219], v[48:51]
	v_mfma_f32_16x16x32_bf16 v[28:31], v[168:171], v[188:191], v[28:31]
	v_mfma_f32_16x16x32_bf16 v[28:31], v[172:175], v[192:195], v[28:31]
	v_mfma_f32_16x16x32_bf16 v[24:27], v[176:179], v[188:191], v[24:27]
	v_mfma_f32_16x16x32_bf16 v[24:27], v[184:187], v[192:195], v[24:27]
	v_mfma_f32_16x16x32_bf16 v[20:23], v[168:171], v[196:199], v[20:23]
	v_mfma_f32_16x16x32_bf16 v[20:23], v[172:175], v[200:203], v[20:23]
	v_mfma_f32_16x16x32_bf16 v[16:19], v[176:179], v[196:199], v[16:19]
	v_mfma_f32_16x16x32_bf16 v[16:19], v[184:187], v[200:203], v[16:19]
	v_mfma_f32_16x16x32_bf16 v[12:15], v[168:171], v[204:207], v[12:15]
	v_mfma_f32_16x16x32_bf16 v[12:15], v[172:175], v[208:211], v[12:15]
	v_mfma_f32_16x16x32_bf16 v[8:11], v[176:179], v[204:207], v[8:11]
	v_mfma_f32_16x16x32_bf16 v[8:11], v[184:187], v[208:211], v[8:11]
	v_mfma_f32_16x16x32_bf16 v[4:7], v[168:171], v[212:215], v[4:7]
	v_mfma_f32_16x16x32_bf16 v[4:7], v[172:175], v[216:219], v[4:7]
	s_barrier
	v_mfma_f32_16x16x32_bf16 v[0:3], v[176:179], v[212:215], v[0:3]
	v_mfma_f32_16x16x32_bf16 v[0:3], v[184:187], v[216:219], v[0:3]
	s_setprio 0
	s_add_i32 s87, s87, 2
	s_add_u32 s60, s60, 0x100
	s_addc_u32 s61, s61, 0
	s_add_u32 s85, s85, 0x100
	s_addc_u32 s86, s86, 0
	s_cmp_gt_u32 s87, 13
	s_cbranch_scc0 .LBB0_935
	s_and_b64 vcc, exec, s[16:17]
	s_cbranch_vccz .LBB0_938
	s_barrier

.LBB0_950:
	s_ashr_i32 s37, s36, 31
	s_lshl_b64 s[44:45], s[36:37], 19
	s_add_u32 s44, s80, s44
	s_addc_u32 s45, s81, s45
	s_and_b64 s[46:47], s[10:11], exec
	s_cselect_b32 s37, s45, s53
	s_cselect_b32 s72, s44, s52
	s_ashr_i32 s19, s18, 31
	s_lshl_b64 s[46:47], s[18:19], 19
	s_add_u32 s46, s58, s46
	s_addc_u32 s47, s59, s47
	s_and_b64 s[56:57], s[10:11], exec
	s_cselect_b32 s19, s47, s55
	s_cselect_b32 s73, s46, s54
	s_add_u32 s52, s52, 0x40080
	s_addc_u32 s53, s53, 0
	s_add_u32 s74, s54, 0x100
	s_addc_u32 s75, s55, 0
	s_mov_b32 s76, -2
	ds_read_b128 v[140:143], v147
	ds_read_b128 v[150:153], v147 offset:1024
	ds_read_b128 v[154:157], v147 offset:2048
	ds_read_b128 v[158:161], v147 offset:3072
	ds_read_b128 v[162:165], v148
	ds_read_b128 v[166:169], v148 offset:1024
	ds_read_b128 v[170:173], v148 offset:2048
	ds_read_b128 v[174:177], v148 offset:3072
	s_add_u32 s54, s52, 0xfffc0080
	s_addc_u32 s55, s53, -1
	s_cmp_eq_u32 s76, 12
	s_cselect_b32 s57, s37, s55
	s_cselect_b32 s56, s72, s54
	s_cselect_b32 s55, s19, s75
	s_cselect_b32 s54, s73, s74
	v_lshl_add_u64 v[178:179], s[52:53], 0, v[132:133]
	s_add_i32 m0, s49, 0xc000
	ds_read_b128 v[184:187], v149
	ds_read_b128 v[188:191], v149 offset:1024
	ds_read_b128 v[192:195], v149 offset:2048
	ds_read_b128 v[196:199], v149 offset:3072
	ds_read_b128 v[200:203], v149 offset:4096
	ds_read_b128 v[204:207], v149 offset:5120
	ds_read_b128 v[208:211], v149 offset:6144
	ds_read_b128 v[212:215], v149 offset:7168
	global_load_lds_dwordx4 v[178:179], off
	v_lshl_add_u64 v[178:179], s[52:53], 0, v[134:135]
	s_add_i32 m0, s49, 0xe000
	s_nop 0
	global_load_lds_dwordx4 v[178:179], off
	s_waitcnt vmcnt(8)
	s_waitcnt lgkmcnt(0)
	s_barrier
	s_waitcnt lgkmcnt(0)
	v_mfma_f32_16x16x32_bf16 v[124:127], v[140:143], v[184:187], 0
	v_mfma_f32_16x16x32_bf16 v[124:127], v[150:153], v[188:191], v[124:127]
	s_setprio 1
	v_mfma_f32_16x16x32_bf16 v[120:123], v[154:157], v[184:187], 0
	v_mfma_f32_16x16x32_bf16 v[120:123], v[158:161], v[188:191], v[120:123]
	v_mfma_f32_16x16x32_bf16 v[108:111], v[140:143], v[192:195], 0
	v_mfma_f32_16x16x32_bf16 v[108:111], v[150:153], v[196:199], v[108:111]
	v_mfma_f32_16x16x32_bf16 v[104:107], v[154:157], v[192:195], 0
	v_mfma_f32_16x16x32_bf16 v[104:107], v[158:161], v[196:199], v[104:107]
	v_mfma_f32_16x16x32_bf16 v[92:95], v[140:143], v[200:203], 0
	v_mfma_f32_16x16x32_bf16 v[92:95], v[150:153], v[204:207], v[92:95]
	v_mfma_f32_16x16x32_bf16 v[88:91], v[154:157], v[200:203], 0
	v_mfma_f32_16x16x32_bf16 v[88:91], v[158:161], v[204:207], v[88:91]
	v_mfma_f32_16x16x32_bf16 v[76:79], v[140:143], v[208:211], 0
	v_mfma_f32_16x16x32_bf16 v[76:79], v[150:153], v[212:215], v[76:79]
	v_mfma_f32_16x16x32_bf16 v[72:75], v[154:157], v[208:211], 0
	v_mfma_f32_16x16x32_bf16 v[72:75], v[158:161], v[212:215], v[72:75]
	v_mfma_f32_16x16x32_bf16 v[116:119], v[162:165], v[184:187], 0
	v_mfma_f32_16x16x32_bf16 v[116:119], v[166:169], v[188:191], v[116:119]
	v_mfma_f32_16x16x32_bf16 v[112:115], v[170:173], v[184:187], 0
	v_mfma_f32_16x16x32_bf16 v[112:115], v[174:177], v[188:191], v[112:115]
	v_mfma_f32_16x16x32_bf16 v[100:103], v[162:165], v[192:195], 0
	v_mfma_f32_16x16x32_bf16 v[100:103], v[166:169], v[196:199], v[100:103]
	v_mfma_f32_16x16x32_bf16 v[96:99], v[170:173], v[192:195], 0
	v_mfma_f32_16x16x32_bf16 v[96:99], v[174:177], v[196:199], v[96:99]
	v_mfma_f32_16x16x32_bf16 v[84:87], v[162:165], v[200:203], 0
	v_mfma_f32_16x16x32_bf16 v[84:87], v[166:169], v[204:207], v[84:87]
	v_mfma_f32_16x16x32_bf16 v[80:83], v[170:173], v[200:203], 0
	v_mfma_f32_16x16x32_bf16 v[80:83], v[174:177], v[204:207], v[80:83]
	v_mfma_f32_16x16x32_bf16 v[68:71], v[162:165], v[208:211], 0
	v_mfma_f32_16x16x32_bf16 v[68:71], v[166:169], v[212:215], v[68:71]
	s_barrier
	v_mfma_f32_16x16x32_bf16 v[64:67], v[170:173], v[208:211], 0
	v_mfma_f32_16x16x32_bf16 v[64:67], v[174:177], v[212:215], v[64:67]
	s_setprio 0
	s_add_i32 s77, s68, s60
	v_lshl_add_u64 v[178:179], s[54:55], 0, v[130:131]
	s_mov_b32 m0, s77
	ds_read_b128 v[184:187], v149 offset:16384
	ds_read_b128 v[188:191], v149 offset:17408
	ds_read_b128 v[192:195], v149 offset:18432
	ds_read_b128 v[196:199], v149 offset:19456
	ds_read_b128 v[200:203], v149 offset:20480
	ds_read_b128 v[204:207], v149 offset:21504
	ds_read_b128 v[208:211], v149 offset:22528
	ds_read_b128 v[212:215], v149 offset:23552
	global_load_lds_dwordx4 v[178:179], off
	s_add_i32 m0, s77, 0x2000
	s_add_u32 s82, s54, 0x40000
	v_lshl_add_u64 v[216:217], s[54:55], 0, v[128:129]
	s_addc_u32 s83, s55, 0
	s_add_i32 s77, s69, s60
	global_load_lds_dwordx4 v[216:217], off
	v_lshl_add_u64 v[218:219], s[82:83], 0, v[130:131]
	s_mov_b32 m0, s77
	v_lshl_add_u64 v[220:221], s[56:57], 0, v[128:129]
	global_load_lds_dwordx4 v[218:219], off
	v_lshl_add_u64 v[218:219], s[82:83], 0, v[128:129]
	s_add_i32 m0, s77, 0x2000
	s_nop 0
	global_load_lds_dwordx4 v[218:219], off
	v_lshl_add_u64 v[218:219], s[56:57], 0, v[130:131]
	s_mov_b32 m0, s49
	s_nop 0
	global_load_lds_dwordx4 v[218:219], off
	s_mov_b32 m0, s62
	s_nop 0
	global_load_lds_dwordx4 v[220:221], off
	s_waitcnt vmcnt(8)
	s_waitcnt lgkmcnt(0)
	s_barrier
	s_waitcnt lgkmcnt(0)
	v_mfma_f32_16x16x32_bf16 v[60:63], v[140:143], v[184:187], 0
	v_mfma_f32_16x16x32_bf16 v[60:63], v[150:153], v[188:191], v[60:63]
	s_setprio 1
	v_mfma_f32_16x16x32_bf16 v[56:59], v[154:157], v[184:187], 0
	v_mfma_f32_16x16x32_bf16 v[56:59], v[158:161], v[188:191], v[56:59]
	v_mfma_f32_16x16x32_bf16 v[44:47], v[140:143], v[192:195], 0
	v_mfma_f32_16x16x32_bf16 v[44:47], v[150:153], v[196:199], v[44:47]
	v_mfma_f32_16x16x32_bf16 v[40:43], v[154:157], v[192:195], 0
	v_mfma_f32_16x16x32_bf16 v[40:43], v[158:161], v[196:199], v[40:43]
	v_mfma_f32_16x16x32_bf16 v[28:31], v[140:143], v[200:203], 0
	v_mfma_f32_16x16x32_bf16 v[28:31], v[150:153], v[204:207], v[28:31]
	v_mfma_f32_16x16x32_bf16 v[24:27], v[154:157], v[200:203], 0
	v_mfma_f32_16x16x32_bf16 v[24:27], v[158:161], v[204:207], v[24:27]
	v_mfma_f32_16x16x32_bf16 v[12:15], v[140:143], v[208:211], 0
	v_mfma_f32_16x16x32_bf16 v[12:15], v[150:153], v[212:215], v[12:15]
	v_mfma_f32_16x16x32_bf16 v[8:11], v[154:157], v[208:211], 0
	v_mfma_f32_16x16x32_bf16 v[8:11], v[158:161], v[212:215], v[8:11]
	v_mfma_f32_16x16x32_bf16 v[52:55], v[162:165], v[184:187], 0
	v_mfma_f32_16x16x32_bf16 v[52:55], v[166:169], v[188:191], v[52:55]
	v_mfma_f32_16x16x32_bf16 v[48:51], v[170:173], v[184:187], 0
	v_mfma_f32_16x16x32_bf16 v[48:51], v[174:177], v[188:191], v[48:51]
	v_mfma_f32_16x16x32_bf16 v[36:39], v[162:165], v[192:195], 0
	v_mfma_f32_16x16x32_bf16 v[36:39], v[166:169], v[196:199], v[36:39]
	v_mfma_f32_16x16x32_bf16 v[32:35], v[170:173], v[192:195], 0
	v_mfma_f32_16x16x32_bf16 v[32:35], v[174:177], v[196:199], v[32:35]
	v_mfma_f32_16x16x32_bf16 v[20:23], v[162:165], v[200:203], 0
	v_mfma_f32_16x16x32_bf16 v[20:23], v[166:169], v[204:207], v[20:23]
	v_mfma_f32_16x16x32_bf16 v[16:19], v[170:173], v[200:203], 0
	v_mfma_f32_16x16x32_bf16 v[16:19], v[174:177], v[204:207], v[16:19]
	v_mfma_f32_16x16x32_bf16 v[4:7], v[162:165], v[208:211], 0
	v_mfma_f32_16x16x32_bf16 v[4:7], v[166:169], v[212:215], v[4:7]
	s_barrier
	v_mfma_f32_16x16x32_bf16 v[0:3], v[170:173], v[208:211], 0
	v_mfma_f32_16x16x32_bf16 v[0:3], v[174:177], v[212:215], v[0:3]
	s_setprio 0
	s_branch .Lmid_gemm7
.LBB0_951:
	ds_read_b128 v[140:143], v147
	ds_read_b128 v[150:153], v147 offset:1024
	ds_read_b128 v[154:157], v147 offset:2048
	ds_read_b128 v[158:161], v147 offset:3072
	ds_read_b128 v[162:165], v148
	ds_read_b128 v[166:169], v148 offset:1024
	ds_read_b128 v[170:173], v148 offset:2048
	ds_read_b128 v[174:177], v148 offset:3072
	s_add_u32 s54, s52, 0xfffc0080
	s_addc_u32 s55, s53, -1
	s_cmp_eq_u32 s76, 12
	s_cselect_b32 s57, s37, s55
	s_cselect_b32 s56, s72, s54
	s_cselect_b32 s55, s19, s75
	s_cselect_b32 s54, s73, s74
	v_lshl_add_u64 v[178:179], s[52:53], 0, v[132:133]
	s_add_i32 m0, s49, 0xc000
	ds_read_b128 v[184:187], v149
	ds_read_b128 v[188:191], v149 offset:1024
	ds_read_b128 v[192:195], v149 offset:2048
	ds_read_b128 v[196:199], v149 offset:3072
	ds_read_b128 v[200:203], v149 offset:4096
	ds_read_b128 v[204:207], v149 offset:5120
	ds_read_b128 v[208:211], v149 offset:6144
	ds_read_b128 v[212:215], v149 offset:7168
	global_load_lds_dwordx4 v[178:179], off
	v_lshl_add_u64 v[178:179], s[52:53], 0, v[134:135]
	s_add_i32 m0, s49, 0xe000
	s_nop 0
	global_load_lds_dwordx4 v[178:179], off
	s_waitcnt vmcnt(8)
	s_waitcnt lgkmcnt(0)
	s_barrier
	s_waitcnt lgkmcnt(0)
	v_mfma_f32_16x16x32_bf16 v[124:127], v[140:143], v[184:187], v[124:127]
	v_mfma_f32_16x16x32_bf16 v[124:127], v[150:153], v[188:191], v[124:127]
	s_setprio 1
	v_mfma_f32_16x16x32_bf16 v[120:123], v[154:157], v[184:187], v[120:123]
	v_mfma_f32_16x16x32_bf16 v[120:123], v[158:161], v[188:191], v[120:123]
	v_mfma_f32_16x16x32_bf16 v[108:111], v[140:143], v[192:195], v[108:111]
	v_mfma_f32_16x16x32_bf16 v[108:111], v[150:153], v[196:199], v[108:111]
	v_mfma_f32_16x16x32_bf16 v[104:107], v[154:157], v[192:195], v[104:107]
	v_mfma_f32_16x16x32_bf16 v[104:107], v[158:161], v[196:199], v[104:107]
	v_mfma_f32_16x16x32_bf16 v[92:95], v[140:143], v[200:203], v[92:95]
	v_mfma_f32_16x16x32_bf16 v[92:95], v[150:153], v[204:207], v[92:95]
	v_mfma_f32_16x16x32_bf16 v[88:91], v[154:157], v[200:203], v[88:91]
	v_mfma_f32_16x16x32_bf16 v[88:91], v[158:161], v[204:207], v[88:91]
	v_mfma_f32_16x16x32_bf16 v[76:79], v[140:143], v[208:211], v[76:79]
	v_mfma_f32_16x16x32_bf16 v[76:79], v[150:153], v[212:215], v[76:79]
	v_mfma_f32_16x16x32_bf16 v[72:75], v[154:157], v[208:211], v[72:75]
	v_mfma_f32_16x16x32_bf16 v[72:75], v[158:161], v[212:215], v[72:75]
	v_mfma_f32_16x16x32_bf16 v[116:119], v[162:165], v[184:187], v[116:119]
	v_mfma_f32_16x16x32_bf16 v[116:119], v[166:169], v[188:191], v[116:119]
	v_mfma_f32_16x16x32_bf16 v[112:115], v[170:173], v[184:187], v[112:115]
	v_mfma_f32_16x16x32_bf16 v[112:115], v[174:177], v[188:191], v[112:115]
	v_mfma_f32_16x16x32_bf16 v[100:103], v[162:165], v[192:195], v[100:103]
	v_mfma_f32_16x16x32_bf16 v[100:103], v[166:169], v[196:199], v[100:103]
	v_mfma_f32_16x16x32_bf16 v[96:99], v[170:173], v[192:195], v[96:99]
	v_mfma_f32_16x16x32_bf16 v[96:99], v[174:177], v[196:199], v[96:99]
	v_mfma_f32_16x16x32_bf16 v[84:87], v[162:165], v[200:203], v[84:87]
	v_mfma_f32_16x16x32_bf16 v[84:87], v[166:169], v[204:207], v[84:87]
	v_mfma_f32_16x16x32_bf16 v[80:83], v[170:173], v[200:203], v[80:83]
	v_mfma_f32_16x16x32_bf16 v[80:83], v[174:177], v[204:207], v[80:83]
	v_mfma_f32_16x16x32_bf16 v[68:71], v[162:165], v[208:211], v[68:71]
	v_mfma_f32_16x16x32_bf16 v[68:71], v[166:169], v[212:215], v[68:71]
	s_barrier
	v_mfma_f32_16x16x32_bf16 v[64:67], v[170:173], v[208:211], v[64:67]
	v_mfma_f32_16x16x32_bf16 v[64:67], v[174:177], v[212:215], v[64:67]
	s_setprio 0
	s_add_i32 s77, s68, s60
	v_lshl_add_u64 v[178:179], s[54:55], 0, v[130:131]
	s_mov_b32 m0, s77
	ds_read_b128 v[184:187], v149 offset:16384
	ds_read_b128 v[188:191], v149 offset:17408
	ds_read_b128 v[192:195], v149 offset:18432
	ds_read_b128 v[196:199], v149 offset:19456
	ds_read_b128 v[200:203], v149 offset:20480
	ds_read_b128 v[204:207], v149 offset:21504
	ds_read_b128 v[208:211], v149 offset:22528
	ds_read_b128 v[212:215], v149 offset:23552
	global_load_lds_dwordx4 v[178:179], off
	s_add_i32 m0, s77, 0x2000
	s_add_u32 s82, s54, 0x40000
	v_lshl_add_u64 v[216:217], s[54:55], 0, v[128:129]
	s_addc_u32 s83, s55, 0
	s_add_i32 s77, s69, s60
	global_load_lds_dwordx4 v[216:217], off
	v_lshl_add_u64 v[218:219], s[82:83], 0, v[130:131]
	s_mov_b32 m0, s77
	v_lshl_add_u64 v[220:221], s[56:57], 0, v[128:129]
	global_load_lds_dwordx4 v[218:219], off
	v_lshl_add_u64 v[218:219], s[82:83], 0, v[128:129]
	s_add_i32 m0, s77, 0x2000
	s_nop 0
	global_load_lds_dwordx4 v[218:219], off
	v_lshl_add_u64 v[218:219], s[56:57], 0, v[130:131]
	s_mov_b32 m0, s49
	s_nop 0
	global_load_lds_dwordx4 v[218:219], off
	s_mov_b32 m0, s62
	s_nop 0
	global_load_lds_dwordx4 v[220:221], off
	s_waitcnt vmcnt(8)
	s_waitcnt lgkmcnt(0)
	s_barrier
	s_waitcnt lgkmcnt(0)
	v_mfma_f32_16x16x32_bf16 v[60:63], v[140:143], v[184:187], v[60:63]
	v_mfma_f32_16x16x32_bf16 v[60:63], v[150:153], v[188:191], v[60:63]
	s_setprio 1
	v_mfma_f32_16x16x32_bf16 v[56:59], v[154:157], v[184:187], v[56:59]
	v_mfma_f32_16x16x32_bf16 v[56:59], v[158:161], v[188:191], v[56:59]
	v_mfma_f32_16x16x32_bf16 v[44:47], v[140:143], v[192:195], v[44:47]
	v_mfma_f32_16x16x32_bf16 v[44:47], v[150:153], v[196:199], v[44:47]
	v_mfma_f32_16x16x32_bf16 v[40:43], v[154:157], v[192:195], v[40:43]
	v_mfma_f32_16x16x32_bf16 v[40:43], v[158:161], v[196:199], v[40:43]
	v_mfma_f32_16x16x32_bf16 v[28:31], v[140:143], v[200:203], v[28:31]
	v_mfma_f32_16x16x32_bf16 v[28:31], v[150:153], v[204:207], v[28:31]
	v_mfma_f32_16x16x32_bf16 v[24:27], v[154:157], v[200:203], v[24:27]
	v_mfma_f32_16x16x32_bf16 v[24:27], v[158:161], v[204:207], v[24:27]
	v_mfma_f32_16x16x32_bf16 v[12:15], v[140:143], v[208:211], v[12:15]
	v_mfma_f32_16x16x32_bf16 v[12:15], v[150:153], v[212:215], v[12:15]
	v_mfma_f32_16x16x32_bf16 v[8:11], v[154:157], v[208:211], v[8:11]
	v_mfma_f32_16x16x32_bf16 v[8:11], v[158:161], v[212:215], v[8:11]
	v_mfma_f32_16x16x32_bf16 v[52:55], v[162:165], v[184:187], v[52:55]
	v_mfma_f32_16x16x32_bf16 v[52:55], v[166:169], v[188:191], v[52:55]
	v_mfma_f32_16x16x32_bf16 v[48:51], v[170:173], v[184:187], v[48:51]
	v_mfma_f32_16x16x32_bf16 v[48:51], v[174:177], v[188:191], v[48:51]
	v_mfma_f32_16x16x32_bf16 v[36:39], v[162:165], v[192:195], v[36:39]
	v_mfma_f32_16x16x32_bf16 v[36:39], v[166:169], v[196:199], v[36:39]
	v_mfma_f32_16x16x32_bf16 v[32:35], v[170:173], v[192:195], v[32:35]
	v_mfma_f32_16x16x32_bf16 v[32:35], v[174:177], v[196:199], v[32:35]
	v_mfma_f32_16x16x32_bf16 v[20:23], v[162:165], v[200:203], v[20:23]
	v_mfma_f32_16x16x32_bf16 v[20:23], v[166:169], v[204:207], v[20:23]
	v_mfma_f32_16x16x32_bf16 v[16:19], v[170:173], v[200:203], v[16:19]
	v_mfma_f32_16x16x32_bf16 v[16:19], v[174:177], v[204:207], v[16:19]
	v_mfma_f32_16x16x32_bf16 v[4:7], v[162:165], v[208:211], v[4:7]
	v_mfma_f32_16x16x32_bf16 v[4:7], v[166:169], v[212:215], v[4:7]
	s_barrier
	v_mfma_f32_16x16x32_bf16 v[0:3], v[170:173], v[208:211], v[0:3]
	v_mfma_f32_16x16x32_bf16 v[0:3], v[174:177], v[212:215], v[0:3]
	s_setprio 0
.Lmid_gemm7:
	s_add_i32 s77, 0, 0x18000
	s_add_i32 s79, 0, 0x1c000
	v_add_u32_e32 v158, s77, v145
	v_add_u32_e32 v174, s79, v145
	ds_read_b128 v[140:143], v158
	ds_read_b128 v[150:153], v158 offset:1024
	ds_read_b128 v[154:157], v158 offset:2048
	ds_read_b128 v[158:161], v158 offset:3072
	ds_read_b128 v[162:165], v174
	ds_read_b128 v[166:169], v174 offset:1024
	ds_read_b128 v[170:173], v174 offset:2048
	ds_read_b128 v[174:177], v174 offset:3072
	s_add_u32 s56, s56, 0x40000
	s_addc_u32 s57, s57, 0
	s_mov_b32 m0, s63
	v_lshl_add_u64 v[222:223], s[56:57], 0, v[130:131]
	ds_read_b128 v[184:187], v149 offset:32768
	ds_read_b128 v[188:191], v149 offset:33792
	ds_read_b128 v[192:195], v149 offset:34816
	ds_read_b128 v[196:199], v149 offset:35840
	ds_read_b128 v[200:203], v149 offset:36864
	ds_read_b128 v[204:207], v149 offset:37888
	ds_read_b128 v[208:211], v149 offset:38912
	ds_read_b128 v[212:215], v149 offset:39936
	global_load_lds_dwordx4 v[222:223], off
	v_lshl_add_u64 v[222:223], s[56:57], 0, v[128:129]
	s_mov_b32 m0, s64
	s_nop 0
	global_load_lds_dwordx4 v[222:223], off
	s_waitcnt vmcnt(8)
	s_waitcnt lgkmcnt(0)
	s_barrier
	s_waitcnt lgkmcnt(0)
	v_mfma_f32_16x16x32_bf16 v[124:127], v[140:143], v[184:187], v[124:127]
	v_mfma_f32_16x16x32_bf16 v[124:127], v[150:153], v[188:191], v[124:127]
	s_setprio 1
	v_mfma_f32_16x16x32_bf16 v[120:123], v[154:157], v[184:187], v[120:123]
	v_mfma_f32_16x16x32_bf16 v[120:123], v[158:161], v[188:191], v[120:123]
	v_mfma_f32_16x16x32_bf16 v[108:111], v[140:143], v[192:195], v[108:111]
	v_mfma_f32_16x16x32_bf16 v[108:111], v[150:153], v[196:199], v[108:111]
	v_mfma_f32_16x16x32_bf16 v[104:107], v[154:157], v[192:195], v[104:107]
	v_mfma_f32_16x16x32_bf16 v[104:107], v[158:161], v[196:199], v[104:107]
	v_mfma_f32_16x16x32_bf16 v[92:95], v[140:143], v[200:203], v[92:95]
	v_mfma_f32_16x16x32_bf16 v[92:95], v[150:153], v[204:207], v[92:95]
	v_mfma_f32_16x16x32_bf16 v[88:91], v[154:157], v[200:203], v[88:91]
	v_mfma_f32_16x16x32_bf16 v[88:91], v[158:161], v[204:207], v[88:91]
	v_mfma_f32_16x16x32_bf16 v[76:79], v[140:143], v[208:211], v[76:79]
	v_mfma_f32_16x16x32_bf16 v[76:79], v[150:153], v[212:215], v[76:79]
	v_mfma_f32_16x16x32_bf16 v[72:75], v[154:157], v[208:211], v[72:75]
	v_mfma_f32_16x16x32_bf16 v[72:75], v[158:161], v[212:215], v[72:75]
	v_mfma_f32_16x16x32_bf16 v[116:119], v[162:165], v[184:187], v[116:119]
	v_mfma_f32_16x16x32_bf16 v[116:119], v[166:169], v[188:191], v[116:119]
	v_mfma_f32_16x16x32_bf16 v[112:115], v[170:173], v[184:187], v[112:115]
	v_mfma_f32_16x16x32_bf16 v[112:115], v[174:177], v[188:191], v[112:115]
	v_mfma_f32_16x16x32_bf16 v[100:103], v[162:165], v[192:195], v[100:103]
	v_mfma_f32_16x16x32_bf16 v[100:103], v[166:169], v[196:199], v[100:103]
	v_mfma_f32_16x16x32_bf16 v[96:99], v[170:173], v[192:195], v[96:99]
	v_mfma_f32_16x16x32_bf16 v[96:99], v[174:177], v[196:199], v[96:99]
	v_mfma_f32_16x16x32_bf16 v[84:87], v[162:165], v[200:203], v[84:87]
	v_mfma_f32_16x16x32_bf16 v[84:87], v[166:169], v[204:207], v[84:87]
	v_mfma_f32_16x16x32_bf16 v[80:83], v[170:173], v[200:203], v[80:83]
	v_mfma_f32_16x16x32_bf16 v[80:83], v[174:177], v[204:207], v[80:83]
	v_mfma_f32_16x16x32_bf16 v[68:71], v[162:165], v[208:211], v[68:71]
	v_mfma_f32_16x16x32_bf16 v[68:71], v[166:169], v[212:215], v[68:71]
	s_barrier
	v_mfma_f32_16x16x32_bf16 v[64:67], v[170:173], v[208:211], v[64:67]
	v_mfma_f32_16x16x32_bf16 v[64:67], v[174:177], v[212:215], v[64:67]
	s_setprio 0
	s_add_i32 s56, s77, s60
	v_lshl_add_u64 v[178:179], v[178:179], 0, s[12:13]
	s_mov_b32 m0, s56
	ds_read_b128 v[184:187], v149 offset:49152
	ds_read_b128 v[188:191], v149 offset:50176
	ds_read_b128 v[192:195], v149 offset:51200
	ds_read_b128 v[196:199], v149 offset:52224
	ds_read_b128 v[200:203], v149 offset:53248
	ds_read_b128 v[204:207], v149 offset:54272
	ds_read_b128 v[208:211], v149 offset:55296
	ds_read_b128 v[212:215], v149 offset:56320
	global_load_lds_dwordx4 v[178:179], off
	s_add_i32 m0, s56, 0x2000
	s_add_u32 s54, s54, 0x40080
	v_lshl_add_u64 v[178:179], v[216:217], 0, s[12:13]
	s_addc_u32 s55, s55, 0
	s_add_i32 s56, s79, s60
	global_load_lds_dwordx4 v[178:179], off
	v_lshl_add_u64 v[178:179], s[54:55], 0, v[130:131]
	s_mov_b32 m0, s56
	s_nop 0
	global_load_lds_dwordx4 v[178:179], off
	v_lshl_add_u64 v[178:179], s[54:55], 0, v[128:129]
	s_add_i32 m0, s56, 0x2000
	s_nop 0
	global_load_lds_dwordx4 v[178:179], off
	v_lshl_add_u64 v[178:179], v[218:219], 0, s[12:13]
	s_mov_b32 m0, s66
	s_nop 0
	global_load_lds_dwordx4 v[178:179], off
	v_lshl_add_u64 v[178:179], v[220:221], 0, s[12:13]
	s_mov_b32 m0, s67
	s_nop 0
	global_load_lds_dwordx4 v[178:179], off
	s_waitcnt vmcnt(8)
	s_waitcnt lgkmcnt(0)
	s_barrier
	s_waitcnt lgkmcnt(0)
	v_mfma_f32_16x16x32_bf16 v[60:63], v[140:143], v[184:187], v[60:63]
	v_mfma_f32_16x16x32_bf16 v[60:63], v[150:153], v[188:191], v[60:63]
	s_setprio 1
	v_mfma_f32_16x16x32_bf16 v[56:59], v[154:157], v[184:187], v[56:59]
	v_mfma_f32_16x16x32_bf16 v[56:59], v[158:161], v[188:191], v[56:59]
	v_mfma_f32_16x16x32_bf16 v[44:47], v[140:143], v[192:195], v[44:47]
	v_mfma_f32_16x16x32_bf16 v[44:47], v[150:153], v[196:199], v[44:47]
	v_mfma_f32_16x16x32_bf16 v[40:43], v[154:157], v[192:195], v[40:43]
	v_mfma_f32_16x16x32_bf16 v[40:43], v[158:161], v[196:199], v[40:43]
	v_mfma_f32_16x16x32_bf16 v[28:31], v[140:143], v[200:203], v[28:31]
	v_mfma_f32_16x16x32_bf16 v[28:31], v[150:153], v[204:207], v[28:31]
	v_mfma_f32_16x16x32_bf16 v[24:27], v[154:157], v[200:203], v[24:27]
	v_mfma_f32_16x16x32_bf16 v[24:27], v[158:161], v[204:207], v[24:27]
	v_mfma_f32_16x16x32_bf16 v[12:15], v[140:143], v[208:211], v[12:15]
	v_mfma_f32_16x16x32_bf16 v[12:15], v[150:153], v[212:215], v[12:15]
	v_mfma_f32_16x16x32_bf16 v[8:11], v[154:157], v[208:211], v[8:11]
	v_mfma_f32_16x16x32_bf16 v[8:11], v[158:161], v[212:215], v[8:11]
	v_mfma_f32_16x16x32_bf16 v[52:55], v[162:165], v[184:187], v[52:55]
	v_mfma_f32_16x16x32_bf16 v[52:55], v[166:169], v[188:191], v[52:55]
	v_mfma_f32_16x16x32_bf16 v[48:51], v[170:173], v[184:187], v[48:51]
	v_mfma_f32_16x16x32_bf16 v[48:51], v[174:177], v[188:191], v[48:51]
	v_mfma_f32_16x16x32_bf16 v[36:39], v[162:165], v[192:195], v[36:39]
	v_mfma_f32_16x16x32_bf16 v[36:39], v[166:169], v[196:199], v[36:39]
	v_mfma_f32_16x16x32_bf16 v[32:35], v[170:173], v[192:195], v[32:35]
	v_mfma_f32_16x16x32_bf16 v[32:35], v[174:177], v[196:199], v[32:35]
	v_mfma_f32_16x16x32_bf16 v[20:23], v[162:165], v[200:203], v[20:23]
	v_mfma_f32_16x16x32_bf16 v[20:23], v[166:169], v[204:207], v[20:23]
	v_mfma_f32_16x16x32_bf16 v[16:19], v[170:173], v[200:203], v[16:19]
	v_mfma_f32_16x16x32_bf16 v[16:19], v[174:177], v[204:207], v[16:19]
	v_mfma_f32_16x16x32_bf16 v[4:7], v[162:165], v[208:211], v[4:7]
	v_mfma_f32_16x16x32_bf16 v[4:7], v[166:169], v[212:215], v[4:7]
	s_barrier
	v_mfma_f32_16x16x32_bf16 v[0:3], v[170:173], v[208:211], v[0:3]
	v_mfma_f32_16x16x32_bf16 v[0:3], v[174:177], v[212:215], v[0:3]
	s_setprio 0
	s_add_i32 s76, s76, 2
	s_add_u32 s52, s52, 0x100
	s_addc_u32 s53, s53, 0
	s_add_u32 s74, s74, 0x100
	s_addc_u32 s75, s75, 0
	s_cmp_gt_u32 s76, 13
	s_cbranch_scc0 .LBB0_951
	s_and_b64 vcc, exec, s[16:17]
	s_cbranch_vccz .LBB0_954
	s_barrier

.LBB0_1030:
	s_add_u32 s86, s56, 0x100
	s_addc_u32 s87, s57, 0
	s_mov_b32 s88, -2
	ds_read_b128 v[152:155], v149
	ds_read_b128 v[156:159], v149 offset:1024
	ds_read_b128 v[160:163], v149 offset:2048
	ds_read_b128 v[164:167], v149 offset:3072
	ds_read_b128 v[168:171], v150
	ds_read_b128 v[172:175], v150 offset:1024
	ds_read_b128 v[176:179], v150 offset:2048
	ds_read_b128 v[184:187], v150 offset:3072
	s_add_u32 s56, s54, 0x100
	s_addc_u32 s57, s55, 0
	s_cmp_eq_u32 s88, 40
	s_cselect_b32 s61, s13, s57
	s_cselect_b32 s60, s12, s56
	s_cselect_b32 s59, s53, s87
	s_cselect_b32 s58, s52, s86
	v_lshl_add_u64 v[144:145], s[54:55], 0, v[136:137]
	s_add_i32 m0, s65, 0xc000
	ds_read_b128 v[188:191], v151
	ds_read_b128 v[192:195], v151 offset:1024
	ds_read_b128 v[196:199], v151 offset:2048
	ds_read_b128 v[200:203], v151 offset:3072
	ds_read_b128 v[204:207], v151 offset:4096
	ds_read_b128 v[208:211], v151 offset:5120
	ds_read_b128 v[212:215], v151 offset:6144
	ds_read_b128 v[216:219], v151 offset:7168
	global_load_lds_dwordx4 v[144:145], off
	v_lshl_add_u64 v[144:145], s[54:55], 0, v[138:139]
	s_add_i32 m0, s65, 0xe000
	s_nop 0
	global_load_lds_dwordx4 v[144:145], off
	s_waitcnt vmcnt(8)
	s_waitcnt lgkmcnt(0)
	s_barrier
	s_waitcnt lgkmcnt(0)
	v_mfma_f32_16x16x32_bf16 v[124:127], v[152:155], v[188:191], 0
	v_mfma_f32_16x16x32_bf16 v[124:127], v[156:159], v[192:195], v[124:127]
	s_setprio 1
	v_mfma_f32_16x16x32_bf16 v[120:123], v[160:163], v[188:191], 0
	v_mfma_f32_16x16x32_bf16 v[120:123], v[164:167], v[192:195], v[120:123]
	v_mfma_f32_16x16x32_bf16 v[116:119], v[152:155], v[196:199], 0
	v_mfma_f32_16x16x32_bf16 v[116:119], v[156:159], v[200:203], v[116:119]
	v_mfma_f32_16x16x32_bf16 v[108:111], v[160:163], v[196:199], 0
	v_mfma_f32_16x16x32_bf16 v[108:111], v[164:167], v[200:203], v[108:111]
	v_mfma_f32_16x16x32_bf16 v[100:103], v[152:155], v[204:207], 0
	v_mfma_f32_16x16x32_bf16 v[100:103], v[156:159], v[208:211], v[100:103]
	v_mfma_f32_16x16x32_bf16 v[92:95], v[160:163], v[204:207], 0
	v_mfma_f32_16x16x32_bf16 v[92:95], v[164:167], v[208:211], v[92:95]
	v_mfma_f32_16x16x32_bf16 v[84:87], v[152:155], v[212:215], 0
	v_mfma_f32_16x16x32_bf16 v[84:87], v[156:159], v[216:219], v[84:87]
	v_mfma_f32_16x16x32_bf16 v[76:79], v[160:163], v[212:215], 0
	v_mfma_f32_16x16x32_bf16 v[76:79], v[164:167], v[216:219], v[76:79]
	v_mfma_f32_16x16x32_bf16 v[112:115], v[168:171], v[188:191], 0
	v_mfma_f32_16x16x32_bf16 v[112:115], v[172:175], v[192:195], v[112:115]
	v_mfma_f32_16x16x32_bf16 v[104:107], v[176:179], v[188:191], 0
	v_mfma_f32_16x16x32_bf16 v[104:107], v[184:187], v[192:195], v[104:107]
	v_mfma_f32_16x16x32_bf16 v[96:99], v[168:171], v[196:199], 0
	v_mfma_f32_16x16x32_bf16 v[96:99], v[172:175], v[200:203], v[96:99]
	v_mfma_f32_16x16x32_bf16 v[88:91], v[176:179], v[196:199], 0
	v_mfma_f32_16x16x32_bf16 v[88:91], v[184:187], v[200:203], v[88:91]
	v_mfma_f32_16x16x32_bf16 v[80:83], v[168:171], v[204:207], 0
	v_mfma_f32_16x16x32_bf16 v[80:83], v[172:175], v[208:211], v[80:83]
	v_mfma_f32_16x16x32_bf16 v[72:75], v[176:179], v[204:207], 0
	v_mfma_f32_16x16x32_bf16 v[72:75], v[184:187], v[208:211], v[72:75]
	v_mfma_f32_16x16x32_bf16 v[68:71], v[168:171], v[212:215], 0
	v_mfma_f32_16x16x32_bf16 v[68:71], v[172:175], v[216:219], v[68:71]
	s_barrier
	v_mfma_f32_16x16x32_bf16 v[64:67], v[176:179], v[212:215], 0
	v_mfma_f32_16x16x32_bf16 v[64:67], v[184:187], v[216:219], v[64:67]
	s_setprio 0
	s_add_i32 s54, s72, s64
	v_lshl_add_u64 v[144:145], s[58:59], 0, v[130:131]
	s_mov_b32 m0, s54
	ds_read_b128 v[188:191], v151 offset:16384
	ds_read_b128 v[192:195], v151 offset:17408
	ds_read_b128 v[196:199], v151 offset:18432
	ds_read_b128 v[200:203], v151 offset:19456
	ds_read_b128 v[204:207], v151 offset:20480
	ds_read_b128 v[208:211], v151 offset:21504
	ds_read_b128 v[212:215], v151 offset:22528
	ds_read_b128 v[216:219], v151 offset:23552
	global_load_lds_dwordx4 v[144:145], off
	s_add_i32 m0, s54, 0x2000
	s_add_u32 s54, s58, 0xb0000
	v_lshl_add_u64 v[220:221], s[58:59], 0, v[134:135]
	s_addc_u32 s55, s59, 0
	s_add_i32 s79, s73, s64
	global_load_lds_dwordx4 v[220:221], off
	v_lshl_add_u64 v[222:223], s[54:55], 0, v[130:131]
	s_mov_b32 m0, s79
	v_lshl_add_u64 v[224:225], s[60:61], 0, v[132:133]
	global_load_lds_dwordx4 v[222:223], off
	v_lshl_add_u64 v[222:223], s[54:55], 0, v[134:135]
	s_add_i32 m0, s79, 0x2000
	s_nop 0
	global_load_lds_dwordx4 v[222:223], off
	v_lshl_add_u64 v[222:223], s[60:61], 0, v[128:129]
	s_mov_b32 m0, s65
	s_nop 0
	global_load_lds_dwordx4 v[222:223], off
	s_mov_b32 m0, s66
	s_nop 0
	global_load_lds_dwordx4 v[224:225], off
	s_waitcnt vmcnt(8)
	s_waitcnt lgkmcnt(0)
	s_barrier
	s_waitcnt lgkmcnt(0)
	v_mfma_f32_16x16x32_bf16 v[60:63], v[152:155], v[188:191], 0
	v_mfma_f32_16x16x32_bf16 v[60:63], v[156:159], v[192:195], v[60:63]
	s_setprio 1
	v_mfma_f32_16x16x32_bf16 v[56:59], v[160:163], v[188:191], 0
	v_mfma_f32_16x16x32_bf16 v[56:59], v[164:167], v[192:195], v[56:59]
	v_mfma_f32_16x16x32_bf16 v[52:55], v[152:155], v[196:199], 0
	v_mfma_f32_16x16x32_bf16 v[52:55], v[156:159], v[200:203], v[52:55]
	v_mfma_f32_16x16x32_bf16 v[44:47], v[160:163], v[196:199], 0
	v_mfma_f32_16x16x32_bf16 v[44:47], v[164:167], v[200:203], v[44:47]
	v_mfma_f32_16x16x32_bf16 v[36:39], v[152:155], v[204:207], 0
	v_mfma_f32_16x16x32_bf16 v[36:39], v[156:159], v[208:211], v[36:39]
	v_mfma_f32_16x16x32_bf16 v[28:31], v[160:163], v[204:207], 0
	v_mfma_f32_16x16x32_bf16 v[28:31], v[164:167], v[208:211], v[28:31]
	v_mfma_f32_16x16x32_bf16 v[20:23], v[152:155], v[212:215], 0
	v_mfma_f32_16x16x32_bf16 v[20:23], v[156:159], v[216:219], v[20:23]
	v_mfma_f32_16x16x32_bf16 v[12:15], v[160:163], v[212:215], 0
	v_mfma_f32_16x16x32_bf16 v[12:15], v[164:167], v[216:219], v[12:15]
	v_mfma_f32_16x16x32_bf16 v[48:51], v[168:171], v[188:191], 0
	v_mfma_f32_16x16x32_bf16 v[48:51], v[172:175], v[192:195], v[48:51]
	v_mfma_f32_16x16x32_bf16 v[40:43], v[176:179], v[188:191], 0
	v_mfma_f32_16x16x32_bf16 v[40:43], v[184:187], v[192:195], v[40:43]
	v_mfma_f32_16x16x32_bf16 v[32:35], v[168:171], v[196:199], 0
	v_mfma_f32_16x16x32_bf16 v[32:35], v[172:175], v[200:203], v[32:35]
	v_mfma_f32_16x16x32_bf16 v[24:27], v[176:179], v[196:199], 0
	v_mfma_f32_16x16x32_bf16 v[24:27], v[184:187], v[200:203], v[24:27]
	v_mfma_f32_16x16x32_bf16 v[16:19], v[168:171], v[204:207], 0
	v_mfma_f32_16x16x32_bf16 v[16:19], v[172:175], v[208:211], v[16:19]
	v_mfma_f32_16x16x32_bf16 v[8:11], v[176:179], v[204:207], 0
	v_mfma_f32_16x16x32_bf16 v[8:11], v[184:187], v[208:211], v[8:11]
	v_mfma_f32_16x16x32_bf16 v[4:7], v[168:171], v[212:215], 0
	v_mfma_f32_16x16x32_bf16 v[4:7], v[172:175], v[216:219], v[4:7]
	s_barrier
	v_mfma_f32_16x16x32_bf16 v[0:3], v[176:179], v[212:215], 0
	v_mfma_f32_16x16x32_bf16 v[0:3], v[184:187], v[216:219], v[0:3]
	s_setprio 0
	s_branch .Lmid_gemm8
.LBB0_1031:
	ds_read_b128 v[152:155], v149
	ds_read_b128 v[156:159], v149 offset:1024
	ds_read_b128 v[160:163], v149 offset:2048
	ds_read_b128 v[164:167], v149 offset:3072
	ds_read_b128 v[168:171], v150
	ds_read_b128 v[172:175], v150 offset:1024
	ds_read_b128 v[176:179], v150 offset:2048
	ds_read_b128 v[184:187], v150 offset:3072
	s_add_u32 s56, s54, 0x100
	s_addc_u32 s57, s55, 0
	s_cmp_eq_u32 s88, 40
	s_cselect_b32 s61, s13, s57
	s_cselect_b32 s60, s12, s56
	s_cselect_b32 s59, s53, s87
	s_cselect_b32 s58, s52, s86
	v_lshl_add_u64 v[144:145], s[54:55], 0, v[136:137]
	s_add_i32 m0, s65, 0xc000
	ds_read_b128 v[188:191], v151
	ds_read_b128 v[192:195], v151 offset:1024
	ds_read_b128 v[196:199], v151 offset:2048
	ds_read_b128 v[200:203], v151 offset:3072
	ds_read_b128 v[204:207], v151 offset:4096
	ds_read_b128 v[208:211], v151 offset:5120
	ds_read_b128 v[212:215], v151 offset:6144
	ds_read_b128 v[216:219], v151 offset:7168
	global_load_lds_dwordx4 v[144:145], off
	v_lshl_add_u64 v[144:145], s[54:55], 0, v[138:139]
	s_add_i32 m0, s65, 0xe000
	s_nop 0
	global_load_lds_dwordx4 v[144:145], off
	s_waitcnt vmcnt(8)
	s_waitcnt lgkmcnt(0)
	s_barrier
	s_waitcnt lgkmcnt(0)
	v_mfma_f32_16x16x32_bf16 v[124:127], v[152:155], v[188:191], v[124:127]
	v_mfma_f32_16x16x32_bf16 v[124:127], v[156:159], v[192:195], v[124:127]
	s_setprio 1
	v_mfma_f32_16x16x32_bf16 v[120:123], v[160:163], v[188:191], v[120:123]
	v_mfma_f32_16x16x32_bf16 v[120:123], v[164:167], v[192:195], v[120:123]
	v_mfma_f32_16x16x32_bf16 v[116:119], v[152:155], v[196:199], v[116:119]
	v_mfma_f32_16x16x32_bf16 v[116:119], v[156:159], v[200:203], v[116:119]
	v_mfma_f32_16x16x32_bf16 v[108:111], v[160:163], v[196:199], v[108:111]
	v_mfma_f32_16x16x32_bf16 v[108:111], v[164:167], v[200:203], v[108:111]
	v_mfma_f32_16x16x32_bf16 v[100:103], v[152:155], v[204:207], v[100:103]
	v_mfma_f32_16x16x32_bf16 v[100:103], v[156:159], v[208:211], v[100:103]
	v_mfma_f32_16x16x32_bf16 v[92:95], v[160:163], v[204:207], v[92:95]
	v_mfma_f32_16x16x32_bf16 v[92:95], v[164:167], v[208:211], v[92:95]
	v_mfma_f32_16x16x32_bf16 v[84:87], v[152:155], v[212:215], v[84:87]
	v_mfma_f32_16x16x32_bf16 v[84:87], v[156:159], v[216:219], v[84:87]
	v_mfma_f32_16x16x32_bf16 v[76:79], v[160:163], v[212:215], v[76:79]
	v_mfma_f32_16x16x32_bf16 v[76:79], v[164:167], v[216:219], v[76:79]
	v_mfma_f32_16x16x32_bf16 v[112:115], v[168:171], v[188:191], v[112:115]
	v_mfma_f32_16x16x32_bf16 v[112:115], v[172:175], v[192:195], v[112:115]
	v_mfma_f32_16x16x32_bf16 v[104:107], v[176:179], v[188:191], v[104:107]
	v_mfma_f32_16x16x32_bf16 v[104:107], v[184:187], v[192:195], v[104:107]
	v_mfma_f32_16x16x32_bf16 v[96:99], v[168:171], v[196:199], v[96:99]
	v_mfma_f32_16x16x32_bf16 v[96:99], v[172:175], v[200:203], v[96:99]
	v_mfma_f32_16x16x32_bf16 v[88:91], v[176:179], v[196:199], v[88:91]
	v_mfma_f32_16x16x32_bf16 v[88:91], v[184:187], v[200:203], v[88:91]
	v_mfma_f32_16x16x32_bf16 v[80:83], v[168:171], v[204:207], v[80:83]
	v_mfma_f32_16x16x32_bf16 v[80:83], v[172:175], v[208:211], v[80:83]
	v_mfma_f32_16x16x32_bf16 v[72:75], v[176:179], v[204:207], v[72:75]
	v_mfma_f32_16x16x32_bf16 v[72:75], v[184:187], v[208:211], v[72:75]
	v_mfma_f32_16x16x32_bf16 v[68:71], v[168:171], v[212:215], v[68:71]
	v_mfma_f32_16x16x32_bf16 v[68:71], v[172:175], v[216:219], v[68:71]
	s_barrier
	v_mfma_f32_16x16x32_bf16 v[64:67], v[176:179], v[212:215], v[64:67]
	v_mfma_f32_16x16x32_bf16 v[64:67], v[184:187], v[216:219], v[64:67]
	s_setprio 0
	s_add_i32 s54, s72, s64
	v_lshl_add_u64 v[144:145], s[58:59], 0, v[130:131]
	s_mov_b32 m0, s54
	ds_read_b128 v[188:191], v151 offset:16384
	ds_read_b128 v[192:195], v151 offset:17408
	ds_read_b128 v[196:199], v151 offset:18432
	ds_read_b128 v[200:203], v151 offset:19456
	ds_read_b128 v[204:207], v151 offset:20480
	ds_read_b128 v[208:211], v151 offset:21504
	ds_read_b128 v[212:215], v151 offset:22528
	ds_read_b128 v[216:219], v151 offset:23552
	global_load_lds_dwordx4 v[144:145], off
	s_add_i32 m0, s54, 0x2000
	s_add_u32 s54, s58, 0xb0000
	v_lshl_add_u64 v[220:221], s[58:59], 0, v[134:135]
	s_addc_u32 s55, s59, 0
	s_add_i32 s79, s73, s64
	global_load_lds_dwordx4 v[220:221], off
	v_lshl_add_u64 v[222:223], s[54:55], 0, v[130:131]
	s_mov_b32 m0, s79
	v_lshl_add_u64 v[224:225], s[60:61], 0, v[132:133]
	global_load_lds_dwordx4 v[222:223], off
	v_lshl_add_u64 v[222:223], s[54:55], 0, v[134:135]
	s_add_i32 m0, s79, 0x2000
	s_nop 0
	global_load_lds_dwordx4 v[222:223], off
	v_lshl_add_u64 v[222:223], s[60:61], 0, v[128:129]
	s_mov_b32 m0, s65
	s_nop 0
	global_load_lds_dwordx4 v[222:223], off
	s_mov_b32 m0, s66
	s_nop 0
	global_load_lds_dwordx4 v[224:225], off
	s_waitcnt vmcnt(8)
	s_waitcnt lgkmcnt(0)
	s_barrier
	s_waitcnt lgkmcnt(0)
	v_mfma_f32_16x16x32_bf16 v[60:63], v[152:155], v[188:191], v[60:63]
	v_mfma_f32_16x16x32_bf16 v[60:63], v[156:159], v[192:195], v[60:63]
	s_setprio 1
	v_mfma_f32_16x16x32_bf16 v[56:59], v[160:163], v[188:191], v[56:59]
	v_mfma_f32_16x16x32_bf16 v[56:59], v[164:167], v[192:195], v[56:59]
	v_mfma_f32_16x16x32_bf16 v[52:55], v[152:155], v[196:199], v[52:55]
	v_mfma_f32_16x16x32_bf16 v[52:55], v[156:159], v[200:203], v[52:55]
	v_mfma_f32_16x16x32_bf16 v[44:47], v[160:163], v[196:199], v[44:47]
	v_mfma_f32_16x16x32_bf16 v[44:47], v[164:167], v[200:203], v[44:47]
	v_mfma_f32_16x16x32_bf16 v[36:39], v[152:155], v[204:207], v[36:39]
	v_mfma_f32_16x16x32_bf16 v[36:39], v[156:159], v[208:211], v[36:39]
	v_mfma_f32_16x16x32_bf16 v[28:31], v[160:163], v[204:207], v[28:31]
	v_mfma_f32_16x16x32_bf16 v[28:31], v[164:167], v[208:211], v[28:31]
	v_mfma_f32_16x16x32_bf16 v[20:23], v[152:155], v[212:215], v[20:23]
	v_mfma_f32_16x16x32_bf16 v[20:23], v[156:159], v[216:219], v[20:23]
	v_mfma_f32_16x16x32_bf16 v[12:15], v[160:163], v[212:215], v[12:15]
	v_mfma_f32_16x16x32_bf16 v[12:15], v[164:167], v[216:219], v[12:15]
	v_mfma_f32_16x16x32_bf16 v[48:51], v[168:171], v[188:191], v[48:51]
	v_mfma_f32_16x16x32_bf16 v[48:51], v[172:175], v[192:195], v[48:51]
	v_mfma_f32_16x16x32_bf16 v[40:43], v[176:179], v[188:191], v[40:43]
	v_mfma_f32_16x16x32_bf16 v[40:43], v[184:187], v[192:195], v[40:43]
	v_mfma_f32_16x16x32_bf16 v[32:35], v[168:171], v[196:199], v[32:35]
	v_mfma_f32_16x16x32_bf16 v[32:35], v[172:175], v[200:203], v[32:35]
	v_mfma_f32_16x16x32_bf16 v[24:27], v[176:179], v[196:199], v[24:27]
	v_mfma_f32_16x16x32_bf16 v[24:27], v[184:187], v[200:203], v[24:27]
	v_mfma_f32_16x16x32_bf16 v[16:19], v[168:171], v[204:207], v[16:19]
	v_mfma_f32_16x16x32_bf16 v[16:19], v[172:175], v[208:211], v[16:19]
	v_mfma_f32_16x16x32_bf16 v[8:11], v[176:179], v[204:207], v[8:11]
	v_mfma_f32_16x16x32_bf16 v[8:11], v[184:187], v[208:211], v[8:11]
	v_mfma_f32_16x16x32_bf16 v[4:7], v[168:171], v[212:215], v[4:7]
	v_mfma_f32_16x16x32_bf16 v[4:7], v[172:175], v[216:219], v[4:7]
	s_barrier
	v_mfma_f32_16x16x32_bf16 v[0:3], v[176:179], v[212:215], v[0:3]
	v_mfma_f32_16x16x32_bf16 v[0:3], v[184:187], v[216:219], v[0:3]
	s_setprio 0
.Lmid_gemm8:
	s_add_i32 s79, 0, 0x18000
	s_add_i32 s89, 0, 0x1c000
	v_add_u32_e32 v164, s79, v147
	v_add_u32_e32 v181, s89, v147
	ds_read_b128 v[152:155], v164
	ds_read_b128 v[156:159], v164 offset:1024
	ds_read_b128 v[160:163], v164 offset:2048
	ds_read_b128 v[164:167], v164 offset:3072
	ds_read_b128 v[168:171], v181
	ds_read_b128 v[172:175], v181 offset:1024
	ds_read_b128 v[176:179], v181 offset:2048
	ds_read_b128 v[184:187], v181 offset:3072
	s_add_u32 s54, s60, 0xb0000
	s_addc_u32 s55, s61, 0
	s_mov_b32 m0, s67
	v_lshl_add_u64 v[226:227], s[54:55], 0, v[128:129]
	ds_read_b128 v[188:191], v151 offset:32768
	ds_read_b128 v[192:195], v151 offset:33792
	ds_read_b128 v[196:199], v151 offset:34816
	ds_read_b128 v[200:203], v151 offset:35840
	ds_read_b128 v[204:207], v151 offset:36864
	ds_read_b128 v[208:211], v151 offset:37888
	ds_read_b128 v[212:215], v151 offset:38912
	ds_read_b128 v[216:219], v151 offset:39936
	global_load_lds_dwordx4 v[226:227], off
	v_lshl_add_u64 v[226:227], s[54:55], 0, v[132:133]
	s_mov_b32 m0, s68
	s_nop 0
	global_load_lds_dwordx4 v[226:227], off
	s_waitcnt vmcnt(8)
	s_waitcnt lgkmcnt(0)
	s_barrier
	s_waitcnt lgkmcnt(0)
	v_mfma_f32_16x16x32_bf16 v[124:127], v[152:155], v[188:191], v[124:127]
	v_mfma_f32_16x16x32_bf16 v[124:127], v[156:159], v[192:195], v[124:127]
	s_setprio 1
	v_mfma_f32_16x16x32_bf16 v[120:123], v[160:163], v[188:191], v[120:123]
	v_mfma_f32_16x16x32_bf16 v[120:123], v[164:167], v[192:195], v[120:123]
	v_mfma_f32_16x16x32_bf16 v[116:119], v[152:155], v[196:199], v[116:119]
	v_mfma_f32_16x16x32_bf16 v[116:119], v[156:159], v[200:203], v[116:119]
	v_mfma_f32_16x16x32_bf16 v[108:111], v[160:163], v[196:199], v[108:111]
	v_mfma_f32_16x16x32_bf16 v[108:111], v[164:167], v[200:203], v[108:111]
	v_mfma_f32_16x16x32_bf16 v[100:103], v[152:155], v[204:207], v[100:103]
	v_mfma_f32_16x16x32_bf16 v[100:103], v[156:159], v[208:211], v[100:103]
	v_mfma_f32_16x16x32_bf16 v[92:95], v[160:163], v[204:207], v[92:95]
	v_mfma_f32_16x16x32_bf16 v[92:95], v[164:167], v[208:211], v[92:95]
	v_mfma_f32_16x16x32_bf16 v[84:87], v[152:155], v[212:215], v[84:87]
	v_mfma_f32_16x16x32_bf16 v[84:87], v[156:159], v[216:219], v[84:87]
	v_mfma_f32_16x16x32_bf16 v[76:79], v[160:163], v[212:215], v[76:79]
	v_mfma_f32_16x16x32_bf16 v[76:79], v[164:167], v[216:219], v[76:79]
	v_mfma_f32_16x16x32_bf16 v[112:115], v[168:171], v[188:191], v[112:115]
	v_mfma_f32_16x16x32_bf16 v[112:115], v[172:175], v[192:195], v[112:115]
	v_mfma_f32_16x16x32_bf16 v[104:107], v[176:179], v[188:191], v[104:107]
	v_mfma_f32_16x16x32_bf16 v[104:107], v[184:187], v[192:195], v[104:107]
	v_mfma_f32_16x16x32_bf16 v[96:99], v[168:171], v[196:199], v[96:99]
	v_mfma_f32_16x16x32_bf16 v[96:99], v[172:175], v[200:203], v[96:99]
	v_mfma_f32_16x16x32_bf16 v[88:91], v[176:179], v[196:199], v[88:91]
	v_mfma_f32_16x16x32_bf16 v[88:91], v[184:187], v[200:203], v[88:91]
	v_mfma_f32_16x16x32_bf16 v[80:83], v[168:171], v[204:207], v[80:83]
	v_mfma_f32_16x16x32_bf16 v[80:83], v[172:175], v[208:211], v[80:83]
	v_mfma_f32_16x16x32_bf16 v[72:75], v[176:179], v[204:207], v[72:75]
	v_mfma_f32_16x16x32_bf16 v[72:75], v[184:187], v[208:211], v[72:75]
	v_mfma_f32_16x16x32_bf16 v[68:71], v[168:171], v[212:215], v[68:71]
	v_mfma_f32_16x16x32_bf16 v[68:71], v[172:175], v[216:219], v[68:71]
	s_barrier
	v_mfma_f32_16x16x32_bf16 v[64:67], v[176:179], v[212:215], v[64:67]
	v_mfma_f32_16x16x32_bf16 v[64:67], v[184:187], v[216:219], v[64:67]
	s_setprio 0
	s_add_i32 s54, s79, s64
	v_lshl_add_u64 v[144:145], v[144:145], 0, s[16:17]
	s_mov_b32 m0, s54
	ds_read_b128 v[188:191], v151 offset:49152
	ds_read_b128 v[192:195], v151 offset:50176
	ds_read_b128 v[196:199], v151 offset:51200
	ds_read_b128 v[200:203], v151 offset:52224
	ds_read_b128 v[204:207], v151 offset:53248
	ds_read_b128 v[208:211], v151 offset:54272
	ds_read_b128 v[212:215], v151 offset:55296
	ds_read_b128 v[216:219], v151 offset:56320
	global_load_lds_dwordx4 v[144:145], off
	s_add_i32 m0, s54, 0x2000
	s_add_u32 s54, s58, 0xb0080
	v_lshl_add_u64 v[144:145], v[220:221], 0, s[16:17]
	s_addc_u32 s55, s59, 0
	s_add_i32 s58, s89, s64
	global_load_lds_dwordx4 v[144:145], off
	v_lshl_add_u64 v[144:145], s[54:55], 0, v[130:131]
	s_mov_b32 m0, s58
	s_nop 0
	global_load_lds_dwordx4 v[144:145], off
	v_lshl_add_u64 v[144:145], s[54:55], 0, v[134:135]
	s_add_i32 m0, s58, 0x2000
	s_nop 0
	global_load_lds_dwordx4 v[144:145], off
	v_lshl_add_u64 v[144:145], v[222:223], 0, s[16:17]
	s_mov_b32 m0, s70
	s_nop 0
	global_load_lds_dwordx4 v[144:145], off
	v_lshl_add_u64 v[144:145], v[224:225], 0, s[16:17]
	s_mov_b32 m0, s71
	s_nop 0
	global_load_lds_dwordx4 v[144:145], off
	s_waitcnt vmcnt(8)
	s_waitcnt lgkmcnt(0)
	s_barrier
	s_waitcnt lgkmcnt(0)
	v_mfma_f32_16x16x32_bf16 v[60:63], v[152:155], v[188:191], v[60:63]
	v_mfma_f32_16x16x32_bf16 v[60:63], v[156:159], v[192:195], v[60:63]
	s_setprio 1
	v_mfma_f32_16x16x32_bf16 v[56:59], v[160:163], v[188:191], v[56:59]
	v_mfma_f32_16x16x32_bf16 v[56:59], v[164:167], v[192:195], v[56:59]
	v_mfma_f32_16x16x32_bf16 v[52:55], v[152:155], v[196:199], v[52:55]
	v_mfma_f32_16x16x32_bf16 v[52:55], v[156:159], v[200:203], v[52:55]
	v_mfma_f32_16x16x32_bf16 v[44:47], v[160:163], v[196:199], v[44:47]
	v_mfma_f32_16x16x32_bf16 v[44:47], v[164:167], v[200:203], v[44:47]
	v_mfma_f32_16x16x32_bf16 v[36:39], v[152:155], v[204:207], v[36:39]
	v_mfma_f32_16x16x32_bf16 v[36:39], v[156:159], v[208:211], v[36:39]
	v_mfma_f32_16x16x32_bf16 v[28:31], v[160:163], v[204:207], v[28:31]
	v_mfma_f32_16x16x32_bf16 v[28:31], v[164:167], v[208:211], v[28:31]
	v_mfma_f32_16x16x32_bf16 v[20:23], v[152:155], v[212:215], v[20:23]
	v_mfma_f32_16x16x32_bf16 v[20:23], v[156:159], v[216:219], v[20:23]
	v_mfma_f32_16x16x32_bf16 v[12:15], v[160:163], v[212:215], v[12:15]
	v_mfma_f32_16x16x32_bf16 v[12:15], v[164:167], v[216:219], v[12:15]
	v_mfma_f32_16x16x32_bf16 v[48:51], v[168:171], v[188:191], v[48:51]
	v_mfma_f32_16x16x32_bf16 v[48:51], v[172:175], v[192:195], v[48:51]
	v_mfma_f32_16x16x32_bf16 v[40:43], v[176:179], v[188:191], v[40:43]
	v_mfma_f32_16x16x32_bf16 v[40:43], v[184:187], v[192:195], v[40:43]
	v_mfma_f32_16x16x32_bf16 v[32:35], v[168:171], v[196:199], v[32:35]
	v_mfma_f32_16x16x32_bf16 v[32:35], v[172:175], v[200:203], v[32:35]
	v_mfma_f32_16x16x32_bf16 v[24:27], v[176:179], v[196:199], v[24:27]
	v_mfma_f32_16x16x32_bf16 v[24:27], v[184:187], v[200:203], v[24:27]
	v_mfma_f32_16x16x32_bf16 v[16:19], v[168:171], v[204:207], v[16:19]
	v_mfma_f32_16x16x32_bf16 v[16:19], v[172:175], v[208:211], v[16:19]
	v_mfma_f32_16x16x32_bf16 v[8:11], v[176:179], v[204:207], v[8:11]
	v_mfma_f32_16x16x32_bf16 v[8:11], v[184:187], v[208:211], v[8:11]
	v_mfma_f32_16x16x32_bf16 v[4:7], v[168:171], v[212:215], v[4:7]
	v_mfma_f32_16x16x32_bf16 v[4:7], v[172:175], v[216:219], v[4:7]
	s_barrier
	v_mfma_f32_16x16x32_bf16 v[0:3], v[176:179], v[212:215], v[0:3]
	v_mfma_f32_16x16x32_bf16 v[0:3], v[184:187], v[216:219], v[0:3]
	s_setprio 0
	s_add_i32 s88, s88, 2
	s_add_u32 s86, s86, 0x100
	s_addc_u32 s87, s87, 0
	s_cmp_gt_u32 s88, 41
	s_mov_b64 s[54:55], s[56:57]
	s_cbranch_scc0 .LBB0_1031
	s_and_b64 vcc, exec, s[18:19]
	s_cbranch_vccz .LBB0_1034
	s_barrier

.LBB0_1161:
	s_ashr_i32 s53, s52, 31
	s_lshl_b64 s[54:55], s[52:53], 19
	s_add_u32 s54, s80, s54
	s_addc_u32 s55, s81, s55
	s_and_b64 s[56:57], s[10:11], exec
	s_cselect_b32 s53, s55, s61
	s_cselect_b32 s83, s54, s60
	s_ashr_i32 s49, s48, 31
	s_lshl_b64 s[56:57], s[48:49], 19
	s_add_u32 s56, s66, s56
	s_addc_u32 s57, s67, s57
	s_and_b64 s[64:65], s[10:11], exec
	s_cselect_b32 s49, s57, s63
	s_cselect_b32 s84, s56, s62
	s_add_u32 s60, s60, 0x40080
	s_addc_u32 s61, s61, 0
	s_add_u32 s85, s62, 0x100
	s_addc_u32 s86, s63, 0
	s_mov_b32 s87, -2
	ds_read_b128 v[152:155], v148
	ds_read_b128 v[156:159], v148 offset:1024
	ds_read_b128 v[160:163], v148 offset:2048
	ds_read_b128 v[164:167], v148 offset:3072
	ds_read_b128 v[168:171], v149
	ds_read_b128 v[172:175], v149 offset:1024
	ds_read_b128 v[176:179], v149 offset:2048
	ds_read_b128 v[184:187], v149 offset:3072
	s_add_u32 s62, s60, 0xfffc0080
	s_addc_u32 s63, s61, -1
	s_cmp_eq_u32 s87, 12
	s_cselect_b32 s65, s53, s63
	s_cselect_b32 s64, s83, s62
	s_cselect_b32 s63, s49, s86
	s_cselect_b32 s62, s84, s85
	v_lshl_add_u64 v[220:221], s[60:61], 0, v[138:139]
	s_add_i32 m0, s69, 0xc000
	ds_read_b128 v[188:191], v150
	ds_read_b128 v[192:195], v150 offset:1024
	ds_read_b128 v[196:199], v150 offset:2048
	ds_read_b128 v[200:203], v150 offset:3072
	ds_read_b128 v[204:207], v150 offset:4096
	ds_read_b128 v[208:211], v150 offset:5120
	ds_read_b128 v[212:215], v150 offset:6144
	ds_read_b128 v[216:219], v150 offset:7168
	global_load_lds_dwordx4 v[220:221], off
	v_lshl_add_u64 v[220:221], s[60:61], 0, v[140:141]
	s_add_i32 m0, s69, 0xe000
	s_nop 0
	global_load_lds_dwordx4 v[220:221], off
	s_waitcnt vmcnt(8)
	s_waitcnt lgkmcnt(0)
	s_barrier
	s_waitcnt lgkmcnt(0)
	v_mfma_f32_16x16x32_bf16 v[124:127], v[152:155], v[188:191], 0
	v_mfma_f32_16x16x32_bf16 v[124:127], v[156:159], v[192:195], v[124:127]
	s_setprio 1
	v_mfma_f32_16x16x32_bf16 v[120:123], v[160:163], v[188:191], 0
	v_mfma_f32_16x16x32_bf16 v[120:123], v[164:167], v[192:195], v[120:123]
	v_mfma_f32_16x16x32_bf16 v[116:119], v[152:155], v[196:199], 0
	v_mfma_f32_16x16x32_bf16 v[116:119], v[156:159], v[200:203], v[116:119]
	v_mfma_f32_16x16x32_bf16 v[112:115], v[160:163], v[196:199], 0
	v_mfma_f32_16x16x32_bf16 v[112:115], v[164:167], v[200:203], v[112:115]
	v_mfma_f32_16x16x32_bf16 v[108:111], v[152:155], v[204:207], 0
	v_mfma_f32_16x16x32_bf16 v[108:111], v[156:159], v[208:211], v[108:111]
	v_mfma_f32_16x16x32_bf16 v[104:107], v[160:163], v[204:207], 0
	v_mfma_f32_16x16x32_bf16 v[104:107], v[164:167], v[208:211], v[104:107]
	v_mfma_f32_16x16x32_bf16 v[100:103], v[152:155], v[212:215], 0
	v_mfma_f32_16x16x32_bf16 v[100:103], v[156:159], v[216:219], v[100:103]
	v_mfma_f32_16x16x32_bf16 v[96:99], v[160:163], v[212:215], 0
	v_mfma_f32_16x16x32_bf16 v[96:99], v[164:167], v[216:219], v[96:99]
	v_mfma_f32_16x16x32_bf16 v[68:71], v[168:171], v[188:191], 0
	v_mfma_f32_16x16x32_bf16 v[68:71], v[172:175], v[192:195], v[68:71]
	v_mfma_f32_16x16x32_bf16 v[64:67], v[176:179], v[188:191], 0
	v_mfma_f32_16x16x32_bf16 v[64:67], v[184:187], v[192:195], v[64:67]
	v_mfma_f32_16x16x32_bf16 v[52:55], v[168:171], v[196:199], 0
	v_mfma_f32_16x16x32_bf16 v[52:55], v[172:175], v[200:203], v[52:55]
	v_mfma_f32_16x16x32_bf16 v[48:51], v[176:179], v[196:199], 0
	v_mfma_f32_16x16x32_bf16 v[48:51], v[184:187], v[200:203], v[48:51]
	v_mfma_f32_16x16x32_bf16 v[44:47], v[168:171], v[204:207], 0
	v_mfma_f32_16x16x32_bf16 v[44:47], v[172:175], v[208:211], v[44:47]
	v_mfma_f32_16x16x32_bf16 v[40:43], v[176:179], v[204:207], 0
	v_mfma_f32_16x16x32_bf16 v[40:43], v[184:187], v[208:211], v[40:43]
	v_mfma_f32_16x16x32_bf16 v[36:39], v[168:171], v[212:215], 0
	v_mfma_f32_16x16x32_bf16 v[36:39], v[172:175], v[216:219], v[36:39]
	s_barrier
	v_mfma_f32_16x16x32_bf16 v[32:35], v[176:179], v[212:215], 0
	v_mfma_f32_16x16x32_bf16 v[32:35], v[184:187], v[216:219], v[32:35]
	s_setprio 0
	s_add_i32 s79, s77, s68
	v_lshl_add_u64 v[220:221], s[62:63], 0, v[130:131]
	s_mov_b32 m0, s79
	ds_read_b128 v[188:191], v150 offset:16384
	ds_read_b128 v[192:195], v150 offset:17408
	ds_read_b128 v[196:199], v150 offset:18432
	ds_read_b128 v[200:203], v150 offset:19456
	ds_read_b128 v[204:207], v150 offset:20480
	ds_read_b128 v[208:211], v150 offset:21504
	ds_read_b128 v[212:215], v150 offset:22528
	ds_read_b128 v[216:219], v150 offset:23552
	global_load_lds_dwordx4 v[220:221], off
	s_add_i32 m0, s79, 0x2000
	s_add_u32 s88, s62, 0x40000
	v_lshl_add_u64 v[222:223], s[62:63], 0, v[134:135]
	s_addc_u32 s89, s63, 0
	s_add_i32 s79, s82, s68
	global_load_lds_dwordx4 v[222:223], off
	v_lshl_add_u64 v[224:225], s[88:89], 0, v[130:131]
	s_mov_b32 m0, s79
	v_lshl_add_u64 v[226:227], s[64:65], 0, v[132:133]
	global_load_lds_dwordx4 v[224:225], off
	v_lshl_add_u64 v[224:225], s[88:89], 0, v[134:135]
	s_add_i32 m0, s79, 0x2000
	s_nop 0
	global_load_lds_dwordx4 v[224:225], off
	v_lshl_add_u64 v[224:225], s[64:65], 0, v[128:129]
	s_mov_b32 m0, s69
	s_nop 0
	global_load_lds_dwordx4 v[224:225], off
	s_mov_b32 m0, s70
	s_nop 0
	global_load_lds_dwordx4 v[226:227], off
	s_waitcnt vmcnt(8)
	s_waitcnt lgkmcnt(0)
	s_barrier
	s_waitcnt lgkmcnt(0)
	v_mfma_f32_16x16x32_bf16 v[92:95], v[152:155], v[188:191], 0
	v_mfma_f32_16x16x32_bf16 v[92:95], v[156:159], v[192:195], v[92:95]
	s_setprio 1
	v_mfma_f32_16x16x32_bf16 v[88:91], v[160:163], v[188:191], 0
	v_mfma_f32_16x16x32_bf16 v[88:91], v[164:167], v[192:195], v[88:91]
	v_mfma_f32_16x16x32_bf16 v[84:87], v[152:155], v[196:199], 0
	v_mfma_f32_16x16x32_bf16 v[84:87], v[156:159], v[200:203], v[84:87]
	v_mfma_f32_16x16x32_bf16 v[80:83], v[160:163], v[196:199], 0
	v_mfma_f32_16x16x32_bf16 v[80:83], v[164:167], v[200:203], v[80:83]
	v_mfma_f32_16x16x32_bf16 v[76:79], v[152:155], v[204:207], 0
	v_mfma_f32_16x16x32_bf16 v[76:79], v[156:159], v[208:211], v[76:79]
	v_mfma_f32_16x16x32_bf16 v[72:75], v[160:163], v[204:207], 0
	v_mfma_f32_16x16x32_bf16 v[72:75], v[164:167], v[208:211], v[72:75]
	v_mfma_f32_16x16x32_bf16 v[60:63], v[152:155], v[212:215], 0
	v_mfma_f32_16x16x32_bf16 v[60:63], v[156:159], v[216:219], v[60:63]
	v_mfma_f32_16x16x32_bf16 v[56:59], v[160:163], v[212:215], 0
	v_mfma_f32_16x16x32_bf16 v[56:59], v[164:167], v[216:219], v[56:59]
	v_mfma_f32_16x16x32_bf16 v[28:31], v[168:171], v[188:191], 0
	v_mfma_f32_16x16x32_bf16 v[28:31], v[172:175], v[192:195], v[28:31]
	v_mfma_f32_16x16x32_bf16 v[24:27], v[176:179], v[188:191], 0
	v_mfma_f32_16x16x32_bf16 v[24:27], v[184:187], v[192:195], v[24:27]
	v_mfma_f32_16x16x32_bf16 v[20:23], v[168:171], v[196:199], 0
	v_mfma_f32_16x16x32_bf16 v[20:23], v[172:175], v[200:203], v[20:23]
	v_mfma_f32_16x16x32_bf16 v[16:19], v[176:179], v[196:199], 0
	v_mfma_f32_16x16x32_bf16 v[16:19], v[184:187], v[200:203], v[16:19]
	v_mfma_f32_16x16x32_bf16 v[12:15], v[168:171], v[204:207], 0
	v_mfma_f32_16x16x32_bf16 v[12:15], v[172:175], v[208:211], v[12:15]
	v_mfma_f32_16x16x32_bf16 v[8:11], v[176:179], v[204:207], 0
	v_mfma_f32_16x16x32_bf16 v[8:11], v[184:187], v[208:211], v[8:11]
	v_mfma_f32_16x16x32_bf16 v[4:7], v[168:171], v[212:215], 0
	v_mfma_f32_16x16x32_bf16 v[4:7], v[172:175], v[216:219], v[4:7]
	s_barrier
	v_mfma_f32_16x16x32_bf16 v[0:3], v[176:179], v[212:215], 0
	v_mfma_f32_16x16x32_bf16 v[0:3], v[184:187], v[216:219], v[0:3]
	s_setprio 0
	s_branch .Lmid_gemm9
.LBB0_1162:
	ds_read_b128 v[152:155], v148
	ds_read_b128 v[156:159], v148 offset:1024
	ds_read_b128 v[160:163], v148 offset:2048
	ds_read_b128 v[164:167], v148 offset:3072
	ds_read_b128 v[168:171], v149
	ds_read_b128 v[172:175], v149 offset:1024
	ds_read_b128 v[176:179], v149 offset:2048
	ds_read_b128 v[184:187], v149 offset:3072
	s_add_u32 s62, s60, 0xfffc0080
	s_addc_u32 s63, s61, -1
	s_cmp_eq_u32 s87, 12
	s_cselect_b32 s65, s53, s63
	s_cselect_b32 s64, s83, s62
	s_cselect_b32 s63, s49, s86
	s_cselect_b32 s62, s84, s85
	v_lshl_add_u64 v[220:221], s[60:61], 0, v[138:139]
	s_add_i32 m0, s69, 0xc000
	ds_read_b128 v[188:191], v150
	ds_read_b128 v[192:195], v150 offset:1024
	ds_read_b128 v[196:199], v150 offset:2048
	ds_read_b128 v[200:203], v150 offset:3072
	ds_read_b128 v[204:207], v150 offset:4096
	ds_read_b128 v[208:211], v150 offset:5120
	ds_read_b128 v[212:215], v150 offset:6144
	ds_read_b128 v[216:219], v150 offset:7168
	global_load_lds_dwordx4 v[220:221], off
	v_lshl_add_u64 v[220:221], s[60:61], 0, v[140:141]
	s_add_i32 m0, s69, 0xe000
	s_nop 0
	global_load_lds_dwordx4 v[220:221], off
	s_waitcnt vmcnt(8)
	s_waitcnt lgkmcnt(0)
	s_barrier
	s_waitcnt lgkmcnt(0)
	v_mfma_f32_16x16x32_bf16 v[124:127], v[152:155], v[188:191], v[124:127]
	v_mfma_f32_16x16x32_bf16 v[124:127], v[156:159], v[192:195], v[124:127]
	s_setprio 1
	v_mfma_f32_16x16x32_bf16 v[120:123], v[160:163], v[188:191], v[120:123]
	v_mfma_f32_16x16x32_bf16 v[120:123], v[164:167], v[192:195], v[120:123]
	v_mfma_f32_16x16x32_bf16 v[116:119], v[152:155], v[196:199], v[116:119]
	v_mfma_f32_16x16x32_bf16 v[116:119], v[156:159], v[200:203], v[116:119]
	v_mfma_f32_16x16x32_bf16 v[112:115], v[160:163], v[196:199], v[112:115]
	v_mfma_f32_16x16x32_bf16 v[112:115], v[164:167], v[200:203], v[112:115]
	v_mfma_f32_16x16x32_bf16 v[108:111], v[152:155], v[204:207], v[108:111]
	v_mfma_f32_16x16x32_bf16 v[108:111], v[156:159], v[208:211], v[108:111]
	v_mfma_f32_16x16x32_bf16 v[104:107], v[160:163], v[204:207], v[104:107]
	v_mfma_f32_16x16x32_bf16 v[104:107], v[164:167], v[208:211], v[104:107]
	v_mfma_f32_16x16x32_bf16 v[100:103], v[152:155], v[212:215], v[100:103]
	v_mfma_f32_16x16x32_bf16 v[100:103], v[156:159], v[216:219], v[100:103]
	v_mfma_f32_16x16x32_bf16 v[96:99], v[160:163], v[212:215], v[96:99]
	v_mfma_f32_16x16x32_bf16 v[96:99], v[164:167], v[216:219], v[96:99]
	v_mfma_f32_16x16x32_bf16 v[68:71], v[168:171], v[188:191], v[68:71]
	v_mfma_f32_16x16x32_bf16 v[68:71], v[172:175], v[192:195], v[68:71]
	v_mfma_f32_16x16x32_bf16 v[64:67], v[176:179], v[188:191], v[64:67]
	v_mfma_f32_16x16x32_bf16 v[64:67], v[184:187], v[192:195], v[64:67]
	v_mfma_f32_16x16x32_bf16 v[52:55], v[168:171], v[196:199], v[52:55]
	v_mfma_f32_16x16x32_bf16 v[52:55], v[172:175], v[200:203], v[52:55]
	v_mfma_f32_16x16x32_bf16 v[48:51], v[176:179], v[196:199], v[48:51]
	v_mfma_f32_16x16x32_bf16 v[48:51], v[184:187], v[200:203], v[48:51]
	v_mfma_f32_16x16x32_bf16 v[44:47], v[168:171], v[204:207], v[44:47]
	v_mfma_f32_16x16x32_bf16 v[44:47], v[172:175], v[208:211], v[44:47]
	v_mfma_f32_16x16x32_bf16 v[40:43], v[176:179], v[204:207], v[40:43]
	v_mfma_f32_16x16x32_bf16 v[40:43], v[184:187], v[208:211], v[40:43]
	v_mfma_f32_16x16x32_bf16 v[36:39], v[168:171], v[212:215], v[36:39]
	v_mfma_f32_16x16x32_bf16 v[36:39], v[172:175], v[216:219], v[36:39]
	s_barrier
	v_mfma_f32_16x16x32_bf16 v[32:35], v[176:179], v[212:215], v[32:35]
	v_mfma_f32_16x16x32_bf16 v[32:35], v[184:187], v[216:219], v[32:35]
	s_setprio 0
	s_add_i32 s79, s77, s68
	v_lshl_add_u64 v[220:221], s[62:63], 0, v[130:131]
	s_mov_b32 m0, s79
	ds_read_b128 v[188:191], v150 offset:16384
	ds_read_b128 v[192:195], v150 offset:17408
	ds_read_b128 v[196:199], v150 offset:18432
	ds_read_b128 v[200:203], v150 offset:19456
	ds_read_b128 v[204:207], v150 offset:20480
	ds_read_b128 v[208:211], v150 offset:21504
	ds_read_b128 v[212:215], v150 offset:22528
	ds_read_b128 v[216:219], v150 offset:23552
	global_load_lds_dwordx4 v[220:221], off
	s_add_i32 m0, s79, 0x2000
	s_add_u32 s88, s62, 0x40000
	v_lshl_add_u64 v[222:223], s[62:63], 0, v[134:135]
	s_addc_u32 s89, s63, 0
	s_add_i32 s79, s82, s68
	global_load_lds_dwordx4 v[222:223], off
	v_lshl_add_u64 v[224:225], s[88:89], 0, v[130:131]
	s_mov_b32 m0, s79
	v_lshl_add_u64 v[226:227], s[64:65], 0, v[132:133]
	global_load_lds_dwordx4 v[224:225], off
	v_lshl_add_u64 v[224:225], s[88:89], 0, v[134:135]
	s_add_i32 m0, s79, 0x2000
	s_nop 0
	global_load_lds_dwordx4 v[224:225], off
	v_lshl_add_u64 v[224:225], s[64:65], 0, v[128:129]
	s_mov_b32 m0, s69
	s_nop 0
	global_load_lds_dwordx4 v[224:225], off
	s_mov_b32 m0, s70
	s_nop 0
	global_load_lds_dwordx4 v[226:227], off
	s_waitcnt vmcnt(8)
	s_waitcnt lgkmcnt(0)
	s_barrier
	s_waitcnt lgkmcnt(0)
	v_mfma_f32_16x16x32_bf16 v[92:95], v[152:155], v[188:191], v[92:95]
	v_mfma_f32_16x16x32_bf16 v[92:95], v[156:159], v[192:195], v[92:95]
	s_setprio 1
	v_mfma_f32_16x16x32_bf16 v[88:91], v[160:163], v[188:191], v[88:91]
	v_mfma_f32_16x16x32_bf16 v[88:91], v[164:167], v[192:195], v[88:91]
	v_mfma_f32_16x16x32_bf16 v[84:87], v[152:155], v[196:199], v[84:87]
	v_mfma_f32_16x16x32_bf16 v[84:87], v[156:159], v[200:203], v[84:87]
	v_mfma_f32_16x16x32_bf16 v[80:83], v[160:163], v[196:199], v[80:83]
	v_mfma_f32_16x16x32_bf16 v[80:83], v[164:167], v[200:203], v[80:83]
	v_mfma_f32_16x16x32_bf16 v[76:79], v[152:155], v[204:207], v[76:79]
	v_mfma_f32_16x16x32_bf16 v[76:79], v[156:159], v[208:211], v[76:79]
	v_mfma_f32_16x16x32_bf16 v[72:75], v[160:163], v[204:207], v[72:75]
	v_mfma_f32_16x16x32_bf16 v[72:75], v[164:167], v[208:211], v[72:75]
	v_mfma_f32_16x16x32_bf16 v[60:63], v[152:155], v[212:215], v[60:63]
	v_mfma_f32_16x16x32_bf16 v[60:63], v[156:159], v[216:219], v[60:63]
	v_mfma_f32_16x16x32_bf16 v[56:59], v[160:163], v[212:215], v[56:59]
	v_mfma_f32_16x16x32_bf16 v[56:59], v[164:167], v[216:219], v[56:59]
	v_mfma_f32_16x16x32_bf16 v[28:31], v[168:171], v[188:191], v[28:31]
	v_mfma_f32_16x16x32_bf16 v[28:31], v[172:175], v[192:195], v[28:31]
	v_mfma_f32_16x16x32_bf16 v[24:27], v[176:179], v[188:191], v[24:27]
	v_mfma_f32_16x16x32_bf16 v[24:27], v[184:187], v[192:195], v[24:27]
	v_mfma_f32_16x16x32_bf16 v[20:23], v[168:171], v[196:199], v[20:23]
	v_mfma_f32_16x16x32_bf16 v[20:23], v[172:175], v[200:203], v[20:23]
	v_mfma_f32_16x16x32_bf16 v[16:19], v[176:179], v[196:199], v[16:19]
	v_mfma_f32_16x16x32_bf16 v[16:19], v[184:187], v[200:203], v[16:19]
	v_mfma_f32_16x16x32_bf16 v[12:15], v[168:171], v[204:207], v[12:15]
	v_mfma_f32_16x16x32_bf16 v[12:15], v[172:175], v[208:211], v[12:15]
	v_mfma_f32_16x16x32_bf16 v[8:11], v[176:179], v[204:207], v[8:11]
	v_mfma_f32_16x16x32_bf16 v[8:11], v[184:187], v[208:211], v[8:11]
	v_mfma_f32_16x16x32_bf16 v[4:7], v[168:171], v[212:215], v[4:7]
	v_mfma_f32_16x16x32_bf16 v[4:7], v[172:175], v[216:219], v[4:7]
	s_barrier
	v_mfma_f32_16x16x32_bf16 v[0:3], v[176:179], v[212:215], v[0:3]
	v_mfma_f32_16x16x32_bf16 v[0:3], v[184:187], v[216:219], v[0:3]
	s_setprio 0
.Lmid_gemm9:
	s_add_i32 s79, 0, 0x18000
	s_add_i32 s88, 0, 0x1c000
	v_add_u32_e32 v164, s79, v147
	v_add_u32_e32 v181, s88, v147
	ds_read_b128 v[152:155], v164
	ds_read_b128 v[156:159], v164 offset:1024
	ds_read_b128 v[160:163], v164 offset:2048
	ds_read_b128 v[164:167], v164 offset:3072
	ds_read_b128 v[168:171], v181
	ds_read_b128 v[172:175], v181 offset:1024
	ds_read_b128 v[176:179], v181 offset:2048
	ds_read_b128 v[184:187], v181 offset:3072
	s_add_u32 s64, s64, 0x40000
	s_addc_u32 s65, s65, 0
	s_mov_b32 m0, s71
	v_lshl_add_u64 v[228:229], s[64:65], 0, v[128:129]
	ds_read_b128 v[188:191], v150 offset:32768
	ds_read_b128 v[192:195], v150 offset:33792
	ds_read_b128 v[196:199], v150 offset:34816
	ds_read_b128 v[200:203], v150 offset:35840
	ds_read_b128 v[204:207], v150 offset:36864
	ds_read_b128 v[208:211], v150 offset:37888
	ds_read_b128 v[212:215], v150 offset:38912
	ds_read_b128 v[216:219], v150 offset:39936
	global_load_lds_dwordx4 v[228:229], off
	v_lshl_add_u64 v[228:229], s[64:65], 0, v[132:133]
	s_mov_b32 m0, s72
	s_nop 0
	global_load_lds_dwordx4 v[228:229], off
	s_waitcnt vmcnt(8)
	s_waitcnt lgkmcnt(0)
	s_barrier
	s_waitcnt lgkmcnt(0)
	v_mfma_f32_16x16x32_bf16 v[124:127], v[152:155], v[188:191], v[124:127]
	v_mfma_f32_16x16x32_bf16 v[124:127], v[156:159], v[192:195], v[124:127]
	s_setprio 1
	v_mfma_f32_16x16x32_bf16 v[120:123], v[160:163], v[188:191], v[120:123]
	v_mfma_f32_16x16x32_bf16 v[120:123], v[164:167], v[192:195], v[120:123]
	v_mfma_f32_16x16x32_bf16 v[116:119], v[152:155], v[196:199], v[116:119]
	v_mfma_f32_16x16x32_bf16 v[116:119], v[156:159], v[200:203], v[116:119]
	v_mfma_f32_16x16x32_bf16 v[112:115], v[160:163], v[196:199], v[112:115]
	v_mfma_f32_16x16x32_bf16 v[112:115], v[164:167], v[200:203], v[112:115]
	v_mfma_f32_16x16x32_bf16 v[108:111], v[152:155], v[204:207], v[108:111]
	v_mfma_f32_16x16x32_bf16 v[108:111], v[156:159], v[208:211], v[108:111]
	v_mfma_f32_16x16x32_bf16 v[104:107], v[160:163], v[204:207], v[104:107]
	v_mfma_f32_16x16x32_bf16 v[104:107], v[164:167], v[208:211], v[104:107]
	v_mfma_f32_16x16x32_bf16 v[100:103], v[152:155], v[212:215], v[100:103]
	v_mfma_f32_16x16x32_bf16 v[100:103], v[156:159], v[216:219], v[100:103]
	v_mfma_f32_16x16x32_bf16 v[96:99], v[160:163], v[212:215], v[96:99]
	v_mfma_f32_16x16x32_bf16 v[96:99], v[164:167], v[216:219], v[96:99]
	v_mfma_f32_16x16x32_bf16 v[68:71], v[168:171], v[188:191], v[68:71]
	v_mfma_f32_16x16x32_bf16 v[68:71], v[172:175], v[192:195], v[68:71]
	v_mfma_f32_16x16x32_bf16 v[64:67], v[176:179], v[188:191], v[64:67]
	v_mfma_f32_16x16x32_bf16 v[64:67], v[184:187], v[192:195], v[64:67]
	v_mfma_f32_16x16x32_bf16 v[52:55], v[168:171], v[196:199], v[52:55]
	v_mfma_f32_16x16x32_bf16 v[52:55], v[172:175], v[200:203], v[52:55]
	v_mfma_f32_16x16x32_bf16 v[48:51], v[176:179], v[196:199], v[48:51]
	v_mfma_f32_16x16x32_bf16 v[48:51], v[184:187], v[200:203], v[48:51]
	v_mfma_f32_16x16x32_bf16 v[44:47], v[168:171], v[204:207], v[44:47]
	v_mfma_f32_16x16x32_bf16 v[44:47], v[172:175], v[208:211], v[44:47]
	v_mfma_f32_16x16x32_bf16 v[40:43], v[176:179], v[204:207], v[40:43]
	v_mfma_f32_16x16x32_bf16 v[40:43], v[184:187], v[208:211], v[40:43]
	v_mfma_f32_16x16x32_bf16 v[36:39], v[168:171], v[212:215], v[36:39]
	v_mfma_f32_16x16x32_bf16 v[36:39], v[172:175], v[216:219], v[36:39]
	s_barrier
	v_mfma_f32_16x16x32_bf16 v[32:35], v[176:179], v[212:215], v[32:35]
	v_mfma_f32_16x16x32_bf16 v[32:35], v[184:187], v[216:219], v[32:35]
	s_setprio 0
	s_add_i32 s64, s79, s68
	v_lshl_add_u64 v[220:221], v[220:221], 0, s[12:13]
	s_mov_b32 m0, s64
	ds_read_b128 v[188:191], v150 offset:49152
	ds_read_b128 v[192:195], v150 offset:50176
	ds_read_b128 v[196:199], v150 offset:51200
	ds_read_b128 v[200:203], v150 offset:52224
	ds_read_b128 v[204:207], v150 offset:53248
	ds_read_b128 v[208:211], v150 offset:54272
	ds_read_b128 v[212:215], v150 offset:55296
	ds_read_b128 v[216:219], v150 offset:56320
	global_load_lds_dwordx4 v[220:221], off
	s_add_i32 m0, s64, 0x2000
	s_add_u32 s62, s62, 0x40080
	v_lshl_add_u64 v[220:221], v[222:223], 0, s[12:13]
	s_addc_u32 s63, s63, 0
	s_add_i32 s64, s88, s68
	global_load_lds_dwordx4 v[220:221], off
	v_lshl_add_u64 v[220:221], s[62:63], 0, v[130:131]
	s_mov_b32 m0, s64
	s_nop 0
	global_load_lds_dwordx4 v[220:221], off
	v_lshl_add_u64 v[220:221], s[62:63], 0, v[134:135]
	s_add_i32 m0, s64, 0x2000
	s_nop 0
	global_load_lds_dwordx4 v[220:221], off
	v_lshl_add_u64 v[220:221], v[224:225], 0, s[12:13]
	s_mov_b32 m0, s75
	s_nop 0
	global_load_lds_dwordx4 v[220:221], off
	v_lshl_add_u64 v[220:221], v[226:227], 0, s[12:13]
	s_mov_b32 m0, s76
	s_nop 0
	global_load_lds_dwordx4 v[220:221], off
	s_waitcnt vmcnt(8)
	s_waitcnt lgkmcnt(0)
	s_barrier
	s_waitcnt lgkmcnt(0)
	v_mfma_f32_16x16x32_bf16 v[92:95], v[152:155], v[188:191], v[92:95]
	v_mfma_f32_16x16x32_bf16 v[92:95], v[156:159], v[192:195], v[92:95]
	s_setprio 1
	v_mfma_f32_16x16x32_bf16 v[88:91], v[160:163], v[188:191], v[88:91]
	v_mfma_f32_16x16x32_bf16 v[88:91], v[164:167], v[192:195], v[88:91]
	v_mfma_f32_16x16x32_bf16 v[84:87], v[152:155], v[196:199], v[84:87]
	v_mfma_f32_16x16x32_bf16 v[84:87], v[156:159], v[200:203], v[84:87]
	v_mfma_f32_16x16x32_bf16 v[80:83], v[160:163], v[196:199], v[80:83]
	v_mfma_f32_16x16x32_bf16 v[80:83], v[164:167], v[200:203], v[80:83]
	v_mfma_f32_16x16x32_bf16 v[76:79], v[152:155], v[204:207], v[76:79]
	v_mfma_f32_16x16x32_bf16 v[76:79], v[156:159], v[208:211], v[76:79]
	v_mfma_f32_16x16x32_bf16 v[72:75], v[160:163], v[204:207], v[72:75]
	v_mfma_f32_16x16x32_bf16 v[72:75], v[164:167], v[208:211], v[72:75]
	v_mfma_f32_16x16x32_bf16 v[60:63], v[152:155], v[212:215], v[60:63]
	v_mfma_f32_16x16x32_bf16 v[60:63], v[156:159], v[216:219], v[60:63]
	v_mfma_f32_16x16x32_bf16 v[56:59], v[160:163], v[212:215], v[56:59]
	v_mfma_f32_16x16x32_bf16 v[56:59], v[164:167], v[216:219], v[56:59]
	v_mfma_f32_16x16x32_bf16 v[28:31], v[168:171], v[188:191], v[28:31]
	v_mfma_f32_16x16x32_bf16 v[28:31], v[172:175], v[192:195], v[28:31]
	v_mfma_f32_16x16x32_bf16 v[24:27], v[176:179], v[188:191], v[24:27]
	v_mfma_f32_16x16x32_bf16 v[24:27], v[184:187], v[192:195], v[24:27]
	v_mfma_f32_16x16x32_bf16 v[20:23], v[168:171], v[196:199], v[20:23]
	v_mfma_f32_16x16x32_bf16 v[20:23], v[172:175], v[200:203], v[20:23]
	v_mfma_f32_16x16x32_bf16 v[16:19], v[176:179], v[196:199], v[16:19]
	v_mfma_f32_16x16x32_bf16 v[16:19], v[184:187], v[200:203], v[16:19]
	v_mfma_f32_16x16x32_bf16 v[12:15], v[168:171], v[204:207], v[12:15]
	v_mfma_f32_16x16x32_bf16 v[12:15], v[172:175], v[208:211], v[12:15]
	v_mfma_f32_16x16x32_bf16 v[8:11], v[176:179], v[204:207], v[8:11]
	v_mfma_f32_16x16x32_bf16 v[8:11], v[184:187], v[208:211], v[8:11]
	v_mfma_f32_16x16x32_bf16 v[4:7], v[168:171], v[212:215], v[4:7]
	v_mfma_f32_16x16x32_bf16 v[4:7], v[172:175], v[216:219], v[4:7]
	s_barrier
	v_mfma_f32_16x16x32_bf16 v[0:3], v[176:179], v[212:215], v[0:3]
	v_mfma_f32_16x16x32_bf16 v[0:3], v[184:187], v[216:219], v[0:3]
	s_setprio 0
	s_add_i32 s87, s87, 2
	s_add_u32 s60, s60, 0x100
	s_addc_u32 s61, s61, 0
	s_add_u32 s85, s85, 0x100
	s_addc_u32 s86, s86, 0
	s_cmp_gt_u32 s87, 13
	s_cbranch_scc0 .LBB0_1162
	s_and_b64 vcc, exec, s[16:17]
	s_cbranch_vccz .LBB0_1165
	s_barrier

.LBB0_1310:
	s_ashr_i32 s49, s48, 31
	s_lshl_b64 s[50:51], s[48:49], 19
	s_add_u32 s50, s38, s50
	s_addc_u32 s51, s39, s51
	s_and_b64 s[52:53], s[10:11], exec
	s_cselect_b32 s49, s51, s57
	s_cselect_b32 s82, s50, s56
	s_ashr_i32 s47, s46, 31
	s_lshl_b64 s[52:53], s[46:47], 19
	s_add_u32 s52, s62, s52
	s_addc_u32 s53, s63, s53
	s_and_b64 s[60:61], s[10:11], exec
	s_cselect_b32 s47, s53, s59
	s_cselect_b32 s83, s52, s58
	s_add_u32 s56, s56, 0x40080
	s_addc_u32 s57, s57, 0
	s_add_u32 s84, s58, 0x100
	s_addc_u32 s85, s59, 0
	s_mov_b32 s86, -2
	ds_read_b128 v[152:155], v149
	ds_read_b128 v[156:159], v149 offset:1024
	ds_read_b128 v[160:163], v149 offset:2048
	ds_read_b128 v[164:167], v149 offset:3072
	ds_read_b128 v[168:171], v150
	ds_read_b128 v[172:175], v150 offset:1024
	ds_read_b128 v[176:179], v150 offset:2048
	ds_read_b128 v[184:187], v150 offset:3072
	s_add_u32 s58, s56, 0xfffc0080
	s_addc_u32 s59, s57, -1
	s_cmp_eq_u32 s86, 12
	s_cselect_b32 s61, s49, s59
	s_cselect_b32 s60, s82, s58
	s_cselect_b32 s59, s47, s85
	s_cselect_b32 s58, s83, s84
	v_lshl_add_u64 v[144:145], s[56:57], 0, v[136:137]
	s_add_i32 m0, s55, 0xc000
	ds_read_b128 v[188:191], v151
	ds_read_b128 v[192:195], v151 offset:1024
	ds_read_b128 v[196:199], v151 offset:2048
	ds_read_b128 v[200:203], v151 offset:3072
	ds_read_b128 v[204:207], v151 offset:4096
	ds_read_b128 v[208:211], v151 offset:5120
	ds_read_b128 v[212:215], v151 offset:6144
	ds_read_b128 v[216:219], v151 offset:7168
	global_load_lds_dwordx4 v[144:145], off
	v_lshl_add_u64 v[144:145], s[56:57], 0, v[138:139]
	s_add_i32 m0, s55, 0xe000
	s_nop 0
	global_load_lds_dwordx4 v[144:145], off
	s_waitcnt vmcnt(8)
	s_waitcnt lgkmcnt(0)
	s_barrier
	s_waitcnt lgkmcnt(0)
	v_mfma_f32_16x16x32_bf16 v[124:127], v[152:155], v[188:191], 0
	v_mfma_f32_16x16x32_bf16 v[124:127], v[156:159], v[192:195], v[124:127]
	s_setprio 1
	v_mfma_f32_16x16x32_bf16 v[120:123], v[160:163], v[188:191], 0
	v_mfma_f32_16x16x32_bf16 v[120:123], v[164:167], v[192:195], v[120:123]
	v_mfma_f32_16x16x32_bf16 v[116:119], v[152:155], v[196:199], 0
	v_mfma_f32_16x16x32_bf16 v[116:119], v[156:159], v[200:203], v[116:119]
	v_mfma_f32_16x16x32_bf16 v[108:111], v[160:163], v[196:199], 0
	v_mfma_f32_16x16x32_bf16 v[108:111], v[164:167], v[200:203], v[108:111]
	v_mfma_f32_16x16x32_bf16 v[100:103], v[152:155], v[204:207], 0
	v_mfma_f32_16x16x32_bf16 v[100:103], v[156:159], v[208:211], v[100:103]
	v_mfma_f32_16x16x32_bf16 v[92:95], v[160:163], v[204:207], 0
	v_mfma_f32_16x16x32_bf16 v[92:95], v[164:167], v[208:211], v[92:95]
	v_mfma_f32_16x16x32_bf16 v[84:87], v[152:155], v[212:215], 0
	v_mfma_f32_16x16x32_bf16 v[84:87], v[156:159], v[216:219], v[84:87]
	v_mfma_f32_16x16x32_bf16 v[76:79], v[160:163], v[212:215], 0
	v_mfma_f32_16x16x32_bf16 v[76:79], v[164:167], v[216:219], v[76:79]
	v_mfma_f32_16x16x32_bf16 v[112:115], v[168:171], v[188:191], 0
	v_mfma_f32_16x16x32_bf16 v[112:115], v[172:175], v[192:195], v[112:115]
	v_mfma_f32_16x16x32_bf16 v[104:107], v[176:179], v[188:191], 0
	v_mfma_f32_16x16x32_bf16 v[104:107], v[184:187], v[192:195], v[104:107]
	v_mfma_f32_16x16x32_bf16 v[96:99], v[168:171], v[196:199], 0
	v_mfma_f32_16x16x32_bf16 v[96:99], v[172:175], v[200:203], v[96:99]
	v_mfma_f32_16x16x32_bf16 v[88:91], v[176:179], v[196:199], 0
	v_mfma_f32_16x16x32_bf16 v[88:91], v[184:187], v[200:203], v[88:91]
	v_mfma_f32_16x16x32_bf16 v[80:83], v[168:171], v[204:207], 0
	v_mfma_f32_16x16x32_bf16 v[80:83], v[172:175], v[208:211], v[80:83]
	v_mfma_f32_16x16x32_bf16 v[72:75], v[176:179], v[204:207], 0
	v_mfma_f32_16x16x32_bf16 v[72:75], v[184:187], v[208:211], v[72:75]
	v_mfma_f32_16x16x32_bf16 v[68:71], v[168:171], v[212:215], 0
	v_mfma_f32_16x16x32_bf16 v[68:71], v[172:175], v[216:219], v[68:71]
	s_barrier
	v_mfma_f32_16x16x32_bf16 v[64:67], v[176:179], v[212:215], 0
	v_mfma_f32_16x16x32_bf16 v[64:67], v[184:187], v[216:219], v[64:67]
	s_setprio 0
	s_add_i32 s79, s71, s64
	v_lshl_add_u64 v[144:145], s[58:59], 0, v[130:131]
	s_mov_b32 m0, s79
	ds_read_b128 v[188:191], v151 offset:16384
	ds_read_b128 v[192:195], v151 offset:17408
	ds_read_b128 v[196:199], v151 offset:18432
	ds_read_b128 v[200:203], v151 offset:19456
	ds_read_b128 v[204:207], v151 offset:20480
	ds_read_b128 v[208:211], v151 offset:21504
	ds_read_b128 v[212:215], v151 offset:22528
	ds_read_b128 v[216:219], v151 offset:23552
	global_load_lds_dwordx4 v[144:145], off
	s_add_i32 m0, s79, 0x2000
	s_add_u32 s88, s58, 0x40000
	v_lshl_add_u64 v[220:221], s[58:59], 0, v[134:135]
	s_addc_u32 s89, s59, 0
	s_add_i32 s79, s72, s64
	global_load_lds_dwordx4 v[220:221], off
	v_lshl_add_u64 v[222:223], s[88:89], 0, v[130:131]
	s_mov_b32 m0, s79
	v_lshl_add_u64 v[224:225], s[60:61], 0, v[132:133]
	global_load_lds_dwordx4 v[222:223], off
	v_lshl_add_u64 v[222:223], s[88:89], 0, v[134:135]
	s_add_i32 m0, s79, 0x2000
	s_nop 0
	global_load_lds_dwordx4 v[222:223], off
	v_lshl_add_u64 v[222:223], s[60:61], 0, v[128:129]
	s_mov_b32 m0, s55
	s_nop 0
	global_load_lds_dwordx4 v[222:223], off
	s_mov_b32 m0, s65
	s_nop 0
	global_load_lds_dwordx4 v[224:225], off
	s_waitcnt vmcnt(8)
	s_waitcnt lgkmcnt(0)
	s_barrier
	s_waitcnt lgkmcnt(0)
	v_mfma_f32_16x16x32_bf16 v[60:63], v[152:155], v[188:191], 0
	v_mfma_f32_16x16x32_bf16 v[60:63], v[156:159], v[192:195], v[60:63]
	s_setprio 1
	v_mfma_f32_16x16x32_bf16 v[56:59], v[160:163], v[188:191], 0
	v_mfma_f32_16x16x32_bf16 v[56:59], v[164:167], v[192:195], v[56:59]
	v_mfma_f32_16x16x32_bf16 v[52:55], v[152:155], v[196:199], 0
	v_mfma_f32_16x16x32_bf16 v[52:55], v[156:159], v[200:203], v[52:55]
	v_mfma_f32_16x16x32_bf16 v[44:47], v[160:163], v[196:199], 0
	v_mfma_f32_16x16x32_bf16 v[44:47], v[164:167], v[200:203], v[44:47]
	v_mfma_f32_16x16x32_bf16 v[36:39], v[152:155], v[204:207], 0
	v_mfma_f32_16x16x32_bf16 v[36:39], v[156:159], v[208:211], v[36:39]
	v_mfma_f32_16x16x32_bf16 v[28:31], v[160:163], v[204:207], 0
	v_mfma_f32_16x16x32_bf16 v[28:31], v[164:167], v[208:211], v[28:31]
	v_mfma_f32_16x16x32_bf16 v[20:23], v[152:155], v[212:215], 0
	v_mfma_f32_16x16x32_bf16 v[20:23], v[156:159], v[216:219], v[20:23]
	v_mfma_f32_16x16x32_bf16 v[12:15], v[160:163], v[212:215], 0
	v_mfma_f32_16x16x32_bf16 v[12:15], v[164:167], v[216:219], v[12:15]
	v_mfma_f32_16x16x32_bf16 v[48:51], v[168:171], v[188:191], 0
	v_mfma_f32_16x16x32_bf16 v[48:51], v[172:175], v[192:195], v[48:51]
	v_mfma_f32_16x16x32_bf16 v[40:43], v[176:179], v[188:191], 0
	v_mfma_f32_16x16x32_bf16 v[40:43], v[184:187], v[192:195], v[40:43]
	v_mfma_f32_16x16x32_bf16 v[32:35], v[168:171], v[196:199], 0
	v_mfma_f32_16x16x32_bf16 v[32:35], v[172:175], v[200:203], v[32:35]
	v_mfma_f32_16x16x32_bf16 v[24:27], v[176:179], v[196:199], 0
	v_mfma_f32_16x16x32_bf16 v[24:27], v[184:187], v[200:203], v[24:27]
	v_mfma_f32_16x16x32_bf16 v[16:19], v[168:171], v[204:207], 0
	v_mfma_f32_16x16x32_bf16 v[16:19], v[172:175], v[208:211], v[16:19]
	v_mfma_f32_16x16x32_bf16 v[8:11], v[176:179], v[204:207], 0
	v_mfma_f32_16x16x32_bf16 v[8:11], v[184:187], v[208:211], v[8:11]
	v_mfma_f32_16x16x32_bf16 v[4:7], v[168:171], v[212:215], 0
	v_mfma_f32_16x16x32_bf16 v[4:7], v[172:175], v[216:219], v[4:7]
	s_barrier
	v_mfma_f32_16x16x32_bf16 v[0:3], v[176:179], v[212:215], 0
	v_mfma_f32_16x16x32_bf16 v[0:3], v[184:187], v[216:219], v[0:3]
	s_setprio 0
	s_branch .Lmid_gemm10
.LBB0_1311:
	ds_read_b128 v[152:155], v149
	ds_read_b128 v[156:159], v149 offset:1024
	ds_read_b128 v[160:163], v149 offset:2048
	ds_read_b128 v[164:167], v149 offset:3072
	ds_read_b128 v[168:171], v150
	ds_read_b128 v[172:175], v150 offset:1024
	ds_read_b128 v[176:179], v150 offset:2048
	ds_read_b128 v[184:187], v150 offset:3072
	s_add_u32 s58, s56, 0xfffc0080
	s_addc_u32 s59, s57, -1
	s_cmp_eq_u32 s86, 12
	s_cselect_b32 s61, s49, s59
	s_cselect_b32 s60, s82, s58
	s_cselect_b32 s59, s47, s85
	s_cselect_b32 s58, s83, s84
	v_lshl_add_u64 v[144:145], s[56:57], 0, v[136:137]
	s_add_i32 m0, s55, 0xc000
	ds_read_b128 v[188:191], v151
	ds_read_b128 v[192:195], v151 offset:1024
	ds_read_b128 v[196:199], v151 offset:2048
	ds_read_b128 v[200:203], v151 offset:3072
	ds_read_b128 v[204:207], v151 offset:4096
	ds_read_b128 v[208:211], v151 offset:5120
	ds_read_b128 v[212:215], v151 offset:6144
	ds_read_b128 v[216:219], v151 offset:7168
	global_load_lds_dwordx4 v[144:145], off
	v_lshl_add_u64 v[144:145], s[56:57], 0, v[138:139]
	s_add_i32 m0, s55, 0xe000
	s_nop 0
	global_load_lds_dwordx4 v[144:145], off
	s_waitcnt vmcnt(8)
	s_waitcnt lgkmcnt(0)
	s_barrier
	s_waitcnt lgkmcnt(0)
	v_mfma_f32_16x16x32_bf16 v[124:127], v[152:155], v[188:191], v[124:127]
	v_mfma_f32_16x16x32_bf16 v[124:127], v[156:159], v[192:195], v[124:127]
	s_setprio 1
	v_mfma_f32_16x16x32_bf16 v[120:123], v[160:163], v[188:191], v[120:123]
	v_mfma_f32_16x16x32_bf16 v[120:123], v[164:167], v[192:195], v[120:123]
	v_mfma_f32_16x16x32_bf16 v[116:119], v[152:155], v[196:199], v[116:119]
	v_mfma_f32_16x16x32_bf16 v[116:119], v[156:159], v[200:203], v[116:119]
	v_mfma_f32_16x16x32_bf16 v[108:111], v[160:163], v[196:199], v[108:111]
	v_mfma_f32_16x16x32_bf16 v[108:111], v[164:167], v[200:203], v[108:111]
	v_mfma_f32_16x16x32_bf16 v[100:103], v[152:155], v[204:207], v[100:103]
	v_mfma_f32_16x16x32_bf16 v[100:103], v[156:159], v[208:211], v[100:103]
	v_mfma_f32_16x16x32_bf16 v[92:95], v[160:163], v[204:207], v[92:95]
	v_mfma_f32_16x16x32_bf16 v[92:95], v[164:167], v[208:211], v[92:95]
	v_mfma_f32_16x16x32_bf16 v[84:87], v[152:155], v[212:215], v[84:87]
	v_mfma_f32_16x16x32_bf16 v[84:87], v[156:159], v[216:219], v[84:87]
	v_mfma_f32_16x16x32_bf16 v[76:79], v[160:163], v[212:215], v[76:79]
	v_mfma_f32_16x16x32_bf16 v[76:79], v[164:167], v[216:219], v[76:79]
	v_mfma_f32_16x16x32_bf16 v[112:115], v[168:171], v[188:191], v[112:115]
	v_mfma_f32_16x16x32_bf16 v[112:115], v[172:175], v[192:195], v[112:115]
	v_mfma_f32_16x16x32_bf16 v[104:107], v[176:179], v[188:191], v[104:107]
	v_mfma_f32_16x16x32_bf16 v[104:107], v[184:187], v[192:195], v[104:107]
	v_mfma_f32_16x16x32_bf16 v[96:99], v[168:171], v[196:199], v[96:99]
	v_mfma_f32_16x16x32_bf16 v[96:99], v[172:175], v[200:203], v[96:99]
	v_mfma_f32_16x16x32_bf16 v[88:91], v[176:179], v[196:199], v[88:91]
	v_mfma_f32_16x16x32_bf16 v[88:91], v[184:187], v[200:203], v[88:91]
	v_mfma_f32_16x16x32_bf16 v[80:83], v[168:171], v[204:207], v[80:83]
	v_mfma_f32_16x16x32_bf16 v[80:83], v[172:175], v[208:211], v[80:83]
	v_mfma_f32_16x16x32_bf16 v[72:75], v[176:179], v[204:207], v[72:75]
	v_mfma_f32_16x16x32_bf16 v[72:75], v[184:187], v[208:211], v[72:75]
	v_mfma_f32_16x16x32_bf16 v[68:71], v[168:171], v[212:215], v[68:71]
	v_mfma_f32_16x16x32_bf16 v[68:71], v[172:175], v[216:219], v[68:71]
	s_barrier
	v_mfma_f32_16x16x32_bf16 v[64:67], v[176:179], v[212:215], v[64:67]
	v_mfma_f32_16x16x32_bf16 v[64:67], v[184:187], v[216:219], v[64:67]
	s_setprio 0
	s_add_i32 s79, s71, s64
	v_lshl_add_u64 v[144:145], s[58:59], 0, v[130:131]
	s_mov_b32 m0, s79
	ds_read_b128 v[188:191], v151 offset:16384
	ds_read_b128 v[192:195], v151 offset:17408
	ds_read_b128 v[196:199], v151 offset:18432
	ds_read_b128 v[200:203], v151 offset:19456
	ds_read_b128 v[204:207], v151 offset:20480
	ds_read_b128 v[208:211], v151 offset:21504
	ds_read_b128 v[212:215], v151 offset:22528
	ds_read_b128 v[216:219], v151 offset:23552
	global_load_lds_dwordx4 v[144:145], off
	s_add_i32 m0, s79, 0x2000
	s_add_u32 s88, s58, 0x40000
	v_lshl_add_u64 v[220:221], s[58:59], 0, v[134:135]
	s_addc_u32 s89, s59, 0
	s_add_i32 s79, s72, s64
	global_load_lds_dwordx4 v[220:221], off
	v_lshl_add_u64 v[222:223], s[88:89], 0, v[130:131]
	s_mov_b32 m0, s79
	v_lshl_add_u64 v[224:225], s[60:61], 0, v[132:133]
	global_load_lds_dwordx4 v[222:223], off
	v_lshl_add_u64 v[222:223], s[88:89], 0, v[134:135]
	s_add_i32 m0, s79, 0x2000
	s_nop 0
	global_load_lds_dwordx4 v[222:223], off
	v_lshl_add_u64 v[222:223], s[60:61], 0, v[128:129]
	s_mov_b32 m0, s55
	s_nop 0
	global_load_lds_dwordx4 v[222:223], off
	s_mov_b32 m0, s65
	s_nop 0
	global_load_lds_dwordx4 v[224:225], off
	s_waitcnt vmcnt(8)
	s_waitcnt lgkmcnt(0)
	s_barrier
	s_waitcnt lgkmcnt(0)
	v_mfma_f32_16x16x32_bf16 v[60:63], v[152:155], v[188:191], v[60:63]
	v_mfma_f32_16x16x32_bf16 v[60:63], v[156:159], v[192:195], v[60:63]
	s_setprio 1
	v_mfma_f32_16x16x32_bf16 v[56:59], v[160:163], v[188:191], v[56:59]
	v_mfma_f32_16x16x32_bf16 v[56:59], v[164:167], v[192:195], v[56:59]
	v_mfma_f32_16x16x32_bf16 v[52:55], v[152:155], v[196:199], v[52:55]
	v_mfma_f32_16x16x32_bf16 v[52:55], v[156:159], v[200:203], v[52:55]
	v_mfma_f32_16x16x32_bf16 v[44:47], v[160:163], v[196:199], v[44:47]
	v_mfma_f32_16x16x32_bf16 v[44:47], v[164:167], v[200:203], v[44:47]
	v_mfma_f32_16x16x32_bf16 v[36:39], v[152:155], v[204:207], v[36:39]
	v_mfma_f32_16x16x32_bf16 v[36:39], v[156:159], v[208:211], v[36:39]
	v_mfma_f32_16x16x32_bf16 v[28:31], v[160:163], v[204:207], v[28:31]
	v_mfma_f32_16x16x32_bf16 v[28:31], v[164:167], v[208:211], v[28:31]
	v_mfma_f32_16x16x32_bf16 v[20:23], v[152:155], v[212:215], v[20:23]
	v_mfma_f32_16x16x32_bf16 v[20:23], v[156:159], v[216:219], v[20:23]
	v_mfma_f32_16x16x32_bf16 v[12:15], v[160:163], v[212:215], v[12:15]
	v_mfma_f32_16x16x32_bf16 v[12:15], v[164:167], v[216:219], v[12:15]
	v_mfma_f32_16x16x32_bf16 v[48:51], v[168:171], v[188:191], v[48:51]
	v_mfma_f32_16x16x32_bf16 v[48:51], v[172:175], v[192:195], v[48:51]
	v_mfma_f32_16x16x32_bf16 v[40:43], v[176:179], v[188:191], v[40:43]
	v_mfma_f32_16x16x32_bf16 v[40:43], v[184:187], v[192:195], v[40:43]
	v_mfma_f32_16x16x32_bf16 v[32:35], v[168:171], v[196:199], v[32:35]
	v_mfma_f32_16x16x32_bf16 v[32:35], v[172:175], v[200:203], v[32:35]
	v_mfma_f32_16x16x32_bf16 v[24:27], v[176:179], v[196:199], v[24:27]
	v_mfma_f32_16x16x32_bf16 v[24:27], v[184:187], v[200:203], v[24:27]
	v_mfma_f32_16x16x32_bf16 v[16:19], v[168:171], v[204:207], v[16:19]
	v_mfma_f32_16x16x32_bf16 v[16:19], v[172:175], v[208:211], v[16:19]
	v_mfma_f32_16x16x32_bf16 v[8:11], v[176:179], v[204:207], v[8:11]
	v_mfma_f32_16x16x32_bf16 v[8:11], v[184:187], v[208:211], v[8:11]
	v_mfma_f32_16x16x32_bf16 v[4:7], v[168:171], v[212:215], v[4:7]
	v_mfma_f32_16x16x32_bf16 v[4:7], v[172:175], v[216:219], v[4:7]
	s_barrier
	v_mfma_f32_16x16x32_bf16 v[0:3], v[176:179], v[212:215], v[0:3]
	v_mfma_f32_16x16x32_bf16 v[0:3], v[184:187], v[216:219], v[0:3]
	s_setprio 0
.Lmid_gemm10:
	s_add_i32 s79, 0, 0x18000
	s_add_i32 s87, 0, 0x1c000
	v_add_u32_e32 v164, s79, v147
	v_add_u32_e32 v181, s87, v147
	ds_read_b128 v[152:155], v164
	ds_read_b128 v[156:159], v164 offset:1024
	ds_read_b128 v[160:163], v164 offset:2048
	ds_read_b128 v[164:167], v164 offset:3072
	ds_read_b128 v[168:171], v181
	ds_read_b128 v[172:175], v181 offset:1024
	ds_read_b128 v[176:179], v181 offset:2048
	ds_read_b128 v[184:187], v181 offset:3072
	s_add_u32 s60, s60, 0x40000
	s_addc_u32 s61, s61, 0
	s_mov_b32 m0, s66
	v_lshl_add_u64 v[226:227], s[60:61], 0, v[128:129]
	ds_read_b128 v[188:191], v151 offset:32768
	ds_read_b128 v[192:195], v151 offset:33792
	ds_read_b128 v[196:199], v151 offset:34816
	ds_read_b128 v[200:203], v151 offset:35840
	ds_read_b128 v[204:207], v151 offset:36864
	ds_read_b128 v[208:211], v151 offset:37888
	ds_read_b128 v[212:215], v151 offset:38912
	ds_read_b128 v[216:219], v151 offset:39936
	global_load_lds_dwordx4 v[226:227], off
	v_lshl_add_u64 v[226:227], s[60:61], 0, v[132:133]
	s_mov_b32 m0, s67
	s_nop 0
	global_load_lds_dwordx4 v[226:227], off
	s_waitcnt vmcnt(8)
	s_waitcnt lgkmcnt(0)
	s_barrier
	s_waitcnt lgkmcnt(0)
	v_mfma_f32_16x16x32_bf16 v[124:127], v[152:155], v[188:191], v[124:127]
	v_mfma_f32_16x16x32_bf16 v[124:127], v[156:159], v[192:195], v[124:127]
	s_setprio 1
	v_mfma_f32_16x16x32_bf16 v[120:123], v[160:163], v[188:191], v[120:123]
	v_mfma_f32_16x16x32_bf16 v[120:123], v[164:167], v[192:195], v[120:123]
	v_mfma_f32_16x16x32_bf16 v[116:119], v[152:155], v[196:199], v[116:119]
	v_mfma_f32_16x16x32_bf16 v[116:119], v[156:159], v[200:203], v[116:119]
	v_mfma_f32_16x16x32_bf16 v[108:111], v[160:163], v[196:199], v[108:111]
	v_mfma_f32_16x16x32_bf16 v[108:111], v[164:167], v[200:203], v[108:111]
	v_mfma_f32_16x16x32_bf16 v[100:103], v[152:155], v[204:207], v[100:103]
	v_mfma_f32_16x16x32_bf16 v[100:103], v[156:159], v[208:211], v[100:103]
	v_mfma_f32_16x16x32_bf16 v[92:95], v[160:163], v[204:207], v[92:95]
	v_mfma_f32_16x16x32_bf16 v[92:95], v[164:167], v[208:211], v[92:95]
	v_mfma_f32_16x16x32_bf16 v[84:87], v[152:155], v[212:215], v[84:87]
	v_mfma_f32_16x16x32_bf16 v[84:87], v[156:159], v[216:219], v[84:87]
	v_mfma_f32_16x16x32_bf16 v[76:79], v[160:163], v[212:215], v[76:79]
	v_mfma_f32_16x16x32_bf16 v[76:79], v[164:167], v[216:219], v[76:79]
	v_mfma_f32_16x16x32_bf16 v[112:115], v[168:171], v[188:191], v[112:115]
	v_mfma_f32_16x16x32_bf16 v[112:115], v[172:175], v[192:195], v[112:115]
	v_mfma_f32_16x16x32_bf16 v[104:107], v[176:179], v[188:191], v[104:107]
	v_mfma_f32_16x16x32_bf16 v[104:107], v[184:187], v[192:195], v[104:107]
	v_mfma_f32_16x16x32_bf16 v[96:99], v[168:171], v[196:199], v[96:99]
	v_mfma_f32_16x16x32_bf16 v[96:99], v[172:175], v[200:203], v[96:99]
	v_mfma_f32_16x16x32_bf16 v[88:91], v[176:179], v[196:199], v[88:91]
	v_mfma_f32_16x16x32_bf16 v[88:91], v[184:187], v[200:203], v[88:91]
	v_mfma_f32_16x16x32_bf16 v[80:83], v[168:171], v[204:207], v[80:83]
	v_mfma_f32_16x16x32_bf16 v[80:83], v[172:175], v[208:211], v[80:83]
	v_mfma_f32_16x16x32_bf16 v[72:75], v[176:179], v[204:207], v[72:75]
	v_mfma_f32_16x16x32_bf16 v[72:75], v[184:187], v[208:211], v[72:75]
	v_mfma_f32_16x16x32_bf16 v[68:71], v[168:171], v[212:215], v[68:71]
	v_mfma_f32_16x16x32_bf16 v[68:71], v[172:175], v[216:219], v[68:71]
	s_barrier
	v_mfma_f32_16x16x32_bf16 v[64:67], v[176:179], v[212:215], v[64:67]
	v_mfma_f32_16x16x32_bf16 v[64:67], v[184:187], v[216:219], v[64:67]
	s_setprio 0
	s_add_i32 s60, s79, s64
	v_lshl_add_u64 v[144:145], v[144:145], 0, s[16:17]
	s_mov_b32 m0, s60
	ds_read_b128 v[188:191], v151 offset:49152
	ds_read_b128 v[192:195], v151 offset:50176
	ds_read_b128 v[196:199], v151 offset:51200
	ds_read_b128 v[200:203], v151 offset:52224
	ds_read_b128 v[204:207], v151 offset:53248
	ds_read_b128 v[208:211], v151 offset:54272
	ds_read_b128 v[212:215], v151 offset:55296
	ds_read_b128 v[216:219], v151 offset:56320
	global_load_lds_dwordx4 v[144:145], off
	s_add_i32 m0, s60, 0x2000
	s_add_u32 s58, s58, 0x40080
	v_lshl_add_u64 v[144:145], v[220:221], 0, s[16:17]
	s_addc_u32 s59, s59, 0
	s_add_i32 s60, s87, s64
	global_load_lds_dwordx4 v[144:145], off
	v_lshl_add_u64 v[144:145], s[58:59], 0, v[130:131]
	s_mov_b32 m0, s60
	s_nop 0
	global_load_lds_dwordx4 v[144:145], off
	v_lshl_add_u64 v[144:145], s[58:59], 0, v[134:135]
	s_add_i32 m0, s60, 0x2000
	s_nop 0
	global_load_lds_dwordx4 v[144:145], off
	v_lshl_add_u64 v[144:145], v[222:223], 0, s[16:17]
	s_mov_b32 m0, s69
	s_nop 0
	global_load_lds_dwordx4 v[144:145], off
	v_lshl_add_u64 v[144:145], v[224:225], 0, s[16:17]
	s_mov_b32 m0, s70
	s_nop 0
	global_load_lds_dwordx4 v[144:145], off
	s_waitcnt vmcnt(8)
	s_waitcnt lgkmcnt(0)
	s_barrier
	s_waitcnt lgkmcnt(0)
	v_mfma_f32_16x16x32_bf16 v[60:63], v[152:155], v[188:191], v[60:63]
	v_mfma_f32_16x16x32_bf16 v[60:63], v[156:159], v[192:195], v[60:63]
	s_setprio 1
	v_mfma_f32_16x16x32_bf16 v[56:59], v[160:163], v[188:191], v[56:59]
	v_mfma_f32_16x16x32_bf16 v[56:59], v[164:167], v[192:195], v[56:59]
	v_mfma_f32_16x16x32_bf16 v[52:55], v[152:155], v[196:199], v[52:55]
	v_mfma_f32_16x16x32_bf16 v[52:55], v[156:159], v[200:203], v[52:55]
	v_mfma_f32_16x16x32_bf16 v[44:47], v[160:163], v[196:199], v[44:47]
	v_mfma_f32_16x16x32_bf16 v[44:47], v[164:167], v[200:203], v[44:47]
	v_mfma_f32_16x16x32_bf16 v[36:39], v[152:155], v[204:207], v[36:39]
	v_mfma_f32_16x16x32_bf16 v[36:39], v[156:159], v[208:211], v[36:39]
	v_mfma_f32_16x16x32_bf16 v[28:31], v[160:163], v[204:207], v[28:31]
	v_mfma_f32_16x16x32_bf16 v[28:31], v[164:167], v[208:211], v[28:31]
	v_mfma_f32_16x16x32_bf16 v[20:23], v[152:155], v[212:215], v[20:23]
	v_mfma_f32_16x16x32_bf16 v[20:23], v[156:159], v[216:219], v[20:23]
	v_mfma_f32_16x16x32_bf16 v[12:15], v[160:163], v[212:215], v[12:15]
	v_mfma_f32_16x16x32_bf16 v[12:15], v[164:167], v[216:219], v[12:15]
	v_mfma_f32_16x16x32_bf16 v[48:51], v[168:171], v[188:191], v[48:51]
	v_mfma_f32_16x16x32_bf16 v[48:51], v[172:175], v[192:195], v[48:51]
	v_mfma_f32_16x16x32_bf16 v[40:43], v[176:179], v[188:191], v[40:43]
	v_mfma_f32_16x16x32_bf16 v[40:43], v[184:187], v[192:195], v[40:43]
	v_mfma_f32_16x16x32_bf16 v[32:35], v[168:171], v[196:199], v[32:35]
	v_mfma_f32_16x16x32_bf16 v[32:35], v[172:175], v[200:203], v[32:35]
	v_mfma_f32_16x16x32_bf16 v[24:27], v[176:179], v[196:199], v[24:27]
	v_mfma_f32_16x16x32_bf16 v[24:27], v[184:187], v[200:203], v[24:27]
	v_mfma_f32_16x16x32_bf16 v[16:19], v[168:171], v[204:207], v[16:19]
	v_mfma_f32_16x16x32_bf16 v[16:19], v[172:175], v[208:211], v[16:19]
	v_mfma_f32_16x16x32_bf16 v[8:11], v[176:179], v[204:207], v[8:11]
	v_mfma_f32_16x16x32_bf16 v[8:11], v[184:187], v[208:211], v[8:11]
	v_mfma_f32_16x16x32_bf16 v[4:7], v[168:171], v[212:215], v[4:7]
	v_mfma_f32_16x16x32_bf16 v[4:7], v[172:175], v[216:219], v[4:7]
	s_barrier
	v_mfma_f32_16x16x32_bf16 v[0:3], v[176:179], v[212:215], v[0:3]
	v_mfma_f32_16x16x32_bf16 v[0:3], v[184:187], v[216:219], v[0:3]
	s_setprio 0
	s_add_i32 s86, s86, 2
	s_add_u32 s56, s56, 0x100
	s_addc_u32 s57, s57, 0
	s_add_u32 s84, s84, 0x100
	s_addc_u32 s85, s85, 0
	s_cmp_gt_u32 s86, 13
	s_cbranch_scc0 .LBB0_1311
	s_and_b64 vcc, exec, s[18:19]
	s_cbranch_vccz .LBB0_1314
	s_barrier

.LBB0_1433:
	s_ashr_i32 s19, s18, 31
	s_lshl_b64 s[30:31], s[18:19], 19
	s_add_u32 s30, s80, s30
	s_addc_u32 s31, s81, s31
	s_and_b64 s[36:37], s[8:9], exec
	s_cselect_b32 s19, s31, s47
	s_cselect_b32 s66, s30, s46
	s_ashr_i32 s17, s16, 31
	s_lshl_b64 s[36:37], s[16:17], 19
	s_add_u32 s36, s52, s36
	s_addc_u32 s37, s53, s37
	s_and_b64 s[50:51], s[8:9], exec
	s_cselect_b32 s17, s37, s49
	s_cselect_b32 s67, s36, s48
	s_add_u32 s46, s46, 0x40080
	s_addc_u32 s47, s47, 0
	s_add_u32 s68, s48, 0x100
	s_addc_u32 s69, s49, 0
	s_mov_b32 s70, -2
	ds_read_b128 v[140:143], v147
	ds_read_b128 v[150:153], v147 offset:1024
	ds_read_b128 v[154:157], v147 offset:2048
	ds_read_b128 v[158:161], v147 offset:3072
	ds_read_b128 v[162:165], v148
	ds_read_b128 v[166:169], v148 offset:1024
	ds_read_b128 v[170:173], v148 offset:2048
	ds_read_b128 v[174:177], v148 offset:3072
	s_add_u32 s48, s46, 0xfffc0080
	s_addc_u32 s49, s47, -1
	s_cmp_eq_u32 s70, 12
	s_cselect_b32 s51, s19, s49
	s_cselect_b32 s50, s66, s48
	s_cselect_b32 s49, s17, s69
	s_cselect_b32 s48, s67, s68
	v_lshl_add_u64 v[178:179], s[46:47], 0, v[132:133]
	s_add_i32 m0, s45, 0xc000
	ds_read_b128 v[184:187], v149
	ds_read_b128 v[188:191], v149 offset:1024
	ds_read_b128 v[192:195], v149 offset:2048
	ds_read_b128 v[196:199], v149 offset:3072
	ds_read_b128 v[200:203], v149 offset:4096
	ds_read_b128 v[204:207], v149 offset:5120
	ds_read_b128 v[208:211], v149 offset:6144
	ds_read_b128 v[212:215], v149 offset:7168
	global_load_lds_dwordx4 v[178:179], off
	v_lshl_add_u64 v[178:179], s[46:47], 0, v[134:135]
	s_add_i32 m0, s45, 0xe000
	s_nop 0
	global_load_lds_dwordx4 v[178:179], off
	s_waitcnt vmcnt(8)
	s_waitcnt lgkmcnt(0)
	s_barrier
	s_waitcnt lgkmcnt(0)
	v_mfma_f32_16x16x32_bf16 v[124:127], v[140:143], v[184:187], 0
	v_mfma_f32_16x16x32_bf16 v[124:127], v[150:153], v[188:191], v[124:127]
	s_setprio 1
	v_mfma_f32_16x16x32_bf16 v[120:123], v[154:157], v[184:187], 0
	v_mfma_f32_16x16x32_bf16 v[120:123], v[158:161], v[188:191], v[120:123]
	v_mfma_f32_16x16x32_bf16 v[108:111], v[140:143], v[192:195], 0
	v_mfma_f32_16x16x32_bf16 v[108:111], v[150:153], v[196:199], v[108:111]
	v_mfma_f32_16x16x32_bf16 v[104:107], v[154:157], v[192:195], 0
	v_mfma_f32_16x16x32_bf16 v[104:107], v[158:161], v[196:199], v[104:107]
	v_mfma_f32_16x16x32_bf16 v[92:95], v[140:143], v[200:203], 0
	v_mfma_f32_16x16x32_bf16 v[92:95], v[150:153], v[204:207], v[92:95]
	v_mfma_f32_16x16x32_bf16 v[88:91], v[154:157], v[200:203], 0
	v_mfma_f32_16x16x32_bf16 v[88:91], v[158:161], v[204:207], v[88:91]
	v_mfma_f32_16x16x32_bf16 v[76:79], v[140:143], v[208:211], 0
	v_mfma_f32_16x16x32_bf16 v[76:79], v[150:153], v[212:215], v[76:79]
	v_mfma_f32_16x16x32_bf16 v[72:75], v[154:157], v[208:211], 0
	v_mfma_f32_16x16x32_bf16 v[72:75], v[158:161], v[212:215], v[72:75]
	v_mfma_f32_16x16x32_bf16 v[116:119], v[162:165], v[184:187], 0
	v_mfma_f32_16x16x32_bf16 v[116:119], v[166:169], v[188:191], v[116:119]
	v_mfma_f32_16x16x32_bf16 v[112:115], v[170:173], v[184:187], 0
	v_mfma_f32_16x16x32_bf16 v[112:115], v[174:177], v[188:191], v[112:115]
	v_mfma_f32_16x16x32_bf16 v[100:103], v[162:165], v[192:195], 0
	v_mfma_f32_16x16x32_bf16 v[100:103], v[166:169], v[196:199], v[100:103]
	v_mfma_f32_16x16x32_bf16 v[96:99], v[170:173], v[192:195], 0
	v_mfma_f32_16x16x32_bf16 v[96:99], v[174:177], v[196:199], v[96:99]
	v_mfma_f32_16x16x32_bf16 v[84:87], v[162:165], v[200:203], 0
	v_mfma_f32_16x16x32_bf16 v[84:87], v[166:169], v[204:207], v[84:87]
	v_mfma_f32_16x16x32_bf16 v[80:83], v[170:173], v[200:203], 0
	v_mfma_f32_16x16x32_bf16 v[80:83], v[174:177], v[204:207], v[80:83]
	v_mfma_f32_16x16x32_bf16 v[68:71], v[162:165], v[208:211], 0
	v_mfma_f32_16x16x32_bf16 v[68:71], v[166:169], v[212:215], v[68:71]
	s_barrier
	v_mfma_f32_16x16x32_bf16 v[64:67], v[170:173], v[208:211], 0
	v_mfma_f32_16x16x32_bf16 v[64:67], v[174:177], v[212:215], v[64:67]
	s_setprio 0
	s_add_i32 s71, s62, s54
	v_lshl_add_u64 v[178:179], s[48:49], 0, v[130:131]
	s_mov_b32 m0, s71
	ds_read_b128 v[184:187], v149 offset:16384
	ds_read_b128 v[188:191], v149 offset:17408
	ds_read_b128 v[192:195], v149 offset:18432
	ds_read_b128 v[196:199], v149 offset:19456
	ds_read_b128 v[200:203], v149 offset:20480
	ds_read_b128 v[204:207], v149 offset:21504
	ds_read_b128 v[208:211], v149 offset:22528
	ds_read_b128 v[212:215], v149 offset:23552
	global_load_lds_dwordx4 v[178:179], off
	s_add_i32 m0, s71, 0x2000
	s_add_u32 s72, s48, 0x40000
	v_lshl_add_u64 v[216:217], s[48:49], 0, v[128:129]
	s_addc_u32 s73, s49, 0
	s_add_i32 s71, s63, s54
	global_load_lds_dwordx4 v[216:217], off
	v_lshl_add_u64 v[218:219], s[72:73], 0, v[130:131]
	s_mov_b32 m0, s71
	v_lshl_add_u64 v[220:221], s[50:51], 0, v[128:129]
	global_load_lds_dwordx4 v[218:219], off
	v_lshl_add_u64 v[218:219], s[72:73], 0, v[128:129]
	s_add_i32 m0, s71, 0x2000
	s_nop 0
	global_load_lds_dwordx4 v[218:219], off
	v_lshl_add_u64 v[218:219], s[50:51], 0, v[130:131]
	s_mov_b32 m0, s45
	s_nop 0
	global_load_lds_dwordx4 v[218:219], off
	s_mov_b32 m0, s56
	s_nop 0
	global_load_lds_dwordx4 v[220:221], off
	s_waitcnt vmcnt(8)
	s_waitcnt lgkmcnt(0)
	s_barrier
	s_waitcnt lgkmcnt(0)
	v_mfma_f32_16x16x32_bf16 v[60:63], v[140:143], v[184:187], 0
	v_mfma_f32_16x16x32_bf16 v[60:63], v[150:153], v[188:191], v[60:63]
	s_setprio 1
	v_mfma_f32_16x16x32_bf16 v[56:59], v[154:157], v[184:187], 0
	v_mfma_f32_16x16x32_bf16 v[56:59], v[158:161], v[188:191], v[56:59]
	v_mfma_f32_16x16x32_bf16 v[44:47], v[140:143], v[192:195], 0
	v_mfma_f32_16x16x32_bf16 v[44:47], v[150:153], v[196:199], v[44:47]
	v_mfma_f32_16x16x32_bf16 v[40:43], v[154:157], v[192:195], 0
	v_mfma_f32_16x16x32_bf16 v[40:43], v[158:161], v[196:199], v[40:43]
	v_mfma_f32_16x16x32_bf16 v[28:31], v[140:143], v[200:203], 0
	v_mfma_f32_16x16x32_bf16 v[28:31], v[150:153], v[204:207], v[28:31]
	v_mfma_f32_16x16x32_bf16 v[24:27], v[154:157], v[200:203], 0
	v_mfma_f32_16x16x32_bf16 v[24:27], v[158:161], v[204:207], v[24:27]
	v_mfma_f32_16x16x32_bf16 v[12:15], v[140:143], v[208:211], 0
	v_mfma_f32_16x16x32_bf16 v[12:15], v[150:153], v[212:215], v[12:15]
	v_mfma_f32_16x16x32_bf16 v[8:11], v[154:157], v[208:211], 0
	v_mfma_f32_16x16x32_bf16 v[8:11], v[158:161], v[212:215], v[8:11]
	v_mfma_f32_16x16x32_bf16 v[52:55], v[162:165], v[184:187], 0
	v_mfma_f32_16x16x32_bf16 v[52:55], v[166:169], v[188:191], v[52:55]
	v_mfma_f32_16x16x32_bf16 v[48:51], v[170:173], v[184:187], 0
	v_mfma_f32_16x16x32_bf16 v[48:51], v[174:177], v[188:191], v[48:51]
	v_mfma_f32_16x16x32_bf16 v[36:39], v[162:165], v[192:195], 0
	v_mfma_f32_16x16x32_bf16 v[36:39], v[166:169], v[196:199], v[36:39]
	v_mfma_f32_16x16x32_bf16 v[32:35], v[170:173], v[192:195], 0
	v_mfma_f32_16x16x32_bf16 v[32:35], v[174:177], v[196:199], v[32:35]
	v_mfma_f32_16x16x32_bf16 v[20:23], v[162:165], v[200:203], 0
	v_mfma_f32_16x16x32_bf16 v[20:23], v[166:169], v[204:207], v[20:23]
	v_mfma_f32_16x16x32_bf16 v[16:19], v[170:173], v[200:203], 0
	v_mfma_f32_16x16x32_bf16 v[16:19], v[174:177], v[204:207], v[16:19]
	v_mfma_f32_16x16x32_bf16 v[4:7], v[162:165], v[208:211], 0
	v_mfma_f32_16x16x32_bf16 v[4:7], v[166:169], v[212:215], v[4:7]
	s_barrier
	v_mfma_f32_16x16x32_bf16 v[0:3], v[170:173], v[208:211], 0
	v_mfma_f32_16x16x32_bf16 v[0:3], v[174:177], v[212:215], v[0:3]
	s_setprio 0
	s_branch .Lmid_gemm11
.LBB0_1434:
	ds_read_b128 v[140:143], v147
	ds_read_b128 v[150:153], v147 offset:1024
	ds_read_b128 v[154:157], v147 offset:2048
	ds_read_b128 v[158:161], v147 offset:3072
	ds_read_b128 v[162:165], v148
	ds_read_b128 v[166:169], v148 offset:1024
	ds_read_b128 v[170:173], v148 offset:2048
	ds_read_b128 v[174:177], v148 offset:3072
	s_add_u32 s48, s46, 0xfffc0080
	s_addc_u32 s49, s47, -1
	s_cmp_eq_u32 s70, 12
	s_cselect_b32 s51, s19, s49
	s_cselect_b32 s50, s66, s48
	s_cselect_b32 s49, s17, s69
	s_cselect_b32 s48, s67, s68
	v_lshl_add_u64 v[178:179], s[46:47], 0, v[132:133]
	s_add_i32 m0, s45, 0xc000
	ds_read_b128 v[184:187], v149
	ds_read_b128 v[188:191], v149 offset:1024
	ds_read_b128 v[192:195], v149 offset:2048
	ds_read_b128 v[196:199], v149 offset:3072
	ds_read_b128 v[200:203], v149 offset:4096
	ds_read_b128 v[204:207], v149 offset:5120
	ds_read_b128 v[208:211], v149 offset:6144
	ds_read_b128 v[212:215], v149 offset:7168
	global_load_lds_dwordx4 v[178:179], off
	v_lshl_add_u64 v[178:179], s[46:47], 0, v[134:135]
	s_add_i32 m0, s45, 0xe000
	s_nop 0
	global_load_lds_dwordx4 v[178:179], off
	s_waitcnt vmcnt(8)
	s_waitcnt lgkmcnt(0)
	s_barrier
	s_waitcnt lgkmcnt(0)
	v_mfma_f32_16x16x32_bf16 v[124:127], v[140:143], v[184:187], v[124:127]
	v_mfma_f32_16x16x32_bf16 v[124:127], v[150:153], v[188:191], v[124:127]
	s_setprio 1
	v_mfma_f32_16x16x32_bf16 v[120:123], v[154:157], v[184:187], v[120:123]
	v_mfma_f32_16x16x32_bf16 v[120:123], v[158:161], v[188:191], v[120:123]
	v_mfma_f32_16x16x32_bf16 v[108:111], v[140:143], v[192:195], v[108:111]
	v_mfma_f32_16x16x32_bf16 v[108:111], v[150:153], v[196:199], v[108:111]
	v_mfma_f32_16x16x32_bf16 v[104:107], v[154:157], v[192:195], v[104:107]
	v_mfma_f32_16x16x32_bf16 v[104:107], v[158:161], v[196:199], v[104:107]
	v_mfma_f32_16x16x32_bf16 v[92:95], v[140:143], v[200:203], v[92:95]
	v_mfma_f32_16x16x32_bf16 v[92:95], v[150:153], v[204:207], v[92:95]
	v_mfma_f32_16x16x32_bf16 v[88:91], v[154:157], v[200:203], v[88:91]
	v_mfma_f32_16x16x32_bf16 v[88:91], v[158:161], v[204:207], v[88:91]
	v_mfma_f32_16x16x32_bf16 v[76:79], v[140:143], v[208:211], v[76:79]
	v_mfma_f32_16x16x32_bf16 v[76:79], v[150:153], v[212:215], v[76:79]
	v_mfma_f32_16x16x32_bf16 v[72:75], v[154:157], v[208:211], v[72:75]
	v_mfma_f32_16x16x32_bf16 v[72:75], v[158:161], v[212:215], v[72:75]
	v_mfma_f32_16x16x32_bf16 v[116:119], v[162:165], v[184:187], v[116:119]
	v_mfma_f32_16x16x32_bf16 v[116:119], v[166:169], v[188:191], v[116:119]
	v_mfma_f32_16x16x32_bf16 v[112:115], v[170:173], v[184:187], v[112:115]
	v_mfma_f32_16x16x32_bf16 v[112:115], v[174:177], v[188:191], v[112:115]
	v_mfma_f32_16x16x32_bf16 v[100:103], v[162:165], v[192:195], v[100:103]
	v_mfma_f32_16x16x32_bf16 v[100:103], v[166:169], v[196:199], v[100:103]
	v_mfma_f32_16x16x32_bf16 v[96:99], v[170:173], v[192:195], v[96:99]
	v_mfma_f32_16x16x32_bf16 v[96:99], v[174:177], v[196:199], v[96:99]
	v_mfma_f32_16x16x32_bf16 v[84:87], v[162:165], v[200:203], v[84:87]
	v_mfma_f32_16x16x32_bf16 v[84:87], v[166:169], v[204:207], v[84:87]
	v_mfma_f32_16x16x32_bf16 v[80:83], v[170:173], v[200:203], v[80:83]
	v_mfma_f32_16x16x32_bf16 v[80:83], v[174:177], v[204:207], v[80:83]
	v_mfma_f32_16x16x32_bf16 v[68:71], v[162:165], v[208:211], v[68:71]
	v_mfma_f32_16x16x32_bf16 v[68:71], v[166:169], v[212:215], v[68:71]
	s_barrier
	v_mfma_f32_16x16x32_bf16 v[64:67], v[170:173], v[208:211], v[64:67]
	v_mfma_f32_16x16x32_bf16 v[64:67], v[174:177], v[212:215], v[64:67]
	s_setprio 0
	s_add_i32 s71, s62, s54
	v_lshl_add_u64 v[178:179], s[48:49], 0, v[130:131]
	s_mov_b32 m0, s71
	ds_read_b128 v[184:187], v149 offset:16384
	ds_read_b128 v[188:191], v149 offset:17408
	ds_read_b128 v[192:195], v149 offset:18432
	ds_read_b128 v[196:199], v149 offset:19456
	ds_read_b128 v[200:203], v149 offset:20480
	ds_read_b128 v[204:207], v149 offset:21504
	ds_read_b128 v[208:211], v149 offset:22528
	ds_read_b128 v[212:215], v149 offset:23552
	global_load_lds_dwordx4 v[178:179], off
	s_add_i32 m0, s71, 0x2000
	s_add_u32 s72, s48, 0x40000
	v_lshl_add_u64 v[216:217], s[48:49], 0, v[128:129]
	s_addc_u32 s73, s49, 0
	s_add_i32 s71, s63, s54
	global_load_lds_dwordx4 v[216:217], off
	v_lshl_add_u64 v[218:219], s[72:73], 0, v[130:131]
	s_mov_b32 m0, s71
	v_lshl_add_u64 v[220:221], s[50:51], 0, v[128:129]
	global_load_lds_dwordx4 v[218:219], off
	v_lshl_add_u64 v[218:219], s[72:73], 0, v[128:129]
	s_add_i32 m0, s71, 0x2000
	s_nop 0
	global_load_lds_dwordx4 v[218:219], off
	v_lshl_add_u64 v[218:219], s[50:51], 0, v[130:131]
	s_mov_b32 m0, s45
	s_nop 0
	global_load_lds_dwordx4 v[218:219], off
	s_mov_b32 m0, s56
	s_nop 0
	global_load_lds_dwordx4 v[220:221], off
	s_waitcnt vmcnt(8)
	s_waitcnt lgkmcnt(0)
	s_barrier
	s_waitcnt lgkmcnt(0)
	v_mfma_f32_16x16x32_bf16 v[60:63], v[140:143], v[184:187], v[60:63]
	v_mfma_f32_16x16x32_bf16 v[60:63], v[150:153], v[188:191], v[60:63]
	s_setprio 1
	v_mfma_f32_16x16x32_bf16 v[56:59], v[154:157], v[184:187], v[56:59]
	v_mfma_f32_16x16x32_bf16 v[56:59], v[158:161], v[188:191], v[56:59]
	v_mfma_f32_16x16x32_bf16 v[44:47], v[140:143], v[192:195], v[44:47]
	v_mfma_f32_16x16x32_bf16 v[44:47], v[150:153], v[196:199], v[44:47]
	v_mfma_f32_16x16x32_bf16 v[40:43], v[154:157], v[192:195], v[40:43]
	v_mfma_f32_16x16x32_bf16 v[40:43], v[158:161], v[196:199], v[40:43]
	v_mfma_f32_16x16x32_bf16 v[28:31], v[140:143], v[200:203], v[28:31]
	v_mfma_f32_16x16x32_bf16 v[28:31], v[150:153], v[204:207], v[28:31]
	v_mfma_f32_16x16x32_bf16 v[24:27], v[154:157], v[200:203], v[24:27]
	v_mfma_f32_16x16x32_bf16 v[24:27], v[158:161], v[204:207], v[24:27]
	v_mfma_f32_16x16x32_bf16 v[12:15], v[140:143], v[208:211], v[12:15]
	v_mfma_f32_16x16x32_bf16 v[12:15], v[150:153], v[212:215], v[12:15]
	v_mfma_f32_16x16x32_bf16 v[8:11], v[154:157], v[208:211], v[8:11]
	v_mfma_f32_16x16x32_bf16 v[8:11], v[158:161], v[212:215], v[8:11]
	v_mfma_f32_16x16x32_bf16 v[52:55], v[162:165], v[184:187], v[52:55]
	v_mfma_f32_16x16x32_bf16 v[52:55], v[166:169], v[188:191], v[52:55]
	v_mfma_f32_16x16x32_bf16 v[48:51], v[170:173], v[184:187], v[48:51]
	v_mfma_f32_16x16x32_bf16 v[48:51], v[174:177], v[188:191], v[48:51]
	v_mfma_f32_16x16x32_bf16 v[36:39], v[162:165], v[192:195], v[36:39]
	v_mfma_f32_16x16x32_bf16 v[36:39], v[166:169], v[196:199], v[36:39]
	v_mfma_f32_16x16x32_bf16 v[32:35], v[170:173], v[192:195], v[32:35]
	v_mfma_f32_16x16x32_bf16 v[32:35], v[174:177], v[196:199], v[32:35]
	v_mfma_f32_16x16x32_bf16 v[20:23], v[162:165], v[200:203], v[20:23]
	v_mfma_f32_16x16x32_bf16 v[20:23], v[166:169], v[204:207], v[20:23]
	v_mfma_f32_16x16x32_bf16 v[16:19], v[170:173], v[200:203], v[16:19]
	v_mfma_f32_16x16x32_bf16 v[16:19], v[174:177], v[204:207], v[16:19]
	v_mfma_f32_16x16x32_bf16 v[4:7], v[162:165], v[208:211], v[4:7]
	v_mfma_f32_16x16x32_bf16 v[4:7], v[166:169], v[212:215], v[4:7]
	s_barrier
	v_mfma_f32_16x16x32_bf16 v[0:3], v[170:173], v[208:211], v[0:3]
	v_mfma_f32_16x16x32_bf16 v[0:3], v[174:177], v[212:215], v[0:3]
	s_setprio 0
.Lmid_gemm11:
	s_add_i32 s71, 0, 0x18000
	s_add_i32 s72, 0, 0x1c000
	v_add_u32_e32 v158, s71, v145
	v_add_u32_e32 v174, s72, v145
	ds_read_b128 v[140:143], v158
	ds_read_b128 v[150:153], v158 offset:1024
	ds_read_b128 v[154:157], v158 offset:2048
	ds_read_b128 v[158:161], v158 offset:3072
	ds_read_b128 v[162:165], v174
	ds_read_b128 v[166:169], v174 offset:1024
	ds_read_b128 v[170:173], v174 offset:2048
	ds_read_b128 v[174:177], v174 offset:3072
	s_add_u32 s50, s50, 0x40000
	s_addc_u32 s51, s51, 0
	s_mov_b32 m0, s57
	v_lshl_add_u64 v[222:223], s[50:51], 0, v[130:131]
	ds_read_b128 v[184:187], v149 offset:32768
	ds_read_b128 v[188:191], v149 offset:33792
	ds_read_b128 v[192:195], v149 offset:34816
	ds_read_b128 v[196:199], v149 offset:35840
	ds_read_b128 v[200:203], v149 offset:36864
	ds_read_b128 v[204:207], v149 offset:37888
	ds_read_b128 v[208:211], v149 offset:38912
	ds_read_b128 v[212:215], v149 offset:39936
	global_load_lds_dwordx4 v[222:223], off
	v_lshl_add_u64 v[222:223], s[50:51], 0, v[128:129]
	s_mov_b32 m0, s58
	s_nop 0
	global_load_lds_dwordx4 v[222:223], off
	s_waitcnt vmcnt(8)
	s_waitcnt lgkmcnt(0)
	s_barrier
	s_waitcnt lgkmcnt(0)
	v_mfma_f32_16x16x32_bf16 v[124:127], v[140:143], v[184:187], v[124:127]
	v_mfma_f32_16x16x32_bf16 v[124:127], v[150:153], v[188:191], v[124:127]
	s_setprio 1
	v_mfma_f32_16x16x32_bf16 v[120:123], v[154:157], v[184:187], v[120:123]
	v_mfma_f32_16x16x32_bf16 v[120:123], v[158:161], v[188:191], v[120:123]
	v_mfma_f32_16x16x32_bf16 v[108:111], v[140:143], v[192:195], v[108:111]
	v_mfma_f32_16x16x32_bf16 v[108:111], v[150:153], v[196:199], v[108:111]
	v_mfma_f32_16x16x32_bf16 v[104:107], v[154:157], v[192:195], v[104:107]
	v_mfma_f32_16x16x32_bf16 v[104:107], v[158:161], v[196:199], v[104:107]
	v_mfma_f32_16x16x32_bf16 v[92:95], v[140:143], v[200:203], v[92:95]
	v_mfma_f32_16x16x32_bf16 v[92:95], v[150:153], v[204:207], v[92:95]
	v_mfma_f32_16x16x32_bf16 v[88:91], v[154:157], v[200:203], v[88:91]
	v_mfma_f32_16x16x32_bf16 v[88:91], v[158:161], v[204:207], v[88:91]
	v_mfma_f32_16x16x32_bf16 v[76:79], v[140:143], v[208:211], v[76:79]
	v_mfma_f32_16x16x32_bf16 v[76:79], v[150:153], v[212:215], v[76:79]
	v_mfma_f32_16x16x32_bf16 v[72:75], v[154:157], v[208:211], v[72:75]
	v_mfma_f32_16x16x32_bf16 v[72:75], v[158:161], v[212:215], v[72:75]
	v_mfma_f32_16x16x32_bf16 v[116:119], v[162:165], v[184:187], v[116:119]
	v_mfma_f32_16x16x32_bf16 v[116:119], v[166:169], v[188:191], v[116:119]
	v_mfma_f32_16x16x32_bf16 v[112:115], v[170:173], v[184:187], v[112:115]
	v_mfma_f32_16x16x32_bf16 v[112:115], v[174:177], v[188:191], v[112:115]
	v_mfma_f32_16x16x32_bf16 v[100:103], v[162:165], v[192:195], v[100:103]
	v_mfma_f32_16x16x32_bf16 v[100:103], v[166:169], v[196:199], v[100:103]
	v_mfma_f32_16x16x32_bf16 v[96:99], v[170:173], v[192:195], v[96:99]
	v_mfma_f32_16x16x32_bf16 v[96:99], v[174:177], v[196:199], v[96:99]
	v_mfma_f32_16x16x32_bf16 v[84:87], v[162:165], v[200:203], v[84:87]
	v_mfma_f32_16x16x32_bf16 v[84:87], v[166:169], v[204:207], v[84:87]
	v_mfma_f32_16x16x32_bf16 v[80:83], v[170:173], v[200:203], v[80:83]
	v_mfma_f32_16x16x32_bf16 v[80:83], v[174:177], v[204:207], v[80:83]
	v_mfma_f32_16x16x32_bf16 v[68:71], v[162:165], v[208:211], v[68:71]
	v_mfma_f32_16x16x32_bf16 v[68:71], v[166:169], v[212:215], v[68:71]
	s_barrier
	v_mfma_f32_16x16x32_bf16 v[64:67], v[170:173], v[208:211], v[64:67]
	v_mfma_f32_16x16x32_bf16 v[64:67], v[174:177], v[212:215], v[64:67]
	s_setprio 0
	s_add_i32 s50, s71, s54
	v_lshl_add_u64 v[178:179], v[178:179], 0, s[10:11]
	s_mov_b32 m0, s50
	ds_read_b128 v[184:187], v149 offset:49152
	ds_read_b128 v[188:191], v149 offset:50176
	ds_read_b128 v[192:195], v149 offset:51200
	ds_read_b128 v[196:199], v149 offset:52224
	ds_read_b128 v[200:203], v149 offset:53248
	ds_read_b128 v[204:207], v149 offset:54272
	ds_read_b128 v[208:211], v149 offset:55296
	ds_read_b128 v[212:215], v149 offset:56320
	global_load_lds_dwordx4 v[178:179], off
	s_add_i32 m0, s50, 0x2000
	s_add_u32 s48, s48, 0x40080
	v_lshl_add_u64 v[178:179], v[216:217], 0, s[10:11]
	s_addc_u32 s49, s49, 0
	s_add_i32 s50, s72, s54
	global_load_lds_dwordx4 v[178:179], off
	v_lshl_add_u64 v[178:179], s[48:49], 0, v[130:131]
	s_mov_b32 m0, s50
	s_nop 0
	global_load_lds_dwordx4 v[178:179], off
	v_lshl_add_u64 v[178:179], s[48:49], 0, v[128:129]
	s_add_i32 m0, s50, 0x2000
	s_nop 0
	global_load_lds_dwordx4 v[178:179], off
	v_lshl_add_u64 v[178:179], v[218:219], 0, s[10:11]
	s_mov_b32 m0, s60
	s_nop 0
	global_load_lds_dwordx4 v[178:179], off
	v_lshl_add_u64 v[178:179], v[220:221], 0, s[10:11]
	s_mov_b32 m0, s61
	s_nop 0
	global_load_lds_dwordx4 v[178:179], off
	s_waitcnt vmcnt(8)
	s_waitcnt lgkmcnt(0)
	s_barrier
	s_waitcnt lgkmcnt(0)
	v_mfma_f32_16x16x32_bf16 v[60:63], v[140:143], v[184:187], v[60:63]
	v_mfma_f32_16x16x32_bf16 v[60:63], v[150:153], v[188:191], v[60:63]
	s_setprio 1
	v_mfma_f32_16x16x32_bf16 v[56:59], v[154:157], v[184:187], v[56:59]
	v_mfma_f32_16x16x32_bf16 v[56:59], v[158:161], v[188:191], v[56:59]
	v_mfma_f32_16x16x32_bf16 v[44:47], v[140:143], v[192:195], v[44:47]
	v_mfma_f32_16x16x32_bf16 v[44:47], v[150:153], v[196:199], v[44:47]
	v_mfma_f32_16x16x32_bf16 v[40:43], v[154:157], v[192:195], v[40:43]
	v_mfma_f32_16x16x32_bf16 v[40:43], v[158:161], v[196:199], v[40:43]
	v_mfma_f32_16x16x32_bf16 v[28:31], v[140:143], v[200:203], v[28:31]
	v_mfma_f32_16x16x32_bf16 v[28:31], v[150:153], v[204:207], v[28:31]
	v_mfma_f32_16x16x32_bf16 v[24:27], v[154:157], v[200:203], v[24:27]
	v_mfma_f32_16x16x32_bf16 v[24:27], v[158:161], v[204:207], v[24:27]
	v_mfma_f32_16x16x32_bf16 v[12:15], v[140:143], v[208:211], v[12:15]
	v_mfma_f32_16x16x32_bf16 v[12:15], v[150:153], v[212:215], v[12:15]
	v_mfma_f32_16x16x32_bf16 v[8:11], v[154:157], v[208:211], v[8:11]
	v_mfma_f32_16x16x32_bf16 v[8:11], v[158:161], v[212:215], v[8:11]
	v_mfma_f32_16x16x32_bf16 v[52:55], v[162:165], v[184:187], v[52:55]
	v_mfma_f32_16x16x32_bf16 v[52:55], v[166:169], v[188:191], v[52:55]
	v_mfma_f32_16x16x32_bf16 v[48:51], v[170:173], v[184:187], v[48:51]
	v_mfma_f32_16x16x32_bf16 v[48:51], v[174:177], v[188:191], v[48:51]
	v_mfma_f32_16x16x32_bf16 v[36:39], v[162:165], v[192:195], v[36:39]
	v_mfma_f32_16x16x32_bf16 v[36:39], v[166:169], v[196:199], v[36:39]
	v_mfma_f32_16x16x32_bf16 v[32:35], v[170:173], v[192:195], v[32:35]
	v_mfma_f32_16x16x32_bf16 v[32:35], v[174:177], v[196:199], v[32:35]
	v_mfma_f32_16x16x32_bf16 v[20:23], v[162:165], v[200:203], v[20:23]
	v_mfma_f32_16x16x32_bf16 v[20:23], v[166:169], v[204:207], v[20:23]
	v_mfma_f32_16x16x32_bf16 v[16:19], v[170:173], v[200:203], v[16:19]
	v_mfma_f32_16x16x32_bf16 v[16:19], v[174:177], v[204:207], v[16:19]
	v_mfma_f32_16x16x32_bf16 v[4:7], v[162:165], v[208:211], v[4:7]
	v_mfma_f32_16x16x32_bf16 v[4:7], v[166:169], v[212:215], v[4:7]
	s_barrier
	v_mfma_f32_16x16x32_bf16 v[0:3], v[170:173], v[208:211], v[0:3]
	v_mfma_f32_16x16x32_bf16 v[0:3], v[174:177], v[212:215], v[0:3]
	s_setprio 0
	s_add_i32 s70, s70, 2
	s_add_u32 s46, s46, 0x100
	s_addc_u32 s47, s47, 0
	s_add_u32 s68, s68, 0x100
	s_addc_u32 s69, s69, 0
	s_cmp_gt_u32 s70, 13
	s_cbranch_scc0 .LBB0_1434
	s_and_b64 vcc, exec, s[12:13]
	s_cbranch_vccz .LBB0_1437
	s_barrier

.LBB0_1513:
	s_add_u32 s74, s48, 0x100
	s_addc_u32 s75, s49, 0
	s_mov_b32 s76, -2
	ds_read_b128 v[152:155], v149
	ds_read_b128 v[156:159], v149 offset:1024
	ds_read_b128 v[160:163], v149 offset:2048
	ds_read_b128 v[164:167], v149 offset:3072
	ds_read_b128 v[168:171], v150
	ds_read_b128 v[172:175], v150 offset:1024
	ds_read_b128 v[176:179], v150 offset:2048
	ds_read_b128 v[184:187], v150 offset:3072
	s_add_u32 s48, s46, 0x100
	s_addc_u32 s49, s47, 0
	s_cmp_eq_u32 s76, 40
	s_cselect_b32 s53, s9, s49
	s_cselect_b32 s52, s8, s48
	s_cselect_b32 s51, s45, s75
	s_cselect_b32 s50, s44, s74
	v_lshl_add_u64 v[144:145], s[46:47], 0, v[136:137]
	s_add_i32 m0, s57, 0xc000
	ds_read_b128 v[188:191], v151
	ds_read_b128 v[192:195], v151 offset:1024
	ds_read_b128 v[196:199], v151 offset:2048
	ds_read_b128 v[200:203], v151 offset:3072
	ds_read_b128 v[204:207], v151 offset:4096
	ds_read_b128 v[208:211], v151 offset:5120
	ds_read_b128 v[212:215], v151 offset:6144
	ds_read_b128 v[216:219], v151 offset:7168
	global_load_lds_dwordx4 v[144:145], off
	v_lshl_add_u64 v[144:145], s[46:47], 0, v[138:139]
	s_add_i32 m0, s57, 0xe000
	s_nop 0
	global_load_lds_dwordx4 v[144:145], off
	s_waitcnt vmcnt(8)
	s_waitcnt lgkmcnt(0)
	s_barrier
	s_waitcnt lgkmcnt(0)
	v_mfma_f32_16x16x32_bf16 v[124:127], v[152:155], v[188:191], 0
	v_mfma_f32_16x16x32_bf16 v[124:127], v[156:159], v[192:195], v[124:127]
	s_setprio 1
	v_mfma_f32_16x16x32_bf16 v[120:123], v[160:163], v[188:191], 0
	v_mfma_f32_16x16x32_bf16 v[120:123], v[164:167], v[192:195], v[120:123]
	v_mfma_f32_16x16x32_bf16 v[116:119], v[152:155], v[196:199], 0
	v_mfma_f32_16x16x32_bf16 v[116:119], v[156:159], v[200:203], v[116:119]
	v_mfma_f32_16x16x32_bf16 v[108:111], v[160:163], v[196:199], 0
	v_mfma_f32_16x16x32_bf16 v[108:111], v[164:167], v[200:203], v[108:111]
	v_mfma_f32_16x16x32_bf16 v[100:103], v[152:155], v[204:207], 0
	v_mfma_f32_16x16x32_bf16 v[100:103], v[156:159], v[208:211], v[100:103]
	v_mfma_f32_16x16x32_bf16 v[92:95], v[160:163], v[204:207], 0
	v_mfma_f32_16x16x32_bf16 v[92:95], v[164:167], v[208:211], v[92:95]
	v_mfma_f32_16x16x32_bf16 v[84:87], v[152:155], v[212:215], 0
	v_mfma_f32_16x16x32_bf16 v[84:87], v[156:159], v[216:219], v[84:87]
	v_mfma_f32_16x16x32_bf16 v[76:79], v[160:163], v[212:215], 0
	v_mfma_f32_16x16x32_bf16 v[76:79], v[164:167], v[216:219], v[76:79]
	v_mfma_f32_16x16x32_bf16 v[112:115], v[168:171], v[188:191], 0
	v_mfma_f32_16x16x32_bf16 v[112:115], v[172:175], v[192:195], v[112:115]
	v_mfma_f32_16x16x32_bf16 v[104:107], v[176:179], v[188:191], 0
	v_mfma_f32_16x16x32_bf16 v[104:107], v[184:187], v[192:195], v[104:107]
	v_mfma_f32_16x16x32_bf16 v[96:99], v[168:171], v[196:199], 0
	v_mfma_f32_16x16x32_bf16 v[96:99], v[172:175], v[200:203], v[96:99]
	v_mfma_f32_16x16x32_bf16 v[88:91], v[176:179], v[196:199], 0
	v_mfma_f32_16x16x32_bf16 v[88:91], v[184:187], v[200:203], v[88:91]
	v_mfma_f32_16x16x32_bf16 v[80:83], v[168:171], v[204:207], 0
	v_mfma_f32_16x16x32_bf16 v[80:83], v[172:175], v[208:211], v[80:83]
	v_mfma_f32_16x16x32_bf16 v[72:75], v[176:179], v[204:207], 0
	v_mfma_f32_16x16x32_bf16 v[72:75], v[184:187], v[208:211], v[72:75]
	v_mfma_f32_16x16x32_bf16 v[68:71], v[168:171], v[212:215], 0
	v_mfma_f32_16x16x32_bf16 v[68:71], v[172:175], v[216:219], v[68:71]
	s_barrier
	v_mfma_f32_16x16x32_bf16 v[64:67], v[176:179], v[212:215], 0
	v_mfma_f32_16x16x32_bf16 v[64:67], v[184:187], v[216:219], v[64:67]
	s_setprio 0
	s_add_i32 s46, s64, s56
	v_lshl_add_u64 v[144:145], s[50:51], 0, v[130:131]
	s_mov_b32 m0, s46
	ds_read_b128 v[188:191], v151 offset:16384
	ds_read_b128 v[192:195], v151 offset:17408
	ds_read_b128 v[196:199], v151 offset:18432
	ds_read_b128 v[200:203], v151 offset:19456
	ds_read_b128 v[204:207], v151 offset:20480
	ds_read_b128 v[208:211], v151 offset:21504
	ds_read_b128 v[212:215], v151 offset:22528
	ds_read_b128 v[216:219], v151 offset:23552
	global_load_lds_dwordx4 v[144:145], off
	s_add_i32 m0, s46, 0x2000
	s_add_u32 s46, s50, 0xb0000
	v_lshl_add_u64 v[220:221], s[50:51], 0, v[134:135]
	s_addc_u32 s47, s51, 0
	s_add_i32 s77, s65, s56
	global_load_lds_dwordx4 v[220:221], off
	v_lshl_add_u64 v[222:223], s[46:47], 0, v[130:131]
	s_mov_b32 m0, s77
	v_lshl_add_u64 v[224:225], s[52:53], 0, v[132:133]
	global_load_lds_dwordx4 v[222:223], off
	v_lshl_add_u64 v[222:223], s[46:47], 0, v[134:135]
	s_add_i32 m0, s77, 0x2000
	s_nop 0
	global_load_lds_dwordx4 v[222:223], off
	v_lshl_add_u64 v[222:223], s[52:53], 0, v[128:129]
	s_mov_b32 m0, s57
	s_nop 0
	global_load_lds_dwordx4 v[222:223], off
	s_mov_b32 m0, s58
	s_nop 0
	global_load_lds_dwordx4 v[224:225], off
	s_waitcnt vmcnt(8)
	s_waitcnt lgkmcnt(0)
	s_barrier
	s_waitcnt lgkmcnt(0)
	v_mfma_f32_16x16x32_bf16 v[60:63], v[152:155], v[188:191], 0
	v_mfma_f32_16x16x32_bf16 v[60:63], v[156:159], v[192:195], v[60:63]
	s_setprio 1
	v_mfma_f32_16x16x32_bf16 v[56:59], v[160:163], v[188:191], 0
	v_mfma_f32_16x16x32_bf16 v[56:59], v[164:167], v[192:195], v[56:59]
	v_mfma_f32_16x16x32_bf16 v[52:55], v[152:155], v[196:199], 0
	v_mfma_f32_16x16x32_bf16 v[52:55], v[156:159], v[200:203], v[52:55]
	v_mfma_f32_16x16x32_bf16 v[44:47], v[160:163], v[196:199], 0
	v_mfma_f32_16x16x32_bf16 v[44:47], v[164:167], v[200:203], v[44:47]
	v_mfma_f32_16x16x32_bf16 v[36:39], v[152:155], v[204:207], 0
	v_mfma_f32_16x16x32_bf16 v[36:39], v[156:159], v[208:211], v[36:39]
	v_mfma_f32_16x16x32_bf16 v[28:31], v[160:163], v[204:207], 0
	v_mfma_f32_16x16x32_bf16 v[28:31], v[164:167], v[208:211], v[28:31]
	v_mfma_f32_16x16x32_bf16 v[20:23], v[152:155], v[212:215], 0
	v_mfma_f32_16x16x32_bf16 v[20:23], v[156:159], v[216:219], v[20:23]
	v_mfma_f32_16x16x32_bf16 v[12:15], v[160:163], v[212:215], 0
	v_mfma_f32_16x16x32_bf16 v[12:15], v[164:167], v[216:219], v[12:15]
	v_mfma_f32_16x16x32_bf16 v[48:51], v[168:171], v[188:191], 0
	v_mfma_f32_16x16x32_bf16 v[48:51], v[172:175], v[192:195], v[48:51]
	v_mfma_f32_16x16x32_bf16 v[40:43], v[176:179], v[188:191], 0
	v_mfma_f32_16x16x32_bf16 v[40:43], v[184:187], v[192:195], v[40:43]
	v_mfma_f32_16x16x32_bf16 v[32:35], v[168:171], v[196:199], 0
	v_mfma_f32_16x16x32_bf16 v[32:35], v[172:175], v[200:203], v[32:35]
	v_mfma_f32_16x16x32_bf16 v[24:27], v[176:179], v[196:199], 0
	v_mfma_f32_16x16x32_bf16 v[24:27], v[184:187], v[200:203], v[24:27]
	v_mfma_f32_16x16x32_bf16 v[16:19], v[168:171], v[204:207], 0
	v_mfma_f32_16x16x32_bf16 v[16:19], v[172:175], v[208:211], v[16:19]
	v_mfma_f32_16x16x32_bf16 v[8:11], v[176:179], v[204:207], 0
	v_mfma_f32_16x16x32_bf16 v[8:11], v[184:187], v[208:211], v[8:11]
	v_mfma_f32_16x16x32_bf16 v[4:7], v[168:171], v[212:215], 0
	v_mfma_f32_16x16x32_bf16 v[4:7], v[172:175], v[216:219], v[4:7]
	s_barrier
	v_mfma_f32_16x16x32_bf16 v[0:3], v[176:179], v[212:215], 0
	v_mfma_f32_16x16x32_bf16 v[0:3], v[184:187], v[216:219], v[0:3]
	s_setprio 0
	s_branch .Lmid_gemm12
.LBB0_1514:
	ds_read_b128 v[152:155], v149
	ds_read_b128 v[156:159], v149 offset:1024
	ds_read_b128 v[160:163], v149 offset:2048
	ds_read_b128 v[164:167], v149 offset:3072
	ds_read_b128 v[168:171], v150
	ds_read_b128 v[172:175], v150 offset:1024
	ds_read_b128 v[176:179], v150 offset:2048
	ds_read_b128 v[184:187], v150 offset:3072
	s_add_u32 s48, s46, 0x100
	s_addc_u32 s49, s47, 0
	s_cmp_eq_u32 s76, 40
	s_cselect_b32 s53, s9, s49
	s_cselect_b32 s52, s8, s48
	s_cselect_b32 s51, s45, s75
	s_cselect_b32 s50, s44, s74
	v_lshl_add_u64 v[144:145], s[46:47], 0, v[136:137]
	s_add_i32 m0, s57, 0xc000
	ds_read_b128 v[188:191], v151
	ds_read_b128 v[192:195], v151 offset:1024
	ds_read_b128 v[196:199], v151 offset:2048
	ds_read_b128 v[200:203], v151 offset:3072
	ds_read_b128 v[204:207], v151 offset:4096
	ds_read_b128 v[208:211], v151 offset:5120
	ds_read_b128 v[212:215], v151 offset:6144
	ds_read_b128 v[216:219], v151 offset:7168
	global_load_lds_dwordx4 v[144:145], off
	v_lshl_add_u64 v[144:145], s[46:47], 0, v[138:139]
	s_add_i32 m0, s57, 0xe000
	s_nop 0
	global_load_lds_dwordx4 v[144:145], off
	s_waitcnt vmcnt(8)
	s_waitcnt lgkmcnt(0)
	s_barrier
	s_waitcnt lgkmcnt(0)
	v_mfma_f32_16x16x32_bf16 v[124:127], v[152:155], v[188:191], v[124:127]
	v_mfma_f32_16x16x32_bf16 v[124:127], v[156:159], v[192:195], v[124:127]
	s_setprio 1
	v_mfma_f32_16x16x32_bf16 v[120:123], v[160:163], v[188:191], v[120:123]
	v_mfma_f32_16x16x32_bf16 v[120:123], v[164:167], v[192:195], v[120:123]
	v_mfma_f32_16x16x32_bf16 v[116:119], v[152:155], v[196:199], v[116:119]
	v_mfma_f32_16x16x32_bf16 v[116:119], v[156:159], v[200:203], v[116:119]
	v_mfma_f32_16x16x32_bf16 v[108:111], v[160:163], v[196:199], v[108:111]
	v_mfma_f32_16x16x32_bf16 v[108:111], v[164:167], v[200:203], v[108:111]
	v_mfma_f32_16x16x32_bf16 v[100:103], v[152:155], v[204:207], v[100:103]
	v_mfma_f32_16x16x32_bf16 v[100:103], v[156:159], v[208:211], v[100:103]
	v_mfma_f32_16x16x32_bf16 v[92:95], v[160:163], v[204:207], v[92:95]
	v_mfma_f32_16x16x32_bf16 v[92:95], v[164:167], v[208:211], v[92:95]
	v_mfma_f32_16x16x32_bf16 v[84:87], v[152:155], v[212:215], v[84:87]
	v_mfma_f32_16x16x32_bf16 v[84:87], v[156:159], v[216:219], v[84:87]
	v_mfma_f32_16x16x32_bf16 v[76:79], v[160:163], v[212:215], v[76:79]
	v_mfma_f32_16x16x32_bf16 v[76:79], v[164:167], v[216:219], v[76:79]
	v_mfma_f32_16x16x32_bf16 v[112:115], v[168:171], v[188:191], v[112:115]
	v_mfma_f32_16x16x32_bf16 v[112:115], v[172:175], v[192:195], v[112:115]
	v_mfma_f32_16x16x32_bf16 v[104:107], v[176:179], v[188:191], v[104:107]
	v_mfma_f32_16x16x32_bf16 v[104:107], v[184:187], v[192:195], v[104:107]
	v_mfma_f32_16x16x32_bf16 v[96:99], v[168:171], v[196:199], v[96:99]
	v_mfma_f32_16x16x32_bf16 v[96:99], v[172:175], v[200:203], v[96:99]
	v_mfma_f32_16x16x32_bf16 v[88:91], v[176:179], v[196:199], v[88:91]
	v_mfma_f32_16x16x32_bf16 v[88:91], v[184:187], v[200:203], v[88:91]
	v_mfma_f32_16x16x32_bf16 v[80:83], v[168:171], v[204:207], v[80:83]
	v_mfma_f32_16x16x32_bf16 v[80:83], v[172:175], v[208:211], v[80:83]
	v_mfma_f32_16x16x32_bf16 v[72:75], v[176:179], v[204:207], v[72:75]
	v_mfma_f32_16x16x32_bf16 v[72:75], v[184:187], v[208:211], v[72:75]
	v_mfma_f32_16x16x32_bf16 v[68:71], v[168:171], v[212:215], v[68:71]
	v_mfma_f32_16x16x32_bf16 v[68:71], v[172:175], v[216:219], v[68:71]
	s_barrier
	v_mfma_f32_16x16x32_bf16 v[64:67], v[176:179], v[212:215], v[64:67]
	v_mfma_f32_16x16x32_bf16 v[64:67], v[184:187], v[216:219], v[64:67]
	s_setprio 0
	s_add_i32 s46, s64, s56
	v_lshl_add_u64 v[144:145], s[50:51], 0, v[130:131]
	s_mov_b32 m0, s46
	ds_read_b128 v[188:191], v151 offset:16384
	ds_read_b128 v[192:195], v151 offset:17408
	ds_read_b128 v[196:199], v151 offset:18432
	ds_read_b128 v[200:203], v151 offset:19456
	ds_read_b128 v[204:207], v151 offset:20480
	ds_read_b128 v[208:211], v151 offset:21504
	ds_read_b128 v[212:215], v151 offset:22528
	ds_read_b128 v[216:219], v151 offset:23552
	global_load_lds_dwordx4 v[144:145], off
	s_add_i32 m0, s46, 0x2000
	s_add_u32 s46, s50, 0xb0000
	v_lshl_add_u64 v[220:221], s[50:51], 0, v[134:135]
	s_addc_u32 s47, s51, 0
	s_add_i32 s77, s65, s56
	global_load_lds_dwordx4 v[220:221], off
	v_lshl_add_u64 v[222:223], s[46:47], 0, v[130:131]
	s_mov_b32 m0, s77
	v_lshl_add_u64 v[224:225], s[52:53], 0, v[132:133]
	global_load_lds_dwordx4 v[222:223], off
	v_lshl_add_u64 v[222:223], s[46:47], 0, v[134:135]
	s_add_i32 m0, s77, 0x2000
	s_nop 0
	global_load_lds_dwordx4 v[222:223], off
	v_lshl_add_u64 v[222:223], s[52:53], 0, v[128:129]
	s_mov_b32 m0, s57
	s_nop 0
	global_load_lds_dwordx4 v[222:223], off
	s_mov_b32 m0, s58
	s_nop 0
	global_load_lds_dwordx4 v[224:225], off
	s_waitcnt vmcnt(8)
	s_waitcnt lgkmcnt(0)
	s_barrier
	s_waitcnt lgkmcnt(0)
	v_mfma_f32_16x16x32_bf16 v[60:63], v[152:155], v[188:191], v[60:63]
	v_mfma_f32_16x16x32_bf16 v[60:63], v[156:159], v[192:195], v[60:63]
	s_setprio 1
	v_mfma_f32_16x16x32_bf16 v[56:59], v[160:163], v[188:191], v[56:59]
	v_mfma_f32_16x16x32_bf16 v[56:59], v[164:167], v[192:195], v[56:59]
	v_mfma_f32_16x16x32_bf16 v[52:55], v[152:155], v[196:199], v[52:55]
	v_mfma_f32_16x16x32_bf16 v[52:55], v[156:159], v[200:203], v[52:55]
	v_mfma_f32_16x16x32_bf16 v[44:47], v[160:163], v[196:199], v[44:47]
	v_mfma_f32_16x16x32_bf16 v[44:47], v[164:167], v[200:203], v[44:47]
	v_mfma_f32_16x16x32_bf16 v[36:39], v[152:155], v[204:207], v[36:39]
	v_mfma_f32_16x16x32_bf16 v[36:39], v[156:159], v[208:211], v[36:39]
	v_mfma_f32_16x16x32_bf16 v[28:31], v[160:163], v[204:207], v[28:31]
	v_mfma_f32_16x16x32_bf16 v[28:31], v[164:167], v[208:211], v[28:31]
	v_mfma_f32_16x16x32_bf16 v[20:23], v[152:155], v[212:215], v[20:23]
	v_mfma_f32_16x16x32_bf16 v[20:23], v[156:159], v[216:219], v[20:23]
	v_mfma_f32_16x16x32_bf16 v[12:15], v[160:163], v[212:215], v[12:15]
	v_mfma_f32_16x16x32_bf16 v[12:15], v[164:167], v[216:219], v[12:15]
	v_mfma_f32_16x16x32_bf16 v[48:51], v[168:171], v[188:191], v[48:51]
	v_mfma_f32_16x16x32_bf16 v[48:51], v[172:175], v[192:195], v[48:51]
	v_mfma_f32_16x16x32_bf16 v[40:43], v[176:179], v[188:191], v[40:43]
	v_mfma_f32_16x16x32_bf16 v[40:43], v[184:187], v[192:195], v[40:43]
	v_mfma_f32_16x16x32_bf16 v[32:35], v[168:171], v[196:199], v[32:35]
	v_mfma_f32_16x16x32_bf16 v[32:35], v[172:175], v[200:203], v[32:35]
	v_mfma_f32_16x16x32_bf16 v[24:27], v[176:179], v[196:199], v[24:27]
	v_mfma_f32_16x16x32_bf16 v[24:27], v[184:187], v[200:203], v[24:27]
	v_mfma_f32_16x16x32_bf16 v[16:19], v[168:171], v[204:207], v[16:19]
	v_mfma_f32_16x16x32_bf16 v[16:19], v[172:175], v[208:211], v[16:19]
	v_mfma_f32_16x16x32_bf16 v[8:11], v[176:179], v[204:207], v[8:11]
	v_mfma_f32_16x16x32_bf16 v[8:11], v[184:187], v[208:211], v[8:11]
	v_mfma_f32_16x16x32_bf16 v[4:7], v[168:171], v[212:215], v[4:7]
	v_mfma_f32_16x16x32_bf16 v[4:7], v[172:175], v[216:219], v[4:7]
	s_barrier
	v_mfma_f32_16x16x32_bf16 v[0:3], v[176:179], v[212:215], v[0:3]
	v_mfma_f32_16x16x32_bf16 v[0:3], v[184:187], v[216:219], v[0:3]
	s_setprio 0
.Lmid_gemm12:
	s_add_i32 s77, 0, 0x18000
	s_add_i32 s79, 0, 0x1c000
	v_add_u32_e32 v164, s77, v147
	v_add_u32_e32 v181, s79, v147
	ds_read_b128 v[152:155], v164
	ds_read_b128 v[156:159], v164 offset:1024
	ds_read_b128 v[160:163], v164 offset:2048
	ds_read_b128 v[164:167], v164 offset:3072
	ds_read_b128 v[168:171], v181
	ds_read_b128 v[172:175], v181 offset:1024
	ds_read_b128 v[176:179], v181 offset:2048
	ds_read_b128 v[184:187], v181 offset:3072
	s_add_u32 s46, s52, 0xb0000
	s_addc_u32 s47, s53, 0
	s_mov_b32 m0, s59
	v_lshl_add_u64 v[226:227], s[46:47], 0, v[128:129]
	ds_read_b128 v[188:191], v151 offset:32768
	ds_read_b128 v[192:195], v151 offset:33792
	ds_read_b128 v[196:199], v151 offset:34816
	ds_read_b128 v[200:203], v151 offset:35840
	ds_read_b128 v[204:207], v151 offset:36864
	ds_read_b128 v[208:211], v151 offset:37888
	ds_read_b128 v[212:215], v151 offset:38912
	ds_read_b128 v[216:219], v151 offset:39936
	global_load_lds_dwordx4 v[226:227], off
	v_lshl_add_u64 v[226:227], s[46:47], 0, v[132:133]
	s_mov_b32 m0, s60
	s_nop 0
	global_load_lds_dwordx4 v[226:227], off
	s_waitcnt vmcnt(8)
	s_waitcnt lgkmcnt(0)
	s_barrier
	s_waitcnt lgkmcnt(0)
	v_mfma_f32_16x16x32_bf16 v[124:127], v[152:155], v[188:191], v[124:127]
	v_mfma_f32_16x16x32_bf16 v[124:127], v[156:159], v[192:195], v[124:127]
	s_setprio 1
	v_mfma_f32_16x16x32_bf16 v[120:123], v[160:163], v[188:191], v[120:123]
	v_mfma_f32_16x16x32_bf16 v[120:123], v[164:167], v[192:195], v[120:123]
	v_mfma_f32_16x16x32_bf16 v[116:119], v[152:155], v[196:199], v[116:119]
	v_mfma_f32_16x16x32_bf16 v[116:119], v[156:159], v[200:203], v[116:119]
	v_mfma_f32_16x16x32_bf16 v[108:111], v[160:163], v[196:199], v[108:111]
	v_mfma_f32_16x16x32_bf16 v[108:111], v[164:167], v[200:203], v[108:111]
	v_mfma_f32_16x16x32_bf16 v[100:103], v[152:155], v[204:207], v[100:103]
	v_mfma_f32_16x16x32_bf16 v[100:103], v[156:159], v[208:211], v[100:103]
	v_mfma_f32_16x16x32_bf16 v[92:95], v[160:163], v[204:207], v[92:95]
	v_mfma_f32_16x16x32_bf16 v[92:95], v[164:167], v[208:211], v[92:95]
	v_mfma_f32_16x16x32_bf16 v[84:87], v[152:155], v[212:215], v[84:87]
	v_mfma_f32_16x16x32_bf16 v[84:87], v[156:159], v[216:219], v[84:87]
	v_mfma_f32_16x16x32_bf16 v[76:79], v[160:163], v[212:215], v[76:79]
	v_mfma_f32_16x16x32_bf16 v[76:79], v[164:167], v[216:219], v[76:79]
	v_mfma_f32_16x16x32_bf16 v[112:115], v[168:171], v[188:191], v[112:115]
	v_mfma_f32_16x16x32_bf16 v[112:115], v[172:175], v[192:195], v[112:115]
	v_mfma_f32_16x16x32_bf16 v[104:107], v[176:179], v[188:191], v[104:107]
	v_mfma_f32_16x16x32_bf16 v[104:107], v[184:187], v[192:195], v[104:107]
	v_mfma_f32_16x16x32_bf16 v[96:99], v[168:171], v[196:199], v[96:99]
	v_mfma_f32_16x16x32_bf16 v[96:99], v[172:175], v[200:203], v[96:99]
	v_mfma_f32_16x16x32_bf16 v[88:91], v[176:179], v[196:199], v[88:91]
	v_mfma_f32_16x16x32_bf16 v[88:91], v[184:187], v[200:203], v[88:91]
	v_mfma_f32_16x16x32_bf16 v[80:83], v[168:171], v[204:207], v[80:83]
	v_mfma_f32_16x16x32_bf16 v[80:83], v[172:175], v[208:211], v[80:83]
	v_mfma_f32_16x16x32_bf16 v[72:75], v[176:179], v[204:207], v[72:75]
	v_mfma_f32_16x16x32_bf16 v[72:75], v[184:187], v[208:211], v[72:75]
	v_mfma_f32_16x16x32_bf16 v[68:71], v[168:171], v[212:215], v[68:71]
	v_mfma_f32_16x16x32_bf16 v[68:71], v[172:175], v[216:219], v[68:71]
	s_barrier
	v_mfma_f32_16x16x32_bf16 v[64:67], v[176:179], v[212:215], v[64:67]
	v_mfma_f32_16x16x32_bf16 v[64:67], v[184:187], v[216:219], v[64:67]
	s_setprio 0
	s_add_i32 s46, s77, s56
	v_lshl_add_u64 v[144:145], v[144:145], 0, s[10:11]
	s_mov_b32 m0, s46
	ds_read_b128 v[188:191], v151 offset:49152
	ds_read_b128 v[192:195], v151 offset:50176
	ds_read_b128 v[196:199], v151 offset:51200
	ds_read_b128 v[200:203], v151 offset:52224
	ds_read_b128 v[204:207], v151 offset:53248
	ds_read_b128 v[208:211], v151 offset:54272
	ds_read_b128 v[212:215], v151 offset:55296
	ds_read_b128 v[216:219], v151 offset:56320
	global_load_lds_dwordx4 v[144:145], off
	s_add_i32 m0, s46, 0x2000
	s_add_u32 s46, s50, 0xb0080
	v_lshl_add_u64 v[144:145], v[220:221], 0, s[10:11]
	s_addc_u32 s47, s51, 0
	s_add_i32 s50, s79, s56
	global_load_lds_dwordx4 v[144:145], off
	v_lshl_add_u64 v[144:145], s[46:47], 0, v[130:131]
	s_mov_b32 m0, s50
	s_nop 0
	global_load_lds_dwordx4 v[144:145], off
	v_lshl_add_u64 v[144:145], s[46:47], 0, v[134:135]
	s_add_i32 m0, s50, 0x2000
	s_nop 0
	global_load_lds_dwordx4 v[144:145], off
	v_lshl_add_u64 v[144:145], v[222:223], 0, s[10:11]
	s_mov_b32 m0, s62
	s_nop 0
	global_load_lds_dwordx4 v[144:145], off
	v_lshl_add_u64 v[144:145], v[224:225], 0, s[10:11]
	s_mov_b32 m0, s63
	s_nop 0
	global_load_lds_dwordx4 v[144:145], off
	s_waitcnt vmcnt(8)
	s_waitcnt lgkmcnt(0)
	s_barrier
	s_waitcnt lgkmcnt(0)
	v_mfma_f32_16x16x32_bf16 v[60:63], v[152:155], v[188:191], v[60:63]
	v_mfma_f32_16x16x32_bf16 v[60:63], v[156:159], v[192:195], v[60:63]
	s_setprio 1
	v_mfma_f32_16x16x32_bf16 v[56:59], v[160:163], v[188:191], v[56:59]
	v_mfma_f32_16x16x32_bf16 v[56:59], v[164:167], v[192:195], v[56:59]
	v_mfma_f32_16x16x32_bf16 v[52:55], v[152:155], v[196:199], v[52:55]
	v_mfma_f32_16x16x32_bf16 v[52:55], v[156:159], v[200:203], v[52:55]
	v_mfma_f32_16x16x32_bf16 v[44:47], v[160:163], v[196:199], v[44:47]
	v_mfma_f32_16x16x32_bf16 v[44:47], v[164:167], v[200:203], v[44:47]
	v_mfma_f32_16x16x32_bf16 v[36:39], v[152:155], v[204:207], v[36:39]
	v_mfma_f32_16x16x32_bf16 v[36:39], v[156:159], v[208:211], v[36:39]
	v_mfma_f32_16x16x32_bf16 v[28:31], v[160:163], v[204:207], v[28:31]
	v_mfma_f32_16x16x32_bf16 v[28:31], v[164:167], v[208:211], v[28:31]
	v_mfma_f32_16x16x32_bf16 v[20:23], v[152:155], v[212:215], v[20:23]
	v_mfma_f32_16x16x32_bf16 v[20:23], v[156:159], v[216:219], v[20:23]
	v_mfma_f32_16x16x32_bf16 v[12:15], v[160:163], v[212:215], v[12:15]
	v_mfma_f32_16x16x32_bf16 v[12:15], v[164:167], v[216:219], v[12:15]
	v_mfma_f32_16x16x32_bf16 v[48:51], v[168:171], v[188:191], v[48:51]
	v_mfma_f32_16x16x32_bf16 v[48:51], v[172:175], v[192:195], v[48:51]
	v_mfma_f32_16x16x32_bf16 v[40:43], v[176:179], v[188:191], v[40:43]
	v_mfma_f32_16x16x32_bf16 v[40:43], v[184:187], v[192:195], v[40:43]
	v_mfma_f32_16x16x32_bf16 v[32:35], v[168:171], v[196:199], v[32:35]
	v_mfma_f32_16x16x32_bf16 v[32:35], v[172:175], v[200:203], v[32:35]
	v_mfma_f32_16x16x32_bf16 v[24:27], v[176:179], v[196:199], v[24:27]
	v_mfma_f32_16x16x32_bf16 v[24:27], v[184:187], v[200:203], v[24:27]
	v_mfma_f32_16x16x32_bf16 v[16:19], v[168:171], v[204:207], v[16:19]
	v_mfma_f32_16x16x32_bf16 v[16:19], v[172:175], v[208:211], v[16:19]
	v_mfma_f32_16x16x32_bf16 v[8:11], v[176:179], v[204:207], v[8:11]
	v_mfma_f32_16x16x32_bf16 v[8:11], v[184:187], v[208:211], v[8:11]
	v_mfma_f32_16x16x32_bf16 v[4:7], v[168:171], v[212:215], v[4:7]
	v_mfma_f32_16x16x32_bf16 v[4:7], v[172:175], v[216:219], v[4:7]
	s_barrier
	v_mfma_f32_16x16x32_bf16 v[0:3], v[176:179], v[212:215], v[0:3]
	v_mfma_f32_16x16x32_bf16 v[0:3], v[184:187], v[216:219], v[0:3]
	s_setprio 0
	s_add_i32 s76, s76, 2
	s_add_u32 s74, s74, 0x100
	s_addc_u32 s75, s75, 0
	s_cmp_gt_u32 s76, 41
	s_mov_b64 s[46:47], s[48:49]
	s_cbranch_scc0 .LBB0_1514
	s_and_b64 vcc, exec, s[12:13]
	s_cbranch_vccz .LBB0_1517
	s_barrier
